# HNAQP2S(rstd hoist) + GEMM K-loops: per-phase s_setprio flips removed, one static s_setprio 1 for waves 4-7 during the K-loop (reset to 0 for the epilogue)
# baseline (speedup 1.0000x reference)
; __device__ __forceinline__ float row_rstd(const float* ss, int row) { return 1.0f / sqrtf(ss[row] * (1.0f / DM) + 1e-6f); }
; #define PG8_STAGE(bufoff, gbase, voff) do { _Pragma("unroll") for (int _i = 0; _i < 2; ++_i) \
;         __builtin_amdgcn_global_load_lds((const unsigned*)((const char*)(gbase) + (voff)[_i]), (LAS unsigned*)(lds + (bufoff) + ldsw + _i * 8192), 16, 0, 0); } while (0)
; #define PG8_LDA(dst, b, h) do { _Pragma("unroll") for (int m = 0; m < 4; ++m) _Pragma("unroll") for (int k = 0; k < 2; ++k) dst[m][k] = *(const LAS bf16x8*)(lds + PG8_SA(b, h) + aoff + m * 2048 + k * 1024); } while (0)
; #define PG8_LDB(dst, b, h) do { _Pragma("unroll") for (int n = 0; n < 2; ++n) _Pragma("unroll") for (int k = 0; k < 2; ++k) dst[n][k] = *(const LAS bf16x8*)(lds + PG8_SB(b, h) + boff + n * 2048 + k * 1024); } while (0)
; #define PG8_WAIT_V(n) asm volatile("s_waitcnt vmcnt(" #n ")" ::: "memory")
; #define PG8_WAIT_L(n) asm volatile("s_waitcnt lgkmcnt(" #n ")" ::: "memory")
; #define PG8_BAR __builtin_amdgcn_s_barrier()
; #define PG8_SCHED __builtin_amdgcn_sched_barrier(0)
;     __device__ __forceinline__ void operator()(const f32x4 (&acc)[2][2][4][2], const Unit& u, int wr, int wc, int fr, int fq) const {
;     ...
;         const float* bp = bias + (size_t)s * BIAS_N + u.pn * BM + wc * 32 + 8 * fq;
;         const f32x4 ba0 = *(const f32x4*)bp, ba1 = *(const f32x4*)(bp + 4), bb0 = *(const f32x4*)(bp + HALF), bb1 = *(const f32x4*)(bp + HALF + 4);
;         const int lane = fq * 16 + fr;
;         const float rsl0 = row_rstd(ss, u.pm * BM + wr * 64 + lane), rsl1 = row_rstd(ss, u.pm * BM + HALF + wr * 64 + lane);
; template <class Epi, class Sched, bool ALIGN_EPI = false, bool SP2 = false>
; __device__ __forceinline__ void gemm_phase(LAS unsigned char* lds, const Gemm g, const Sched& S, const Epi& E) {
;     ...
;             PG8_LDB(B0, 0, 0); PG8_LDB(B1, 0, 1); PG8_SCHED; PG8_LDA(At, 0, 0); PG8_STAGE(PG8_SA(1, 1), a1 + hstep, voffA);
;             PG8_WAIT_V(8); PG8_WAIT_L(0); PG8_BAR; PG8_MMA(0, 0, At, B0); PG8_MMA(0, 1, At, B1); PG8_BAR; PG8_SCHED;
;             PG8_LDA(At, 0, 1); PG8_STAGE(PG8_SB(0, 0), b2, voffB); PG8_STAGE(PG8_SB(0, 1), b2 + hstepB, voffB); PG8_STAGE(PG8_SA(0, 0), a2, voffA);
;             PG8_WAIT_V(8); PG8_WAIT_L(0); PG8_BAR; PG8_MMA(1, 0, At, B0); PG8_MMA(1, 1, At, B1); PG8_BAR; PG8_SCHED;
.Lpre_up1l0:
	s_lshl_b64 s[98:99], s[98:99], 2
	s_add_u32 s98, s68, s98
	s_addc_u32 s99, s69, s99
	s_lshl_b32 s100, s0, 8
	s_ashr_i32 s101, s100, 31
	s_lshl_b64 s[100:101], s[100:101], 2
	s_add_u32 s98, s98, s100
	s_addc_u32 s99, s99, s101
	s_add_u32 s98, s98, s60
	s_addc_u32 s99, s99, 0
	s_lshl_b32 s100, s2, 8
	s_add_i32 s100, s100, s54
	v_or_b32_e32 v162, s100, v171
	v_ashrrev_i32_e32 v163, 31, v162
	v_lshl_add_u64 v[162:163], v[162:163], 2, s[8:9]
	v_add_u32_e32 v164, s100, v172
	v_ashrrev_i32_e32 v165, 31, v164
	v_lshl_add_u64 v[164:165], v[164:165], 2, s[8:9]
	global_load_dwordx4 v[234:237], v177, s[98:99] offset:16
	global_load_dwordx4 v[238:241], v177, s[98:99]
	global_load_dwordx4 v[242:245], v177, s[98:99] offset:528
	global_load_dwordx4 v[246:249], v177, s[98:99] offset:512
	global_load_dword v250, v[162:163], off
	global_load_dword v251, v[164:165], off
	v_readfirstlane_b32 s98, v0
	s_nop 3
	s_lshr_b32 s98, s98, 6
	s_cmp_ge_u32 s98, 4
	s_cbranch_scc0 .Lprio_188
	s_setprio 1
.Lprio_188:
	ds_read_b128 v[66:69], v174
	ds_read_b128 v[70:73], v174 offset:1024
	ds_read_b128 v[74:77], v174 offset:2048
	ds_read_b128 v[78:81], v174 offset:3072
	ds_read_b128 v[162:165], v175
	ds_read_b128 v[182:185], v175 offset:1024
	ds_read_b128 v[186:189], v175 offset:2048
	ds_read_b128 v[190:193], v175 offset:3072
	s_add_u32 s20, s16, 0xfff80080
	s_addc_u32 s21, s17, -1
	s_cmp_eq_u32 s19, 28
	s_cselect_b32 s53, s3, s21
	s_cselect_b32 s52, s12, s20
	s_cselect_b32 s51, s13, s18
	s_cselect_b32 s50, s14, s15
	v_lshl_add_u64 v[166:167], s[16:17], 0, v[154:155]
	s_add_i32 m0, s33, 0xc000
	ds_read_b128 v[194:197], v176
	ds_read_b128 v[198:201], v176 offset:1024
	ds_read_b128 v[202:205], v176 offset:2048
	ds_read_b128 v[206:209], v176 offset:3072
	ds_read_b128 v[210:213], v176 offset:4096
	ds_read_b128 v[214:217], v176 offset:5120
	ds_read_b128 v[218:221], v176 offset:6144
	ds_read_b128 v[222:225], v176 offset:7168
	global_load_lds_dwordx4 v[166:167], off
	v_lshl_add_u64 v[166:167], s[16:17], 0, v[156:157]
	s_add_i32 m0, s33, 0xe000
	s_nop 0
	global_load_lds_dwordx4 v[166:167], off
	s_waitcnt lgkmcnt(0)
	s_barrier
	s_waitcnt lgkmcnt(0)
	v_mfma_f32_16x16x32_bf16 v[142:145], v[66:69], v[194:197], 0
	v_mfma_f32_16x16x32_bf16 v[138:141], v[74:77], v[194:197], 0
	v_mfma_f32_16x16x32_bf16 v[126:129], v[66:69], v[202:205], 0
	v_mfma_f32_16x16x32_bf16 v[122:125], v[74:77], v[202:205], 0
	v_mfma_f32_16x16x32_bf16 v[110:113], v[66:69], v[210:213], 0
	v_mfma_f32_16x16x32_bf16 v[106:109], v[74:77], v[210:213], 0
	v_mfma_f32_16x16x32_bf16 v[94:97], v[66:69], v[218:221], 0
	v_mfma_f32_16x16x32_bf16 v[90:93], v[74:77], v[218:221], 0
	v_mfma_f32_16x16x32_bf16 v[142:145], v[70:73], v[198:201], v[142:145]
	v_mfma_f32_16x16x32_bf16 v[138:141], v[78:81], v[198:201], v[138:141]
	v_mfma_f32_16x16x32_bf16 v[126:129], v[70:73], v[206:209], v[126:129]
	v_mfma_f32_16x16x32_bf16 v[122:125], v[78:81], v[206:209], v[122:125]
	v_mfma_f32_16x16x32_bf16 v[110:113], v[70:73], v[214:217], v[110:113]
	v_mfma_f32_16x16x32_bf16 v[106:109], v[78:81], v[214:217], v[106:109]
	v_mfma_f32_16x16x32_bf16 v[94:97], v[70:73], v[222:225], v[94:97]
	v_mfma_f32_16x16x32_bf16 v[90:93], v[78:81], v[222:225], v[90:93]
	v_mfma_f32_16x16x32_bf16 v[134:137], v[162:165], v[194:197], 0
	v_mfma_f32_16x16x32_bf16 v[130:133], v[186:189], v[194:197], 0
	v_mfma_f32_16x16x32_bf16 v[118:121], v[162:165], v[202:205], 0
	v_mfma_f32_16x16x32_bf16 v[114:117], v[186:189], v[202:205], 0
	v_mfma_f32_16x16x32_bf16 v[102:105], v[162:165], v[210:213], 0
	v_mfma_f32_16x16x32_bf16 v[98:101], v[186:189], v[210:213], 0
	v_mfma_f32_16x16x32_bf16 v[86:89], v[162:165], v[218:221], 0
	v_mfma_f32_16x16x32_bf16 v[82:85], v[186:189], v[218:221], 0
	v_mfma_f32_16x16x32_bf16 v[134:137], v[182:185], v[198:201], v[134:137]
	v_mfma_f32_16x16x32_bf16 v[130:133], v[190:193], v[198:201], v[130:133]
	v_mfma_f32_16x16x32_bf16 v[118:121], v[182:185], v[206:209], v[118:121]
	v_mfma_f32_16x16x32_bf16 v[114:117], v[190:193], v[206:209], v[114:117]
	v_mfma_f32_16x16x32_bf16 v[102:105], v[182:185], v[214:217], v[102:105]
	v_mfma_f32_16x16x32_bf16 v[98:101], v[190:193], v[214:217], v[98:101]
	v_mfma_f32_16x16x32_bf16 v[86:89], v[182:185], v[222:225], v[86:89]
	v_mfma_f32_16x16x32_bf16 v[82:85], v[190:193], v[222:225], v[82:85]
	s_barrier
	s_add_i32 s20, s57, s27
	v_lshl_add_u64 v[166:167], s[50:51], 0, v[150:151]
	s_mov_b32 m0, s20
	ds_read_b128 v[194:197], v176 offset:16384
	ds_read_b128 v[198:201], v176 offset:17408
	ds_read_b128 v[202:205], v176 offset:18432
	ds_read_b128 v[206:209], v176 offset:19456
	ds_read_b128 v[210:213], v176 offset:20480
	ds_read_b128 v[214:217], v176 offset:21504
	ds_read_b128 v[218:221], v176 offset:22528
	ds_read_b128 v[222:225], v176 offset:23552
	global_load_lds_dwordx4 v[166:167], off
	s_add_i32 m0, s20, 0x2000
	s_add_u32 s20, s50, 0x80000
	v_lshl_add_u64 v[226:227], s[50:51], 0, v[146:147]
	s_addc_u32 s21, s51, 0
	s_add_i32 s22, s58, s27
	global_load_lds_dwordx4 v[226:227], off
	v_lshl_add_u64 v[228:229], s[20:21], 0, v[150:151]
	s_mov_b32 m0, s22
	v_lshl_add_u64 v[230:231], s[52:53], 0, v[148:149]
	global_load_lds_dwordx4 v[228:229], off
	v_lshl_add_u64 v[228:229], s[20:21], 0, v[146:147]
	s_add_i32 m0, s22, 0x2000
	s_nop 0
	global_load_lds_dwordx4 v[228:229], off
	v_lshl_add_u64 v[228:229], s[52:53], 0, v[152:153]
	s_mov_b32 m0, s33
	s_nop 0
	global_load_lds_dwordx4 v[228:229], off
	s_mov_b32 m0, s34
	s_nop 0
	global_load_lds_dwordx4 v[230:231], off
	s_waitcnt lgkmcnt(0)
	s_barrier
; #define PG8_STAGE(bufoff, gbase, voff) do { _Pragma("unroll") for (int _i = 0; _i < 2; ++_i) \
;         __builtin_amdgcn_global_load_lds((const unsigned*)((const char*)(gbase) + (voff)[_i]), (LAS unsigned*)(lds + (bufoff) + ldsw + _i * 8192), 16, 0, 0); } while (0)
; #define PG8_LDA(dst, b, h) do { _Pragma("unroll") for (int m = 0; m < 4; ++m) _Pragma("unroll") for (int k = 0; k < 2; ++k) dst[m][k] = *(const LAS bf16x8*)(lds + PG8_SA(b, h) + aoff + m * 2048 + k * 1024); } while (0)
; #define PG8_LDB(dst, b, h) do { _Pragma("unroll") for (int n = 0; n < 2; ++n) _Pragma("unroll") for (int k = 0; k < 2; ++k) dst[n][k] = *(const LAS bf16x8*)(lds + PG8_SB(b, h) + boff + n * 2048 + k * 1024); } while (0)
; #define PG8_MMA(ai, bj, At, Bt) do { __builtin_amdgcn_s_setprio(1); _Pragma("unroll") for (int m = 0; m < 4; ++m) _Pragma("unroll") for (int n = 0; n < 2; ++n) _Pragma("unroll") for (int k = 0; k < 2; ++k) \
;         acc[ai][bj][m][n] = __builtin_amdgcn_mfma_f32_16x16x32_bf16(Bt[n][k], At[m][k], acc[ai][bj][m][n], 0, 0, 0); __builtin_amdgcn_s_setprio(0); } while (0)
; #define PG8_WAIT_V(n) asm volatile("s_waitcnt vmcnt(" #n ")" ::: "memory")
; #define PG8_WAIT_L(n) asm volatile("s_waitcnt lgkmcnt(" #n ")" ::: "memory")
; #define PG8_BAR __builtin_amdgcn_s_barrier()
; #define PG8_SCHED __builtin_amdgcn_sched_barrier(0)
; template <class Epi, class Sched, bool ALIGN_EPI = false, bool SP2 = false>
; __device__ __forceinline__ void gemm_phase(LAS unsigned char* lds, const Gemm g, const Sched& S, const Epi& E) {
;     ...
;             PG8_WAIT_V(8); PG8_WAIT_L(0); PG8_BAR; PG8_MMA(1, 0, At, B0); PG8_MMA(1, 1, At, B1); PG8_BAR; PG8_SCHED;
;             PG8_LDB(B0, 1, 0); PG8_LDB(B1, 1, 1); PG8_SCHED; PG8_LDA(At, 1, 0); PG8_STAGE(PG8_SA(0, 1), a2 + hstep, voffA);
;             PG8_WAIT_V(8); PG8_WAIT_L(0); PG8_BAR; PG8_MMA(0, 0, At, B0); PG8_MMA(0, 1, At, B1); PG8_BAR; PG8_SCHED;
	s_waitcnt lgkmcnt(0)
	v_mfma_f32_16x16x32_bf16 v[62:65], v[66:69], v[194:197], 0
	v_mfma_f32_16x16x32_bf16 v[58:61], v[74:77], v[194:197], 0
	v_mfma_f32_16x16x32_bf16 v[46:49], v[66:69], v[202:205], 0
	v_mfma_f32_16x16x32_bf16 v[42:45], v[74:77], v[202:205], 0
	v_mfma_f32_16x16x32_bf16 v[30:33], v[66:69], v[210:213], 0
	v_mfma_f32_16x16x32_bf16 v[26:29], v[74:77], v[210:213], 0
	v_mfma_f32_16x16x32_bf16 v[14:17], v[66:69], v[218:221], 0
	v_mfma_f32_16x16x32_bf16 v[10:13], v[74:77], v[218:221], 0
	v_mfma_f32_16x16x32_bf16 v[62:65], v[70:73], v[198:201], v[62:65]
	v_mfma_f32_16x16x32_bf16 v[58:61], v[78:81], v[198:201], v[58:61]
	v_mfma_f32_16x16x32_bf16 v[46:49], v[70:73], v[206:209], v[46:49]
	v_mfma_f32_16x16x32_bf16 v[42:45], v[78:81], v[206:209], v[42:45]
	v_mfma_f32_16x16x32_bf16 v[30:33], v[70:73], v[214:217], v[30:33]
	v_mfma_f32_16x16x32_bf16 v[26:29], v[78:81], v[214:217], v[26:29]
	v_mfma_f32_16x16x32_bf16 v[14:17], v[70:73], v[222:225], v[14:17]
	v_mfma_f32_16x16x32_bf16 v[10:13], v[78:81], v[222:225], v[10:13]
	v_mfma_f32_16x16x32_bf16 v[54:57], v[162:165], v[194:197], 0
	v_mfma_f32_16x16x32_bf16 v[50:53], v[186:189], v[194:197], 0
	v_mfma_f32_16x16x32_bf16 v[38:41], v[162:165], v[202:205], 0
	v_mfma_f32_16x16x32_bf16 v[34:37], v[186:189], v[202:205], 0
	v_mfma_f32_16x16x32_bf16 v[22:25], v[162:165], v[210:213], 0
	v_mfma_f32_16x16x32_bf16 v[18:21], v[186:189], v[210:213], 0
	v_mfma_f32_16x16x32_bf16 v[6:9], v[162:165], v[218:221], 0
	v_mfma_f32_16x16x32_bf16 v[2:5], v[186:189], v[218:221], 0
	v_mfma_f32_16x16x32_bf16 v[54:57], v[182:185], v[198:201], v[54:57]
	v_mfma_f32_16x16x32_bf16 v[50:53], v[190:193], v[198:201], v[50:53]
	v_mfma_f32_16x16x32_bf16 v[38:41], v[182:185], v[206:209], v[38:41]
	v_mfma_f32_16x16x32_bf16 v[34:37], v[190:193], v[206:209], v[34:37]
	v_mfma_f32_16x16x32_bf16 v[22:25], v[182:185], v[214:217], v[22:25]
	v_mfma_f32_16x16x32_bf16 v[18:21], v[190:193], v[214:217], v[18:21]
	v_mfma_f32_16x16x32_bf16 v[6:9], v[182:185], v[222:225], v[6:9]
	v_mfma_f32_16x16x32_bf16 v[2:5], v[190:193], v[222:225], v[2:5]
	s_barrier
	s_add_i32 s22, 0, 0x18000
	s_add_i32 s23, 0, 0x1c000
	v_add_u32_e32 v78, s22, v170
	v_add_u32_e32 v168, s23, v170
	ds_read_b128 v[66:69], v78
	ds_read_b128 v[70:73], v78 offset:1024
	ds_read_b128 v[74:77], v78 offset:2048
	ds_read_b128 v[78:81], v78 offset:3072
	ds_read_b128 v[162:165], v168
	ds_read_b128 v[182:185], v168 offset:1024
	ds_read_b128 v[186:189], v168 offset:2048
	ds_read_b128 v[190:193], v168 offset:3072
	s_add_u32 s20, s52, 0x80000
	s_addc_u32 s21, s53, 0
	s_mov_b32 m0, s35
	v_lshl_add_u64 v[232:233], s[20:21], 0, v[152:153]
	ds_read_b128 v[194:197], v176 offset:32768
	ds_read_b128 v[198:201], v176 offset:33792
	ds_read_b128 v[202:205], v176 offset:34816
	ds_read_b128 v[206:209], v176 offset:35840
	ds_read_b128 v[210:213], v176 offset:36864
	ds_read_b128 v[214:217], v176 offset:37888
	ds_read_b128 v[218:221], v176 offset:38912
	ds_read_b128 v[222:225], v176 offset:39936
	global_load_lds_dwordx4 v[232:233], off
	v_lshl_add_u64 v[232:233], s[20:21], 0, v[148:149]
	s_mov_b32 m0, s36
	s_nop 0
	global_load_lds_dwordx4 v[232:233], off
	s_waitcnt vmcnt(8)
	s_waitcnt lgkmcnt(0)
	s_barrier
	s_waitcnt lgkmcnt(0)
	v_mfma_f32_16x16x32_bf16 v[142:145], v[66:69], v[194:197], v[142:145]
	v_mfma_f32_16x16x32_bf16 v[138:141], v[74:77], v[194:197], v[138:141]
	v_mfma_f32_16x16x32_bf16 v[126:129], v[66:69], v[202:205], v[126:129]
	v_mfma_f32_16x16x32_bf16 v[122:125], v[74:77], v[202:205], v[122:125]
	v_mfma_f32_16x16x32_bf16 v[110:113], v[66:69], v[210:213], v[110:113]
	v_mfma_f32_16x16x32_bf16 v[106:109], v[74:77], v[210:213], v[106:109]
	v_mfma_f32_16x16x32_bf16 v[94:97], v[66:69], v[218:221], v[94:97]
	v_mfma_f32_16x16x32_bf16 v[90:93], v[74:77], v[218:221], v[90:93]
	v_mfma_f32_16x16x32_bf16 v[142:145], v[70:73], v[198:201], v[142:145]
	v_mfma_f32_16x16x32_bf16 v[138:141], v[78:81], v[198:201], v[138:141]
	v_mfma_f32_16x16x32_bf16 v[126:129], v[70:73], v[206:209], v[126:129]
	v_mfma_f32_16x16x32_bf16 v[122:125], v[78:81], v[206:209], v[122:125]
	v_mfma_f32_16x16x32_bf16 v[110:113], v[70:73], v[214:217], v[110:113]
	v_mfma_f32_16x16x32_bf16 v[106:109], v[78:81], v[214:217], v[106:109]
	v_mfma_f32_16x16x32_bf16 v[94:97], v[70:73], v[222:225], v[94:97]
	v_mfma_f32_16x16x32_bf16 v[90:93], v[78:81], v[222:225], v[90:93]
	v_mfma_f32_16x16x32_bf16 v[134:137], v[162:165], v[194:197], v[134:137]
	v_mfma_f32_16x16x32_bf16 v[130:133], v[186:189], v[194:197], v[130:133]
	v_mfma_f32_16x16x32_bf16 v[118:121], v[162:165], v[202:205], v[118:121]
	v_mfma_f32_16x16x32_bf16 v[114:117], v[186:189], v[202:205], v[114:117]
	v_mfma_f32_16x16x32_bf16 v[102:105], v[162:165], v[210:213], v[102:105]
	v_mfma_f32_16x16x32_bf16 v[98:101], v[186:189], v[210:213], v[98:101]
	v_mfma_f32_16x16x32_bf16 v[86:89], v[162:165], v[218:221], v[86:89]
	v_mfma_f32_16x16x32_bf16 v[82:85], v[186:189], v[218:221], v[82:85]
	v_mfma_f32_16x16x32_bf16 v[134:137], v[182:185], v[198:201], v[134:137]
	v_mfma_f32_16x16x32_bf16 v[130:133], v[190:193], v[198:201], v[130:133]
	v_mfma_f32_16x16x32_bf16 v[118:121], v[182:185], v[206:209], v[118:121]
	v_mfma_f32_16x16x32_bf16 v[114:117], v[190:193], v[206:209], v[114:117]
	v_mfma_f32_16x16x32_bf16 v[102:105], v[182:185], v[214:217], v[102:105]
	v_mfma_f32_16x16x32_bf16 v[98:101], v[190:193], v[214:217], v[98:101]
	v_mfma_f32_16x16x32_bf16 v[86:89], v[182:185], v[222:225], v[86:89]
	v_mfma_f32_16x16x32_bf16 v[82:85], v[190:193], v[222:225], v[82:85]
	s_barrier
; #define PG8_STAGE(bufoff, gbase, voff) do { _Pragma("unroll") for (int _i = 0; _i < 2; ++_i) \
;         __builtin_amdgcn_global_load_lds((const unsigned*)((const char*)(gbase) + (voff)[_i]), (LAS unsigned*)(lds + (bufoff) + ldsw + _i * 8192), 16, 0, 0); } while (0)
; #define PG8_LDA(dst, b, h) do { _Pragma("unroll") for (int m = 0; m < 4; ++m) _Pragma("unroll") for (int k = 0; k < 2; ++k) dst[m][k] = *(const LAS bf16x8*)(lds + PG8_SA(b, h) + aoff + m * 2048 + k * 1024); } while (0)
; #define PG8_LDB(dst, b, h) do { _Pragma("unroll") for (int n = 0; n < 2; ++n) _Pragma("unroll") for (int k = 0; k < 2; ++k) dst[n][k] = *(const LAS bf16x8*)(lds + PG8_SB(b, h) + boff + n * 2048 + k * 1024); } while (0)
; #define PG8_MMA(ai, bj, At, Bt) do { __builtin_amdgcn_s_setprio(1); _Pragma("unroll") for (int m = 0; m < 4; ++m) _Pragma("unroll") for (int n = 0; n < 2; ++n) _Pragma("unroll") for (int k = 0; k < 2; ++k) \
;         acc[ai][bj][m][n] = __builtin_amdgcn_mfma_f32_16x16x32_bf16(Bt[n][k], At[m][k], acc[ai][bj][m][n], 0, 0, 0); __builtin_amdgcn_s_setprio(0); } while (0)
; #define PG8_WAIT_V(n) asm volatile("s_waitcnt vmcnt(" #n ")" ::: "memory")
; #define PG8_WAIT_L(n) asm volatile("s_waitcnt lgkmcnt(" #n ")" ::: "memory")
; #define PG8_BAR __builtin_amdgcn_s_barrier()
; #define PG8_SCHED __builtin_amdgcn_sched_barrier(0)
; template <class Epi, class Sched, bool ALIGN_EPI = false, bool SP2 = false>
; __device__ __forceinline__ void gemm_phase(LAS unsigned char* lds, const Gemm g, const Sched& S, const Epi& E) {
;     ...
;             PG8_LDB(B0, 0, 0); PG8_LDB(B1, 0, 1); PG8_SCHED; PG8_LDA(At, 0, 0); PG8_STAGE(PG8_SA(1, 1), a1 + hstep, voffA);
;             PG8_WAIT_V(8); PG8_WAIT_L(0); PG8_BAR; PG8_MMA(0, 0, At, B0); PG8_MMA(0, 1, At, B1); PG8_BAR; PG8_SCHED;
;     ...
;             PG8_LDA(At, 1, 1); PG8_STAGE(PG8_SB(1, 0), b3, voffB); PG8_STAGE(PG8_SB(1, 1), b3 + hstepB, voffB); PG8_STAGE(PG8_SA(1, 0), a3, voffA);
;             PG8_WAIT_V(8); PG8_WAIT_L(0); PG8_BAR; PG8_MMA(1, 0, At, B0); PG8_MMA(1, 1, At, B1); PG8_BAR; PG8_SCHED;
	s_add_i32 s20, s22, s27
	v_lshl_add_u64 v[166:167], v[166:167], 0, s[10:11]
	s_mov_b32 m0, s20
	ds_read_b128 v[194:197], v176 offset:49152
	ds_read_b128 v[198:201], v176 offset:50176
	ds_read_b128 v[202:205], v176 offset:51200
	ds_read_b128 v[206:209], v176 offset:52224
	ds_read_b128 v[210:213], v176 offset:53248
	ds_read_b128 v[214:217], v176 offset:54272
	ds_read_b128 v[218:221], v176 offset:55296
	ds_read_b128 v[222:225], v176 offset:56320
	global_load_lds_dwordx4 v[166:167], off
	s_add_i32 m0, s20, 0x2000
	s_add_u32 s20, s50, 0x80080
	v_lshl_add_u64 v[166:167], v[226:227], 0, s[10:11]
	s_addc_u32 s21, s51, 0
	s_add_i32 s22, s23, s27
	global_load_lds_dwordx4 v[166:167], off
	v_lshl_add_u64 v[166:167], s[20:21], 0, v[150:151]
	s_mov_b32 m0, s22
	s_nop 0
	global_load_lds_dwordx4 v[166:167], off
	v_lshl_add_u64 v[166:167], s[20:21], 0, v[146:147]
	s_add_i32 m0, s22, 0x2000
	s_nop 0
	global_load_lds_dwordx4 v[166:167], off
	v_lshl_add_u64 v[166:167], v[228:229], 0, s[10:11]
	s_mov_b32 m0, s55
	s_nop 0
	global_load_lds_dwordx4 v[166:167], off
	v_lshl_add_u64 v[166:167], v[230:231], 0, s[10:11]
	s_mov_b32 m0, s56
	s_nop 0
	global_load_lds_dwordx4 v[166:167], off
	s_waitcnt vmcnt(8)
	s_waitcnt lgkmcnt(0)
	s_barrier
	s_waitcnt lgkmcnt(0)
	v_mfma_f32_16x16x32_bf16 v[62:65], v[66:69], v[194:197], v[62:65]
	v_mfma_f32_16x16x32_bf16 v[58:61], v[74:77], v[194:197], v[58:61]
	v_mfma_f32_16x16x32_bf16 v[46:49], v[66:69], v[202:205], v[46:49]
	v_mfma_f32_16x16x32_bf16 v[42:45], v[74:77], v[202:205], v[42:45]
	v_mfma_f32_16x16x32_bf16 v[30:33], v[66:69], v[210:213], v[30:33]
	v_mfma_f32_16x16x32_bf16 v[26:29], v[74:77], v[210:213], v[26:29]
	v_mfma_f32_16x16x32_bf16 v[14:17], v[66:69], v[218:221], v[14:17]
	v_mfma_f32_16x16x32_bf16 v[10:13], v[74:77], v[218:221], v[10:13]
	v_mfma_f32_16x16x32_bf16 v[62:65], v[70:73], v[198:201], v[62:65]
	v_mfma_f32_16x16x32_bf16 v[58:61], v[78:81], v[198:201], v[58:61]
	v_mfma_f32_16x16x32_bf16 v[46:49], v[70:73], v[206:209], v[46:49]
	v_mfma_f32_16x16x32_bf16 v[42:45], v[78:81], v[206:209], v[42:45]
	v_mfma_f32_16x16x32_bf16 v[30:33], v[70:73], v[214:217], v[30:33]
	v_mfma_f32_16x16x32_bf16 v[26:29], v[78:81], v[214:217], v[26:29]
	v_mfma_f32_16x16x32_bf16 v[14:17], v[70:73], v[222:225], v[14:17]
	v_mfma_f32_16x16x32_bf16 v[10:13], v[78:81], v[222:225], v[10:13]
	v_mfma_f32_16x16x32_bf16 v[54:57], v[162:165], v[194:197], v[54:57]
	v_mfma_f32_16x16x32_bf16 v[50:53], v[186:189], v[194:197], v[50:53]
	v_mfma_f32_16x16x32_bf16 v[38:41], v[162:165], v[202:205], v[38:41]
	v_mfma_f32_16x16x32_bf16 v[34:37], v[186:189], v[202:205], v[34:37]
	v_mfma_f32_16x16x32_bf16 v[22:25], v[162:165], v[210:213], v[22:25]
	v_mfma_f32_16x16x32_bf16 v[18:21], v[186:189], v[210:213], v[18:21]
	v_mfma_f32_16x16x32_bf16 v[6:9], v[162:165], v[218:221], v[6:9]
	v_mfma_f32_16x16x32_bf16 v[2:5], v[186:189], v[218:221], v[2:5]
	v_mfma_f32_16x16x32_bf16 v[54:57], v[182:185], v[198:201], v[54:57]
	v_mfma_f32_16x16x32_bf16 v[50:53], v[190:193], v[198:201], v[50:53]
	v_mfma_f32_16x16x32_bf16 v[38:41], v[182:185], v[206:209], v[38:41]
	v_mfma_f32_16x16x32_bf16 v[34:37], v[190:193], v[206:209], v[34:37]
	v_mfma_f32_16x16x32_bf16 v[22:25], v[182:185], v[214:217], v[22:25]
	v_mfma_f32_16x16x32_bf16 v[18:21], v[190:193], v[214:217], v[18:21]
	v_mfma_f32_16x16x32_bf16 v[6:9], v[182:185], v[222:225], v[6:9]
	v_mfma_f32_16x16x32_bf16 v[2:5], v[190:193], v[222:225], v[2:5]
	s_barrier
	s_add_i32 s19, s19, 2
	s_add_u32 s16, s16, 0x100
	s_addc_u32 s17, s17, 0
	s_add_u32 s15, s15, 0x100
	s_addc_u32 s18, s18, 0
	s_cmp_gt_u32 s19, 29
.LBB0_188:
	ds_read_b128 v[66:69], v174
	ds_read_b128 v[70:73], v174 offset:1024
	ds_read_b128 v[74:77], v174 offset:2048
	ds_read_b128 v[78:81], v174 offset:3072
	ds_read_b128 v[162:165], v175
	ds_read_b128 v[182:185], v175 offset:1024
	ds_read_b128 v[186:189], v175 offset:2048
	ds_read_b128 v[190:193], v175 offset:3072
	s_add_u32 s20, s16, 0xfff80080
	s_addc_u32 s21, s17, -1
	s_cmp_eq_u32 s19, 28
	s_cselect_b32 s53, s3, s21
	s_cselect_b32 s52, s12, s20
	s_cselect_b32 s51, s13, s18
	s_cselect_b32 s50, s14, s15
	v_lshl_add_u64 v[166:167], s[16:17], 0, v[154:155]
	s_add_i32 m0, s33, 0xc000
	ds_read_b128 v[194:197], v176
	ds_read_b128 v[198:201], v176 offset:1024
	ds_read_b128 v[202:205], v176 offset:2048
	ds_read_b128 v[206:209], v176 offset:3072
	ds_read_b128 v[210:213], v176 offset:4096
	ds_read_b128 v[214:217], v176 offset:5120
	ds_read_b128 v[218:221], v176 offset:6144
	ds_read_b128 v[222:225], v176 offset:7168
	global_load_lds_dwordx4 v[166:167], off
	v_lshl_add_u64 v[166:167], s[16:17], 0, v[156:157]
	s_add_i32 m0, s33, 0xe000
	s_nop 0
	global_load_lds_dwordx4 v[166:167], off
	s_waitcnt vmcnt(8)
	s_waitcnt lgkmcnt(0)
	s_barrier
; #define PG8_STAGE(bufoff, gbase, voff) do { _Pragma("unroll") for (int _i = 0; _i < 2; ++_i) \
;         __builtin_amdgcn_global_load_lds((const unsigned*)((const char*)(gbase) + (voff)[_i]), (LAS unsigned*)(lds + (bufoff) + ldsw + _i * 8192), 16, 0, 0); } while (0)
; #define PG8_LDA(dst, b, h) do { _Pragma("unroll") for (int m = 0; m < 4; ++m) _Pragma("unroll") for (int k = 0; k < 2; ++k) dst[m][k] = *(const LAS bf16x8*)(lds + PG8_SA(b, h) + aoff + m * 2048 + k * 1024); } while (0)
; #define PG8_MMA(ai, bj, At, Bt) do { __builtin_amdgcn_s_setprio(1); _Pragma("unroll") for (int m = 0; m < 4; ++m) _Pragma("unroll") for (int n = 0; n < 2; ++n) _Pragma("unroll") for (int k = 0; k < 2; ++k) \
;         acc[ai][bj][m][n] = __builtin_amdgcn_mfma_f32_16x16x32_bf16(Bt[n][k], At[m][k], acc[ai][bj][m][n], 0, 0, 0); __builtin_amdgcn_s_setprio(0); } while (0)
; #define PG8_WAIT_V(n) asm volatile("s_waitcnt vmcnt(" #n ")" ::: "memory")
; #define PG8_WAIT_L(n) asm volatile("s_waitcnt lgkmcnt(" #n ")" ::: "memory")
; #define PG8_BAR __builtin_amdgcn_s_barrier()
; #define PG8_SCHED __builtin_amdgcn_sched_barrier(0)
; template <class Epi, class Sched, bool ALIGN_EPI = false, bool SP2 = false>
; __device__ __forceinline__ void gemm_phase(LAS unsigned char* lds, const Gemm g, const Sched& S, const Epi& E) {
;     ...
;             PG8_WAIT_V(8); PG8_WAIT_L(0); PG8_BAR; PG8_MMA(0, 0, At, B0); PG8_MMA(0, 1, At, B1); PG8_BAR; PG8_SCHED;
;             PG8_LDA(At, 0, 1); PG8_STAGE(PG8_SB(0, 0), b2, voffB); PG8_STAGE(PG8_SB(0, 1), b2 + hstepB, voffB); PG8_STAGE(PG8_SA(0, 0), a2, voffA);
;             PG8_WAIT_V(8); PG8_WAIT_L(0); PG8_BAR; PG8_MMA(1, 0, At, B0); PG8_MMA(1, 1, At, B1); PG8_BAR; PG8_SCHED;
	s_waitcnt lgkmcnt(0)
	v_mfma_f32_16x16x32_bf16 v[142:145], v[66:69], v[194:197], v[142:145]
	v_mfma_f32_16x16x32_bf16 v[138:141], v[74:77], v[194:197], v[138:141]
	v_mfma_f32_16x16x32_bf16 v[126:129], v[66:69], v[202:205], v[126:129]
	v_mfma_f32_16x16x32_bf16 v[122:125], v[74:77], v[202:205], v[122:125]
	v_mfma_f32_16x16x32_bf16 v[110:113], v[66:69], v[210:213], v[110:113]
	v_mfma_f32_16x16x32_bf16 v[106:109], v[74:77], v[210:213], v[106:109]
	v_mfma_f32_16x16x32_bf16 v[94:97], v[66:69], v[218:221], v[94:97]
	v_mfma_f32_16x16x32_bf16 v[90:93], v[74:77], v[218:221], v[90:93]
	v_mfma_f32_16x16x32_bf16 v[142:145], v[70:73], v[198:201], v[142:145]
	v_mfma_f32_16x16x32_bf16 v[138:141], v[78:81], v[198:201], v[138:141]
	v_mfma_f32_16x16x32_bf16 v[126:129], v[70:73], v[206:209], v[126:129]
	v_mfma_f32_16x16x32_bf16 v[122:125], v[78:81], v[206:209], v[122:125]
	v_mfma_f32_16x16x32_bf16 v[110:113], v[70:73], v[214:217], v[110:113]
	v_mfma_f32_16x16x32_bf16 v[106:109], v[78:81], v[214:217], v[106:109]
	v_mfma_f32_16x16x32_bf16 v[94:97], v[70:73], v[222:225], v[94:97]
	v_mfma_f32_16x16x32_bf16 v[90:93], v[78:81], v[222:225], v[90:93]
	v_mfma_f32_16x16x32_bf16 v[134:137], v[162:165], v[194:197], v[134:137]
	v_mfma_f32_16x16x32_bf16 v[130:133], v[186:189], v[194:197], v[130:133]
	v_mfma_f32_16x16x32_bf16 v[118:121], v[162:165], v[202:205], v[118:121]
	v_mfma_f32_16x16x32_bf16 v[114:117], v[186:189], v[202:205], v[114:117]
	v_mfma_f32_16x16x32_bf16 v[102:105], v[162:165], v[210:213], v[102:105]
	v_mfma_f32_16x16x32_bf16 v[98:101], v[186:189], v[210:213], v[98:101]
	v_mfma_f32_16x16x32_bf16 v[86:89], v[162:165], v[218:221], v[86:89]
	v_mfma_f32_16x16x32_bf16 v[82:85], v[186:189], v[218:221], v[82:85]
	v_mfma_f32_16x16x32_bf16 v[134:137], v[182:185], v[198:201], v[134:137]
	v_mfma_f32_16x16x32_bf16 v[130:133], v[190:193], v[198:201], v[130:133]
	v_mfma_f32_16x16x32_bf16 v[118:121], v[182:185], v[206:209], v[118:121]
	v_mfma_f32_16x16x32_bf16 v[114:117], v[190:193], v[206:209], v[114:117]
	v_mfma_f32_16x16x32_bf16 v[102:105], v[182:185], v[214:217], v[102:105]
	v_mfma_f32_16x16x32_bf16 v[98:101], v[190:193], v[214:217], v[98:101]
	v_mfma_f32_16x16x32_bf16 v[86:89], v[182:185], v[222:225], v[86:89]
	v_mfma_f32_16x16x32_bf16 v[82:85], v[190:193], v[222:225], v[82:85]
	s_barrier
	s_add_i32 s20, s57, s27
	v_lshl_add_u64 v[166:167], s[50:51], 0, v[150:151]
	s_mov_b32 m0, s20
	ds_read_b128 v[194:197], v176 offset:16384
	ds_read_b128 v[198:201], v176 offset:17408
	ds_read_b128 v[202:205], v176 offset:18432
	ds_read_b128 v[206:209], v176 offset:19456
	ds_read_b128 v[210:213], v176 offset:20480
	ds_read_b128 v[214:217], v176 offset:21504
	ds_read_b128 v[218:221], v176 offset:22528
	ds_read_b128 v[222:225], v176 offset:23552
	global_load_lds_dwordx4 v[166:167], off
	s_add_i32 m0, s20, 0x2000
	s_add_u32 s20, s50, 0x80000
	v_lshl_add_u64 v[226:227], s[50:51], 0, v[146:147]
	s_addc_u32 s21, s51, 0
	s_add_i32 s22, s58, s27
	global_load_lds_dwordx4 v[226:227], off
	v_lshl_add_u64 v[228:229], s[20:21], 0, v[150:151]
	s_mov_b32 m0, s22
	v_lshl_add_u64 v[230:231], s[52:53], 0, v[148:149]
	global_load_lds_dwordx4 v[228:229], off
	v_lshl_add_u64 v[228:229], s[20:21], 0, v[146:147]
	s_add_i32 m0, s22, 0x2000
	s_nop 0
	global_load_lds_dwordx4 v[228:229], off
	v_lshl_add_u64 v[228:229], s[52:53], 0, v[152:153]
	s_mov_b32 m0, s33
	s_nop 0
	global_load_lds_dwordx4 v[228:229], off
	s_mov_b32 m0, s34
	s_nop 0
	global_load_lds_dwordx4 v[230:231], off
	s_waitcnt vmcnt(8)
	s_waitcnt lgkmcnt(0)
	s_barrier
	s_waitcnt lgkmcnt(0)
	v_mfma_f32_16x16x32_bf16 v[62:65], v[66:69], v[194:197], v[62:65]
	v_mfma_f32_16x16x32_bf16 v[58:61], v[74:77], v[194:197], v[58:61]
	v_mfma_f32_16x16x32_bf16 v[46:49], v[66:69], v[202:205], v[46:49]
	v_mfma_f32_16x16x32_bf16 v[42:45], v[74:77], v[202:205], v[42:45]
	v_mfma_f32_16x16x32_bf16 v[30:33], v[66:69], v[210:213], v[30:33]
	v_mfma_f32_16x16x32_bf16 v[26:29], v[74:77], v[210:213], v[26:29]
	v_mfma_f32_16x16x32_bf16 v[14:17], v[66:69], v[218:221], v[14:17]
	v_mfma_f32_16x16x32_bf16 v[10:13], v[74:77], v[218:221], v[10:13]
	v_mfma_f32_16x16x32_bf16 v[62:65], v[70:73], v[198:201], v[62:65]
	v_mfma_f32_16x16x32_bf16 v[58:61], v[78:81], v[198:201], v[58:61]
	v_mfma_f32_16x16x32_bf16 v[46:49], v[70:73], v[206:209], v[46:49]
	v_mfma_f32_16x16x32_bf16 v[42:45], v[78:81], v[206:209], v[42:45]
	v_mfma_f32_16x16x32_bf16 v[30:33], v[70:73], v[214:217], v[30:33]
	v_mfma_f32_16x16x32_bf16 v[26:29], v[78:81], v[214:217], v[26:29]
	v_mfma_f32_16x16x32_bf16 v[14:17], v[70:73], v[222:225], v[14:17]
	v_mfma_f32_16x16x32_bf16 v[10:13], v[78:81], v[222:225], v[10:13]
	v_mfma_f32_16x16x32_bf16 v[54:57], v[162:165], v[194:197], v[54:57]
	v_mfma_f32_16x16x32_bf16 v[50:53], v[186:189], v[194:197], v[50:53]
	v_mfma_f32_16x16x32_bf16 v[38:41], v[162:165], v[202:205], v[38:41]
	v_mfma_f32_16x16x32_bf16 v[34:37], v[186:189], v[202:205], v[34:37]
	v_mfma_f32_16x16x32_bf16 v[22:25], v[162:165], v[210:213], v[22:25]
	v_mfma_f32_16x16x32_bf16 v[18:21], v[186:189], v[210:213], v[18:21]
	v_mfma_f32_16x16x32_bf16 v[6:9], v[162:165], v[218:221], v[6:9]
	v_mfma_f32_16x16x32_bf16 v[2:5], v[186:189], v[218:221], v[2:5]
	v_mfma_f32_16x16x32_bf16 v[54:57], v[182:185], v[198:201], v[54:57]
	v_mfma_f32_16x16x32_bf16 v[50:53], v[190:193], v[198:201], v[50:53]
	v_mfma_f32_16x16x32_bf16 v[38:41], v[182:185], v[206:209], v[38:41]
	v_mfma_f32_16x16x32_bf16 v[34:37], v[190:193], v[206:209], v[34:37]
	v_mfma_f32_16x16x32_bf16 v[22:25], v[182:185], v[214:217], v[22:25]
	v_mfma_f32_16x16x32_bf16 v[18:21], v[190:193], v[214:217], v[18:21]
	v_mfma_f32_16x16x32_bf16 v[6:9], v[182:185], v[222:225], v[6:9]
	v_mfma_f32_16x16x32_bf16 v[2:5], v[190:193], v[222:225], v[2:5]
	s_barrier
; #define PG8_STAGE(bufoff, gbase, voff) do { _Pragma("unroll") for (int _i = 0; _i < 2; ++_i) \
;         __builtin_amdgcn_global_load_lds((const unsigned*)((const char*)(gbase) + (voff)[_i]), (LAS unsigned*)(lds + (bufoff) + ldsw + _i * 8192), 16, 0, 0); } while (0)
; #define PG8_LDA(dst, b, h) do { _Pragma("unroll") for (int m = 0; m < 4; ++m) _Pragma("unroll") for (int k = 0; k < 2; ++k) dst[m][k] = *(const LAS bf16x8*)(lds + PG8_SA(b, h) + aoff + m * 2048 + k * 1024); } while (0)
; #define PG8_LDB(dst, b, h) do { _Pragma("unroll") for (int n = 0; n < 2; ++n) _Pragma("unroll") for (int k = 0; k < 2; ++k) dst[n][k] = *(const LAS bf16x8*)(lds + PG8_SB(b, h) + boff + n * 2048 + k * 1024); } while (0)
; #define PG8_MMA(ai, bj, At, Bt) do { __builtin_amdgcn_s_setprio(1); _Pragma("unroll") for (int m = 0; m < 4; ++m) _Pragma("unroll") for (int n = 0; n < 2; ++n) _Pragma("unroll") for (int k = 0; k < 2; ++k) \
;         acc[ai][bj][m][n] = __builtin_amdgcn_mfma_f32_16x16x32_bf16(Bt[n][k], At[m][k], acc[ai][bj][m][n], 0, 0, 0); __builtin_amdgcn_s_setprio(0); } while (0)
; #define PG8_WAIT_V(n) asm volatile("s_waitcnt vmcnt(" #n ")" ::: "memory")
; #define PG8_WAIT_L(n) asm volatile("s_waitcnt lgkmcnt(" #n ")" ::: "memory")
; #define PG8_BAR __builtin_amdgcn_s_barrier()
; #define PG8_SCHED __builtin_amdgcn_sched_barrier(0)
; template <class Epi, class Sched, bool ALIGN_EPI = false, bool SP2 = false>
; __device__ __forceinline__ void gemm_phase(LAS unsigned char* lds, const Gemm g, const Sched& S, const Epi& E) {
;     ...
;             PG8_LDB(B0, 1, 0); PG8_LDB(B1, 1, 1); PG8_SCHED; PG8_LDA(At, 1, 0); PG8_STAGE(PG8_SA(0, 1), a2 + hstep, voffA);
;             PG8_WAIT_V(8); PG8_WAIT_L(0); PG8_BAR; PG8_MMA(0, 0, At, B0); PG8_MMA(0, 1, At, B1); PG8_BAR; PG8_SCHED;
	s_add_i32 s22, 0, 0x18000
	s_add_i32 s23, 0, 0x1c000
	v_add_u32_e32 v78, s22, v170
	v_add_u32_e32 v168, s23, v170
	ds_read_b128 v[66:69], v78
	ds_read_b128 v[70:73], v78 offset:1024
	ds_read_b128 v[74:77], v78 offset:2048
	ds_read_b128 v[78:81], v78 offset:3072
	ds_read_b128 v[162:165], v168
	ds_read_b128 v[182:185], v168 offset:1024
	ds_read_b128 v[186:189], v168 offset:2048
	ds_read_b128 v[190:193], v168 offset:3072
	s_add_u32 s20, s52, 0x80000
	s_addc_u32 s21, s53, 0
	s_mov_b32 m0, s35
	v_lshl_add_u64 v[232:233], s[20:21], 0, v[152:153]
	ds_read_b128 v[194:197], v176 offset:32768
	ds_read_b128 v[198:201], v176 offset:33792
	ds_read_b128 v[202:205], v176 offset:34816
	ds_read_b128 v[206:209], v176 offset:35840
	ds_read_b128 v[210:213], v176 offset:36864
	ds_read_b128 v[214:217], v176 offset:37888
	ds_read_b128 v[218:221], v176 offset:38912
	ds_read_b128 v[222:225], v176 offset:39936
	global_load_lds_dwordx4 v[232:233], off
	v_lshl_add_u64 v[232:233], s[20:21], 0, v[148:149]
	s_mov_b32 m0, s36
	s_nop 0
	global_load_lds_dwordx4 v[232:233], off
	s_waitcnt vmcnt(8)
	s_waitcnt lgkmcnt(0)
	s_barrier
	s_waitcnt lgkmcnt(0)
	v_mfma_f32_16x16x32_bf16 v[142:145], v[66:69], v[194:197], v[142:145]
	v_mfma_f32_16x16x32_bf16 v[138:141], v[74:77], v[194:197], v[138:141]
	v_mfma_f32_16x16x32_bf16 v[126:129], v[66:69], v[202:205], v[126:129]
	v_mfma_f32_16x16x32_bf16 v[122:125], v[74:77], v[202:205], v[122:125]
	v_mfma_f32_16x16x32_bf16 v[110:113], v[66:69], v[210:213], v[110:113]
	v_mfma_f32_16x16x32_bf16 v[106:109], v[74:77], v[210:213], v[106:109]
	v_mfma_f32_16x16x32_bf16 v[94:97], v[66:69], v[218:221], v[94:97]
	v_mfma_f32_16x16x32_bf16 v[90:93], v[74:77], v[218:221], v[90:93]
	v_mfma_f32_16x16x32_bf16 v[142:145], v[70:73], v[198:201], v[142:145]
	v_mfma_f32_16x16x32_bf16 v[138:141], v[78:81], v[198:201], v[138:141]
	v_mfma_f32_16x16x32_bf16 v[126:129], v[70:73], v[206:209], v[126:129]
	v_mfma_f32_16x16x32_bf16 v[122:125], v[78:81], v[206:209], v[122:125]
	v_mfma_f32_16x16x32_bf16 v[110:113], v[70:73], v[214:217], v[110:113]
	v_mfma_f32_16x16x32_bf16 v[106:109], v[78:81], v[214:217], v[106:109]
	v_mfma_f32_16x16x32_bf16 v[94:97], v[70:73], v[222:225], v[94:97]
	v_mfma_f32_16x16x32_bf16 v[90:93], v[78:81], v[222:225], v[90:93]
	v_mfma_f32_16x16x32_bf16 v[134:137], v[162:165], v[194:197], v[134:137]
	v_mfma_f32_16x16x32_bf16 v[130:133], v[186:189], v[194:197], v[130:133]
	v_mfma_f32_16x16x32_bf16 v[118:121], v[162:165], v[202:205], v[118:121]
	v_mfma_f32_16x16x32_bf16 v[114:117], v[186:189], v[202:205], v[114:117]
	v_mfma_f32_16x16x32_bf16 v[102:105], v[162:165], v[210:213], v[102:105]
	v_mfma_f32_16x16x32_bf16 v[98:101], v[186:189], v[210:213], v[98:101]
	v_mfma_f32_16x16x32_bf16 v[86:89], v[162:165], v[218:221], v[86:89]
	v_mfma_f32_16x16x32_bf16 v[82:85], v[186:189], v[218:221], v[82:85]
	v_mfma_f32_16x16x32_bf16 v[134:137], v[182:185], v[198:201], v[134:137]
	v_mfma_f32_16x16x32_bf16 v[130:133], v[190:193], v[198:201], v[130:133]
	v_mfma_f32_16x16x32_bf16 v[118:121], v[182:185], v[206:209], v[118:121]
	v_mfma_f32_16x16x32_bf16 v[114:117], v[190:193], v[206:209], v[114:117]
	v_mfma_f32_16x16x32_bf16 v[102:105], v[182:185], v[214:217], v[102:105]
	v_mfma_f32_16x16x32_bf16 v[98:101], v[190:193], v[214:217], v[98:101]
	v_mfma_f32_16x16x32_bf16 v[86:89], v[182:185], v[222:225], v[86:89]
	v_mfma_f32_16x16x32_bf16 v[82:85], v[190:193], v[222:225], v[82:85]
	s_barrier
; #define PG8_STAGE(bufoff, gbase, voff) do { _Pragma("unroll") for (int _i = 0; _i < 2; ++_i) \
;         __builtin_amdgcn_global_load_lds((const unsigned*)((const char*)(gbase) + (voff)[_i]), (LAS unsigned*)(lds + (bufoff) + ldsw + _i * 8192), 16, 0, 0); } while (0)
; #define PG8_LDA(dst, b, h) do { _Pragma("unroll") for (int m = 0; m < 4; ++m) _Pragma("unroll") for (int k = 0; k < 2; ++k) dst[m][k] = *(const LAS bf16x8*)(lds + PG8_SA(b, h) + aoff + m * 2048 + k * 1024); } while (0)
; #define PG8_WAIT_V(n) asm volatile("s_waitcnt vmcnt(" #n ")" ::: "memory")
; template <class Epi, class Sched, bool ALIGN_EPI = false, bool SP2 = false>
; __device__ __forceinline__ void gemm_phase(LAS unsigned char* lds, const Gemm g, const Sched& S, const Epi& E) {
;     ...
;             PG8_LDA(At, 1, 1); PG8_STAGE(PG8_SB(1, 0), b3, voffB); PG8_STAGE(PG8_SB(1, 1), b3 + hstepB, voffB); PG8_STAGE(PG8_SA(1, 0), a3, voffA);
;             PG8_WAIT_V(8); PG8_WAIT_L(0); PG8_BAR; PG8_MMA(1, 0, At, B0); PG8_MMA(1, 1, At, B1); PG8_BAR; PG8_SCHED;
;             } else {
;             PG8_LDB(B0, 0, 0); PG8_SCHED; PG8_LDA(At, 0, 0); PG8_STAGE(PG8_SA(1, 1), a1 + hstep, voffA);
;             PG8_WAIT_L(8); PG8_BAR; PG8_WAIT_L(0); PG8_MMA(0, 0, At, B0); PG8_BAR; PG8_SCHED;
;             PG8_LDB(B1, 0, 1); PG8_STAGE(PG8_SB(0, 0), b2, voffB);
;             PG8_BAR; PG8_WAIT_L(0); PG8_MMA(0, 1, At, B1); PG8_BAR;
;             PG8_LDA(At, 0, 1); PG8_STAGE(PG8_SA(0, 0), a2, voffA);
;             PG8_BAR; PG8_WAIT_L(0); PG8_MMA(1, 0, At, B0); PG8_BAR; PG8_SCHED;
;             PG8_STAGE(PG8_SB(0, 1), b2 + hstepB, voffB);
;             PG8_WAIT_V(6); PG8_BAR; PG8_MMA(1, 1, At, B1); PG8_BAR;
;             PG8_LDB(B0, 1, 0); PG8_SCHED; PG8_LDA(At, 1, 0); PG8_STAGE(PG8_SA(0, 1), a2 + hstep, voffA);
;             PG8_WAIT_L(8); PG8_BAR; PG8_WAIT_L(0); PG8_MMA(0, 0, At, B0); PG8_BAR; PG8_SCHED;
;             PG8_LDB(B1, 1, 1); PG8_STAGE(PG8_SB(1, 0), b3, voffB);
;             PG8_BAR; PG8_WAIT_L(0); PG8_MMA(0, 1, At, B1); PG8_BAR;
;             PG8_LDA(At, 1, 1); PG8_STAGE(PG8_SA(1, 0), a3, voffA);
;             PG8_BAR; PG8_WAIT_L(0); PG8_MMA(1, 0, At, B0); PG8_BAR; PG8_SCHED;
;             PG8_STAGE(PG8_SB(1, 1), b3 + hstepB, voffB);
;             PG8_WAIT_V(6); PG8_BAR; PG8_MMA(1, 1, At, B1); PG8_BAR;
;             }
;         }
;         if constexpr (ALIGN_EPI) { if (wr == 0) PG8_BAR; }
	s_add_i32 s20, s22, s27
	v_lshl_add_u64 v[166:167], v[166:167], 0, s[10:11]
	s_mov_b32 m0, s20
	ds_read_b128 v[194:197], v176 offset:49152
	ds_read_b128 v[198:201], v176 offset:50176
	ds_read_b128 v[202:205], v176 offset:51200
	ds_read_b128 v[206:209], v176 offset:52224
	ds_read_b128 v[210:213], v176 offset:53248
	ds_read_b128 v[214:217], v176 offset:54272
	ds_read_b128 v[218:221], v176 offset:55296
	ds_read_b128 v[222:225], v176 offset:56320
	global_load_lds_dwordx4 v[166:167], off
	s_add_i32 m0, s20, 0x2000
	s_add_u32 s20, s50, 0x80080
	v_lshl_add_u64 v[166:167], v[226:227], 0, s[10:11]
	s_addc_u32 s21, s51, 0
	s_add_i32 s22, s23, s27
	global_load_lds_dwordx4 v[166:167], off
	v_lshl_add_u64 v[166:167], s[20:21], 0, v[150:151]
	s_mov_b32 m0, s22
	s_nop 0
	global_load_lds_dwordx4 v[166:167], off
	v_lshl_add_u64 v[166:167], s[20:21], 0, v[146:147]
	s_add_i32 m0, s22, 0x2000
	s_nop 0
	global_load_lds_dwordx4 v[166:167], off
	v_lshl_add_u64 v[166:167], v[228:229], 0, s[10:11]
	s_mov_b32 m0, s55
	s_nop 0
	global_load_lds_dwordx4 v[166:167], off
	v_lshl_add_u64 v[166:167], v[230:231], 0, s[10:11]
	s_mov_b32 m0, s56
	s_nop 0
	global_load_lds_dwordx4 v[166:167], off
	s_waitcnt vmcnt(8)
	s_waitcnt lgkmcnt(0)
	s_barrier
	s_waitcnt lgkmcnt(0)
	v_mfma_f32_16x16x32_bf16 v[62:65], v[66:69], v[194:197], v[62:65]
	v_mfma_f32_16x16x32_bf16 v[58:61], v[74:77], v[194:197], v[58:61]
	v_mfma_f32_16x16x32_bf16 v[46:49], v[66:69], v[202:205], v[46:49]
	v_mfma_f32_16x16x32_bf16 v[42:45], v[74:77], v[202:205], v[42:45]
	v_mfma_f32_16x16x32_bf16 v[30:33], v[66:69], v[210:213], v[30:33]
	v_mfma_f32_16x16x32_bf16 v[26:29], v[74:77], v[210:213], v[26:29]
	v_mfma_f32_16x16x32_bf16 v[14:17], v[66:69], v[218:221], v[14:17]
	v_mfma_f32_16x16x32_bf16 v[10:13], v[74:77], v[218:221], v[10:13]
	v_mfma_f32_16x16x32_bf16 v[62:65], v[70:73], v[198:201], v[62:65]
	v_mfma_f32_16x16x32_bf16 v[58:61], v[78:81], v[198:201], v[58:61]
	v_mfma_f32_16x16x32_bf16 v[46:49], v[70:73], v[206:209], v[46:49]
	v_mfma_f32_16x16x32_bf16 v[42:45], v[78:81], v[206:209], v[42:45]
	v_mfma_f32_16x16x32_bf16 v[30:33], v[70:73], v[214:217], v[30:33]
	v_mfma_f32_16x16x32_bf16 v[26:29], v[78:81], v[214:217], v[26:29]
	v_mfma_f32_16x16x32_bf16 v[14:17], v[70:73], v[222:225], v[14:17]
	v_mfma_f32_16x16x32_bf16 v[10:13], v[78:81], v[222:225], v[10:13]
	v_mfma_f32_16x16x32_bf16 v[54:57], v[162:165], v[194:197], v[54:57]
	v_mfma_f32_16x16x32_bf16 v[50:53], v[186:189], v[194:197], v[50:53]
	v_mfma_f32_16x16x32_bf16 v[38:41], v[162:165], v[202:205], v[38:41]
	v_mfma_f32_16x16x32_bf16 v[34:37], v[186:189], v[202:205], v[34:37]
	v_mfma_f32_16x16x32_bf16 v[22:25], v[162:165], v[210:213], v[22:25]
	v_mfma_f32_16x16x32_bf16 v[18:21], v[186:189], v[210:213], v[18:21]
	v_mfma_f32_16x16x32_bf16 v[6:9], v[162:165], v[218:221], v[6:9]
	v_mfma_f32_16x16x32_bf16 v[2:5], v[186:189], v[218:221], v[2:5]
	v_mfma_f32_16x16x32_bf16 v[54:57], v[182:185], v[198:201], v[54:57]
	v_mfma_f32_16x16x32_bf16 v[50:53], v[190:193], v[198:201], v[50:53]
	v_mfma_f32_16x16x32_bf16 v[38:41], v[182:185], v[206:209], v[38:41]
	v_mfma_f32_16x16x32_bf16 v[34:37], v[190:193], v[206:209], v[34:37]
	v_mfma_f32_16x16x32_bf16 v[22:25], v[182:185], v[214:217], v[22:25]
	v_mfma_f32_16x16x32_bf16 v[18:21], v[190:193], v[214:217], v[18:21]
	v_mfma_f32_16x16x32_bf16 v[6:9], v[182:185], v[222:225], v[6:9]
	v_mfma_f32_16x16x32_bf16 v[2:5], v[190:193], v[222:225], v[2:5]
	s_barrier
	s_add_i32 s19, s19, 2
	s_add_u32 s16, s16, 0x100
	s_addc_u32 s17, s17, 0
	s_add_u32 s15, s15, 0x100
	s_addc_u32 s18, s18, 0
	s_cmp_gt_u32 s19, 29
	s_cbranch_scc0 .LBB0_188
	s_setprio 0
	s_and_b64 vcc, exec, s[40:41]
	s_cbranch_vccz .LBB0_191
	s_barrier

;     __device__ bool next(int i, Unit& u) const { if (i != 0 || c >= 128) return false; const int t = c >> 2; u.pm = t & 3; u.pn = t >> 2; u.koff = koff_bytes; u.q = c & 3; return true; }
; #define PG8_STAGE(bufoff, gbase, voff) do { _Pragma("unroll") for (int _i = 0; _i < 2; ++_i) \
;         __builtin_amdgcn_global_load_lds((const unsigned*)((const char*)(gbase) + (voff)[_i]), (LAS unsigned*)(lds + (bufoff) + ldsw + _i * 8192), 16, 0, 0); } while (0)
; #define PG8_LDA(dst, b, h) do { _Pragma("unroll") for (int m = 0; m < 4; ++m) _Pragma("unroll") for (int k = 0; k < 2; ++k) dst[m][k] = *(const LAS bf16x8*)(lds + PG8_SA(b, h) + aoff + m * 2048 + k * 1024); } while (0)
; #define PG8_LDB(dst, b, h) do { _Pragma("unroll") for (int n = 0; n < 2; ++n) _Pragma("unroll") for (int k = 0; k < 2; ++k) dst[n][k] = *(const LAS bf16x8*)(lds + PG8_SB(b, h) + boff + n * 2048 + k * 1024); } while (0)
; #define PG8_WAIT_V(n) asm volatile("s_waitcnt vmcnt(" #n ")" ::: "memory")
; #define PG8_WAIT_L(n) asm volatile("s_waitcnt lgkmcnt(" #n ")" ::: "memory")
; #define PG8_BAR __builtin_amdgcn_s_barrier()
; template <class Epi, class Sched, bool ALIGN_EPI = false, bool SP2 = false>
; __device__ __forceinline__ void gemm_phase(LAS unsigned char* lds, const Gemm g, const Sched& S, const Epi& E) {
;     ...
;         const bool has_next = S.next(ui + 1, nxt);
;         const char* nA = has_next ? (const char*)g.A + (size_t)nxt.pm * tstep + nxt.koff : cA; const char* nB = has_next ? (const char*)g.Bt + (size_t)nxt.pn * tstep + nxt.koff : cB;
;         for (int t = 0; t < nt; t += 2) {
;             const bool last = (t == nt - 2);
;             const char* a1 = cA + (size_t)(t + 1) * kstep;
;             const char* a2 = last ? nA : cA + (size_t)(t + 2) * kstep; const char* b2 = last ? nB : cB + (size_t)(t + 2) * kstep;
;             const char* a3 = a2 + kstep; const char* b3 = b2 + kstep;
;             if (last && has_next) S.a_ready(nxt);
;             if constexpr (SP2) {
;             PG8_LDB(B0, 0, 0); PG8_LDB(B1, 0, 1); PG8_SCHED; PG8_LDA(At, 0, 0); PG8_STAGE(PG8_SA(1, 1), a1 + hstep, voffA);
;             PG8_WAIT_V(8); PG8_WAIT_L(0); PG8_BAR; PG8_MMA(0, 0, At, B0); PG8_MMA(0, 1, At, B1); PG8_BAR; PG8_SCHED;
;             PG8_LDA(At, 0, 1); PG8_STAGE(PG8_SB(0, 0), b2, voffB); PG8_STAGE(PG8_SB(0, 1), b2 + hstepB, voffB); PG8_STAGE(PG8_SA(0, 0), a2, voffA);
.LBB0_316:
	s_add_u32 s5, s22, 0x100
	s_addc_u32 s12, s23, 0
	s_mov_b32 s13, -2
	v_readfirstlane_b32 s98, v0
	s_nop 3
	s_lshr_b32 s98, s98, 6
	s_cmp_ge_u32 s98, 4
	s_cbranch_scc0 .Lprio_317
	s_setprio 1
.Lprio_317:
	ds_read_b128 v[130:133], v196
	ds_read_b128 v[134:137], v196 offset:1024
	ds_read_b128 v[138:141], v196 offset:2048
	ds_read_b128 v[142:145], v196 offset:3072
	ds_read_b128 v[166:169], v197
	ds_read_b128 v[170:173], v197 offset:1024
	ds_read_b128 v[174:177], v197 offset:2048
	ds_read_b128 v[178:181], v197 offset:3072
	s_add_u32 s54, s16, 0x100
	s_addc_u32 s55, s17, 0
	s_cmpk_eq_i32 s13, 0x54
	s_cselect_b32 s59, s3, s55
	s_cselect_b32 s58, s2, s54
	s_cselect_b32 s57, s53, s12
	s_cselect_b32 s56, s52, s5
	v_lshl_add_u64 v[190:191], s[16:17], 0, v[158:159]
	s_add_i32 m0, s29, 0xc000
	ds_read_b128 v[182:185], v198
	ds_read_b128 v[186:189], v198 offset:1024
	ds_read_b128 v[202:205], v198 offset:2048
	ds_read_b128 v[206:209], v198 offset:3072
	ds_read_b128 v[210:213], v198 offset:4096
	ds_read_b128 v[214:217], v198 offset:5120
	ds_read_b128 v[218:221], v198 offset:6144
	ds_read_b128 v[222:225], v198 offset:7168
	global_load_lds_dwordx4 v[190:191], off
	v_lshl_add_u64 v[190:191], s[16:17], 0, v[160:161]
	s_add_i32 m0, s29, 0xe000
	s_nop 0
	global_load_lds_dwordx4 v[190:191], off
	s_waitcnt lgkmcnt(0)
	s_barrier
	s_waitcnt lgkmcnt(0)
	v_mfma_f32_16x16x32_bf16 v[126:129], v[130:133], v[182:185], 0
	v_mfma_f32_16x16x32_bf16 v[122:125], v[138:141], v[182:185], 0
	v_mfma_f32_16x16x32_bf16 v[110:113], v[130:133], v[202:205], 0
	v_mfma_f32_16x16x32_bf16 v[106:109], v[138:141], v[202:205], 0
	v_mfma_f32_16x16x32_bf16 v[94:97], v[130:133], v[210:213], 0
	v_mfma_f32_16x16x32_bf16 v[90:93], v[138:141], v[210:213], 0
	v_mfma_f32_16x16x32_bf16 v[78:81], v[130:133], v[218:221], 0
	v_mfma_f32_16x16x32_bf16 v[74:77], v[138:141], v[218:221], 0
	v_mfma_f32_16x16x32_bf16 v[126:129], v[134:137], v[186:189], v[126:129]
	v_mfma_f32_16x16x32_bf16 v[122:125], v[142:145], v[186:189], v[122:125]
	v_mfma_f32_16x16x32_bf16 v[110:113], v[134:137], v[206:209], v[110:113]
	v_mfma_f32_16x16x32_bf16 v[106:109], v[142:145], v[206:209], v[106:109]
	v_mfma_f32_16x16x32_bf16 v[94:97], v[134:137], v[214:217], v[94:97]
	v_mfma_f32_16x16x32_bf16 v[90:93], v[142:145], v[214:217], v[90:93]
	v_mfma_f32_16x16x32_bf16 v[78:81], v[134:137], v[222:225], v[78:81]
	v_mfma_f32_16x16x32_bf16 v[74:77], v[142:145], v[222:225], v[74:77]
	v_mfma_f32_16x16x32_bf16 v[118:121], v[166:169], v[182:185], 0
	v_mfma_f32_16x16x32_bf16 v[114:117], v[174:177], v[182:185], 0
	v_mfma_f32_16x16x32_bf16 v[102:105], v[166:169], v[202:205], 0
	v_mfma_f32_16x16x32_bf16 v[98:101], v[174:177], v[202:205], 0
	v_mfma_f32_16x16x32_bf16 v[86:89], v[166:169], v[210:213], 0
	v_mfma_f32_16x16x32_bf16 v[82:85], v[174:177], v[210:213], 0
	v_mfma_f32_16x16x32_bf16 v[70:73], v[166:169], v[218:221], 0
	v_mfma_f32_16x16x32_bf16 v[66:69], v[174:177], v[218:221], 0
	v_mfma_f32_16x16x32_bf16 v[118:121], v[170:173], v[186:189], v[118:121]
	v_mfma_f32_16x16x32_bf16 v[114:117], v[178:181], v[186:189], v[114:117]
	v_mfma_f32_16x16x32_bf16 v[102:105], v[170:173], v[206:209], v[102:105]
	v_mfma_f32_16x16x32_bf16 v[98:101], v[178:181], v[206:209], v[98:101]
	v_mfma_f32_16x16x32_bf16 v[86:89], v[170:173], v[214:217], v[86:89]
	v_mfma_f32_16x16x32_bf16 v[82:85], v[178:181], v[214:217], v[82:85]
	v_mfma_f32_16x16x32_bf16 v[70:73], v[170:173], v[222:225], v[70:73]
	v_mfma_f32_16x16x32_bf16 v[66:69], v[178:181], v[222:225], v[66:69]
	s_barrier
	s_add_i32 s14, s64, s28
	v_lshl_add_u64 v[190:191], s[56:57], 0, v[148:149]
	s_mov_b32 m0, s14
	ds_read_b128 v[182:185], v198 offset:16384
	ds_read_b128 v[186:189], v198 offset:17408
	ds_read_b128 v[202:205], v198 offset:18432
	ds_read_b128 v[206:209], v198 offset:19456
	ds_read_b128 v[210:213], v198 offset:20480
	ds_read_b128 v[214:217], v198 offset:21504
	ds_read_b128 v[218:221], v198 offset:22528
	ds_read_b128 v[222:225], v198 offset:23552
	global_load_lds_dwordx4 v[190:191], off
	s_add_i32 m0, s14, 0x2000
	s_add_u32 s14, s56, 0x58000
	v_lshl_add_u64 v[226:227], s[56:57], 0, v[152:153]
	s_addc_u32 s15, s57, 0
	s_add_i32 s16, s65, s28
	global_load_lds_dwordx4 v[226:227], off
	v_lshl_add_u64 v[228:229], s[14:15], 0, v[148:149]
	s_mov_b32 m0, s16
	v_lshl_add_u64 v[230:231], s[58:59], 0, v[150:151]
	global_load_lds_dwordx4 v[228:229], off
	v_lshl_add_u64 v[228:229], s[14:15], 0, v[152:153]
	s_add_i32 m0, s16, 0x2000
	s_nop 0
	global_load_lds_dwordx4 v[228:229], off
	v_lshl_add_u64 v[228:229], s[58:59], 0, v[146:147]
	s_mov_b32 m0, s29
	s_nop 0
	global_load_lds_dwordx4 v[228:229], off
	s_mov_b32 m0, s30
	s_nop 0
	global_load_lds_dwordx4 v[230:231], off
	s_waitcnt lgkmcnt(0)
	s_barrier
; #define PG8_STAGE(bufoff, gbase, voff) do { _Pragma("unroll") for (int _i = 0; _i < 2; ++_i) \
;         __builtin_amdgcn_global_load_lds((const unsigned*)((const char*)(gbase) + (voff)[_i]), (LAS unsigned*)(lds + (bufoff) + ldsw + _i * 8192), 16, 0, 0); } while (0)
; #define PG8_LDA(dst, b, h) do { _Pragma("unroll") for (int m = 0; m < 4; ++m) _Pragma("unroll") for (int k = 0; k < 2; ++k) dst[m][k] = *(const LAS bf16x8*)(lds + PG8_SA(b, h) + aoff + m * 2048 + k * 1024); } while (0)
; #define PG8_LDB(dst, b, h) do { _Pragma("unroll") for (int n = 0; n < 2; ++n) _Pragma("unroll") for (int k = 0; k < 2; ++k) dst[n][k] = *(const LAS bf16x8*)(lds + PG8_SB(b, h) + boff + n * 2048 + k * 1024); } while (0)
; #define PG8_MMA(ai, bj, At, Bt) do { __builtin_amdgcn_s_setprio(1); _Pragma("unroll") for (int m = 0; m < 4; ++m) _Pragma("unroll") for (int n = 0; n < 2; ++n) _Pragma("unroll") for (int k = 0; k < 2; ++k) \
;         acc[ai][bj][m][n] = __builtin_amdgcn_mfma_f32_16x16x32_bf16(Bt[n][k], At[m][k], acc[ai][bj][m][n], 0, 0, 0); __builtin_amdgcn_s_setprio(0); } while (0)
; #define PG8_WAIT_V(n) asm volatile("s_waitcnt vmcnt(" #n ")" ::: "memory")
; #define PG8_WAIT_L(n) asm volatile("s_waitcnt lgkmcnt(" #n ")" ::: "memory")
; #define PG8_BAR __builtin_amdgcn_s_barrier()
; #define PG8_SCHED __builtin_amdgcn_sched_barrier(0)
; template <class Epi, class Sched, bool ALIGN_EPI = false, bool SP2 = false>
; __device__ __forceinline__ void gemm_phase(LAS unsigned char* lds, const Gemm g, const Sched& S, const Epi& E) {
;     ...
;             PG8_WAIT_V(8); PG8_WAIT_L(0); PG8_BAR; PG8_MMA(0, 0, At, B0); PG8_MMA(0, 1, At, B1); PG8_BAR; PG8_SCHED;
;             PG8_LDA(At, 0, 1); PG8_STAGE(PG8_SB(0, 0), b2, voffB); PG8_STAGE(PG8_SB(0, 1), b2 + hstepB, voffB); PG8_STAGE(PG8_SA(0, 0), a2, voffA);
;             PG8_WAIT_V(8); PG8_WAIT_L(0); PG8_BAR; PG8_MMA(1, 0, At, B0); PG8_MMA(1, 1, At, B1); PG8_BAR; PG8_SCHED;
;             PG8_LDB(B0, 1, 0); PG8_LDB(B1, 1, 1); PG8_SCHED; PG8_LDA(At, 1, 0); PG8_STAGE(PG8_SA(0, 1), a2 + hstep, voffA);
;             PG8_WAIT_V(8); PG8_WAIT_L(0); PG8_BAR; PG8_MMA(0, 0, At, B0); PG8_MMA(0, 1, At, B1); PG8_BAR; PG8_SCHED;
	s_waitcnt lgkmcnt(0)
	v_mfma_f32_16x16x32_bf16 v[62:65], v[130:133], v[182:185], 0
	v_mfma_f32_16x16x32_bf16 v[58:61], v[138:141], v[182:185], 0
	v_mfma_f32_16x16x32_bf16 v[46:49], v[130:133], v[202:205], 0
	v_mfma_f32_16x16x32_bf16 v[42:45], v[138:141], v[202:205], 0
	v_mfma_f32_16x16x32_bf16 v[30:33], v[130:133], v[210:213], 0
	v_mfma_f32_16x16x32_bf16 v[26:29], v[138:141], v[210:213], 0
	v_mfma_f32_16x16x32_bf16 v[14:17], v[130:133], v[218:221], 0
	v_mfma_f32_16x16x32_bf16 v[10:13], v[138:141], v[218:221], 0
	v_mfma_f32_16x16x32_bf16 v[62:65], v[134:137], v[186:189], v[62:65]
	v_mfma_f32_16x16x32_bf16 v[58:61], v[142:145], v[186:189], v[58:61]
	v_mfma_f32_16x16x32_bf16 v[46:49], v[134:137], v[206:209], v[46:49]
	v_mfma_f32_16x16x32_bf16 v[42:45], v[142:145], v[206:209], v[42:45]
	v_mfma_f32_16x16x32_bf16 v[30:33], v[134:137], v[214:217], v[30:33]
	v_mfma_f32_16x16x32_bf16 v[26:29], v[142:145], v[214:217], v[26:29]
	v_mfma_f32_16x16x32_bf16 v[14:17], v[134:137], v[222:225], v[14:17]
	v_mfma_f32_16x16x32_bf16 v[10:13], v[142:145], v[222:225], v[10:13]
	v_mfma_f32_16x16x32_bf16 v[54:57], v[166:169], v[182:185], 0
	v_mfma_f32_16x16x32_bf16 v[50:53], v[174:177], v[182:185], 0
	v_mfma_f32_16x16x32_bf16 v[38:41], v[166:169], v[202:205], 0
	v_mfma_f32_16x16x32_bf16 v[34:37], v[174:177], v[202:205], 0
	v_mfma_f32_16x16x32_bf16 v[22:25], v[166:169], v[210:213], 0
	v_mfma_f32_16x16x32_bf16 v[18:21], v[174:177], v[210:213], 0
	v_mfma_f32_16x16x32_bf16 v[6:9], v[166:169], v[218:221], 0
	v_mfma_f32_16x16x32_bf16 v[2:5], v[174:177], v[218:221], 0
	v_mfma_f32_16x16x32_bf16 v[54:57], v[170:173], v[186:189], v[54:57]
	v_mfma_f32_16x16x32_bf16 v[50:53], v[178:181], v[186:189], v[50:53]
	v_mfma_f32_16x16x32_bf16 v[38:41], v[170:173], v[206:209], v[38:41]
	v_mfma_f32_16x16x32_bf16 v[34:37], v[178:181], v[206:209], v[34:37]
	v_mfma_f32_16x16x32_bf16 v[22:25], v[170:173], v[214:217], v[22:25]
	v_mfma_f32_16x16x32_bf16 v[18:21], v[178:181], v[214:217], v[18:21]
	v_mfma_f32_16x16x32_bf16 v[6:9], v[170:173], v[222:225], v[6:9]
	v_mfma_f32_16x16x32_bf16 v[2:5], v[178:181], v[222:225], v[2:5]
	s_barrier
	s_add_i32 s16, 0, 0x18000
	s_add_i32 s17, 0, 0x1c000
	v_add_u32_e32 v142, s16, v1
	v_add_u32_e32 v154, s17, v1
	ds_read_b128 v[130:133], v142
	ds_read_b128 v[134:137], v142 offset:1024
	ds_read_b128 v[138:141], v142 offset:2048
	ds_read_b128 v[142:145], v142 offset:3072
	ds_read_b128 v[166:169], v154
	ds_read_b128 v[170:173], v154 offset:1024
	ds_read_b128 v[174:177], v154 offset:2048
	ds_read_b128 v[178:181], v154 offset:3072
	s_add_u32 s14, s58, 0x160000
	s_addc_u32 s15, s59, 0
	s_mov_b32 m0, s31
	v_lshl_add_u64 v[232:233], s[14:15], 0, v[146:147]
	ds_read_b128 v[182:185], v198 offset:32768
	ds_read_b128 v[186:189], v198 offset:33792
	ds_read_b128 v[202:205], v198 offset:34816
	ds_read_b128 v[206:209], v198 offset:35840
	ds_read_b128 v[210:213], v198 offset:36864
	ds_read_b128 v[214:217], v198 offset:37888
	ds_read_b128 v[218:221], v198 offset:38912
	ds_read_b128 v[222:225], v198 offset:39936
	global_load_lds_dwordx4 v[232:233], off
	v_lshl_add_u64 v[232:233], s[14:15], 0, v[150:151]
	s_mov_b32 m0, s33
	s_nop 0
	global_load_lds_dwordx4 v[232:233], off
	s_waitcnt vmcnt(8)
	s_waitcnt lgkmcnt(0)
	s_barrier
	s_waitcnt lgkmcnt(0)
	v_mfma_f32_16x16x32_bf16 v[126:129], v[130:133], v[182:185], v[126:129]
	v_mfma_f32_16x16x32_bf16 v[122:125], v[138:141], v[182:185], v[122:125]
	v_mfma_f32_16x16x32_bf16 v[110:113], v[130:133], v[202:205], v[110:113]
	v_mfma_f32_16x16x32_bf16 v[106:109], v[138:141], v[202:205], v[106:109]
	v_mfma_f32_16x16x32_bf16 v[94:97], v[130:133], v[210:213], v[94:97]
	v_mfma_f32_16x16x32_bf16 v[90:93], v[138:141], v[210:213], v[90:93]
	v_mfma_f32_16x16x32_bf16 v[78:81], v[130:133], v[218:221], v[78:81]
	v_mfma_f32_16x16x32_bf16 v[74:77], v[138:141], v[218:221], v[74:77]
	v_mfma_f32_16x16x32_bf16 v[126:129], v[134:137], v[186:189], v[126:129]
	v_mfma_f32_16x16x32_bf16 v[122:125], v[142:145], v[186:189], v[122:125]
	v_mfma_f32_16x16x32_bf16 v[110:113], v[134:137], v[206:209], v[110:113]
	v_mfma_f32_16x16x32_bf16 v[106:109], v[142:145], v[206:209], v[106:109]
	v_mfma_f32_16x16x32_bf16 v[94:97], v[134:137], v[214:217], v[94:97]
	v_mfma_f32_16x16x32_bf16 v[90:93], v[142:145], v[214:217], v[90:93]
	v_mfma_f32_16x16x32_bf16 v[78:81], v[134:137], v[222:225], v[78:81]
	v_mfma_f32_16x16x32_bf16 v[74:77], v[142:145], v[222:225], v[74:77]
	v_mfma_f32_16x16x32_bf16 v[118:121], v[166:169], v[182:185], v[118:121]
	v_mfma_f32_16x16x32_bf16 v[114:117], v[174:177], v[182:185], v[114:117]
	v_mfma_f32_16x16x32_bf16 v[102:105], v[166:169], v[202:205], v[102:105]
	v_mfma_f32_16x16x32_bf16 v[98:101], v[174:177], v[202:205], v[98:101]
	v_mfma_f32_16x16x32_bf16 v[86:89], v[166:169], v[210:213], v[86:89]
	v_mfma_f32_16x16x32_bf16 v[82:85], v[174:177], v[210:213], v[82:85]
	v_mfma_f32_16x16x32_bf16 v[70:73], v[166:169], v[218:221], v[70:73]
	v_mfma_f32_16x16x32_bf16 v[66:69], v[174:177], v[218:221], v[66:69]
	v_mfma_f32_16x16x32_bf16 v[118:121], v[170:173], v[186:189], v[118:121]
	v_mfma_f32_16x16x32_bf16 v[114:117], v[178:181], v[186:189], v[114:117]
	v_mfma_f32_16x16x32_bf16 v[102:105], v[170:173], v[206:209], v[102:105]
	v_mfma_f32_16x16x32_bf16 v[98:101], v[178:181], v[206:209], v[98:101]
	v_mfma_f32_16x16x32_bf16 v[86:89], v[170:173], v[214:217], v[86:89]
	v_mfma_f32_16x16x32_bf16 v[82:85], v[178:181], v[214:217], v[82:85]
	v_mfma_f32_16x16x32_bf16 v[70:73], v[170:173], v[222:225], v[70:73]
	v_mfma_f32_16x16x32_bf16 v[66:69], v[178:181], v[222:225], v[66:69]
	s_barrier
; #define PG8_STAGE(bufoff, gbase, voff) do { _Pragma("unroll") for (int _i = 0; _i < 2; ++_i) \
;         __builtin_amdgcn_global_load_lds((const unsigned*)((const char*)(gbase) + (voff)[_i]), (LAS unsigned*)(lds + (bufoff) + ldsw + _i * 8192), 16, 0, 0); } while (0)
; #define PG8_LDA(dst, b, h) do { _Pragma("unroll") for (int m = 0; m < 4; ++m) _Pragma("unroll") for (int k = 0; k < 2; ++k) dst[m][k] = *(const LAS bf16x8*)(lds + PG8_SA(b, h) + aoff + m * 2048 + k * 1024); } while (0)
; #define PG8_LDB(dst, b, h) do { _Pragma("unroll") for (int n = 0; n < 2; ++n) _Pragma("unroll") for (int k = 0; k < 2; ++k) dst[n][k] = *(const LAS bf16x8*)(lds + PG8_SB(b, h) + boff + n * 2048 + k * 1024); } while (0)
; template <class Epi, class Sched, bool ALIGN_EPI = false, bool SP2 = false>
; __device__ __forceinline__ void gemm_phase(LAS unsigned char* lds, const Gemm g, const Sched& S, const Epi& E) {
;     ...
;         for (int t = 0; t < nt; t += 2) {
;             const bool last = (t == nt - 2);
;             const char* a1 = cA + (size_t)(t + 1) * kstep;
;             const char* a2 = last ? nA : cA + (size_t)(t + 2) * kstep; const char* b2 = last ? nB : cB + (size_t)(t + 2) * kstep;
;             const char* a3 = a2 + kstep; const char* b3 = b2 + kstep;
;             if (last && has_next) S.a_ready(nxt);
;             if constexpr (SP2) {
;             PG8_LDB(B0, 0, 0); PG8_LDB(B1, 0, 1); PG8_SCHED; PG8_LDA(At, 0, 0); PG8_STAGE(PG8_SA(1, 1), a1 + hstep, voffA);
;             PG8_WAIT_V(8); PG8_WAIT_L(0); PG8_BAR; PG8_MMA(0, 0, At, B0); PG8_MMA(0, 1, At, B1); PG8_BAR; PG8_SCHED;
;             PG8_LDA(At, 0, 1); PG8_STAGE(PG8_SB(0, 0), b2, voffB); PG8_STAGE(PG8_SB(0, 1), b2 + hstepB, voffB); PG8_STAGE(PG8_SA(0, 0), a2, voffA);
;             PG8_WAIT_V(8); PG8_WAIT_L(0); PG8_BAR; PG8_MMA(1, 0, At, B0); PG8_MMA(1, 1, At, B1); PG8_BAR; PG8_SCHED;
;             PG8_LDB(B0, 1, 0); PG8_LDB(B1, 1, 1); PG8_SCHED; PG8_LDA(At, 1, 0); PG8_STAGE(PG8_SA(0, 1), a2 + hstep, voffA);
;             PG8_WAIT_V(8); PG8_WAIT_L(0); PG8_BAR; PG8_MMA(0, 0, At, B0); PG8_MMA(0, 1, At, B1); PG8_BAR; PG8_SCHED;
;             PG8_LDA(At, 1, 1); PG8_STAGE(PG8_SB(1, 0), b3, voffB); PG8_STAGE(PG8_SB(1, 1), b3 + hstepB, voffB); PG8_STAGE(PG8_SA(1, 0), a3, voffA);
;             PG8_WAIT_V(8); PG8_WAIT_L(0); PG8_BAR; PG8_MMA(1, 0, At, B0); PG8_MMA(1, 1, At, B1); PG8_BAR; PG8_SCHED;
	s_add_i32 s14, s16, s28
	v_lshl_add_u64 v[190:191], v[190:191], 0, s[48:49]
	s_mov_b32 m0, s14
	ds_read_b128 v[182:185], v198 offset:49152
	ds_read_b128 v[186:189], v198 offset:50176
	ds_read_b128 v[202:205], v198 offset:51200
	ds_read_b128 v[206:209], v198 offset:52224
	ds_read_b128 v[210:213], v198 offset:53248
	ds_read_b128 v[214:217], v198 offset:54272
	ds_read_b128 v[218:221], v198 offset:55296
	ds_read_b128 v[222:225], v198 offset:56320
	global_load_lds_dwordx4 v[190:191], off
	s_add_i32 m0, s14, 0x2000
	s_add_u32 s14, s56, 0x58080
	v_lshl_add_u64 v[190:191], v[226:227], 0, s[48:49]
	s_addc_u32 s15, s57, 0
	s_add_i32 s16, s17, s28
	global_load_lds_dwordx4 v[190:191], off
	v_lshl_add_u64 v[190:191], s[14:15], 0, v[148:149]
	s_mov_b32 m0, s16
	s_nop 0
	global_load_lds_dwordx4 v[190:191], off
	v_lshl_add_u64 v[190:191], s[14:15], 0, v[152:153]
	s_add_i32 m0, s16, 0x2000
	s_nop 0
	global_load_lds_dwordx4 v[190:191], off
	v_lshl_add_u64 v[190:191], v[228:229], 0, s[48:49]
	s_mov_b32 m0, s61
	s_nop 0
	global_load_lds_dwordx4 v[190:191], off
	v_lshl_add_u64 v[190:191], v[230:231], 0, s[48:49]
	s_mov_b32 m0, s62
	s_nop 0
	global_load_lds_dwordx4 v[190:191], off
	s_waitcnt vmcnt(8)
	s_waitcnt lgkmcnt(0)
	s_barrier
	s_waitcnt lgkmcnt(0)
	v_mfma_f32_16x16x32_bf16 v[62:65], v[130:133], v[182:185], v[62:65]
	v_mfma_f32_16x16x32_bf16 v[58:61], v[138:141], v[182:185], v[58:61]
	v_mfma_f32_16x16x32_bf16 v[46:49], v[130:133], v[202:205], v[46:49]
	v_mfma_f32_16x16x32_bf16 v[42:45], v[138:141], v[202:205], v[42:45]
	v_mfma_f32_16x16x32_bf16 v[30:33], v[130:133], v[210:213], v[30:33]
	v_mfma_f32_16x16x32_bf16 v[26:29], v[138:141], v[210:213], v[26:29]
	v_mfma_f32_16x16x32_bf16 v[14:17], v[130:133], v[218:221], v[14:17]
	v_mfma_f32_16x16x32_bf16 v[10:13], v[138:141], v[218:221], v[10:13]
	v_mfma_f32_16x16x32_bf16 v[62:65], v[134:137], v[186:189], v[62:65]
	v_mfma_f32_16x16x32_bf16 v[58:61], v[142:145], v[186:189], v[58:61]
	v_mfma_f32_16x16x32_bf16 v[46:49], v[134:137], v[206:209], v[46:49]
	v_mfma_f32_16x16x32_bf16 v[42:45], v[142:145], v[206:209], v[42:45]
	v_mfma_f32_16x16x32_bf16 v[30:33], v[134:137], v[214:217], v[30:33]
	v_mfma_f32_16x16x32_bf16 v[26:29], v[142:145], v[214:217], v[26:29]
	v_mfma_f32_16x16x32_bf16 v[14:17], v[134:137], v[222:225], v[14:17]
	v_mfma_f32_16x16x32_bf16 v[10:13], v[142:145], v[222:225], v[10:13]
	v_mfma_f32_16x16x32_bf16 v[54:57], v[166:169], v[182:185], v[54:57]
	v_mfma_f32_16x16x32_bf16 v[50:53], v[174:177], v[182:185], v[50:53]
	v_mfma_f32_16x16x32_bf16 v[38:41], v[166:169], v[202:205], v[38:41]
	v_mfma_f32_16x16x32_bf16 v[34:37], v[174:177], v[202:205], v[34:37]
	v_mfma_f32_16x16x32_bf16 v[22:25], v[166:169], v[210:213], v[22:25]
	v_mfma_f32_16x16x32_bf16 v[18:21], v[174:177], v[210:213], v[18:21]
	v_mfma_f32_16x16x32_bf16 v[6:9], v[166:169], v[218:221], v[6:9]
	v_mfma_f32_16x16x32_bf16 v[2:5], v[174:177], v[218:221], v[2:5]
	v_mfma_f32_16x16x32_bf16 v[54:57], v[170:173], v[186:189], v[54:57]
	v_mfma_f32_16x16x32_bf16 v[50:53], v[178:181], v[186:189], v[50:53]
	v_mfma_f32_16x16x32_bf16 v[38:41], v[170:173], v[206:209], v[38:41]
	v_mfma_f32_16x16x32_bf16 v[34:37], v[178:181], v[206:209], v[34:37]
	v_mfma_f32_16x16x32_bf16 v[22:25], v[170:173], v[214:217], v[22:25]
	v_mfma_f32_16x16x32_bf16 v[18:21], v[178:181], v[214:217], v[18:21]
	v_mfma_f32_16x16x32_bf16 v[6:9], v[170:173], v[222:225], v[6:9]
	v_mfma_f32_16x16x32_bf16 v[2:5], v[178:181], v[222:225], v[2:5]
	s_barrier
	s_add_i32 s13, s13, 2
	s_add_u32 s5, s5, 0x100
	s_addc_u32 s12, s12, 0
	s_cmpk_gt_u32 s13, 0x55
	s_mov_b64 s[16:17], s[54:55]
.LBB0_317:
	ds_read_b128 v[130:133], v196
	ds_read_b128 v[134:137], v196 offset:1024
	ds_read_b128 v[138:141], v196 offset:2048
	ds_read_b128 v[142:145], v196 offset:3072
	ds_read_b128 v[166:169], v197
	ds_read_b128 v[170:173], v197 offset:1024
	ds_read_b128 v[174:177], v197 offset:2048
	ds_read_b128 v[178:181], v197 offset:3072
	s_add_u32 s54, s16, 0x100
	s_addc_u32 s55, s17, 0
	s_cmpk_eq_i32 s13, 0x54
	s_cselect_b32 s59, s3, s55
	s_cselect_b32 s58, s2, s54
	s_cselect_b32 s57, s53, s12
	s_cselect_b32 s56, s52, s5
	v_lshl_add_u64 v[190:191], s[16:17], 0, v[158:159]
	s_add_i32 m0, s29, 0xc000
	ds_read_b128 v[182:185], v198
	ds_read_b128 v[186:189], v198 offset:1024
	ds_read_b128 v[202:205], v198 offset:2048
	ds_read_b128 v[206:209], v198 offset:3072
	ds_read_b128 v[210:213], v198 offset:4096
	ds_read_b128 v[214:217], v198 offset:5120
	ds_read_b128 v[218:221], v198 offset:6144
	ds_read_b128 v[222:225], v198 offset:7168
	global_load_lds_dwordx4 v[190:191], off
	v_lshl_add_u64 v[190:191], s[16:17], 0, v[160:161]
	s_add_i32 m0, s29, 0xe000
	s_nop 0
	global_load_lds_dwordx4 v[190:191], off
	s_waitcnt vmcnt(8)
	s_waitcnt lgkmcnt(0)
	s_barrier
; #define PG8_STAGE(bufoff, gbase, voff) do { _Pragma("unroll") for (int _i = 0; _i < 2; ++_i) \
;         __builtin_amdgcn_global_load_lds((const unsigned*)((const char*)(gbase) + (voff)[_i]), (LAS unsigned*)(lds + (bufoff) + ldsw + _i * 8192), 16, 0, 0); } while (0)
; #define PG8_LDA(dst, b, h) do { _Pragma("unroll") for (int m = 0; m < 4; ++m) _Pragma("unroll") for (int k = 0; k < 2; ++k) dst[m][k] = *(const LAS bf16x8*)(lds + PG8_SA(b, h) + aoff + m * 2048 + k * 1024); } while (0)
; #define PG8_LDB(dst, b, h) do { _Pragma("unroll") for (int n = 0; n < 2; ++n) _Pragma("unroll") for (int k = 0; k < 2; ++k) dst[n][k] = *(const LAS bf16x8*)(lds + PG8_SB(b, h) + boff + n * 2048 + k * 1024); } while (0)
; #define PG8_MMA(ai, bj, At, Bt) do { __builtin_amdgcn_s_setprio(1); _Pragma("unroll") for (int m = 0; m < 4; ++m) _Pragma("unroll") for (int n = 0; n < 2; ++n) _Pragma("unroll") for (int k = 0; k < 2; ++k) \
;         acc[ai][bj][m][n] = __builtin_amdgcn_mfma_f32_16x16x32_bf16(Bt[n][k], At[m][k], acc[ai][bj][m][n], 0, 0, 0); __builtin_amdgcn_s_setprio(0); } while (0)
; #define PG8_WAIT_V(n) asm volatile("s_waitcnt vmcnt(" #n ")" ::: "memory")
; #define PG8_WAIT_L(n) asm volatile("s_waitcnt lgkmcnt(" #n ")" ::: "memory")
; #define PG8_BAR __builtin_amdgcn_s_barrier()
; #define PG8_SCHED __builtin_amdgcn_sched_barrier(0)
; template <class Epi, class Sched, bool ALIGN_EPI = false, bool SP2 = false>
; __device__ __forceinline__ void gemm_phase(LAS unsigned char* lds, const Gemm g, const Sched& S, const Epi& E) {
;     ...
;             PG8_LDB(B0, 0, 0); PG8_LDB(B1, 0, 1); PG8_SCHED; PG8_LDA(At, 0, 0); PG8_STAGE(PG8_SA(1, 1), a1 + hstep, voffA);
;             PG8_WAIT_V(8); PG8_WAIT_L(0); PG8_BAR; PG8_MMA(0, 0, At, B0); PG8_MMA(0, 1, At, B1); PG8_BAR; PG8_SCHED;
;             PG8_LDA(At, 0, 1); PG8_STAGE(PG8_SB(0, 0), b2, voffB); PG8_STAGE(PG8_SB(0, 1), b2 + hstepB, voffB); PG8_STAGE(PG8_SA(0, 0), a2, voffA);
;             PG8_WAIT_V(8); PG8_WAIT_L(0); PG8_BAR; PG8_MMA(1, 0, At, B0); PG8_MMA(1, 1, At, B1); PG8_BAR; PG8_SCHED;
;             PG8_LDB(B0, 1, 0); PG8_LDB(B1, 1, 1); PG8_SCHED; PG8_LDA(At, 1, 0); PG8_STAGE(PG8_SA(0, 1), a2 + hstep, voffA);
	s_waitcnt lgkmcnt(0)
	v_mfma_f32_16x16x32_bf16 v[126:129], v[130:133], v[182:185], v[126:129]
	v_mfma_f32_16x16x32_bf16 v[122:125], v[138:141], v[182:185], v[122:125]
	v_mfma_f32_16x16x32_bf16 v[110:113], v[130:133], v[202:205], v[110:113]
	v_mfma_f32_16x16x32_bf16 v[106:109], v[138:141], v[202:205], v[106:109]
	v_mfma_f32_16x16x32_bf16 v[94:97], v[130:133], v[210:213], v[94:97]
	v_mfma_f32_16x16x32_bf16 v[90:93], v[138:141], v[210:213], v[90:93]
	v_mfma_f32_16x16x32_bf16 v[78:81], v[130:133], v[218:221], v[78:81]
	v_mfma_f32_16x16x32_bf16 v[74:77], v[138:141], v[218:221], v[74:77]
	v_mfma_f32_16x16x32_bf16 v[126:129], v[134:137], v[186:189], v[126:129]
	v_mfma_f32_16x16x32_bf16 v[122:125], v[142:145], v[186:189], v[122:125]
	v_mfma_f32_16x16x32_bf16 v[110:113], v[134:137], v[206:209], v[110:113]
	v_mfma_f32_16x16x32_bf16 v[106:109], v[142:145], v[206:209], v[106:109]
	v_mfma_f32_16x16x32_bf16 v[94:97], v[134:137], v[214:217], v[94:97]
	v_mfma_f32_16x16x32_bf16 v[90:93], v[142:145], v[214:217], v[90:93]
	v_mfma_f32_16x16x32_bf16 v[78:81], v[134:137], v[222:225], v[78:81]
	v_mfma_f32_16x16x32_bf16 v[74:77], v[142:145], v[222:225], v[74:77]
	v_mfma_f32_16x16x32_bf16 v[118:121], v[166:169], v[182:185], v[118:121]
	v_mfma_f32_16x16x32_bf16 v[114:117], v[174:177], v[182:185], v[114:117]
	v_mfma_f32_16x16x32_bf16 v[102:105], v[166:169], v[202:205], v[102:105]
	v_mfma_f32_16x16x32_bf16 v[98:101], v[174:177], v[202:205], v[98:101]
	v_mfma_f32_16x16x32_bf16 v[86:89], v[166:169], v[210:213], v[86:89]
	v_mfma_f32_16x16x32_bf16 v[82:85], v[174:177], v[210:213], v[82:85]
	v_mfma_f32_16x16x32_bf16 v[70:73], v[166:169], v[218:221], v[70:73]
	v_mfma_f32_16x16x32_bf16 v[66:69], v[174:177], v[218:221], v[66:69]
	v_mfma_f32_16x16x32_bf16 v[118:121], v[170:173], v[186:189], v[118:121]
	v_mfma_f32_16x16x32_bf16 v[114:117], v[178:181], v[186:189], v[114:117]
	v_mfma_f32_16x16x32_bf16 v[102:105], v[170:173], v[206:209], v[102:105]
	v_mfma_f32_16x16x32_bf16 v[98:101], v[178:181], v[206:209], v[98:101]
	v_mfma_f32_16x16x32_bf16 v[86:89], v[170:173], v[214:217], v[86:89]
	v_mfma_f32_16x16x32_bf16 v[82:85], v[178:181], v[214:217], v[82:85]
	v_mfma_f32_16x16x32_bf16 v[70:73], v[170:173], v[222:225], v[70:73]
	v_mfma_f32_16x16x32_bf16 v[66:69], v[178:181], v[222:225], v[66:69]
	s_barrier
	s_add_i32 s14, s64, s28
	v_lshl_add_u64 v[190:191], s[56:57], 0, v[148:149]
	s_mov_b32 m0, s14
	ds_read_b128 v[182:185], v198 offset:16384
	ds_read_b128 v[186:189], v198 offset:17408
	ds_read_b128 v[202:205], v198 offset:18432
	ds_read_b128 v[206:209], v198 offset:19456
	ds_read_b128 v[210:213], v198 offset:20480
	ds_read_b128 v[214:217], v198 offset:21504
	ds_read_b128 v[218:221], v198 offset:22528
	ds_read_b128 v[222:225], v198 offset:23552
	global_load_lds_dwordx4 v[190:191], off
	s_add_i32 m0, s14, 0x2000
	s_add_u32 s14, s56, 0x58000
	v_lshl_add_u64 v[226:227], s[56:57], 0, v[152:153]
	s_addc_u32 s15, s57, 0
	s_add_i32 s16, s65, s28
	global_load_lds_dwordx4 v[226:227], off
	v_lshl_add_u64 v[228:229], s[14:15], 0, v[148:149]
	s_mov_b32 m0, s16
	v_lshl_add_u64 v[230:231], s[58:59], 0, v[150:151]
	global_load_lds_dwordx4 v[228:229], off
	v_lshl_add_u64 v[228:229], s[14:15], 0, v[152:153]
	s_add_i32 m0, s16, 0x2000
	s_nop 0
	global_load_lds_dwordx4 v[228:229], off
	v_lshl_add_u64 v[228:229], s[58:59], 0, v[146:147]
	s_mov_b32 m0, s29
	s_nop 0
	global_load_lds_dwordx4 v[228:229], off
	s_mov_b32 m0, s30
	s_nop 0
	global_load_lds_dwordx4 v[230:231], off
	s_waitcnt vmcnt(8)
	s_waitcnt lgkmcnt(0)
	s_barrier
	s_waitcnt lgkmcnt(0)
	v_mfma_f32_16x16x32_bf16 v[62:65], v[130:133], v[182:185], v[62:65]
	v_mfma_f32_16x16x32_bf16 v[58:61], v[138:141], v[182:185], v[58:61]
	v_mfma_f32_16x16x32_bf16 v[46:49], v[130:133], v[202:205], v[46:49]
	v_mfma_f32_16x16x32_bf16 v[42:45], v[138:141], v[202:205], v[42:45]
	v_mfma_f32_16x16x32_bf16 v[30:33], v[130:133], v[210:213], v[30:33]
	v_mfma_f32_16x16x32_bf16 v[26:29], v[138:141], v[210:213], v[26:29]
	v_mfma_f32_16x16x32_bf16 v[14:17], v[130:133], v[218:221], v[14:17]
	v_mfma_f32_16x16x32_bf16 v[10:13], v[138:141], v[218:221], v[10:13]
	v_mfma_f32_16x16x32_bf16 v[62:65], v[134:137], v[186:189], v[62:65]
	v_mfma_f32_16x16x32_bf16 v[58:61], v[142:145], v[186:189], v[58:61]
	v_mfma_f32_16x16x32_bf16 v[46:49], v[134:137], v[206:209], v[46:49]
	v_mfma_f32_16x16x32_bf16 v[42:45], v[142:145], v[206:209], v[42:45]
	v_mfma_f32_16x16x32_bf16 v[30:33], v[134:137], v[214:217], v[30:33]
	v_mfma_f32_16x16x32_bf16 v[26:29], v[142:145], v[214:217], v[26:29]
	v_mfma_f32_16x16x32_bf16 v[14:17], v[134:137], v[222:225], v[14:17]
	v_mfma_f32_16x16x32_bf16 v[10:13], v[142:145], v[222:225], v[10:13]
	v_mfma_f32_16x16x32_bf16 v[54:57], v[166:169], v[182:185], v[54:57]
	v_mfma_f32_16x16x32_bf16 v[50:53], v[174:177], v[182:185], v[50:53]
	v_mfma_f32_16x16x32_bf16 v[38:41], v[166:169], v[202:205], v[38:41]
	v_mfma_f32_16x16x32_bf16 v[34:37], v[174:177], v[202:205], v[34:37]
	v_mfma_f32_16x16x32_bf16 v[22:25], v[166:169], v[210:213], v[22:25]
	v_mfma_f32_16x16x32_bf16 v[18:21], v[174:177], v[210:213], v[18:21]
	v_mfma_f32_16x16x32_bf16 v[6:9], v[166:169], v[218:221], v[6:9]
	v_mfma_f32_16x16x32_bf16 v[2:5], v[174:177], v[218:221], v[2:5]
	v_mfma_f32_16x16x32_bf16 v[54:57], v[170:173], v[186:189], v[54:57]
	v_mfma_f32_16x16x32_bf16 v[50:53], v[178:181], v[186:189], v[50:53]
	v_mfma_f32_16x16x32_bf16 v[38:41], v[170:173], v[206:209], v[38:41]
	v_mfma_f32_16x16x32_bf16 v[34:37], v[178:181], v[206:209], v[34:37]
	v_mfma_f32_16x16x32_bf16 v[22:25], v[170:173], v[214:217], v[22:25]
	v_mfma_f32_16x16x32_bf16 v[18:21], v[178:181], v[214:217], v[18:21]
	v_mfma_f32_16x16x32_bf16 v[6:9], v[170:173], v[222:225], v[6:9]
	v_mfma_f32_16x16x32_bf16 v[2:5], v[178:181], v[222:225], v[2:5]
	s_barrier
; #define PG8_STAGE(bufoff, gbase, voff) do { _Pragma("unroll") for (int _i = 0; _i < 2; ++_i) \
;         __builtin_amdgcn_global_load_lds((const unsigned*)((const char*)(gbase) + (voff)[_i]), (LAS unsigned*)(lds + (bufoff) + ldsw + _i * 8192), 16, 0, 0); } while (0)
; #define PG8_LDA(dst, b, h) do { _Pragma("unroll") for (int m = 0; m < 4; ++m) _Pragma("unroll") for (int k = 0; k < 2; ++k) dst[m][k] = *(const LAS bf16x8*)(lds + PG8_SA(b, h) + aoff + m * 2048 + k * 1024); } while (0)
; #define PG8_LDB(dst, b, h) do { _Pragma("unroll") for (int n = 0; n < 2; ++n) _Pragma("unroll") for (int k = 0; k < 2; ++k) dst[n][k] = *(const LAS bf16x8*)(lds + PG8_SB(b, h) + boff + n * 2048 + k * 1024); } while (0)
; #define PG8_MMA(ai, bj, At, Bt) do { __builtin_amdgcn_s_setprio(1); _Pragma("unroll") for (int m = 0; m < 4; ++m) _Pragma("unroll") for (int n = 0; n < 2; ++n) _Pragma("unroll") for (int k = 0; k < 2; ++k) \
;         acc[ai][bj][m][n] = __builtin_amdgcn_mfma_f32_16x16x32_bf16(Bt[n][k], At[m][k], acc[ai][bj][m][n], 0, 0, 0); __builtin_amdgcn_s_setprio(0); } while (0)
; #define PG8_WAIT_V(n) asm volatile("s_waitcnt vmcnt(" #n ")" ::: "memory")
; #define PG8_WAIT_L(n) asm volatile("s_waitcnt lgkmcnt(" #n ")" ::: "memory")
; #define PG8_BAR __builtin_amdgcn_s_barrier()
; #define PG8_SCHED __builtin_amdgcn_sched_barrier(0)
; template <class Epi, class Sched, bool ALIGN_EPI = false, bool SP2 = false>
; __device__ __forceinline__ void gemm_phase(LAS unsigned char* lds, const Gemm g, const Sched& S, const Epi& E) {
;     ...
;             PG8_LDB(B0, 1, 0); PG8_LDB(B1, 1, 1); PG8_SCHED; PG8_LDA(At, 1, 0); PG8_STAGE(PG8_SA(0, 1), a2 + hstep, voffA);
;             PG8_WAIT_V(8); PG8_WAIT_L(0); PG8_BAR; PG8_MMA(0, 0, At, B0); PG8_MMA(0, 1, At, B1); PG8_BAR; PG8_SCHED;
	s_add_i32 s16, 0, 0x18000
	s_add_i32 s17, 0, 0x1c000
	v_add_u32_e32 v142, s16, v1
	v_add_u32_e32 v154, s17, v1
	ds_read_b128 v[130:133], v142
	ds_read_b128 v[134:137], v142 offset:1024
	ds_read_b128 v[138:141], v142 offset:2048
	ds_read_b128 v[142:145], v142 offset:3072
	ds_read_b128 v[166:169], v154
	ds_read_b128 v[170:173], v154 offset:1024
	ds_read_b128 v[174:177], v154 offset:2048
	ds_read_b128 v[178:181], v154 offset:3072
	s_add_u32 s14, s58, 0x160000
	s_addc_u32 s15, s59, 0
	s_mov_b32 m0, s31
	v_lshl_add_u64 v[232:233], s[14:15], 0, v[146:147]
	ds_read_b128 v[182:185], v198 offset:32768
	ds_read_b128 v[186:189], v198 offset:33792
	ds_read_b128 v[202:205], v198 offset:34816
	ds_read_b128 v[206:209], v198 offset:35840
	ds_read_b128 v[210:213], v198 offset:36864
	ds_read_b128 v[214:217], v198 offset:37888
	ds_read_b128 v[218:221], v198 offset:38912
	ds_read_b128 v[222:225], v198 offset:39936
	global_load_lds_dwordx4 v[232:233], off
	v_lshl_add_u64 v[232:233], s[14:15], 0, v[150:151]
	s_mov_b32 m0, s33
	s_nop 0
	global_load_lds_dwordx4 v[232:233], off
	s_waitcnt vmcnt(8)
	s_waitcnt lgkmcnt(0)
	s_barrier
	s_waitcnt lgkmcnt(0)
	v_mfma_f32_16x16x32_bf16 v[126:129], v[130:133], v[182:185], v[126:129]
	v_mfma_f32_16x16x32_bf16 v[122:125], v[138:141], v[182:185], v[122:125]
	v_mfma_f32_16x16x32_bf16 v[110:113], v[130:133], v[202:205], v[110:113]
	v_mfma_f32_16x16x32_bf16 v[106:109], v[138:141], v[202:205], v[106:109]
	v_mfma_f32_16x16x32_bf16 v[94:97], v[130:133], v[210:213], v[94:97]
	v_mfma_f32_16x16x32_bf16 v[90:93], v[138:141], v[210:213], v[90:93]
	v_mfma_f32_16x16x32_bf16 v[78:81], v[130:133], v[218:221], v[78:81]
	v_mfma_f32_16x16x32_bf16 v[74:77], v[138:141], v[218:221], v[74:77]
	v_mfma_f32_16x16x32_bf16 v[126:129], v[134:137], v[186:189], v[126:129]
	v_mfma_f32_16x16x32_bf16 v[122:125], v[142:145], v[186:189], v[122:125]
	v_mfma_f32_16x16x32_bf16 v[110:113], v[134:137], v[206:209], v[110:113]
	v_mfma_f32_16x16x32_bf16 v[106:109], v[142:145], v[206:209], v[106:109]
	v_mfma_f32_16x16x32_bf16 v[94:97], v[134:137], v[214:217], v[94:97]
	v_mfma_f32_16x16x32_bf16 v[90:93], v[142:145], v[214:217], v[90:93]
	v_mfma_f32_16x16x32_bf16 v[78:81], v[134:137], v[222:225], v[78:81]
	v_mfma_f32_16x16x32_bf16 v[74:77], v[142:145], v[222:225], v[74:77]
	v_mfma_f32_16x16x32_bf16 v[118:121], v[166:169], v[182:185], v[118:121]
	v_mfma_f32_16x16x32_bf16 v[114:117], v[174:177], v[182:185], v[114:117]
	v_mfma_f32_16x16x32_bf16 v[102:105], v[166:169], v[202:205], v[102:105]
	v_mfma_f32_16x16x32_bf16 v[98:101], v[174:177], v[202:205], v[98:101]
	v_mfma_f32_16x16x32_bf16 v[86:89], v[166:169], v[210:213], v[86:89]
	v_mfma_f32_16x16x32_bf16 v[82:85], v[174:177], v[210:213], v[82:85]
	v_mfma_f32_16x16x32_bf16 v[70:73], v[166:169], v[218:221], v[70:73]
	v_mfma_f32_16x16x32_bf16 v[66:69], v[174:177], v[218:221], v[66:69]
	v_mfma_f32_16x16x32_bf16 v[118:121], v[170:173], v[186:189], v[118:121]
	v_mfma_f32_16x16x32_bf16 v[114:117], v[178:181], v[186:189], v[114:117]
	v_mfma_f32_16x16x32_bf16 v[102:105], v[170:173], v[206:209], v[102:105]
	v_mfma_f32_16x16x32_bf16 v[98:101], v[178:181], v[206:209], v[98:101]
	v_mfma_f32_16x16x32_bf16 v[86:89], v[170:173], v[214:217], v[86:89]
	v_mfma_f32_16x16x32_bf16 v[82:85], v[178:181], v[214:217], v[82:85]
	v_mfma_f32_16x16x32_bf16 v[70:73], v[170:173], v[222:225], v[70:73]
	v_mfma_f32_16x16x32_bf16 v[66:69], v[178:181], v[222:225], v[66:69]
	s_barrier
; #define PG8_STAGE(bufoff, gbase, voff) do { _Pragma("unroll") for (int _i = 0; _i < 2; ++_i) \
;         __builtin_amdgcn_global_load_lds((const unsigned*)((const char*)(gbase) + (voff)[_i]), (LAS unsigned*)(lds + (bufoff) + ldsw + _i * 8192), 16, 0, 0); } while (0)
; #define PG8_LDA(dst, b, h) do { _Pragma("unroll") for (int m = 0; m < 4; ++m) _Pragma("unroll") for (int k = 0; k < 2; ++k) dst[m][k] = *(const LAS bf16x8*)(lds + PG8_SA(b, h) + aoff + m * 2048 + k * 1024); } while (0)
; #define PG8_WAIT_V(n) asm volatile("s_waitcnt vmcnt(" #n ")" ::: "memory")
; template <class Epi, class Sched, bool ALIGN_EPI = false, bool SP2 = false>
; __device__ __forceinline__ void gemm_phase(LAS unsigned char* lds, const Gemm g, const Sched& S, const Epi& E) {
;     ...
;             PG8_LDA(At, 1, 1); PG8_STAGE(PG8_SB(1, 0), b3, voffB); PG8_STAGE(PG8_SB(1, 1), b3 + hstepB, voffB); PG8_STAGE(PG8_SA(1, 0), a3, voffA);
;             PG8_WAIT_V(8); PG8_WAIT_L(0); PG8_BAR; PG8_MMA(1, 0, At, B0); PG8_MMA(1, 1, At, B1); PG8_BAR; PG8_SCHED;
;             } else {
;             PG8_LDB(B0, 0, 0); PG8_SCHED; PG8_LDA(At, 0, 0); PG8_STAGE(PG8_SA(1, 1), a1 + hstep, voffA);
;             PG8_WAIT_L(8); PG8_BAR; PG8_WAIT_L(0); PG8_MMA(0, 0, At, B0); PG8_BAR; PG8_SCHED;
;             PG8_LDB(B1, 0, 1); PG8_STAGE(PG8_SB(0, 0), b2, voffB);
;             PG8_BAR; PG8_WAIT_L(0); PG8_MMA(0, 1, At, B1); PG8_BAR;
;             PG8_LDA(At, 0, 1); PG8_STAGE(PG8_SA(0, 0), a2, voffA);
;             PG8_BAR; PG8_WAIT_L(0); PG8_MMA(1, 0, At, B0); PG8_BAR; PG8_SCHED;
;             PG8_STAGE(PG8_SB(0, 1), b2 + hstepB, voffB);
;             PG8_WAIT_V(6); PG8_BAR; PG8_MMA(1, 1, At, B1); PG8_BAR;
;             PG8_LDB(B0, 1, 0); PG8_SCHED; PG8_LDA(At, 1, 0); PG8_STAGE(PG8_SA(0, 1), a2 + hstep, voffA);
;             PG8_WAIT_L(8); PG8_BAR; PG8_WAIT_L(0); PG8_MMA(0, 0, At, B0); PG8_BAR; PG8_SCHED;
;             PG8_LDB(B1, 1, 1); PG8_STAGE(PG8_SB(1, 0), b3, voffB);
;             PG8_BAR; PG8_WAIT_L(0); PG8_MMA(0, 1, At, B1); PG8_BAR;
;             PG8_LDA(At, 1, 1); PG8_STAGE(PG8_SA(1, 0), a3, voffA);
;             PG8_BAR; PG8_WAIT_L(0); PG8_MMA(1, 0, At, B0); PG8_BAR; PG8_SCHED;
;             PG8_STAGE(PG8_SB(1, 1), b3 + hstepB, voffB);
;             PG8_WAIT_V(6); PG8_BAR; PG8_MMA(1, 1, At, B1); PG8_BAR;
;             }
;         }
;         if constexpr (ALIGN_EPI) { if (wr == 0) PG8_BAR; }
	s_add_i32 s14, s16, s28
	v_lshl_add_u64 v[190:191], v[190:191], 0, s[48:49]
	s_mov_b32 m0, s14
	ds_read_b128 v[182:185], v198 offset:49152
	ds_read_b128 v[186:189], v198 offset:50176
	ds_read_b128 v[202:205], v198 offset:51200
	ds_read_b128 v[206:209], v198 offset:52224
	ds_read_b128 v[210:213], v198 offset:53248
	ds_read_b128 v[214:217], v198 offset:54272
	ds_read_b128 v[218:221], v198 offset:55296
	ds_read_b128 v[222:225], v198 offset:56320
	global_load_lds_dwordx4 v[190:191], off
	s_add_i32 m0, s14, 0x2000
	s_add_u32 s14, s56, 0x58080
	v_lshl_add_u64 v[190:191], v[226:227], 0, s[48:49]
	s_addc_u32 s15, s57, 0
	s_add_i32 s16, s17, s28
	global_load_lds_dwordx4 v[190:191], off
	v_lshl_add_u64 v[190:191], s[14:15], 0, v[148:149]
	s_mov_b32 m0, s16
	s_nop 0
	global_load_lds_dwordx4 v[190:191], off
	v_lshl_add_u64 v[190:191], s[14:15], 0, v[152:153]
	s_add_i32 m0, s16, 0x2000
	s_nop 0
	global_load_lds_dwordx4 v[190:191], off
	v_lshl_add_u64 v[190:191], v[228:229], 0, s[48:49]
	s_mov_b32 m0, s61
	s_nop 0
	global_load_lds_dwordx4 v[190:191], off
	v_lshl_add_u64 v[190:191], v[230:231], 0, s[48:49]
	s_mov_b32 m0, s62
	s_nop 0
	global_load_lds_dwordx4 v[190:191], off
	s_waitcnt vmcnt(8)
	s_waitcnt lgkmcnt(0)
	s_barrier
	s_waitcnt lgkmcnt(0)
	v_mfma_f32_16x16x32_bf16 v[62:65], v[130:133], v[182:185], v[62:65]
	v_mfma_f32_16x16x32_bf16 v[58:61], v[138:141], v[182:185], v[58:61]
	v_mfma_f32_16x16x32_bf16 v[46:49], v[130:133], v[202:205], v[46:49]
	v_mfma_f32_16x16x32_bf16 v[42:45], v[138:141], v[202:205], v[42:45]
	v_mfma_f32_16x16x32_bf16 v[30:33], v[130:133], v[210:213], v[30:33]
	v_mfma_f32_16x16x32_bf16 v[26:29], v[138:141], v[210:213], v[26:29]
	v_mfma_f32_16x16x32_bf16 v[14:17], v[130:133], v[218:221], v[14:17]
	v_mfma_f32_16x16x32_bf16 v[10:13], v[138:141], v[218:221], v[10:13]
	v_mfma_f32_16x16x32_bf16 v[62:65], v[134:137], v[186:189], v[62:65]
	v_mfma_f32_16x16x32_bf16 v[58:61], v[142:145], v[186:189], v[58:61]
	v_mfma_f32_16x16x32_bf16 v[46:49], v[134:137], v[206:209], v[46:49]
	v_mfma_f32_16x16x32_bf16 v[42:45], v[142:145], v[206:209], v[42:45]
	v_mfma_f32_16x16x32_bf16 v[30:33], v[134:137], v[214:217], v[30:33]
	v_mfma_f32_16x16x32_bf16 v[26:29], v[142:145], v[214:217], v[26:29]
	v_mfma_f32_16x16x32_bf16 v[14:17], v[134:137], v[222:225], v[14:17]
	v_mfma_f32_16x16x32_bf16 v[10:13], v[142:145], v[222:225], v[10:13]
	v_mfma_f32_16x16x32_bf16 v[54:57], v[166:169], v[182:185], v[54:57]
	v_mfma_f32_16x16x32_bf16 v[50:53], v[174:177], v[182:185], v[50:53]
	v_mfma_f32_16x16x32_bf16 v[38:41], v[166:169], v[202:205], v[38:41]
	v_mfma_f32_16x16x32_bf16 v[34:37], v[174:177], v[202:205], v[34:37]
	v_mfma_f32_16x16x32_bf16 v[22:25], v[166:169], v[210:213], v[22:25]
	v_mfma_f32_16x16x32_bf16 v[18:21], v[174:177], v[210:213], v[18:21]
	v_mfma_f32_16x16x32_bf16 v[6:9], v[166:169], v[218:221], v[6:9]
	v_mfma_f32_16x16x32_bf16 v[2:5], v[174:177], v[218:221], v[2:5]
	v_mfma_f32_16x16x32_bf16 v[54:57], v[170:173], v[186:189], v[54:57]
	v_mfma_f32_16x16x32_bf16 v[50:53], v[178:181], v[186:189], v[50:53]
	v_mfma_f32_16x16x32_bf16 v[38:41], v[170:173], v[206:209], v[38:41]
	v_mfma_f32_16x16x32_bf16 v[34:37], v[178:181], v[206:209], v[34:37]
	v_mfma_f32_16x16x32_bf16 v[22:25], v[170:173], v[214:217], v[22:25]
	v_mfma_f32_16x16x32_bf16 v[18:21], v[178:181], v[214:217], v[18:21]
	v_mfma_f32_16x16x32_bf16 v[6:9], v[170:173], v[222:225], v[6:9]
	v_mfma_f32_16x16x32_bf16 v[2:5], v[178:181], v[222:225], v[2:5]
	s_barrier
	s_add_i32 s13, s13, 2
	s_add_u32 s5, s5, 0x100
	s_addc_u32 s12, s12, 0
	s_cmpk_gt_u32 s13, 0x55
	s_mov_b64 s[16:17], s[54:55]
	s_cbranch_scc0 .LBB0_317
	s_setprio 0
	s_and_b64 vcc, exec, s[50:51]
	s_cbranch_vccz .LBB0_320
	s_barrier

;     __device__ bool next(int i, Unit& u) const { if (i != 0 || c >= 128) return false; const int t = c >> 2; u.pm = t & 3; u.pn = t >> 2; u.koff = koff_bytes; u.q = c & 3; return true; }
; #define PG8_STAGE(bufoff, gbase, voff) do { _Pragma("unroll") for (int _i = 0; _i < 2; ++_i) \
;         __builtin_amdgcn_global_load_lds((const unsigned*)((const char*)(gbase) + (voff)[_i]), (LAS unsigned*)(lds + (bufoff) + ldsw + _i * 8192), 16, 0, 0); } while (0)
; #define PG8_LDA(dst, b, h) do { _Pragma("unroll") for (int m = 0; m < 4; ++m) _Pragma("unroll") for (int k = 0; k < 2; ++k) dst[m][k] = *(const LAS bf16x8*)(lds + PG8_SA(b, h) + aoff + m * 2048 + k * 1024); } while (0)
; #define PG8_LDB(dst, b, h) do { _Pragma("unroll") for (int n = 0; n < 2; ++n) _Pragma("unroll") for (int k = 0; k < 2; ++k) dst[n][k] = *(const LAS bf16x8*)(lds + PG8_SB(b, h) + boff + n * 2048 + k * 1024); } while (0)
; #define PG8_WAIT_V(n) asm volatile("s_waitcnt vmcnt(" #n ")" ::: "memory")
; #define PG8_WAIT_L(n) asm volatile("s_waitcnt lgkmcnt(" #n ")" ::: "memory")
; #define PG8_BAR __builtin_amdgcn_s_barrier()
; template <class Epi, class Sched, bool ALIGN_EPI = false, bool SP2 = false>
; __device__ __forceinline__ void gemm_phase(LAS unsigned char* lds, const Gemm g, const Sched& S, const Epi& E) {
;     ...
;         const bool has_next = S.next(ui + 1, nxt);
;         const char* nA = has_next ? (const char*)g.A + (size_t)nxt.pm * tstep + nxt.koff : cA; const char* nB = has_next ? (const char*)g.Bt + (size_t)nxt.pn * tstep + nxt.koff : cB;
;         for (int t = 0; t < nt; t += 2) {
;             const bool last = (t == nt - 2);
;             const char* a1 = cA + (size_t)(t + 1) * kstep;
;             const char* a2 = last ? nA : cA + (size_t)(t + 2) * kstep; const char* b2 = last ? nB : cB + (size_t)(t + 2) * kstep;
;             const char* a3 = a2 + kstep; const char* b3 = b2 + kstep;
;             if (last && has_next) S.a_ready(nxt);
;             if constexpr (SP2) {
;             PG8_LDB(B0, 0, 0); PG8_LDB(B1, 0, 1); PG8_SCHED; PG8_LDA(At, 0, 0); PG8_STAGE(PG8_SA(1, 1), a1 + hstep, voffA);
;             PG8_WAIT_V(8); PG8_WAIT_L(0); PG8_BAR; PG8_MMA(0, 0, At, B0); PG8_MMA(0, 1, At, B1); PG8_BAR; PG8_SCHED;
;             PG8_LDA(At, 0, 1); PG8_STAGE(PG8_SB(0, 0), b2, voffB); PG8_STAGE(PG8_SB(0, 1), b2 + hstepB, voffB); PG8_STAGE(PG8_SA(0, 0), a2, voffA);
.LBB0_534:
	s_ashr_i32 s53, s52, 31
	s_lshl_b64 s[14:15], s[52:53], 20
	s_add_u32 s54, s93, s14
	s_addc_u32 s55, s92, s15
	s_and_b64 s[14:15], s[44:45], exec
	s_cselect_b32 s0, s55, s17
	s_cselect_b32 s3, s54, s16
	s_ashr_i32 s51, s50, 31
	s_lshl_b64 s[14:15], s[50:51], 20
	s_add_u32 s56, s27, s14
	s_addc_u32 s57, s28, s15
	s_and_b64 s[14:15], s[44:45], exec
	s_cselect_b32 s14, s57, s49
	s_cselect_b32 s15, s56, s48
	s_add_u32 s16, s16, 0x80080
	s_addc_u32 s17, s17, 0
	s_add_u32 s18, s48, 0x100
	s_addc_u32 s19, s49, 0
	s_mov_b32 s20, -2
	v_readfirstlane_b32 s98, v0
	s_nop 3
	s_lshr_b32 s98, s98, 6
	s_cmp_ge_u32 s98, 4
	s_cbranch_scc0 .Lprio_535
	s_setprio 1
.Lprio_535:
	ds_read_b128 v[34:37], v203
	ds_read_b128 v[38:41], v203 offset:1024
	ds_read_b128 v[42:45], v203 offset:2048
	ds_read_b128 v[46:49], v203 offset:3072
	s_waitcnt vmcnt(0)
	ds_read_b128 v[98:101], v204
	ds_read_b128 v[102:105], v204 offset:1024
	ds_read_b128 v[106:109], v204 offset:2048
	ds_read_b128 v[110:113], v204 offset:3072
	s_add_u32 s21, s16, 0xfff80080
	s_addc_u32 s22, s17, -1
	s_cmp_eq_u32 s20, 28
	s_cselect_b32 s59, s0, s22
	s_cselect_b32 s58, s3, s21
	s_cselect_b32 s49, s14, s19
	s_cselect_b32 s48, s15, s18
	v_lshl_add_u64 v[182:183], s[16:17], 0, v[172:173]
	s_add_i32 m0, s30, 0xc000
	ds_read_b128 v[212:215], v205
	ds_read_b128 v[216:219], v205 offset:1024
	ds_read_b128 v[220:223], v205 offset:2048
	ds_read_b128 v[224:227], v205 offset:3072
	ds_read_b128 v[228:231], v205 offset:4096
	ds_read_b128 v[232:235], v205 offset:5120
	ds_read_b128 v[236:239], v205 offset:6144
	ds_read_b128 v[240:243], v205 offset:7168
	global_load_lds_dwordx4 v[182:183], off
	v_lshl_add_u64 v[182:183], s[16:17], 0, v[174:175]
	s_add_i32 m0, s30, 0xe000
	s_nop 0
	global_load_lds_dwordx4 v[182:183], off
	s_waitcnt lgkmcnt(0)
	s_barrier
	s_waitcnt lgkmcnt(0)
	v_mfma_f32_16x16x32_bf16 v[158:161], v[34:37], v[212:215], 0
	v_mfma_f32_16x16x32_bf16 v[154:157], v[42:45], v[212:215], 0
	v_mfma_f32_16x16x32_bf16 v[142:145], v[34:37], v[220:223], 0
	v_mfma_f32_16x16x32_bf16 v[138:141], v[42:45], v[220:223], 0
	v_mfma_f32_16x16x32_bf16 v[126:129], v[34:37], v[228:231], 0
	v_mfma_f32_16x16x32_bf16 v[122:125], v[42:45], v[228:231], 0
	v_mfma_f32_16x16x32_bf16 v[94:97], v[34:37], v[236:239], 0
	v_mfma_f32_16x16x32_bf16 v[90:93], v[42:45], v[236:239], 0
	v_mfma_f32_16x16x32_bf16 v[158:161], v[38:41], v[216:219], v[158:161]
	v_mfma_f32_16x16x32_bf16 v[154:157], v[46:49], v[216:219], v[154:157]
	v_mfma_f32_16x16x32_bf16 v[142:145], v[38:41], v[224:227], v[142:145]
	v_mfma_f32_16x16x32_bf16 v[138:141], v[46:49], v[224:227], v[138:141]
	v_mfma_f32_16x16x32_bf16 v[126:129], v[38:41], v[232:235], v[126:129]
	v_mfma_f32_16x16x32_bf16 v[122:125], v[46:49], v[232:235], v[122:125]
	v_mfma_f32_16x16x32_bf16 v[94:97], v[38:41], v[240:243], v[94:97]
	v_mfma_f32_16x16x32_bf16 v[90:93], v[46:49], v[240:243], v[90:93]
	v_mfma_f32_16x16x32_bf16 v[150:153], v[98:101], v[212:215], 0
	v_mfma_f32_16x16x32_bf16 v[146:149], v[106:109], v[212:215], 0
	v_mfma_f32_16x16x32_bf16 v[134:137], v[98:101], v[220:223], 0
	v_mfma_f32_16x16x32_bf16 v[130:133], v[106:109], v[220:223], 0
	v_mfma_f32_16x16x32_bf16 v[118:121], v[98:101], v[228:231], 0
	v_mfma_f32_16x16x32_bf16 v[114:117], v[106:109], v[228:231], 0
	v_mfma_f32_16x16x32_bf16 v[86:89], v[98:101], v[236:239], 0
	v_mfma_f32_16x16x32_bf16 v[82:85], v[106:109], v[236:239], 0
	v_mfma_f32_16x16x32_bf16 v[150:153], v[102:105], v[216:219], v[150:153]
	v_mfma_f32_16x16x32_bf16 v[146:149], v[110:113], v[216:219], v[146:149]
	v_mfma_f32_16x16x32_bf16 v[134:137], v[102:105], v[224:227], v[134:137]
	v_mfma_f32_16x16x32_bf16 v[130:133], v[110:113], v[224:227], v[130:133]
	v_mfma_f32_16x16x32_bf16 v[118:121], v[102:105], v[232:235], v[118:121]
	v_mfma_f32_16x16x32_bf16 v[114:117], v[110:113], v[232:235], v[114:117]
	v_mfma_f32_16x16x32_bf16 v[86:89], v[102:105], v[240:243], v[86:89]
	v_mfma_f32_16x16x32_bf16 v[82:85], v[110:113], v[240:243], v[82:85]
	s_barrier
	s_add_i32 s21, s68, s29
	v_lshl_add_u64 v[182:183], s[48:49], 0, v[164:165]
	s_mov_b32 m0, s21
	ds_read_b128 v[212:215], v205 offset:16384
	ds_read_b128 v[216:219], v205 offset:17408
	ds_read_b128 v[220:223], v205 offset:18432
	ds_read_b128 v[224:227], v205 offset:19456
	ds_read_b128 v[228:231], v205 offset:20480
	ds_read_b128 v[232:235], v205 offset:21504
	ds_read_b128 v[236:239], v205 offset:22528
	ds_read_b128 v[240:243], v205 offset:23552
	global_load_lds_dwordx4 v[182:183], off
	s_add_i32 m0, s21, 0x2000
	s_add_u32 s22, s48, 0x20000
	v_lshl_add_u64 v[244:245], s[48:49], 0, v[168:169]
	s_addc_u32 s23, s49, 0
	s_add_i32 s21, s69, s29
	global_load_lds_dwordx4 v[244:245], off
	v_lshl_add_u64 v[246:247], s[22:23], 0, v[164:165]
	s_mov_b32 m0, s21
	v_lshl_add_u64 v[248:249], s[58:59], 0, v[166:167]
	global_load_lds_dwordx4 v[246:247], off
	v_lshl_add_u64 v[246:247], s[22:23], 0, v[168:169]
	s_add_i32 m0, s21, 0x2000
	s_nop 0
	global_load_lds_dwordx4 v[246:247], off
	v_lshl_add_u64 v[246:247], s[58:59], 0, v[162:163]
	s_mov_b32 m0, s30
	s_nop 0
	global_load_lds_dwordx4 v[246:247], off
	s_mov_b32 m0, s31
	s_nop 0
	global_load_lds_dwordx4 v[248:249], off
	s_waitcnt lgkmcnt(0)
	s_barrier
; #define PG8_STAGE(bufoff, gbase, voff) do { _Pragma("unroll") for (int _i = 0; _i < 2; ++_i) \
;         __builtin_amdgcn_global_load_lds((const unsigned*)((const char*)(gbase) + (voff)[_i]), (LAS unsigned*)(lds + (bufoff) + ldsw + _i * 8192), 16, 0, 0); } while (0)
; #define PG8_LDA(dst, b, h) do { _Pragma("unroll") for (int m = 0; m < 4; ++m) _Pragma("unroll") for (int k = 0; k < 2; ++k) dst[m][k] = *(const LAS bf16x8*)(lds + PG8_SA(b, h) + aoff + m * 2048 + k * 1024); } while (0)
; #define PG8_LDB(dst, b, h) do { _Pragma("unroll") for (int n = 0; n < 2; ++n) _Pragma("unroll") for (int k = 0; k < 2; ++k) dst[n][k] = *(const LAS bf16x8*)(lds + PG8_SB(b, h) + boff + n * 2048 + k * 1024); } while (0)
; #define PG8_MMA(ai, bj, At, Bt) do { __builtin_amdgcn_s_setprio(1); _Pragma("unroll") for (int m = 0; m < 4; ++m) _Pragma("unroll") for (int n = 0; n < 2; ++n) _Pragma("unroll") for (int k = 0; k < 2; ++k) \
;         acc[ai][bj][m][n] = __builtin_amdgcn_mfma_f32_16x16x32_bf16(Bt[n][k], At[m][k], acc[ai][bj][m][n], 0, 0, 0); __builtin_amdgcn_s_setprio(0); } while (0)
; #define PG8_WAIT_V(n) asm volatile("s_waitcnt vmcnt(" #n ")" ::: "memory")
; #define PG8_WAIT_L(n) asm volatile("s_waitcnt lgkmcnt(" #n ")" ::: "memory")
; #define PG8_BAR __builtin_amdgcn_s_barrier()
; #define PG8_SCHED __builtin_amdgcn_sched_barrier(0)
; template <class Epi, class Sched, bool ALIGN_EPI = false, bool SP2 = false>
; __device__ __forceinline__ void gemm_phase(LAS unsigned char* lds, const Gemm g, const Sched& S, const Epi& E) {
;     ...
;             PG8_WAIT_V(8); PG8_WAIT_L(0); PG8_BAR; PG8_MMA(0, 0, At, B0); PG8_MMA(0, 1, At, B1); PG8_BAR; PG8_SCHED;
;             PG8_LDA(At, 0, 1); PG8_STAGE(PG8_SB(0, 0), b2, voffB); PG8_STAGE(PG8_SB(0, 1), b2 + hstepB, voffB); PG8_STAGE(PG8_SA(0, 0), a2, voffA);
;             PG8_WAIT_V(8); PG8_WAIT_L(0); PG8_BAR; PG8_MMA(1, 0, At, B0); PG8_MMA(1, 1, At, B1); PG8_BAR; PG8_SCHED;
;             PG8_LDB(B0, 1, 0); PG8_LDB(B1, 1, 1); PG8_SCHED; PG8_LDA(At, 1, 0); PG8_STAGE(PG8_SA(0, 1), a2 + hstep, voffA);
;             PG8_WAIT_V(8); PG8_WAIT_L(0); PG8_BAR; PG8_MMA(0, 0, At, B0); PG8_MMA(0, 1, At, B1); PG8_BAR; PG8_SCHED;
	s_waitcnt lgkmcnt(0)
	v_mfma_f32_16x16x32_bf16 v[78:81], v[34:37], v[212:215], 0
	v_mfma_f32_16x16x32_bf16 v[74:77], v[42:45], v[212:215], 0
	v_mfma_f32_16x16x32_bf16 v[62:65], v[34:37], v[220:223], 0
	v_mfma_f32_16x16x32_bf16 v[58:61], v[42:45], v[220:223], 0
	v_mfma_f32_16x16x32_bf16 v[30:33], v[34:37], v[228:231], 0
	v_mfma_f32_16x16x32_bf16 v[26:29], v[42:45], v[228:231], 0
	v_mfma_f32_16x16x32_bf16 v[14:17], v[34:37], v[236:239], 0
	v_mfma_f32_16x16x32_bf16 v[10:13], v[42:45], v[236:239], 0
	v_mfma_f32_16x16x32_bf16 v[78:81], v[38:41], v[216:219], v[78:81]
	v_mfma_f32_16x16x32_bf16 v[74:77], v[46:49], v[216:219], v[74:77]
	v_mfma_f32_16x16x32_bf16 v[62:65], v[38:41], v[224:227], v[62:65]
	v_mfma_f32_16x16x32_bf16 v[58:61], v[46:49], v[224:227], v[58:61]
	v_mfma_f32_16x16x32_bf16 v[30:33], v[38:41], v[232:235], v[30:33]
	v_mfma_f32_16x16x32_bf16 v[26:29], v[46:49], v[232:235], v[26:29]
	v_mfma_f32_16x16x32_bf16 v[14:17], v[38:41], v[240:243], v[14:17]
	v_mfma_f32_16x16x32_bf16 v[10:13], v[46:49], v[240:243], v[10:13]
	v_mfma_f32_16x16x32_bf16 v[22:25], v[98:101], v[228:231], 0
	v_mfma_f32_16x16x32_bf16 v[18:21], v[106:109], v[228:231], 0
	v_mfma_f32_16x16x32_bf16 v[6:9], v[98:101], v[236:239], 0
	v_mfma_f32_16x16x32_bf16 v[2:5], v[106:109], v[236:239], 0
	v_mfma_f32_16x16x32_bf16 v[34:37], v[98:101], v[212:215], 0
	v_mfma_f32_16x16x32_bf16 v[38:41], v[106:109], v[212:215], 0
	v_mfma_f32_16x16x32_bf16 v[42:45], v[98:101], v[220:223], 0
	v_mfma_f32_16x16x32_bf16 v[46:49], v[106:109], v[220:223], 0
	v_mfma_f32_16x16x32_bf16 v[22:25], v[102:105], v[232:235], v[22:25]
	v_mfma_f32_16x16x32_bf16 v[18:21], v[110:113], v[232:235], v[18:21]
	v_mfma_f32_16x16x32_bf16 v[6:9], v[102:105], v[240:243], v[6:9]
	v_mfma_f32_16x16x32_bf16 v[2:5], v[110:113], v[240:243], v[2:5]
	v_mfma_f32_16x16x32_bf16 v[34:37], v[102:105], v[216:219], v[34:37]
	v_mfma_f32_16x16x32_bf16 v[38:41], v[110:113], v[216:219], v[38:41]
	v_mfma_f32_16x16x32_bf16 v[42:45], v[102:105], v[224:227], v[42:45]
	v_mfma_f32_16x16x32_bf16 v[46:49], v[110:113], v[224:227], v[46:49]
	s_barrier
	s_add_i32 s21, 0, 0x18000
	s_add_i32 s24, 0, 0x1c000
	v_add_u32_e32 v70, s21, v186
	v_add_u32_e32 v110, s24, v186
	ds_read_b128 v[50:53], v70
	ds_read_b128 v[54:57], v70 offset:1024
	ds_read_b128 v[66:69], v70 offset:2048
	ds_read_b128 v[70:73], v70 offset:3072
	ds_read_b128 v[98:101], v110
	ds_read_b128 v[102:105], v110 offset:1024
	ds_read_b128 v[106:109], v110 offset:2048
	ds_read_b128 v[110:113], v110 offset:3072
	s_add_u32 s22, s58, 0x80000
	s_addc_u32 s23, s59, 0
	s_mov_b32 m0, s33
	v_lshl_add_u64 v[250:251], s[22:23], 0, v[162:163]
	ds_read_b128 v[212:215], v205 offset:32768
	ds_read_b128 v[216:219], v205 offset:33792
	ds_read_b128 v[220:223], v205 offset:34816
	ds_read_b128 v[224:227], v205 offset:35840
	ds_read_b128 v[228:231], v205 offset:36864
	ds_read_b128 v[232:235], v205 offset:37888
	ds_read_b128 v[236:239], v205 offset:38912
	ds_read_b128 v[240:243], v205 offset:39936
	global_load_lds_dwordx4 v[250:251], off
	v_lshl_add_u64 v[250:251], s[22:23], 0, v[166:167]
	s_mov_b32 m0, s60
	s_nop 0
	global_load_lds_dwordx4 v[250:251], off
	s_waitcnt vmcnt(8)
	s_waitcnt lgkmcnt(0)
	s_barrier
	s_waitcnt lgkmcnt(0)
	v_mfma_f32_16x16x32_bf16 v[158:161], v[50:53], v[212:215], v[158:161]
	v_mfma_f32_16x16x32_bf16 v[154:157], v[66:69], v[212:215], v[154:157]
	v_mfma_f32_16x16x32_bf16 v[142:145], v[50:53], v[220:223], v[142:145]
	v_mfma_f32_16x16x32_bf16 v[138:141], v[66:69], v[220:223], v[138:141]
	v_mfma_f32_16x16x32_bf16 v[126:129], v[50:53], v[228:231], v[126:129]
	v_mfma_f32_16x16x32_bf16 v[122:125], v[66:69], v[228:231], v[122:125]
	v_mfma_f32_16x16x32_bf16 v[94:97], v[50:53], v[236:239], v[94:97]
	v_mfma_f32_16x16x32_bf16 v[90:93], v[66:69], v[236:239], v[90:93]
	v_mfma_f32_16x16x32_bf16 v[158:161], v[54:57], v[216:219], v[158:161]
	v_mfma_f32_16x16x32_bf16 v[154:157], v[70:73], v[216:219], v[154:157]
	v_mfma_f32_16x16x32_bf16 v[142:145], v[54:57], v[224:227], v[142:145]
	v_mfma_f32_16x16x32_bf16 v[138:141], v[70:73], v[224:227], v[138:141]
	v_mfma_f32_16x16x32_bf16 v[126:129], v[54:57], v[232:235], v[126:129]
	v_mfma_f32_16x16x32_bf16 v[122:125], v[70:73], v[232:235], v[122:125]
	v_mfma_f32_16x16x32_bf16 v[94:97], v[54:57], v[240:243], v[94:97]
	v_mfma_f32_16x16x32_bf16 v[90:93], v[70:73], v[240:243], v[90:93]
	v_mfma_f32_16x16x32_bf16 v[150:153], v[98:101], v[212:215], v[150:153]
	v_mfma_f32_16x16x32_bf16 v[146:149], v[106:109], v[212:215], v[146:149]
	v_mfma_f32_16x16x32_bf16 v[134:137], v[98:101], v[220:223], v[134:137]
	v_mfma_f32_16x16x32_bf16 v[130:133], v[106:109], v[220:223], v[130:133]
	v_mfma_f32_16x16x32_bf16 v[118:121], v[98:101], v[228:231], v[118:121]
	v_mfma_f32_16x16x32_bf16 v[114:117], v[106:109], v[228:231], v[114:117]
	v_mfma_f32_16x16x32_bf16 v[86:89], v[98:101], v[236:239], v[86:89]
	v_mfma_f32_16x16x32_bf16 v[82:85], v[106:109], v[236:239], v[82:85]
	v_mfma_f32_16x16x32_bf16 v[150:153], v[102:105], v[216:219], v[150:153]
	v_mfma_f32_16x16x32_bf16 v[146:149], v[110:113], v[216:219], v[146:149]
	v_mfma_f32_16x16x32_bf16 v[134:137], v[102:105], v[224:227], v[134:137]
	v_mfma_f32_16x16x32_bf16 v[130:133], v[110:113], v[224:227], v[130:133]
	v_mfma_f32_16x16x32_bf16 v[118:121], v[102:105], v[232:235], v[118:121]
	v_mfma_f32_16x16x32_bf16 v[114:117], v[110:113], v[232:235], v[114:117]
	v_mfma_f32_16x16x32_bf16 v[86:89], v[102:105], v[240:243], v[86:89]
	v_mfma_f32_16x16x32_bf16 v[82:85], v[110:113], v[240:243], v[82:85]
	s_barrier
; #define PG8_STAGE(bufoff, gbase, voff) do { _Pragma("unroll") for (int _i = 0; _i < 2; ++_i) \
;         __builtin_amdgcn_global_load_lds((const unsigned*)((const char*)(gbase) + (voff)[_i]), (LAS unsigned*)(lds + (bufoff) + ldsw + _i * 8192), 16, 0, 0); } while (0)
; #define PG8_LDA(dst, b, h) do { _Pragma("unroll") for (int m = 0; m < 4; ++m) _Pragma("unroll") for (int k = 0; k < 2; ++k) dst[m][k] = *(const LAS bf16x8*)(lds + PG8_SA(b, h) + aoff + m * 2048 + k * 1024); } while (0)
; #define PG8_LDB(dst, b, h) do { _Pragma("unroll") for (int n = 0; n < 2; ++n) _Pragma("unroll") for (int k = 0; k < 2; ++k) dst[n][k] = *(const LAS bf16x8*)(lds + PG8_SB(b, h) + boff + n * 2048 + k * 1024); } while (0)
; template <class Epi, class Sched, bool ALIGN_EPI = false, bool SP2 = false>
; __device__ __forceinline__ void gemm_phase(LAS unsigned char* lds, const Gemm g, const Sched& S, const Epi& E) {
;     ...
;         for (int t = 0; t < nt; t += 2) {
;             const bool last = (t == nt - 2);
;             const char* a1 = cA + (size_t)(t + 1) * kstep;
;             const char* a2 = last ? nA : cA + (size_t)(t + 2) * kstep; const char* b2 = last ? nB : cB + (size_t)(t + 2) * kstep;
;             const char* a3 = a2 + kstep; const char* b3 = b2 + kstep;
;             if (last && has_next) S.a_ready(nxt);
;             if constexpr (SP2) {
;             PG8_LDB(B0, 0, 0); PG8_LDB(B1, 0, 1); PG8_SCHED; PG8_LDA(At, 0, 0); PG8_STAGE(PG8_SA(1, 1), a1 + hstep, voffA);
;             PG8_WAIT_V(8); PG8_WAIT_L(0); PG8_BAR; PG8_MMA(0, 0, At, B0); PG8_MMA(0, 1, At, B1); PG8_BAR; PG8_SCHED;
;             PG8_LDA(At, 0, 1); PG8_STAGE(PG8_SB(0, 0), b2, voffB); PG8_STAGE(PG8_SB(0, 1), b2 + hstepB, voffB); PG8_STAGE(PG8_SA(0, 0), a2, voffA);
;             PG8_WAIT_V(8); PG8_WAIT_L(0); PG8_BAR; PG8_MMA(1, 0, At, B0); PG8_MMA(1, 1, At, B1); PG8_BAR; PG8_SCHED;
;             PG8_LDB(B0, 1, 0); PG8_LDB(B1, 1, 1); PG8_SCHED; PG8_LDA(At, 1, 0); PG8_STAGE(PG8_SA(0, 1), a2 + hstep, voffA);
;             PG8_WAIT_V(8); PG8_WAIT_L(0); PG8_BAR; PG8_MMA(0, 0, At, B0); PG8_MMA(0, 1, At, B1); PG8_BAR; PG8_SCHED;
;             PG8_LDA(At, 1, 1); PG8_STAGE(PG8_SB(1, 0), b3, voffB); PG8_STAGE(PG8_SB(1, 1), b3 + hstepB, voffB); PG8_STAGE(PG8_SA(1, 0), a3, voffA);
;             PG8_WAIT_V(8); PG8_WAIT_L(0); PG8_BAR; PG8_MMA(1, 0, At, B0); PG8_MMA(1, 1, At, B1); PG8_BAR; PG8_SCHED;
	s_add_i32 s21, s21, s29
	v_lshl_add_u64 v[182:183], v[182:183], 0, s[34:35]
	s_mov_b32 m0, s21
	ds_read_b128 v[212:215], v205 offset:49152
	ds_read_b128 v[216:219], v205 offset:50176
	ds_read_b128 v[220:223], v205 offset:51200
	ds_read_b128 v[224:227], v205 offset:52224
	ds_read_b128 v[228:231], v205 offset:53248
	ds_read_b128 v[232:235], v205 offset:54272
	ds_read_b128 v[236:239], v205 offset:55296
	ds_read_b128 v[240:243], v205 offset:56320
	global_load_lds_dwordx4 v[182:183], off
	s_add_i32 m0, s21, 0x2000
	s_add_u32 s22, s48, 0x20080
	v_lshl_add_u64 v[182:183], v[244:245], 0, s[34:35]
	s_addc_u32 s23, s49, 0
	s_add_i32 s21, s24, s29
	global_load_lds_dwordx4 v[182:183], off
	v_lshl_add_u64 v[182:183], s[22:23], 0, v[164:165]
	s_mov_b32 m0, s21
	s_nop 0
	global_load_lds_dwordx4 v[182:183], off
	v_lshl_add_u64 v[182:183], s[22:23], 0, v[168:169]
	s_add_i32 m0, s21, 0x2000
	s_nop 0
	global_load_lds_dwordx4 v[182:183], off
	v_lshl_add_u64 v[182:183], v[246:247], 0, s[34:35]
	s_mov_b32 m0, s65
	s_nop 0
	global_load_lds_dwordx4 v[182:183], off
	v_lshl_add_u64 v[182:183], v[248:249], 0, s[34:35]
	s_mov_b32 m0, s66
	s_nop 0
	global_load_lds_dwordx4 v[182:183], off
	s_waitcnt vmcnt(8)
	s_waitcnt lgkmcnt(0)
	s_barrier
	s_waitcnt lgkmcnt(0)
	v_mfma_f32_16x16x32_bf16 v[78:81], v[50:53], v[212:215], v[78:81]
	v_mfma_f32_16x16x32_bf16 v[74:77], v[66:69], v[212:215], v[74:77]
	v_mfma_f32_16x16x32_bf16 v[62:65], v[50:53], v[220:223], v[62:65]
	v_mfma_f32_16x16x32_bf16 v[58:61], v[66:69], v[220:223], v[58:61]
	v_mfma_f32_16x16x32_bf16 v[30:33], v[50:53], v[228:231], v[30:33]
	v_mfma_f32_16x16x32_bf16 v[26:29], v[66:69], v[228:231], v[26:29]
	v_mfma_f32_16x16x32_bf16 v[14:17], v[50:53], v[236:239], v[14:17]
	v_mfma_f32_16x16x32_bf16 v[10:13], v[66:69], v[236:239], v[10:13]
	v_mfma_f32_16x16x32_bf16 v[78:81], v[54:57], v[216:219], v[78:81]
	v_mfma_f32_16x16x32_bf16 v[74:77], v[70:73], v[216:219], v[74:77]
	v_mfma_f32_16x16x32_bf16 v[62:65], v[54:57], v[224:227], v[62:65]
	v_mfma_f32_16x16x32_bf16 v[58:61], v[70:73], v[224:227], v[58:61]
	v_mfma_f32_16x16x32_bf16 v[30:33], v[54:57], v[232:235], v[30:33]
	v_mfma_f32_16x16x32_bf16 v[26:29], v[70:73], v[232:235], v[26:29]
	v_mfma_f32_16x16x32_bf16 v[14:17], v[54:57], v[240:243], v[14:17]
	v_mfma_f32_16x16x32_bf16 v[10:13], v[70:73], v[240:243], v[10:13]
	v_mfma_f32_16x16x32_bf16 v[34:37], v[98:101], v[212:215], v[34:37]
	v_mfma_f32_16x16x32_bf16 v[70:73], v[102:105], v[216:219], v[34:37]
	v_mfma_f32_16x16x32_bf16 v[34:37], v[106:109], v[212:215], v[38:41]
	v_mfma_f32_16x16x32_bf16 v[66:69], v[110:113], v[216:219], v[34:37]
	v_mfma_f32_16x16x32_bf16 v[34:37], v[98:101], v[220:223], v[42:45]
	v_mfma_f32_16x16x32_bf16 v[54:57], v[102:105], v[224:227], v[34:37]
	v_mfma_f32_16x16x32_bf16 v[34:37], v[106:109], v[220:223], v[46:49]
	v_mfma_f32_16x16x32_bf16 v[22:25], v[98:101], v[228:231], v[22:25]
	v_mfma_f32_16x16x32_bf16 v[18:21], v[106:109], v[228:231], v[18:21]
	v_mfma_f32_16x16x32_bf16 v[6:9], v[98:101], v[236:239], v[6:9]
	v_mfma_f32_16x16x32_bf16 v[2:5], v[106:109], v[236:239], v[2:5]
	v_mfma_f32_16x16x32_bf16 v[50:53], v[110:113], v[224:227], v[34:37]
	v_mfma_f32_16x16x32_bf16 v[22:25], v[102:105], v[232:235], v[22:25]
	v_mfma_f32_16x16x32_bf16 v[18:21], v[110:113], v[232:235], v[18:21]
	v_mfma_f32_16x16x32_bf16 v[6:9], v[102:105], v[240:243], v[6:9]
	v_mfma_f32_16x16x32_bf16 v[2:5], v[110:113], v[240:243], v[2:5]
	s_barrier
	s_add_i32 s20, s20, 2
	s_add_u32 s16, s16, 0x100
	s_addc_u32 s17, s17, 0
	s_add_u32 s18, s18, 0x100
	s_addc_u32 s19, s19, 0
	s_cmp_gt_u32 s20, 29
.LBB0_535:
	ds_read_b128 v[34:37], v203
	ds_read_b128 v[38:41], v203 offset:1024
	ds_read_b128 v[42:45], v203 offset:2048
	ds_read_b128 v[46:49], v203 offset:3072
	s_waitcnt vmcnt(0)
	ds_read_b128 v[98:101], v204
	ds_read_b128 v[102:105], v204 offset:1024
	ds_read_b128 v[106:109], v204 offset:2048
	ds_read_b128 v[110:113], v204 offset:3072
	s_add_u32 s21, s16, 0xfff80080
	s_addc_u32 s22, s17, -1
	s_cmp_eq_u32 s20, 28
	s_cselect_b32 s59, s0, s22
	s_cselect_b32 s58, s3, s21
	s_cselect_b32 s49, s14, s19
	s_cselect_b32 s48, s15, s18
	v_lshl_add_u64 v[182:183], s[16:17], 0, v[172:173]
	s_add_i32 m0, s30, 0xc000
	ds_read_b128 v[212:215], v205
	ds_read_b128 v[216:219], v205 offset:1024
	ds_read_b128 v[220:223], v205 offset:2048
	ds_read_b128 v[224:227], v205 offset:3072
	ds_read_b128 v[228:231], v205 offset:4096
	ds_read_b128 v[232:235], v205 offset:5120
	ds_read_b128 v[236:239], v205 offset:6144
	ds_read_b128 v[240:243], v205 offset:7168
	global_load_lds_dwordx4 v[182:183], off
	v_lshl_add_u64 v[182:183], s[16:17], 0, v[174:175]
	s_add_i32 m0, s30, 0xe000
	s_nop 0
	global_load_lds_dwordx4 v[182:183], off
	s_waitcnt vmcnt(8)
	s_waitcnt lgkmcnt(0)
	s_barrier
; #define PG8_STAGE(bufoff, gbase, voff) do { _Pragma("unroll") for (int _i = 0; _i < 2; ++_i) \
;         __builtin_amdgcn_global_load_lds((const unsigned*)((const char*)(gbase) + (voff)[_i]), (LAS unsigned*)(lds + (bufoff) + ldsw + _i * 8192), 16, 0, 0); } while (0)
; #define PG8_LDA(dst, b, h) do { _Pragma("unroll") for (int m = 0; m < 4; ++m) _Pragma("unroll") for (int k = 0; k < 2; ++k) dst[m][k] = *(const LAS bf16x8*)(lds + PG8_SA(b, h) + aoff + m * 2048 + k * 1024); } while (0)
; #define PG8_LDB(dst, b, h) do { _Pragma("unroll") for (int n = 0; n < 2; ++n) _Pragma("unroll") for (int k = 0; k < 2; ++k) dst[n][k] = *(const LAS bf16x8*)(lds + PG8_SB(b, h) + boff + n * 2048 + k * 1024); } while (0)
; #define PG8_MMA(ai, bj, At, Bt) do { __builtin_amdgcn_s_setprio(1); _Pragma("unroll") for (int m = 0; m < 4; ++m) _Pragma("unroll") for (int n = 0; n < 2; ++n) _Pragma("unroll") for (int k = 0; k < 2; ++k) \
;         acc[ai][bj][m][n] = __builtin_amdgcn_mfma_f32_16x16x32_bf16(Bt[n][k], At[m][k], acc[ai][bj][m][n], 0, 0, 0); __builtin_amdgcn_s_setprio(0); } while (0)
; #define PG8_WAIT_V(n) asm volatile("s_waitcnt vmcnt(" #n ")" ::: "memory")
; #define PG8_WAIT_L(n) asm volatile("s_waitcnt lgkmcnt(" #n ")" ::: "memory")
; #define PG8_BAR __builtin_amdgcn_s_barrier()
; #define PG8_SCHED __builtin_amdgcn_sched_barrier(0)
; template <class Epi, class Sched, bool ALIGN_EPI = false, bool SP2 = false>
; __device__ __forceinline__ void gemm_phase(LAS unsigned char* lds, const Gemm g, const Sched& S, const Epi& E) {
;     ...
;             PG8_LDB(B0, 0, 0); PG8_LDB(B1, 0, 1); PG8_SCHED; PG8_LDA(At, 0, 0); PG8_STAGE(PG8_SA(1, 1), a1 + hstep, voffA);
;             PG8_WAIT_V(8); PG8_WAIT_L(0); PG8_BAR; PG8_MMA(0, 0, At, B0); PG8_MMA(0, 1, At, B1); PG8_BAR; PG8_SCHED;
;             PG8_LDA(At, 0, 1); PG8_STAGE(PG8_SB(0, 0), b2, voffB); PG8_STAGE(PG8_SB(0, 1), b2 + hstepB, voffB); PG8_STAGE(PG8_SA(0, 0), a2, voffA);
;             PG8_WAIT_V(8); PG8_WAIT_L(0); PG8_BAR; PG8_MMA(1, 0, At, B0); PG8_MMA(1, 1, At, B1); PG8_BAR; PG8_SCHED;
;             PG8_LDB(B0, 1, 0); PG8_LDB(B1, 1, 1); PG8_SCHED; PG8_LDA(At, 1, 0); PG8_STAGE(PG8_SA(0, 1), a2 + hstep, voffA);
	s_waitcnt lgkmcnt(0)
	v_mfma_f32_16x16x32_bf16 v[158:161], v[34:37], v[212:215], v[158:161]
	v_mfma_f32_16x16x32_bf16 v[154:157], v[42:45], v[212:215], v[154:157]
	v_mfma_f32_16x16x32_bf16 v[142:145], v[34:37], v[220:223], v[142:145]
	v_mfma_f32_16x16x32_bf16 v[138:141], v[42:45], v[220:223], v[138:141]
	v_mfma_f32_16x16x32_bf16 v[126:129], v[34:37], v[228:231], v[126:129]
	v_mfma_f32_16x16x32_bf16 v[122:125], v[42:45], v[228:231], v[122:125]
	v_mfma_f32_16x16x32_bf16 v[94:97], v[34:37], v[236:239], v[94:97]
	v_mfma_f32_16x16x32_bf16 v[90:93], v[42:45], v[236:239], v[90:93]
	v_mfma_f32_16x16x32_bf16 v[158:161], v[38:41], v[216:219], v[158:161]
	v_mfma_f32_16x16x32_bf16 v[154:157], v[46:49], v[216:219], v[154:157]
	v_mfma_f32_16x16x32_bf16 v[142:145], v[38:41], v[224:227], v[142:145]
	v_mfma_f32_16x16x32_bf16 v[138:141], v[46:49], v[224:227], v[138:141]
	v_mfma_f32_16x16x32_bf16 v[126:129], v[38:41], v[232:235], v[126:129]
	v_mfma_f32_16x16x32_bf16 v[122:125], v[46:49], v[232:235], v[122:125]
	v_mfma_f32_16x16x32_bf16 v[94:97], v[38:41], v[240:243], v[94:97]
	v_mfma_f32_16x16x32_bf16 v[90:93], v[46:49], v[240:243], v[90:93]
	v_mfma_f32_16x16x32_bf16 v[150:153], v[98:101], v[212:215], v[150:153]
	v_mfma_f32_16x16x32_bf16 v[146:149], v[106:109], v[212:215], v[146:149]
	v_mfma_f32_16x16x32_bf16 v[134:137], v[98:101], v[220:223], v[134:137]
	v_mfma_f32_16x16x32_bf16 v[130:133], v[106:109], v[220:223], v[130:133]
	v_mfma_f32_16x16x32_bf16 v[118:121], v[98:101], v[228:231], v[118:121]
	v_mfma_f32_16x16x32_bf16 v[114:117], v[106:109], v[228:231], v[114:117]
	v_mfma_f32_16x16x32_bf16 v[86:89], v[98:101], v[236:239], v[86:89]
	v_mfma_f32_16x16x32_bf16 v[82:85], v[106:109], v[236:239], v[82:85]
	v_mfma_f32_16x16x32_bf16 v[150:153], v[102:105], v[216:219], v[150:153]
	v_mfma_f32_16x16x32_bf16 v[146:149], v[110:113], v[216:219], v[146:149]
	v_mfma_f32_16x16x32_bf16 v[134:137], v[102:105], v[224:227], v[134:137]
	v_mfma_f32_16x16x32_bf16 v[130:133], v[110:113], v[224:227], v[130:133]
	v_mfma_f32_16x16x32_bf16 v[118:121], v[102:105], v[232:235], v[118:121]
	v_mfma_f32_16x16x32_bf16 v[114:117], v[110:113], v[232:235], v[114:117]
	v_mfma_f32_16x16x32_bf16 v[86:89], v[102:105], v[240:243], v[86:89]
	v_mfma_f32_16x16x32_bf16 v[82:85], v[110:113], v[240:243], v[82:85]
	s_barrier
	s_add_i32 s21, s68, s29
	v_lshl_add_u64 v[182:183], s[48:49], 0, v[164:165]
	s_mov_b32 m0, s21
	ds_read_b128 v[212:215], v205 offset:16384
	ds_read_b128 v[216:219], v205 offset:17408
	ds_read_b128 v[220:223], v205 offset:18432
	ds_read_b128 v[224:227], v205 offset:19456
	ds_read_b128 v[228:231], v205 offset:20480
	ds_read_b128 v[232:235], v205 offset:21504
	ds_read_b128 v[236:239], v205 offset:22528
	ds_read_b128 v[240:243], v205 offset:23552
	global_load_lds_dwordx4 v[182:183], off
	s_add_i32 m0, s21, 0x2000
	s_add_u32 s22, s48, 0x20000
	v_lshl_add_u64 v[244:245], s[48:49], 0, v[168:169]
	s_addc_u32 s23, s49, 0
	s_add_i32 s21, s69, s29
	global_load_lds_dwordx4 v[244:245], off
	v_lshl_add_u64 v[246:247], s[22:23], 0, v[164:165]
	s_mov_b32 m0, s21
	v_lshl_add_u64 v[248:249], s[58:59], 0, v[166:167]
	global_load_lds_dwordx4 v[246:247], off
	v_lshl_add_u64 v[246:247], s[22:23], 0, v[168:169]
	s_add_i32 m0, s21, 0x2000
	s_nop 0
	global_load_lds_dwordx4 v[246:247], off
	v_lshl_add_u64 v[246:247], s[58:59], 0, v[162:163]
	s_mov_b32 m0, s30
	s_nop 0
	global_load_lds_dwordx4 v[246:247], off
	s_mov_b32 m0, s31
	s_nop 0
	global_load_lds_dwordx4 v[248:249], off
	s_waitcnt vmcnt(8)
	s_waitcnt lgkmcnt(0)
	s_barrier
	s_waitcnt lgkmcnt(0)
	v_mfma_f32_16x16x32_bf16 v[78:81], v[34:37], v[212:215], v[78:81]
	v_mfma_f32_16x16x32_bf16 v[74:77], v[42:45], v[212:215], v[74:77]
	v_mfma_f32_16x16x32_bf16 v[62:65], v[34:37], v[220:223], v[62:65]
	v_mfma_f32_16x16x32_bf16 v[58:61], v[42:45], v[220:223], v[58:61]
	v_mfma_f32_16x16x32_bf16 v[30:33], v[34:37], v[228:231], v[30:33]
	v_mfma_f32_16x16x32_bf16 v[26:29], v[42:45], v[228:231], v[26:29]
	v_mfma_f32_16x16x32_bf16 v[14:17], v[34:37], v[236:239], v[14:17]
	v_mfma_f32_16x16x32_bf16 v[10:13], v[42:45], v[236:239], v[10:13]
	v_mfma_f32_16x16x32_bf16 v[78:81], v[38:41], v[216:219], v[78:81]
	v_mfma_f32_16x16x32_bf16 v[74:77], v[46:49], v[216:219], v[74:77]
	v_mfma_f32_16x16x32_bf16 v[62:65], v[38:41], v[224:227], v[62:65]
	v_mfma_f32_16x16x32_bf16 v[58:61], v[46:49], v[224:227], v[58:61]
	v_mfma_f32_16x16x32_bf16 v[30:33], v[38:41], v[232:235], v[30:33]
	v_mfma_f32_16x16x32_bf16 v[26:29], v[46:49], v[232:235], v[26:29]
	v_mfma_f32_16x16x32_bf16 v[14:17], v[38:41], v[240:243], v[14:17]
	v_mfma_f32_16x16x32_bf16 v[10:13], v[46:49], v[240:243], v[10:13]
	v_mfma_f32_16x16x32_bf16 v[22:25], v[98:101], v[228:231], v[22:25]
	v_mfma_f32_16x16x32_bf16 v[18:21], v[106:109], v[228:231], v[18:21]
	v_mfma_f32_16x16x32_bf16 v[6:9], v[98:101], v[236:239], v[6:9]
	v_mfma_f32_16x16x32_bf16 v[2:5], v[106:109], v[236:239], v[2:5]
	v_mfma_f32_16x16x32_bf16 v[34:37], v[98:101], v[212:215], v[70:73]
	v_mfma_f32_16x16x32_bf16 v[38:41], v[106:109], v[212:215], v[66:69]
	v_mfma_f32_16x16x32_bf16 v[42:45], v[98:101], v[220:223], v[54:57]
	v_mfma_f32_16x16x32_bf16 v[46:49], v[106:109], v[220:223], v[50:53]
	v_mfma_f32_16x16x32_bf16 v[22:25], v[102:105], v[232:235], v[22:25]
	v_mfma_f32_16x16x32_bf16 v[18:21], v[110:113], v[232:235], v[18:21]
	v_mfma_f32_16x16x32_bf16 v[6:9], v[102:105], v[240:243], v[6:9]
	v_mfma_f32_16x16x32_bf16 v[2:5], v[110:113], v[240:243], v[2:5]
	v_mfma_f32_16x16x32_bf16 v[34:37], v[102:105], v[216:219], v[34:37]
	v_mfma_f32_16x16x32_bf16 v[38:41], v[110:113], v[216:219], v[38:41]
	v_mfma_f32_16x16x32_bf16 v[42:45], v[102:105], v[224:227], v[42:45]
	v_mfma_f32_16x16x32_bf16 v[46:49], v[110:113], v[224:227], v[46:49]
	s_barrier
; #define PG8_STAGE(bufoff, gbase, voff) do { _Pragma("unroll") for (int _i = 0; _i < 2; ++_i) \
;         __builtin_amdgcn_global_load_lds((const unsigned*)((const char*)(gbase) + (voff)[_i]), (LAS unsigned*)(lds + (bufoff) + ldsw + _i * 8192), 16, 0, 0); } while (0)
; #define PG8_LDA(dst, b, h) do { _Pragma("unroll") for (int m = 0; m < 4; ++m) _Pragma("unroll") for (int k = 0; k < 2; ++k) dst[m][k] = *(const LAS bf16x8*)(lds + PG8_SA(b, h) + aoff + m * 2048 + k * 1024); } while (0)
; #define PG8_LDB(dst, b, h) do { _Pragma("unroll") for (int n = 0; n < 2; ++n) _Pragma("unroll") for (int k = 0; k < 2; ++k) dst[n][k] = *(const LAS bf16x8*)(lds + PG8_SB(b, h) + boff + n * 2048 + k * 1024); } while (0)
; #define PG8_MMA(ai, bj, At, Bt) do { __builtin_amdgcn_s_setprio(1); _Pragma("unroll") for (int m = 0; m < 4; ++m) _Pragma("unroll") for (int n = 0; n < 2; ++n) _Pragma("unroll") for (int k = 0; k < 2; ++k) \
;         acc[ai][bj][m][n] = __builtin_amdgcn_mfma_f32_16x16x32_bf16(Bt[n][k], At[m][k], acc[ai][bj][m][n], 0, 0, 0); __builtin_amdgcn_s_setprio(0); } while (0)
; #define PG8_WAIT_V(n) asm volatile("s_waitcnt vmcnt(" #n ")" ::: "memory")
; #define PG8_WAIT_L(n) asm volatile("s_waitcnt lgkmcnt(" #n ")" ::: "memory")
; #define PG8_BAR __builtin_amdgcn_s_barrier()
; #define PG8_SCHED __builtin_amdgcn_sched_barrier(0)
; template <class Epi, class Sched, bool ALIGN_EPI = false, bool SP2 = false>
; __device__ __forceinline__ void gemm_phase(LAS unsigned char* lds, const Gemm g, const Sched& S, const Epi& E) {
;     ...
;             PG8_LDB(B0, 1, 0); PG8_LDB(B1, 1, 1); PG8_SCHED; PG8_LDA(At, 1, 0); PG8_STAGE(PG8_SA(0, 1), a2 + hstep, voffA);
;             PG8_WAIT_V(8); PG8_WAIT_L(0); PG8_BAR; PG8_MMA(0, 0, At, B0); PG8_MMA(0, 1, At, B1); PG8_BAR; PG8_SCHED;
	s_add_i32 s21, 0, 0x18000
	s_add_i32 s24, 0, 0x1c000
	v_add_u32_e32 v70, s21, v186
	v_add_u32_e32 v110, s24, v186
	ds_read_b128 v[50:53], v70
	ds_read_b128 v[54:57], v70 offset:1024
	ds_read_b128 v[66:69], v70 offset:2048
	ds_read_b128 v[70:73], v70 offset:3072
	ds_read_b128 v[98:101], v110
	ds_read_b128 v[102:105], v110 offset:1024
	ds_read_b128 v[106:109], v110 offset:2048
	ds_read_b128 v[110:113], v110 offset:3072
	s_add_u32 s22, s58, 0x80000
	s_addc_u32 s23, s59, 0
	s_mov_b32 m0, s33
	v_lshl_add_u64 v[250:251], s[22:23], 0, v[162:163]
	ds_read_b128 v[212:215], v205 offset:32768
	ds_read_b128 v[216:219], v205 offset:33792
	ds_read_b128 v[220:223], v205 offset:34816
	ds_read_b128 v[224:227], v205 offset:35840
	ds_read_b128 v[228:231], v205 offset:36864
	ds_read_b128 v[232:235], v205 offset:37888
	ds_read_b128 v[236:239], v205 offset:38912
	ds_read_b128 v[240:243], v205 offset:39936
	global_load_lds_dwordx4 v[250:251], off
	v_lshl_add_u64 v[250:251], s[22:23], 0, v[166:167]
	s_mov_b32 m0, s60
	s_nop 0
	global_load_lds_dwordx4 v[250:251], off
	s_waitcnt vmcnt(8)
	s_waitcnt lgkmcnt(0)
	s_barrier
	s_waitcnt lgkmcnt(0)
	v_mfma_f32_16x16x32_bf16 v[158:161], v[50:53], v[212:215], v[158:161]
	v_mfma_f32_16x16x32_bf16 v[154:157], v[66:69], v[212:215], v[154:157]
	v_mfma_f32_16x16x32_bf16 v[142:145], v[50:53], v[220:223], v[142:145]
	v_mfma_f32_16x16x32_bf16 v[138:141], v[66:69], v[220:223], v[138:141]
	v_mfma_f32_16x16x32_bf16 v[126:129], v[50:53], v[228:231], v[126:129]
	v_mfma_f32_16x16x32_bf16 v[122:125], v[66:69], v[228:231], v[122:125]
	v_mfma_f32_16x16x32_bf16 v[94:97], v[50:53], v[236:239], v[94:97]
	v_mfma_f32_16x16x32_bf16 v[90:93], v[66:69], v[236:239], v[90:93]
	v_mfma_f32_16x16x32_bf16 v[158:161], v[54:57], v[216:219], v[158:161]
	v_mfma_f32_16x16x32_bf16 v[154:157], v[70:73], v[216:219], v[154:157]
	v_mfma_f32_16x16x32_bf16 v[142:145], v[54:57], v[224:227], v[142:145]
	v_mfma_f32_16x16x32_bf16 v[138:141], v[70:73], v[224:227], v[138:141]
	v_mfma_f32_16x16x32_bf16 v[126:129], v[54:57], v[232:235], v[126:129]
	v_mfma_f32_16x16x32_bf16 v[122:125], v[70:73], v[232:235], v[122:125]
	v_mfma_f32_16x16x32_bf16 v[94:97], v[54:57], v[240:243], v[94:97]
	v_mfma_f32_16x16x32_bf16 v[90:93], v[70:73], v[240:243], v[90:93]
	v_mfma_f32_16x16x32_bf16 v[150:153], v[98:101], v[212:215], v[150:153]
	v_mfma_f32_16x16x32_bf16 v[146:149], v[106:109], v[212:215], v[146:149]
	v_mfma_f32_16x16x32_bf16 v[134:137], v[98:101], v[220:223], v[134:137]
	v_mfma_f32_16x16x32_bf16 v[130:133], v[106:109], v[220:223], v[130:133]
	v_mfma_f32_16x16x32_bf16 v[118:121], v[98:101], v[228:231], v[118:121]
	v_mfma_f32_16x16x32_bf16 v[114:117], v[106:109], v[228:231], v[114:117]
	v_mfma_f32_16x16x32_bf16 v[86:89], v[98:101], v[236:239], v[86:89]
	v_mfma_f32_16x16x32_bf16 v[82:85], v[106:109], v[236:239], v[82:85]
	v_mfma_f32_16x16x32_bf16 v[150:153], v[102:105], v[216:219], v[150:153]
	v_mfma_f32_16x16x32_bf16 v[146:149], v[110:113], v[216:219], v[146:149]
	v_mfma_f32_16x16x32_bf16 v[134:137], v[102:105], v[224:227], v[134:137]
	v_mfma_f32_16x16x32_bf16 v[130:133], v[110:113], v[224:227], v[130:133]
	v_mfma_f32_16x16x32_bf16 v[118:121], v[102:105], v[232:235], v[118:121]
	v_mfma_f32_16x16x32_bf16 v[114:117], v[110:113], v[232:235], v[114:117]
	v_mfma_f32_16x16x32_bf16 v[86:89], v[102:105], v[240:243], v[86:89]
	v_mfma_f32_16x16x32_bf16 v[82:85], v[110:113], v[240:243], v[82:85]
	s_barrier
; #define PG8_STAGE(bufoff, gbase, voff) do { _Pragma("unroll") for (int _i = 0; _i < 2; ++_i) \
;         __builtin_amdgcn_global_load_lds((const unsigned*)((const char*)(gbase) + (voff)[_i]), (LAS unsigned*)(lds + (bufoff) + ldsw + _i * 8192), 16, 0, 0); } while (0)
; #define PG8_LDA(dst, b, h) do { _Pragma("unroll") for (int m = 0; m < 4; ++m) _Pragma("unroll") for (int k = 0; k < 2; ++k) dst[m][k] = *(const LAS bf16x8*)(lds + PG8_SA(b, h) + aoff + m * 2048 + k * 1024); } while (0)
; #define PG8_WAIT_V(n) asm volatile("s_waitcnt vmcnt(" #n ")" ::: "memory")
; template <class Epi, class Sched, bool ALIGN_EPI = false, bool SP2 = false>
; __device__ __forceinline__ void gemm_phase(LAS unsigned char* lds, const Gemm g, const Sched& S, const Epi& E) {
;     ...
;             PG8_LDA(At, 1, 1); PG8_STAGE(PG8_SB(1, 0), b3, voffB); PG8_STAGE(PG8_SB(1, 1), b3 + hstepB, voffB); PG8_STAGE(PG8_SA(1, 0), a3, voffA);
;             PG8_WAIT_V(8); PG8_WAIT_L(0); PG8_BAR; PG8_MMA(1, 0, At, B0); PG8_MMA(1, 1, At, B1); PG8_BAR; PG8_SCHED;
;             } else {
;             PG8_LDB(B0, 0, 0); PG8_SCHED; PG8_LDA(At, 0, 0); PG8_STAGE(PG8_SA(1, 1), a1 + hstep, voffA);
;             PG8_WAIT_L(8); PG8_BAR; PG8_WAIT_L(0); PG8_MMA(0, 0, At, B0); PG8_BAR; PG8_SCHED;
;             PG8_LDB(B1, 0, 1); PG8_STAGE(PG8_SB(0, 0), b2, voffB);
;             PG8_BAR; PG8_WAIT_L(0); PG8_MMA(0, 1, At, B1); PG8_BAR;
;             PG8_LDA(At, 0, 1); PG8_STAGE(PG8_SA(0, 0), a2, voffA);
;             PG8_BAR; PG8_WAIT_L(0); PG8_MMA(1, 0, At, B0); PG8_BAR; PG8_SCHED;
;             PG8_STAGE(PG8_SB(0, 1), b2 + hstepB, voffB);
;             PG8_WAIT_V(6); PG8_BAR; PG8_MMA(1, 1, At, B1); PG8_BAR;
;             PG8_LDB(B0, 1, 0); PG8_SCHED; PG8_LDA(At, 1, 0); PG8_STAGE(PG8_SA(0, 1), a2 + hstep, voffA);
;             PG8_WAIT_L(8); PG8_BAR; PG8_WAIT_L(0); PG8_MMA(0, 0, At, B0); PG8_BAR; PG8_SCHED;
;             PG8_LDB(B1, 1, 1); PG8_STAGE(PG8_SB(1, 0), b3, voffB);
;             PG8_BAR; PG8_WAIT_L(0); PG8_MMA(0, 1, At, B1); PG8_BAR;
;             PG8_LDA(At, 1, 1); PG8_STAGE(PG8_SA(1, 0), a3, voffA);
;             PG8_BAR; PG8_WAIT_L(0); PG8_MMA(1, 0, At, B0); PG8_BAR; PG8_SCHED;
;             PG8_STAGE(PG8_SB(1, 1), b3 + hstepB, voffB);
;             PG8_WAIT_V(6); PG8_BAR; PG8_MMA(1, 1, At, B1); PG8_BAR;
;             }
;         }
;         if constexpr (ALIGN_EPI) { if (wr == 0) PG8_BAR; }
	s_add_i32 s21, s21, s29
	v_lshl_add_u64 v[182:183], v[182:183], 0, s[34:35]
	s_mov_b32 m0, s21
	ds_read_b128 v[212:215], v205 offset:49152
	ds_read_b128 v[216:219], v205 offset:50176
	ds_read_b128 v[220:223], v205 offset:51200
	ds_read_b128 v[224:227], v205 offset:52224
	ds_read_b128 v[228:231], v205 offset:53248
	ds_read_b128 v[232:235], v205 offset:54272
	ds_read_b128 v[236:239], v205 offset:55296
	ds_read_b128 v[240:243], v205 offset:56320
	global_load_lds_dwordx4 v[182:183], off
	s_add_i32 m0, s21, 0x2000
	s_add_u32 s22, s48, 0x20080
	v_lshl_add_u64 v[182:183], v[244:245], 0, s[34:35]
	s_addc_u32 s23, s49, 0
	s_add_i32 s21, s24, s29
	global_load_lds_dwordx4 v[182:183], off
	v_lshl_add_u64 v[182:183], s[22:23], 0, v[164:165]
	s_mov_b32 m0, s21
	s_nop 0
	global_load_lds_dwordx4 v[182:183], off
	v_lshl_add_u64 v[182:183], s[22:23], 0, v[168:169]
	s_add_i32 m0, s21, 0x2000
	s_nop 0
	global_load_lds_dwordx4 v[182:183], off
	v_lshl_add_u64 v[182:183], v[246:247], 0, s[34:35]
	s_mov_b32 m0, s65
	s_nop 0
	global_load_lds_dwordx4 v[182:183], off
	v_lshl_add_u64 v[182:183], v[248:249], 0, s[34:35]
	s_mov_b32 m0, s66
	s_nop 0
	global_load_lds_dwordx4 v[182:183], off
	s_waitcnt vmcnt(8)
	s_waitcnt lgkmcnt(0)
	s_barrier
	s_waitcnt lgkmcnt(0)
	v_mfma_f32_16x16x32_bf16 v[78:81], v[50:53], v[212:215], v[78:81]
	v_mfma_f32_16x16x32_bf16 v[74:77], v[66:69], v[212:215], v[74:77]
	v_mfma_f32_16x16x32_bf16 v[62:65], v[50:53], v[220:223], v[62:65]
	v_mfma_f32_16x16x32_bf16 v[58:61], v[66:69], v[220:223], v[58:61]
	v_mfma_f32_16x16x32_bf16 v[30:33], v[50:53], v[228:231], v[30:33]
	v_mfma_f32_16x16x32_bf16 v[26:29], v[66:69], v[228:231], v[26:29]
	v_mfma_f32_16x16x32_bf16 v[14:17], v[50:53], v[236:239], v[14:17]
	v_mfma_f32_16x16x32_bf16 v[10:13], v[66:69], v[236:239], v[10:13]
	v_mfma_f32_16x16x32_bf16 v[78:81], v[54:57], v[216:219], v[78:81]
	v_mfma_f32_16x16x32_bf16 v[74:77], v[70:73], v[216:219], v[74:77]
	v_mfma_f32_16x16x32_bf16 v[62:65], v[54:57], v[224:227], v[62:65]
	v_mfma_f32_16x16x32_bf16 v[58:61], v[70:73], v[224:227], v[58:61]
	v_mfma_f32_16x16x32_bf16 v[30:33], v[54:57], v[232:235], v[30:33]
	v_mfma_f32_16x16x32_bf16 v[26:29], v[70:73], v[232:235], v[26:29]
	v_mfma_f32_16x16x32_bf16 v[14:17], v[54:57], v[240:243], v[14:17]
	v_mfma_f32_16x16x32_bf16 v[10:13], v[70:73], v[240:243], v[10:13]
	v_mfma_f32_16x16x32_bf16 v[34:37], v[98:101], v[212:215], v[34:37]
	v_mfma_f32_16x16x32_bf16 v[70:73], v[102:105], v[216:219], v[34:37]
	v_mfma_f32_16x16x32_bf16 v[34:37], v[106:109], v[212:215], v[38:41]
	v_mfma_f32_16x16x32_bf16 v[66:69], v[110:113], v[216:219], v[34:37]
	v_mfma_f32_16x16x32_bf16 v[34:37], v[98:101], v[220:223], v[42:45]
	v_mfma_f32_16x16x32_bf16 v[54:57], v[102:105], v[224:227], v[34:37]
	v_mfma_f32_16x16x32_bf16 v[34:37], v[106:109], v[220:223], v[46:49]
	v_mfma_f32_16x16x32_bf16 v[22:25], v[98:101], v[228:231], v[22:25]
	v_mfma_f32_16x16x32_bf16 v[18:21], v[106:109], v[228:231], v[18:21]
	v_mfma_f32_16x16x32_bf16 v[6:9], v[98:101], v[236:239], v[6:9]
	v_mfma_f32_16x16x32_bf16 v[2:5], v[106:109], v[236:239], v[2:5]
	v_mfma_f32_16x16x32_bf16 v[50:53], v[110:113], v[224:227], v[34:37]
	v_mfma_f32_16x16x32_bf16 v[22:25], v[102:105], v[232:235], v[22:25]
	v_mfma_f32_16x16x32_bf16 v[18:21], v[110:113], v[232:235], v[18:21]
	v_mfma_f32_16x16x32_bf16 v[6:9], v[102:105], v[240:243], v[6:9]
	v_mfma_f32_16x16x32_bf16 v[2:5], v[110:113], v[240:243], v[2:5]
	s_barrier
	s_add_i32 s20, s20, 2
	s_add_u32 s16, s16, 0x100
	s_addc_u32 s17, s17, 0
	s_add_u32 s18, s18, 0x100
	s_addc_u32 s19, s19, 0
	s_cmp_gt_u32 s20, 29
	s_cbranch_scc0 .LBB0_535
	s_setprio 0
	s_and_b64 vcc, exec, s[76:77]
	s_cbranch_vccz .LBB0_538
	s_barrier

;     __device__ bool next(int i, Unit& u) const { if (i != 0 || c >= 128) return false; const int t = c >> 2; u.pm = t & 3; u.pn = t >> 2; u.koff = koff_bytes; u.q = c & 3; return true; }
; #define PG8_STAGE(bufoff, gbase, voff) do { _Pragma("unroll") for (int _i = 0; _i < 2; ++_i) \
;         __builtin_amdgcn_global_load_lds((const unsigned*)((const char*)(gbase) + (voff)[_i]), (LAS unsigned*)(lds + (bufoff) + ldsw + _i * 8192), 16, 0, 0); } while (0)
; #define PG8_LDA(dst, b, h) do { _Pragma("unroll") for (int m = 0; m < 4; ++m) _Pragma("unroll") for (int k = 0; k < 2; ++k) dst[m][k] = *(const LAS bf16x8*)(lds + PG8_SA(b, h) + aoff + m * 2048 + k * 1024); } while (0)
; #define PG8_LDB(dst, b, h) do { _Pragma("unroll") for (int n = 0; n < 2; ++n) _Pragma("unroll") for (int k = 0; k < 2; ++k) dst[n][k] = *(const LAS bf16x8*)(lds + PG8_SB(b, h) + boff + n * 2048 + k * 1024); } while (0)
; #define PG8_WAIT_V(n) asm volatile("s_waitcnt vmcnt(" #n ")" ::: "memory")
; #define PG8_WAIT_L(n) asm volatile("s_waitcnt lgkmcnt(" #n ")" ::: "memory")
; #define PG8_BAR __builtin_amdgcn_s_barrier()
; template <class Epi, class Sched, bool ALIGN_EPI = false, bool SP2 = false>
; __device__ __forceinline__ void gemm_phase(LAS unsigned char* lds, const Gemm g, const Sched& S, const Epi& E) {
;     ...
;         const bool has_next = S.next(ui + 1, nxt);
;         const char* nA = has_next ? (const char*)g.A + (size_t)nxt.pm * tstep + nxt.koff : cA; const char* nB = has_next ? (const char*)g.Bt + (size_t)nxt.pn * tstep + nxt.koff : cB;
;         for (int t = 0; t < nt; t += 2) {
;             const bool last = (t == nt - 2);
;             const char* a1 = cA + (size_t)(t + 1) * kstep;
;             const char* a2 = last ? nA : cA + (size_t)(t + 2) * kstep; const char* b2 = last ? nB : cB + (size_t)(t + 2) * kstep;
;             const char* a3 = a2 + kstep; const char* b3 = b2 + kstep;
;             if (last && has_next) S.a_ready(nxt);
;             if constexpr (SP2) {
;             PG8_LDB(B0, 0, 0); PG8_LDB(B1, 0, 1); PG8_SCHED; PG8_LDA(At, 0, 0); PG8_STAGE(PG8_SA(1, 1), a1 + hstep, voffA);
;             PG8_WAIT_V(8); PG8_WAIT_L(0); PG8_BAR; PG8_MMA(0, 0, At, B0); PG8_MMA(0, 1, At, B1); PG8_BAR; PG8_SCHED;
;             PG8_LDA(At, 0, 1); PG8_STAGE(PG8_SB(0, 0), b2, voffB); PG8_STAGE(PG8_SB(0, 1), b2 + hstepB, voffB); PG8_STAGE(PG8_SA(0, 0), a2, voffA);
.LBB0_1249:
	s_ashr_i32 s19, s18, 31
	s_lshl_b64 s[20:21], s[18:19], 20
	v_readlane_b32 s0, v252, 25
	s_add_u32 s20, s0, s20
	v_readlane_b32 s0, v252, 26
	s_addc_u32 s21, s0, s21
	s_and_b64 s[22:23], s[44:45], exec
	s_cselect_b32 s0, s21, s17
	s_cselect_b32 s3, s20, s16
	s_ashr_i32 s15, s14, 31
	s_lshl_b64 s[22:23], s[14:15], 20
	s_add_u32 s22, s26, s22
	s_addc_u32 s23, s27, s23
	s_and_b64 s[24:25], s[44:45], exec
	s_cselect_b32 s15, s23, s49
	s_cselect_b32 s19, s22, s48
	s_add_u32 s16, s16, 0x80080
	s_addc_u32 s17, s17, 0
	s_add_u32 s24, s48, 0x100
	s_addc_u32 s25, s49, 0
	s_mov_b32 s47, -2
	s_waitcnt vmcnt(0)
	v_readfirstlane_b32 s98, v0
	s_nop 3
	s_lshr_b32 s98, s98, 6
	s_cmp_ge_u32 s98, 4
	s_cbranch_scc0 .Lprio_1250
	s_setprio 1
.Lprio_1250:
	ds_read_b128 v[50:53], v196
	ds_read_b128 v[54:57], v196 offset:1024
	ds_read_b128 v[138:141], v196 offset:2048
	ds_read_b128 v[142:145], v196 offset:3072
	ds_read_b128 v[146:149], v197
	ds_read_b128 v[150:153], v197 offset:1024
	ds_read_b128 v[174:177], v197 offset:2048
	ds_read_b128 v[178:181], v197 offset:3072
	s_add_u32 s48, s16, 0xfff80080
	s_addc_u32 s49, s17, -1
	s_cmp_eq_u32 s47, 28
	s_cselect_b32 s51, s0, s49
	s_cselect_b32 s50, s3, s48
	s_cselect_b32 s49, s15, s25
	s_cselect_b32 s48, s19, s24
	v_lshl_add_u64 v[190:191], s[16:17], 0, v[166:167]
	s_add_i32 m0, s29, 0xc000
	ds_read_b128 v[182:185], v198
	ds_read_b128 v[186:189], v198 offset:1024
	ds_read_b128 v[202:205], v198 offset:2048
	ds_read_b128 v[206:209], v198 offset:3072
	ds_read_b128 v[210:213], v198 offset:4096
	ds_read_b128 v[214:217], v198 offset:5120
	ds_read_b128 v[218:221], v198 offset:6144
	ds_read_b128 v[222:225], v198 offset:7168
	global_load_lds_dwordx4 v[190:191], off
	v_lshl_add_u64 v[190:191], s[16:17], 0, v[168:169]
	s_add_i32 m0, s29, 0xe000
	s_nop 0
	global_load_lds_dwordx4 v[190:191], off
	s_waitcnt lgkmcnt(0)
	s_barrier
	s_waitcnt lgkmcnt(0)
	v_mfma_f32_16x16x32_bf16 v[134:137], v[50:53], v[182:185], 0
	v_mfma_f32_16x16x32_bf16 v[130:133], v[138:141], v[182:185], 0
	v_mfma_f32_16x16x32_bf16 v[118:121], v[50:53], v[202:205], 0
	v_mfma_f32_16x16x32_bf16 v[114:117], v[138:141], v[202:205], 0
	v_mfma_f32_16x16x32_bf16 v[102:105], v[50:53], v[210:213], 0
	v_mfma_f32_16x16x32_bf16 v[98:101], v[138:141], v[210:213], 0
	v_mfma_f32_16x16x32_bf16 v[86:89], v[50:53], v[218:221], 0
	v_mfma_f32_16x16x32_bf16 v[82:85], v[138:141], v[218:221], 0
	v_mfma_f32_16x16x32_bf16 v[134:137], v[54:57], v[186:189], v[134:137]
	v_mfma_f32_16x16x32_bf16 v[130:133], v[142:145], v[186:189], v[130:133]
	v_mfma_f32_16x16x32_bf16 v[118:121], v[54:57], v[206:209], v[118:121]
	v_mfma_f32_16x16x32_bf16 v[114:117], v[142:145], v[206:209], v[114:117]
	v_mfma_f32_16x16x32_bf16 v[102:105], v[54:57], v[214:217], v[102:105]
	v_mfma_f32_16x16x32_bf16 v[98:101], v[142:145], v[214:217], v[98:101]
	v_mfma_f32_16x16x32_bf16 v[86:89], v[54:57], v[222:225], v[86:89]
	v_mfma_f32_16x16x32_bf16 v[82:85], v[142:145], v[222:225], v[82:85]
	v_mfma_f32_16x16x32_bf16 v[126:129], v[146:149], v[182:185], 0
	v_mfma_f32_16x16x32_bf16 v[122:125], v[174:177], v[182:185], 0
	v_mfma_f32_16x16x32_bf16 v[110:113], v[146:149], v[202:205], 0
	v_mfma_f32_16x16x32_bf16 v[106:109], v[174:177], v[202:205], 0
	v_mfma_f32_16x16x32_bf16 v[94:97], v[146:149], v[210:213], 0
	v_mfma_f32_16x16x32_bf16 v[90:93], v[174:177], v[210:213], 0
	v_mfma_f32_16x16x32_bf16 v[78:81], v[146:149], v[218:221], 0
	v_mfma_f32_16x16x32_bf16 v[74:77], v[174:177], v[218:221], 0
	v_mfma_f32_16x16x32_bf16 v[126:129], v[150:153], v[186:189], v[126:129]
	v_mfma_f32_16x16x32_bf16 v[122:125], v[178:181], v[186:189], v[122:125]
	v_mfma_f32_16x16x32_bf16 v[110:113], v[150:153], v[206:209], v[110:113]
	v_mfma_f32_16x16x32_bf16 v[106:109], v[178:181], v[206:209], v[106:109]
	v_mfma_f32_16x16x32_bf16 v[94:97], v[150:153], v[214:217], v[94:97]
	v_mfma_f32_16x16x32_bf16 v[90:93], v[178:181], v[214:217], v[90:93]
	v_mfma_f32_16x16x32_bf16 v[78:81], v[150:153], v[222:225], v[78:81]
	v_mfma_f32_16x16x32_bf16 v[74:77], v[178:181], v[222:225], v[74:77]
	s_barrier
	s_add_i32 s58, s56, s28
	v_lshl_add_u64 v[190:191], s[48:49], 0, v[156:157]
	s_mov_b32 m0, s58
	ds_read_b128 v[182:185], v198 offset:16384
	ds_read_b128 v[186:189], v198 offset:17408
	ds_read_b128 v[202:205], v198 offset:18432
	ds_read_b128 v[206:209], v198 offset:19456
	ds_read_b128 v[210:213], v198 offset:20480
	ds_read_b128 v[214:217], v198 offset:21504
	ds_read_b128 v[218:221], v198 offset:22528
	ds_read_b128 v[222:225], v198 offset:23552
	global_load_lds_dwordx4 v[190:191], off
	s_add_i32 m0, s58, 0x2000
	s_add_u32 s58, s48, 0x20000
	v_lshl_add_u64 v[226:227], s[48:49], 0, v[160:161]
	s_addc_u32 s59, s49, 0
	s_add_i32 s60, s57, s28
	global_load_lds_dwordx4 v[226:227], off
	v_lshl_add_u64 v[228:229], s[58:59], 0, v[156:157]
	s_mov_b32 m0, s60
	v_lshl_add_u64 v[230:231], s[50:51], 0, v[158:159]
	global_load_lds_dwordx4 v[228:229], off
	v_lshl_add_u64 v[228:229], s[58:59], 0, v[160:161]
	s_add_i32 m0, s60, 0x2000
	s_nop 0
	global_load_lds_dwordx4 v[228:229], off
	v_lshl_add_u64 v[228:229], s[50:51], 0, v[154:155]
	s_mov_b32 m0, s29
	s_nop 0
	global_load_lds_dwordx4 v[228:229], off
	s_mov_b32 m0, s30
	s_nop 0
	global_load_lds_dwordx4 v[230:231], off
	s_waitcnt lgkmcnt(0)
	s_barrier
; #define PG8_STAGE(bufoff, gbase, voff) do { _Pragma("unroll") for (int _i = 0; _i < 2; ++_i) \
;         __builtin_amdgcn_global_load_lds((const unsigned*)((const char*)(gbase) + (voff)[_i]), (LAS unsigned*)(lds + (bufoff) + ldsw + _i * 8192), 16, 0, 0); } while (0)
; #define PG8_LDA(dst, b, h) do { _Pragma("unroll") for (int m = 0; m < 4; ++m) _Pragma("unroll") for (int k = 0; k < 2; ++k) dst[m][k] = *(const LAS bf16x8*)(lds + PG8_SA(b, h) + aoff + m * 2048 + k * 1024); } while (0)
; #define PG8_LDB(dst, b, h) do { _Pragma("unroll") for (int n = 0; n < 2; ++n) _Pragma("unroll") for (int k = 0; k < 2; ++k) dst[n][k] = *(const LAS bf16x8*)(lds + PG8_SB(b, h) + boff + n * 2048 + k * 1024); } while (0)
; #define PG8_MMA(ai, bj, At, Bt) do { __builtin_amdgcn_s_setprio(1); _Pragma("unroll") for (int m = 0; m < 4; ++m) _Pragma("unroll") for (int n = 0; n < 2; ++n) _Pragma("unroll") for (int k = 0; k < 2; ++k) \
;         acc[ai][bj][m][n] = __builtin_amdgcn_mfma_f32_16x16x32_bf16(Bt[n][k], At[m][k], acc[ai][bj][m][n], 0, 0, 0); __builtin_amdgcn_s_setprio(0); } while (0)
; #define PG8_WAIT_V(n) asm volatile("s_waitcnt vmcnt(" #n ")" ::: "memory")
; #define PG8_WAIT_L(n) asm volatile("s_waitcnt lgkmcnt(" #n ")" ::: "memory")
; #define PG8_BAR __builtin_amdgcn_s_barrier()
; #define PG8_SCHED __builtin_amdgcn_sched_barrier(0)
; template <class Epi, class Sched, bool ALIGN_EPI = false, bool SP2 = false>
; __device__ __forceinline__ void gemm_phase(LAS unsigned char* lds, const Gemm g, const Sched& S, const Epi& E) {
;     ...
;             PG8_WAIT_V(8); PG8_WAIT_L(0); PG8_BAR; PG8_MMA(0, 0, At, B0); PG8_MMA(0, 1, At, B1); PG8_BAR; PG8_SCHED;
;             PG8_LDA(At, 0, 1); PG8_STAGE(PG8_SB(0, 0), b2, voffB); PG8_STAGE(PG8_SB(0, 1), b2 + hstepB, voffB); PG8_STAGE(PG8_SA(0, 0), a2, voffA);
;             PG8_WAIT_V(8); PG8_WAIT_L(0); PG8_BAR; PG8_MMA(1, 0, At, B0); PG8_MMA(1, 1, At, B1); PG8_BAR; PG8_SCHED;
;             PG8_LDB(B0, 1, 0); PG8_LDB(B1, 1, 1); PG8_SCHED; PG8_LDA(At, 1, 0); PG8_STAGE(PG8_SA(0, 1), a2 + hstep, voffA);
;             PG8_WAIT_V(8); PG8_WAIT_L(0); PG8_BAR; PG8_MMA(0, 0, At, B0); PG8_MMA(0, 1, At, B1); PG8_BAR; PG8_SCHED;
	s_waitcnt lgkmcnt(0)
	v_mfma_f32_16x16x32_bf16 v[70:73], v[50:53], v[182:185], 0
	v_mfma_f32_16x16x32_bf16 v[66:69], v[138:141], v[182:185], 0
	v_mfma_f32_16x16x32_bf16 v[46:49], v[50:53], v[202:205], 0
	v_mfma_f32_16x16x32_bf16 v[42:45], v[138:141], v[202:205], 0
	v_mfma_f32_16x16x32_bf16 v[30:33], v[50:53], v[210:213], 0
	v_mfma_f32_16x16x32_bf16 v[26:29], v[138:141], v[210:213], 0
	v_mfma_f32_16x16x32_bf16 v[14:17], v[50:53], v[218:221], 0
	v_mfma_f32_16x16x32_bf16 v[10:13], v[138:141], v[218:221], 0
	v_mfma_f32_16x16x32_bf16 v[70:73], v[54:57], v[186:189], v[70:73]
	v_mfma_f32_16x16x32_bf16 v[66:69], v[142:145], v[186:189], v[66:69]
	v_mfma_f32_16x16x32_bf16 v[46:49], v[54:57], v[206:209], v[46:49]
	v_mfma_f32_16x16x32_bf16 v[42:45], v[142:145], v[206:209], v[42:45]
	v_mfma_f32_16x16x32_bf16 v[30:33], v[54:57], v[214:217], v[30:33]
	v_mfma_f32_16x16x32_bf16 v[26:29], v[142:145], v[214:217], v[26:29]
	v_mfma_f32_16x16x32_bf16 v[14:17], v[54:57], v[222:225], v[14:17]
	v_mfma_f32_16x16x32_bf16 v[10:13], v[142:145], v[222:225], v[10:13]
	v_mfma_f32_16x16x32_bf16 v[38:41], v[146:149], v[202:205], 0
	v_mfma_f32_16x16x32_bf16 v[34:37], v[174:177], v[202:205], 0
	v_mfma_f32_16x16x32_bf16 v[22:25], v[146:149], v[210:213], 0
	v_mfma_f32_16x16x32_bf16 v[18:21], v[174:177], v[210:213], 0
	v_mfma_f32_16x16x32_bf16 v[6:9], v[146:149], v[218:221], 0
	v_mfma_f32_16x16x32_bf16 v[2:5], v[174:177], v[218:221], 0
	v_mfma_f32_16x16x32_bf16 v[50:53], v[146:149], v[182:185], 0
	v_mfma_f32_16x16x32_bf16 v[54:57], v[174:177], v[182:185], 0
	v_mfma_f32_16x16x32_bf16 v[38:41], v[150:153], v[206:209], v[38:41]
	v_mfma_f32_16x16x32_bf16 v[34:37], v[178:181], v[206:209], v[34:37]
	v_mfma_f32_16x16x32_bf16 v[22:25], v[150:153], v[214:217], v[22:25]
	v_mfma_f32_16x16x32_bf16 v[18:21], v[178:181], v[214:217], v[18:21]
	v_mfma_f32_16x16x32_bf16 v[6:9], v[150:153], v[222:225], v[6:9]
	v_mfma_f32_16x16x32_bf16 v[2:5], v[178:181], v[222:225], v[2:5]
	v_mfma_f32_16x16x32_bf16 v[50:53], v[150:153], v[186:189], v[50:53]
	v_mfma_f32_16x16x32_bf16 v[54:57], v[178:181], v[186:189], v[54:57]
	s_barrier
	s_add_i32 s58, 0, 0x18000
	s_add_i32 s59, 0, 0x1c000
	v_add_u32_e32 v142, s58, v1
	v_add_u32_e32 v162, s59, v1
	ds_read_b128 v[58:61], v142
	ds_read_b128 v[62:65], v142 offset:1024
	ds_read_b128 v[138:141], v142 offset:2048
	ds_read_b128 v[142:145], v142 offset:3072
	ds_read_b128 v[146:149], v162
	ds_read_b128 v[150:153], v162 offset:1024
	ds_read_b128 v[174:177], v162 offset:2048
	ds_read_b128 v[178:181], v162 offset:3072
	s_add_u32 s50, s50, 0x80000
	s_addc_u32 s51, s51, 0
	s_mov_b32 m0, s31
	v_lshl_add_u64 v[232:233], s[50:51], 0, v[154:155]
	ds_read_b128 v[182:185], v198 offset:32768
	ds_read_b128 v[186:189], v198 offset:33792
	ds_read_b128 v[202:205], v198 offset:34816
	ds_read_b128 v[206:209], v198 offset:35840
	ds_read_b128 v[210:213], v198 offset:36864
	ds_read_b128 v[214:217], v198 offset:37888
	ds_read_b128 v[218:221], v198 offset:38912
	ds_read_b128 v[222:225], v198 offset:39936
	global_load_lds_dwordx4 v[232:233], off
	v_lshl_add_u64 v[232:233], s[50:51], 0, v[158:159]
	s_mov_b32 m0, s33
	s_nop 0
	global_load_lds_dwordx4 v[232:233], off
	s_waitcnt vmcnt(8)
	s_waitcnt lgkmcnt(0)
	s_barrier
	s_waitcnt lgkmcnt(0)
	v_mfma_f32_16x16x32_bf16 v[134:137], v[58:61], v[182:185], v[134:137]
	v_mfma_f32_16x16x32_bf16 v[130:133], v[138:141], v[182:185], v[130:133]
	v_mfma_f32_16x16x32_bf16 v[118:121], v[58:61], v[202:205], v[118:121]
	v_mfma_f32_16x16x32_bf16 v[114:117], v[138:141], v[202:205], v[114:117]
	v_mfma_f32_16x16x32_bf16 v[102:105], v[58:61], v[210:213], v[102:105]
	v_mfma_f32_16x16x32_bf16 v[98:101], v[138:141], v[210:213], v[98:101]
	v_mfma_f32_16x16x32_bf16 v[86:89], v[58:61], v[218:221], v[86:89]
	v_mfma_f32_16x16x32_bf16 v[82:85], v[138:141], v[218:221], v[82:85]
	v_mfma_f32_16x16x32_bf16 v[134:137], v[62:65], v[186:189], v[134:137]
	v_mfma_f32_16x16x32_bf16 v[130:133], v[142:145], v[186:189], v[130:133]
	v_mfma_f32_16x16x32_bf16 v[118:121], v[62:65], v[206:209], v[118:121]
	v_mfma_f32_16x16x32_bf16 v[114:117], v[142:145], v[206:209], v[114:117]
	v_mfma_f32_16x16x32_bf16 v[102:105], v[62:65], v[214:217], v[102:105]
	v_mfma_f32_16x16x32_bf16 v[98:101], v[142:145], v[214:217], v[98:101]
	v_mfma_f32_16x16x32_bf16 v[86:89], v[62:65], v[222:225], v[86:89]
	v_mfma_f32_16x16x32_bf16 v[82:85], v[142:145], v[222:225], v[82:85]
	v_mfma_f32_16x16x32_bf16 v[126:129], v[146:149], v[182:185], v[126:129]
	v_mfma_f32_16x16x32_bf16 v[122:125], v[174:177], v[182:185], v[122:125]
	v_mfma_f32_16x16x32_bf16 v[110:113], v[146:149], v[202:205], v[110:113]
	v_mfma_f32_16x16x32_bf16 v[106:109], v[174:177], v[202:205], v[106:109]
	v_mfma_f32_16x16x32_bf16 v[94:97], v[146:149], v[210:213], v[94:97]
	v_mfma_f32_16x16x32_bf16 v[90:93], v[174:177], v[210:213], v[90:93]
	v_mfma_f32_16x16x32_bf16 v[78:81], v[146:149], v[218:221], v[78:81]
	v_mfma_f32_16x16x32_bf16 v[74:77], v[174:177], v[218:221], v[74:77]
	v_mfma_f32_16x16x32_bf16 v[126:129], v[150:153], v[186:189], v[126:129]
	v_mfma_f32_16x16x32_bf16 v[122:125], v[178:181], v[186:189], v[122:125]
	v_mfma_f32_16x16x32_bf16 v[110:113], v[150:153], v[206:209], v[110:113]
	v_mfma_f32_16x16x32_bf16 v[106:109], v[178:181], v[206:209], v[106:109]
	v_mfma_f32_16x16x32_bf16 v[94:97], v[150:153], v[214:217], v[94:97]
	v_mfma_f32_16x16x32_bf16 v[90:93], v[178:181], v[214:217], v[90:93]
	v_mfma_f32_16x16x32_bf16 v[78:81], v[150:153], v[222:225], v[78:81]
	v_mfma_f32_16x16x32_bf16 v[74:77], v[178:181], v[222:225], v[74:77]
	s_barrier
; #define PG8_STAGE(bufoff, gbase, voff) do { _Pragma("unroll") for (int _i = 0; _i < 2; ++_i) \
;         __builtin_amdgcn_global_load_lds((const unsigned*)((const char*)(gbase) + (voff)[_i]), (LAS unsigned*)(lds + (bufoff) + ldsw + _i * 8192), 16, 0, 0); } while (0)
; #define PG8_LDA(dst, b, h) do { _Pragma("unroll") for (int m = 0; m < 4; ++m) _Pragma("unroll") for (int k = 0; k < 2; ++k) dst[m][k] = *(const LAS bf16x8*)(lds + PG8_SA(b, h) + aoff + m * 2048 + k * 1024); } while (0)
; #define PG8_LDB(dst, b, h) do { _Pragma("unroll") for (int n = 0; n < 2; ++n) _Pragma("unroll") for (int k = 0; k < 2; ++k) dst[n][k] = *(const LAS bf16x8*)(lds + PG8_SB(b, h) + boff + n * 2048 + k * 1024); } while (0)
; template <class Epi, class Sched, bool ALIGN_EPI = false, bool SP2 = false>
; __device__ __forceinline__ void gemm_phase(LAS unsigned char* lds, const Gemm g, const Sched& S, const Epi& E) {
;     ...
;         for (int t = 0; t < nt; t += 2) {
;             const bool last = (t == nt - 2);
;             const char* a1 = cA + (size_t)(t + 1) * kstep;
;             const char* a2 = last ? nA : cA + (size_t)(t + 2) * kstep; const char* b2 = last ? nB : cB + (size_t)(t + 2) * kstep;
;             const char* a3 = a2 + kstep; const char* b3 = b2 + kstep;
;             if (last && has_next) S.a_ready(nxt);
;             if constexpr (SP2) {
;             PG8_LDB(B0, 0, 0); PG8_LDB(B1, 0, 1); PG8_SCHED; PG8_LDA(At, 0, 0); PG8_STAGE(PG8_SA(1, 1), a1 + hstep, voffA);
;             PG8_WAIT_V(8); PG8_WAIT_L(0); PG8_BAR; PG8_MMA(0, 0, At, B0); PG8_MMA(0, 1, At, B1); PG8_BAR; PG8_SCHED;
;             PG8_LDA(At, 0, 1); PG8_STAGE(PG8_SB(0, 0), b2, voffB); PG8_STAGE(PG8_SB(0, 1), b2 + hstepB, voffB); PG8_STAGE(PG8_SA(0, 0), a2, voffA);
;             PG8_WAIT_V(8); PG8_WAIT_L(0); PG8_BAR; PG8_MMA(1, 0, At, B0); PG8_MMA(1, 1, At, B1); PG8_BAR; PG8_SCHED;
;             PG8_LDB(B0, 1, 0); PG8_LDB(B1, 1, 1); PG8_SCHED; PG8_LDA(At, 1, 0); PG8_STAGE(PG8_SA(0, 1), a2 + hstep, voffA);
;             PG8_WAIT_V(8); PG8_WAIT_L(0); PG8_BAR; PG8_MMA(0, 0, At, B0); PG8_MMA(0, 1, At, B1); PG8_BAR; PG8_SCHED;
;             PG8_LDA(At, 1, 1); PG8_STAGE(PG8_SB(1, 0), b3, voffB); PG8_STAGE(PG8_SB(1, 1), b3 + hstepB, voffB); PG8_STAGE(PG8_SA(1, 0), a3, voffA);
;             PG8_WAIT_V(8); PG8_WAIT_L(0); PG8_BAR; PG8_MMA(1, 0, At, B0); PG8_MMA(1, 1, At, B1); PG8_BAR; PG8_SCHED;
	s_add_i32 s50, s58, s28
	v_lshl_add_u64 v[190:191], v[190:191], 0, s[10:11]
	s_mov_b32 m0, s50
	ds_read_b128 v[182:185], v198 offset:49152
	ds_read_b128 v[186:189], v198 offset:50176
	ds_read_b128 v[202:205], v198 offset:51200
	ds_read_b128 v[206:209], v198 offset:52224
	ds_read_b128 v[210:213], v198 offset:53248
	ds_read_b128 v[214:217], v198 offset:54272
	ds_read_b128 v[218:221], v198 offset:55296
	ds_read_b128 v[222:225], v198 offset:56320
	global_load_lds_dwordx4 v[190:191], off
	s_add_i32 m0, s50, 0x2000
	s_add_u32 s48, s48, 0x20080
	v_lshl_add_u64 v[190:191], v[226:227], 0, s[10:11]
	s_addc_u32 s49, s49, 0
	s_add_i32 s50, s59, s28
	global_load_lds_dwordx4 v[190:191], off
	v_lshl_add_u64 v[190:191], s[48:49], 0, v[156:157]
	s_mov_b32 m0, s50
	s_nop 0
	global_load_lds_dwordx4 v[190:191], off
	v_lshl_add_u64 v[190:191], s[48:49], 0, v[160:161]
	s_add_i32 m0, s50, 0x2000
	s_nop 0
	global_load_lds_dwordx4 v[190:191], off
	v_lshl_add_u64 v[190:191], v[228:229], 0, s[10:11]
	s_mov_b32 m0, s53
	s_nop 0
	global_load_lds_dwordx4 v[190:191], off
	v_lshl_add_u64 v[190:191], v[230:231], 0, s[10:11]
	s_mov_b32 m0, s54
	s_nop 0
	global_load_lds_dwordx4 v[190:191], off
	s_waitcnt vmcnt(8)
	s_waitcnt lgkmcnt(0)
	s_barrier
	s_waitcnt lgkmcnt(0)
	v_mfma_f32_16x16x32_bf16 v[70:73], v[58:61], v[182:185], v[70:73]
	v_mfma_f32_16x16x32_bf16 v[66:69], v[138:141], v[182:185], v[66:69]
	v_mfma_f32_16x16x32_bf16 v[46:49], v[58:61], v[202:205], v[46:49]
	v_mfma_f32_16x16x32_bf16 v[42:45], v[138:141], v[202:205], v[42:45]
	v_mfma_f32_16x16x32_bf16 v[30:33], v[58:61], v[210:213], v[30:33]
	v_mfma_f32_16x16x32_bf16 v[26:29], v[138:141], v[210:213], v[26:29]
	v_mfma_f32_16x16x32_bf16 v[14:17], v[58:61], v[218:221], v[14:17]
	v_mfma_f32_16x16x32_bf16 v[10:13], v[138:141], v[218:221], v[10:13]
	v_mfma_f32_16x16x32_bf16 v[70:73], v[62:65], v[186:189], v[70:73]
	v_mfma_f32_16x16x32_bf16 v[66:69], v[142:145], v[186:189], v[66:69]
	v_mfma_f32_16x16x32_bf16 v[46:49], v[62:65], v[206:209], v[46:49]
	v_mfma_f32_16x16x32_bf16 v[42:45], v[142:145], v[206:209], v[42:45]
	v_mfma_f32_16x16x32_bf16 v[30:33], v[62:65], v[214:217], v[30:33]
	v_mfma_f32_16x16x32_bf16 v[26:29], v[142:145], v[214:217], v[26:29]
	v_mfma_f32_16x16x32_bf16 v[14:17], v[62:65], v[222:225], v[14:17]
	v_mfma_f32_16x16x32_bf16 v[10:13], v[142:145], v[222:225], v[10:13]
	v_mfma_f32_16x16x32_bf16 v[50:53], v[146:149], v[182:185], v[50:53]
	v_mfma_f32_16x16x32_bf16 v[62:65], v[150:153], v[186:189], v[50:53]
	v_mfma_f32_16x16x32_bf16 v[50:53], v[174:177], v[182:185], v[54:57]
	v_mfma_f32_16x16x32_bf16 v[38:41], v[146:149], v[202:205], v[38:41]
	v_mfma_f32_16x16x32_bf16 v[34:37], v[174:177], v[202:205], v[34:37]
	v_mfma_f32_16x16x32_bf16 v[22:25], v[146:149], v[210:213], v[22:25]
	v_mfma_f32_16x16x32_bf16 v[18:21], v[174:177], v[210:213], v[18:21]
	v_mfma_f32_16x16x32_bf16 v[6:9], v[146:149], v[218:221], v[6:9]
	v_mfma_f32_16x16x32_bf16 v[2:5], v[174:177], v[218:221], v[2:5]
	v_mfma_f32_16x16x32_bf16 v[58:61], v[178:181], v[186:189], v[50:53]
	v_mfma_f32_16x16x32_bf16 v[38:41], v[150:153], v[206:209], v[38:41]
	v_mfma_f32_16x16x32_bf16 v[34:37], v[178:181], v[206:209], v[34:37]
	v_mfma_f32_16x16x32_bf16 v[22:25], v[150:153], v[214:217], v[22:25]
	v_mfma_f32_16x16x32_bf16 v[18:21], v[178:181], v[214:217], v[18:21]
	v_mfma_f32_16x16x32_bf16 v[6:9], v[150:153], v[222:225], v[6:9]
	v_mfma_f32_16x16x32_bf16 v[2:5], v[178:181], v[222:225], v[2:5]
	s_barrier
	s_add_i32 s47, s47, 2
	s_add_u32 s16, s16, 0x100
	s_addc_u32 s17, s17, 0
	s_add_u32 s24, s24, 0x100
	s_addc_u32 s25, s25, 0
	s_cmp_gt_u32 s47, 29
.LBB0_1250:
	ds_read_b128 v[50:53], v196
	ds_read_b128 v[54:57], v196 offset:1024
	ds_read_b128 v[138:141], v196 offset:2048
	ds_read_b128 v[142:145], v196 offset:3072
	ds_read_b128 v[146:149], v197
	ds_read_b128 v[150:153], v197 offset:1024
	ds_read_b128 v[174:177], v197 offset:2048
	ds_read_b128 v[178:181], v197 offset:3072
	s_add_u32 s48, s16, 0xfff80080
	s_addc_u32 s49, s17, -1
	s_cmp_eq_u32 s47, 28
	s_cselect_b32 s51, s0, s49
	s_cselect_b32 s50, s3, s48
	s_cselect_b32 s49, s15, s25
	s_cselect_b32 s48, s19, s24
	v_lshl_add_u64 v[190:191], s[16:17], 0, v[166:167]
	s_add_i32 m0, s29, 0xc000
	ds_read_b128 v[182:185], v198
	ds_read_b128 v[186:189], v198 offset:1024
	ds_read_b128 v[202:205], v198 offset:2048
	ds_read_b128 v[206:209], v198 offset:3072
	ds_read_b128 v[210:213], v198 offset:4096
	ds_read_b128 v[214:217], v198 offset:5120
	ds_read_b128 v[218:221], v198 offset:6144
	ds_read_b128 v[222:225], v198 offset:7168
	global_load_lds_dwordx4 v[190:191], off
	v_lshl_add_u64 v[190:191], s[16:17], 0, v[168:169]
	s_add_i32 m0, s29, 0xe000
	s_nop 0
	global_load_lds_dwordx4 v[190:191], off
	s_waitcnt vmcnt(8)
	s_waitcnt lgkmcnt(0)
	s_barrier
; #define PG8_STAGE(bufoff, gbase, voff) do { _Pragma("unroll") for (int _i = 0; _i < 2; ++_i) \
;         __builtin_amdgcn_global_load_lds((const unsigned*)((const char*)(gbase) + (voff)[_i]), (LAS unsigned*)(lds + (bufoff) + ldsw + _i * 8192), 16, 0, 0); } while (0)
; #define PG8_LDA(dst, b, h) do { _Pragma("unroll") for (int m = 0; m < 4; ++m) _Pragma("unroll") for (int k = 0; k < 2; ++k) dst[m][k] = *(const LAS bf16x8*)(lds + PG8_SA(b, h) + aoff + m * 2048 + k * 1024); } while (0)
; #define PG8_LDB(dst, b, h) do { _Pragma("unroll") for (int n = 0; n < 2; ++n) _Pragma("unroll") for (int k = 0; k < 2; ++k) dst[n][k] = *(const LAS bf16x8*)(lds + PG8_SB(b, h) + boff + n * 2048 + k * 1024); } while (0)
; #define PG8_MMA(ai, bj, At, Bt) do { __builtin_amdgcn_s_setprio(1); _Pragma("unroll") for (int m = 0; m < 4; ++m) _Pragma("unroll") for (int n = 0; n < 2; ++n) _Pragma("unroll") for (int k = 0; k < 2; ++k) \
;         acc[ai][bj][m][n] = __builtin_amdgcn_mfma_f32_16x16x32_bf16(Bt[n][k], At[m][k], acc[ai][bj][m][n], 0, 0, 0); __builtin_amdgcn_s_setprio(0); } while (0)
; #define PG8_WAIT_V(n) asm volatile("s_waitcnt vmcnt(" #n ")" ::: "memory")
; #define PG8_WAIT_L(n) asm volatile("s_waitcnt lgkmcnt(" #n ")" ::: "memory")
; #define PG8_BAR __builtin_amdgcn_s_barrier()
; #define PG8_SCHED __builtin_amdgcn_sched_barrier(0)
; template <class Epi, class Sched, bool ALIGN_EPI = false, bool SP2 = false>
; __device__ __forceinline__ void gemm_phase(LAS unsigned char* lds, const Gemm g, const Sched& S, const Epi& E) {
;     ...
;             PG8_LDB(B0, 0, 0); PG8_LDB(B1, 0, 1); PG8_SCHED; PG8_LDA(At, 0, 0); PG8_STAGE(PG8_SA(1, 1), a1 + hstep, voffA);
;             PG8_WAIT_V(8); PG8_WAIT_L(0); PG8_BAR; PG8_MMA(0, 0, At, B0); PG8_MMA(0, 1, At, B1); PG8_BAR; PG8_SCHED;
;             PG8_LDA(At, 0, 1); PG8_STAGE(PG8_SB(0, 0), b2, voffB); PG8_STAGE(PG8_SB(0, 1), b2 + hstepB, voffB); PG8_STAGE(PG8_SA(0, 0), a2, voffA);
;             PG8_WAIT_V(8); PG8_WAIT_L(0); PG8_BAR; PG8_MMA(1, 0, At, B0); PG8_MMA(1, 1, At, B1); PG8_BAR; PG8_SCHED;
;             PG8_LDB(B0, 1, 0); PG8_LDB(B1, 1, 1); PG8_SCHED; PG8_LDA(At, 1, 0); PG8_STAGE(PG8_SA(0, 1), a2 + hstep, voffA);
	s_waitcnt lgkmcnt(0)
	v_mfma_f32_16x16x32_bf16 v[134:137], v[50:53], v[182:185], v[134:137]
	v_mfma_f32_16x16x32_bf16 v[130:133], v[138:141], v[182:185], v[130:133]
	v_mfma_f32_16x16x32_bf16 v[118:121], v[50:53], v[202:205], v[118:121]
	v_mfma_f32_16x16x32_bf16 v[114:117], v[138:141], v[202:205], v[114:117]
	v_mfma_f32_16x16x32_bf16 v[102:105], v[50:53], v[210:213], v[102:105]
	v_mfma_f32_16x16x32_bf16 v[98:101], v[138:141], v[210:213], v[98:101]
	v_mfma_f32_16x16x32_bf16 v[86:89], v[50:53], v[218:221], v[86:89]
	v_mfma_f32_16x16x32_bf16 v[82:85], v[138:141], v[218:221], v[82:85]
	v_mfma_f32_16x16x32_bf16 v[134:137], v[54:57], v[186:189], v[134:137]
	v_mfma_f32_16x16x32_bf16 v[130:133], v[142:145], v[186:189], v[130:133]
	v_mfma_f32_16x16x32_bf16 v[118:121], v[54:57], v[206:209], v[118:121]
	v_mfma_f32_16x16x32_bf16 v[114:117], v[142:145], v[206:209], v[114:117]
	v_mfma_f32_16x16x32_bf16 v[102:105], v[54:57], v[214:217], v[102:105]
	v_mfma_f32_16x16x32_bf16 v[98:101], v[142:145], v[214:217], v[98:101]
	v_mfma_f32_16x16x32_bf16 v[86:89], v[54:57], v[222:225], v[86:89]
	v_mfma_f32_16x16x32_bf16 v[82:85], v[142:145], v[222:225], v[82:85]
	v_mfma_f32_16x16x32_bf16 v[126:129], v[146:149], v[182:185], v[126:129]
	v_mfma_f32_16x16x32_bf16 v[122:125], v[174:177], v[182:185], v[122:125]
	v_mfma_f32_16x16x32_bf16 v[110:113], v[146:149], v[202:205], v[110:113]
	v_mfma_f32_16x16x32_bf16 v[106:109], v[174:177], v[202:205], v[106:109]
	v_mfma_f32_16x16x32_bf16 v[94:97], v[146:149], v[210:213], v[94:97]
	v_mfma_f32_16x16x32_bf16 v[90:93], v[174:177], v[210:213], v[90:93]
	v_mfma_f32_16x16x32_bf16 v[78:81], v[146:149], v[218:221], v[78:81]
	v_mfma_f32_16x16x32_bf16 v[74:77], v[174:177], v[218:221], v[74:77]
	v_mfma_f32_16x16x32_bf16 v[126:129], v[150:153], v[186:189], v[126:129]
	v_mfma_f32_16x16x32_bf16 v[122:125], v[178:181], v[186:189], v[122:125]
	v_mfma_f32_16x16x32_bf16 v[110:113], v[150:153], v[206:209], v[110:113]
	v_mfma_f32_16x16x32_bf16 v[106:109], v[178:181], v[206:209], v[106:109]
	v_mfma_f32_16x16x32_bf16 v[94:97], v[150:153], v[214:217], v[94:97]
	v_mfma_f32_16x16x32_bf16 v[90:93], v[178:181], v[214:217], v[90:93]
	v_mfma_f32_16x16x32_bf16 v[78:81], v[150:153], v[222:225], v[78:81]
	v_mfma_f32_16x16x32_bf16 v[74:77], v[178:181], v[222:225], v[74:77]
	s_barrier
	s_add_i32 s58, s56, s28
	v_lshl_add_u64 v[190:191], s[48:49], 0, v[156:157]
	s_mov_b32 m0, s58
	ds_read_b128 v[182:185], v198 offset:16384
	ds_read_b128 v[186:189], v198 offset:17408
	ds_read_b128 v[202:205], v198 offset:18432
	ds_read_b128 v[206:209], v198 offset:19456
	ds_read_b128 v[210:213], v198 offset:20480
	ds_read_b128 v[214:217], v198 offset:21504
	ds_read_b128 v[218:221], v198 offset:22528
	ds_read_b128 v[222:225], v198 offset:23552
	global_load_lds_dwordx4 v[190:191], off
	s_add_i32 m0, s58, 0x2000
	s_add_u32 s58, s48, 0x20000
	v_lshl_add_u64 v[226:227], s[48:49], 0, v[160:161]
	s_addc_u32 s59, s49, 0
	s_add_i32 s60, s57, s28
	global_load_lds_dwordx4 v[226:227], off
	v_lshl_add_u64 v[228:229], s[58:59], 0, v[156:157]
	s_mov_b32 m0, s60
	v_lshl_add_u64 v[230:231], s[50:51], 0, v[158:159]
	global_load_lds_dwordx4 v[228:229], off
	v_lshl_add_u64 v[228:229], s[58:59], 0, v[160:161]
	s_add_i32 m0, s60, 0x2000
	s_nop 0
	global_load_lds_dwordx4 v[228:229], off
	v_lshl_add_u64 v[228:229], s[50:51], 0, v[154:155]
	s_mov_b32 m0, s29
	s_nop 0
	global_load_lds_dwordx4 v[228:229], off
	s_mov_b32 m0, s30
	s_nop 0
	global_load_lds_dwordx4 v[230:231], off
	s_waitcnt vmcnt(8)
	s_waitcnt lgkmcnt(0)
	s_barrier
	s_waitcnt lgkmcnt(0)
	v_mfma_f32_16x16x32_bf16 v[70:73], v[50:53], v[182:185], v[70:73]
	v_mfma_f32_16x16x32_bf16 v[66:69], v[138:141], v[182:185], v[66:69]
	v_mfma_f32_16x16x32_bf16 v[46:49], v[50:53], v[202:205], v[46:49]
	v_mfma_f32_16x16x32_bf16 v[42:45], v[138:141], v[202:205], v[42:45]
	v_mfma_f32_16x16x32_bf16 v[30:33], v[50:53], v[210:213], v[30:33]
	v_mfma_f32_16x16x32_bf16 v[26:29], v[138:141], v[210:213], v[26:29]
	v_mfma_f32_16x16x32_bf16 v[14:17], v[50:53], v[218:221], v[14:17]
	v_mfma_f32_16x16x32_bf16 v[10:13], v[138:141], v[218:221], v[10:13]
	v_mfma_f32_16x16x32_bf16 v[70:73], v[54:57], v[186:189], v[70:73]
	v_mfma_f32_16x16x32_bf16 v[66:69], v[142:145], v[186:189], v[66:69]
	v_mfma_f32_16x16x32_bf16 v[46:49], v[54:57], v[206:209], v[46:49]
	v_mfma_f32_16x16x32_bf16 v[42:45], v[142:145], v[206:209], v[42:45]
	v_mfma_f32_16x16x32_bf16 v[30:33], v[54:57], v[214:217], v[30:33]
	v_mfma_f32_16x16x32_bf16 v[26:29], v[142:145], v[214:217], v[26:29]
	v_mfma_f32_16x16x32_bf16 v[14:17], v[54:57], v[222:225], v[14:17]
	v_mfma_f32_16x16x32_bf16 v[10:13], v[142:145], v[222:225], v[10:13]
	v_mfma_f32_16x16x32_bf16 v[38:41], v[146:149], v[202:205], v[38:41]
	v_mfma_f32_16x16x32_bf16 v[34:37], v[174:177], v[202:205], v[34:37]
	v_mfma_f32_16x16x32_bf16 v[22:25], v[146:149], v[210:213], v[22:25]
	v_mfma_f32_16x16x32_bf16 v[18:21], v[174:177], v[210:213], v[18:21]
	v_mfma_f32_16x16x32_bf16 v[6:9], v[146:149], v[218:221], v[6:9]
	v_mfma_f32_16x16x32_bf16 v[2:5], v[174:177], v[218:221], v[2:5]
	v_mfma_f32_16x16x32_bf16 v[50:53], v[146:149], v[182:185], v[62:65]
	v_mfma_f32_16x16x32_bf16 v[54:57], v[174:177], v[182:185], v[58:61]
	v_mfma_f32_16x16x32_bf16 v[38:41], v[150:153], v[206:209], v[38:41]
	v_mfma_f32_16x16x32_bf16 v[34:37], v[178:181], v[206:209], v[34:37]
	v_mfma_f32_16x16x32_bf16 v[22:25], v[150:153], v[214:217], v[22:25]
	v_mfma_f32_16x16x32_bf16 v[18:21], v[178:181], v[214:217], v[18:21]
	v_mfma_f32_16x16x32_bf16 v[6:9], v[150:153], v[222:225], v[6:9]
	v_mfma_f32_16x16x32_bf16 v[2:5], v[178:181], v[222:225], v[2:5]
	v_mfma_f32_16x16x32_bf16 v[50:53], v[150:153], v[186:189], v[50:53]
	v_mfma_f32_16x16x32_bf16 v[54:57], v[178:181], v[186:189], v[54:57]
	s_barrier
; #define PG8_STAGE(bufoff, gbase, voff) do { _Pragma("unroll") for (int _i = 0; _i < 2; ++_i) \
;         __builtin_amdgcn_global_load_lds((const unsigned*)((const char*)(gbase) + (voff)[_i]), (LAS unsigned*)(lds + (bufoff) + ldsw + _i * 8192), 16, 0, 0); } while (0)
; #define PG8_LDA(dst, b, h) do { _Pragma("unroll") for (int m = 0; m < 4; ++m) _Pragma("unroll") for (int k = 0; k < 2; ++k) dst[m][k] = *(const LAS bf16x8*)(lds + PG8_SA(b, h) + aoff + m * 2048 + k * 1024); } while (0)
; #define PG8_LDB(dst, b, h) do { _Pragma("unroll") for (int n = 0; n < 2; ++n) _Pragma("unroll") for (int k = 0; k < 2; ++k) dst[n][k] = *(const LAS bf16x8*)(lds + PG8_SB(b, h) + boff + n * 2048 + k * 1024); } while (0)
; #define PG8_MMA(ai, bj, At, Bt) do { __builtin_amdgcn_s_setprio(1); _Pragma("unroll") for (int m = 0; m < 4; ++m) _Pragma("unroll") for (int n = 0; n < 2; ++n) _Pragma("unroll") for (int k = 0; k < 2; ++k) \
;         acc[ai][bj][m][n] = __builtin_amdgcn_mfma_f32_16x16x32_bf16(Bt[n][k], At[m][k], acc[ai][bj][m][n], 0, 0, 0); __builtin_amdgcn_s_setprio(0); } while (0)
; #define PG8_WAIT_V(n) asm volatile("s_waitcnt vmcnt(" #n ")" ::: "memory")
; #define PG8_WAIT_L(n) asm volatile("s_waitcnt lgkmcnt(" #n ")" ::: "memory")
; #define PG8_BAR __builtin_amdgcn_s_barrier()
; #define PG8_SCHED __builtin_amdgcn_sched_barrier(0)
; template <class Epi, class Sched, bool ALIGN_EPI = false, bool SP2 = false>
; __device__ __forceinline__ void gemm_phase(LAS unsigned char* lds, const Gemm g, const Sched& S, const Epi& E) {
;     ...
;             PG8_LDB(B0, 1, 0); PG8_LDB(B1, 1, 1); PG8_SCHED; PG8_LDA(At, 1, 0); PG8_STAGE(PG8_SA(0, 1), a2 + hstep, voffA);
;             PG8_WAIT_V(8); PG8_WAIT_L(0); PG8_BAR; PG8_MMA(0, 0, At, B0); PG8_MMA(0, 1, At, B1); PG8_BAR; PG8_SCHED;
	s_add_i32 s58, 0, 0x18000
	s_add_i32 s59, 0, 0x1c000
	v_add_u32_e32 v142, s58, v1
	v_add_u32_e32 v162, s59, v1
	ds_read_b128 v[58:61], v142
	ds_read_b128 v[62:65], v142 offset:1024
	ds_read_b128 v[138:141], v142 offset:2048
	ds_read_b128 v[142:145], v142 offset:3072
	ds_read_b128 v[146:149], v162
	ds_read_b128 v[150:153], v162 offset:1024
	ds_read_b128 v[174:177], v162 offset:2048
	ds_read_b128 v[178:181], v162 offset:3072
	s_add_u32 s50, s50, 0x80000
	s_addc_u32 s51, s51, 0
	s_mov_b32 m0, s31
	v_lshl_add_u64 v[232:233], s[50:51], 0, v[154:155]
	ds_read_b128 v[182:185], v198 offset:32768
	ds_read_b128 v[186:189], v198 offset:33792
	ds_read_b128 v[202:205], v198 offset:34816
	ds_read_b128 v[206:209], v198 offset:35840
	ds_read_b128 v[210:213], v198 offset:36864
	ds_read_b128 v[214:217], v198 offset:37888
	ds_read_b128 v[218:221], v198 offset:38912
	ds_read_b128 v[222:225], v198 offset:39936
	global_load_lds_dwordx4 v[232:233], off
	v_lshl_add_u64 v[232:233], s[50:51], 0, v[158:159]
	s_mov_b32 m0, s33
	s_nop 0
	global_load_lds_dwordx4 v[232:233], off
	s_waitcnt vmcnt(8)
	s_waitcnt lgkmcnt(0)
	s_barrier
	s_waitcnt lgkmcnt(0)
	v_mfma_f32_16x16x32_bf16 v[134:137], v[58:61], v[182:185], v[134:137]
	v_mfma_f32_16x16x32_bf16 v[130:133], v[138:141], v[182:185], v[130:133]
	v_mfma_f32_16x16x32_bf16 v[118:121], v[58:61], v[202:205], v[118:121]
	v_mfma_f32_16x16x32_bf16 v[114:117], v[138:141], v[202:205], v[114:117]
	v_mfma_f32_16x16x32_bf16 v[102:105], v[58:61], v[210:213], v[102:105]
	v_mfma_f32_16x16x32_bf16 v[98:101], v[138:141], v[210:213], v[98:101]
	v_mfma_f32_16x16x32_bf16 v[86:89], v[58:61], v[218:221], v[86:89]
	v_mfma_f32_16x16x32_bf16 v[82:85], v[138:141], v[218:221], v[82:85]
	v_mfma_f32_16x16x32_bf16 v[134:137], v[62:65], v[186:189], v[134:137]
	v_mfma_f32_16x16x32_bf16 v[130:133], v[142:145], v[186:189], v[130:133]
	v_mfma_f32_16x16x32_bf16 v[118:121], v[62:65], v[206:209], v[118:121]
	v_mfma_f32_16x16x32_bf16 v[114:117], v[142:145], v[206:209], v[114:117]
	v_mfma_f32_16x16x32_bf16 v[102:105], v[62:65], v[214:217], v[102:105]
	v_mfma_f32_16x16x32_bf16 v[98:101], v[142:145], v[214:217], v[98:101]
	v_mfma_f32_16x16x32_bf16 v[86:89], v[62:65], v[222:225], v[86:89]
	v_mfma_f32_16x16x32_bf16 v[82:85], v[142:145], v[222:225], v[82:85]
	v_mfma_f32_16x16x32_bf16 v[126:129], v[146:149], v[182:185], v[126:129]
	v_mfma_f32_16x16x32_bf16 v[122:125], v[174:177], v[182:185], v[122:125]
	v_mfma_f32_16x16x32_bf16 v[110:113], v[146:149], v[202:205], v[110:113]
	v_mfma_f32_16x16x32_bf16 v[106:109], v[174:177], v[202:205], v[106:109]
	v_mfma_f32_16x16x32_bf16 v[94:97], v[146:149], v[210:213], v[94:97]
	v_mfma_f32_16x16x32_bf16 v[90:93], v[174:177], v[210:213], v[90:93]
	v_mfma_f32_16x16x32_bf16 v[78:81], v[146:149], v[218:221], v[78:81]
	v_mfma_f32_16x16x32_bf16 v[74:77], v[174:177], v[218:221], v[74:77]
	v_mfma_f32_16x16x32_bf16 v[126:129], v[150:153], v[186:189], v[126:129]
	v_mfma_f32_16x16x32_bf16 v[122:125], v[178:181], v[186:189], v[122:125]
	v_mfma_f32_16x16x32_bf16 v[110:113], v[150:153], v[206:209], v[110:113]
	v_mfma_f32_16x16x32_bf16 v[106:109], v[178:181], v[206:209], v[106:109]
	v_mfma_f32_16x16x32_bf16 v[94:97], v[150:153], v[214:217], v[94:97]
	v_mfma_f32_16x16x32_bf16 v[90:93], v[178:181], v[214:217], v[90:93]
	v_mfma_f32_16x16x32_bf16 v[78:81], v[150:153], v[222:225], v[78:81]
	v_mfma_f32_16x16x32_bf16 v[74:77], v[178:181], v[222:225], v[74:77]
	s_barrier
; #define PG8_STAGE(bufoff, gbase, voff) do { _Pragma("unroll") for (int _i = 0; _i < 2; ++_i) \
;         __builtin_amdgcn_global_load_lds((const unsigned*)((const char*)(gbase) + (voff)[_i]), (LAS unsigned*)(lds + (bufoff) + ldsw + _i * 8192), 16, 0, 0); } while (0)
; #define PG8_LDA(dst, b, h) do { _Pragma("unroll") for (int m = 0; m < 4; ++m) _Pragma("unroll") for (int k = 0; k < 2; ++k) dst[m][k] = *(const LAS bf16x8*)(lds + PG8_SA(b, h) + aoff + m * 2048 + k * 1024); } while (0)
; #define PG8_WAIT_V(n) asm volatile("s_waitcnt vmcnt(" #n ")" ::: "memory")
; template <class Epi, class Sched, bool ALIGN_EPI = false, bool SP2 = false>
; __device__ __forceinline__ void gemm_phase(LAS unsigned char* lds, const Gemm g, const Sched& S, const Epi& E) {
;     ...
;             PG8_LDA(At, 1, 1); PG8_STAGE(PG8_SB(1, 0), b3, voffB); PG8_STAGE(PG8_SB(1, 1), b3 + hstepB, voffB); PG8_STAGE(PG8_SA(1, 0), a3, voffA);
;             PG8_WAIT_V(8); PG8_WAIT_L(0); PG8_BAR; PG8_MMA(1, 0, At, B0); PG8_MMA(1, 1, At, B1); PG8_BAR; PG8_SCHED;
;             } else {
;             PG8_LDB(B0, 0, 0); PG8_SCHED; PG8_LDA(At, 0, 0); PG8_STAGE(PG8_SA(1, 1), a1 + hstep, voffA);
;             PG8_WAIT_L(8); PG8_BAR; PG8_WAIT_L(0); PG8_MMA(0, 0, At, B0); PG8_BAR; PG8_SCHED;
;             PG8_LDB(B1, 0, 1); PG8_STAGE(PG8_SB(0, 0), b2, voffB);
;             PG8_BAR; PG8_WAIT_L(0); PG8_MMA(0, 1, At, B1); PG8_BAR;
;             PG8_LDA(At, 0, 1); PG8_STAGE(PG8_SA(0, 0), a2, voffA);
;             PG8_BAR; PG8_WAIT_L(0); PG8_MMA(1, 0, At, B0); PG8_BAR; PG8_SCHED;
;             PG8_STAGE(PG8_SB(0, 1), b2 + hstepB, voffB);
;             PG8_WAIT_V(6); PG8_BAR; PG8_MMA(1, 1, At, B1); PG8_BAR;
;             PG8_LDB(B0, 1, 0); PG8_SCHED; PG8_LDA(At, 1, 0); PG8_STAGE(PG8_SA(0, 1), a2 + hstep, voffA);
;             PG8_WAIT_L(8); PG8_BAR; PG8_WAIT_L(0); PG8_MMA(0, 0, At, B0); PG8_BAR; PG8_SCHED;
;             PG8_LDB(B1, 1, 1); PG8_STAGE(PG8_SB(1, 0), b3, voffB);
;             PG8_BAR; PG8_WAIT_L(0); PG8_MMA(0, 1, At, B1); PG8_BAR;
;             PG8_LDA(At, 1, 1); PG8_STAGE(PG8_SA(1, 0), a3, voffA);
;             PG8_BAR; PG8_WAIT_L(0); PG8_MMA(1, 0, At, B0); PG8_BAR; PG8_SCHED;
;             PG8_STAGE(PG8_SB(1, 1), b3 + hstepB, voffB);
;             PG8_WAIT_V(6); PG8_BAR; PG8_MMA(1, 1, At, B1); PG8_BAR;
;             }
;         }
;         if constexpr (ALIGN_EPI) { if (wr == 0) PG8_BAR; }
	s_add_i32 s50, s58, s28
	v_lshl_add_u64 v[190:191], v[190:191], 0, s[10:11]
	s_mov_b32 m0, s50
	ds_read_b128 v[182:185], v198 offset:49152
	ds_read_b128 v[186:189], v198 offset:50176
	ds_read_b128 v[202:205], v198 offset:51200
	ds_read_b128 v[206:209], v198 offset:52224
	ds_read_b128 v[210:213], v198 offset:53248
	ds_read_b128 v[214:217], v198 offset:54272
	ds_read_b128 v[218:221], v198 offset:55296
	ds_read_b128 v[222:225], v198 offset:56320
	global_load_lds_dwordx4 v[190:191], off
	s_add_i32 m0, s50, 0x2000
	s_add_u32 s48, s48, 0x20080
	v_lshl_add_u64 v[190:191], v[226:227], 0, s[10:11]
	s_addc_u32 s49, s49, 0
	s_add_i32 s50, s59, s28
	global_load_lds_dwordx4 v[190:191], off
	v_lshl_add_u64 v[190:191], s[48:49], 0, v[156:157]
	s_mov_b32 m0, s50
	s_nop 0
	global_load_lds_dwordx4 v[190:191], off
	v_lshl_add_u64 v[190:191], s[48:49], 0, v[160:161]
	s_add_i32 m0, s50, 0x2000
	s_nop 0
	global_load_lds_dwordx4 v[190:191], off
	v_lshl_add_u64 v[190:191], v[228:229], 0, s[10:11]
	s_mov_b32 m0, s53
	s_nop 0
	global_load_lds_dwordx4 v[190:191], off
	v_lshl_add_u64 v[190:191], v[230:231], 0, s[10:11]
	s_mov_b32 m0, s54
	s_nop 0
	global_load_lds_dwordx4 v[190:191], off
	s_waitcnt vmcnt(8)
	s_waitcnt lgkmcnt(0)
	s_barrier
	s_waitcnt lgkmcnt(0)
	v_mfma_f32_16x16x32_bf16 v[70:73], v[58:61], v[182:185], v[70:73]
	v_mfma_f32_16x16x32_bf16 v[66:69], v[138:141], v[182:185], v[66:69]
	v_mfma_f32_16x16x32_bf16 v[46:49], v[58:61], v[202:205], v[46:49]
	v_mfma_f32_16x16x32_bf16 v[42:45], v[138:141], v[202:205], v[42:45]
	v_mfma_f32_16x16x32_bf16 v[30:33], v[58:61], v[210:213], v[30:33]
	v_mfma_f32_16x16x32_bf16 v[26:29], v[138:141], v[210:213], v[26:29]
	v_mfma_f32_16x16x32_bf16 v[14:17], v[58:61], v[218:221], v[14:17]
	v_mfma_f32_16x16x32_bf16 v[10:13], v[138:141], v[218:221], v[10:13]
	v_mfma_f32_16x16x32_bf16 v[70:73], v[62:65], v[186:189], v[70:73]
	v_mfma_f32_16x16x32_bf16 v[66:69], v[142:145], v[186:189], v[66:69]
	v_mfma_f32_16x16x32_bf16 v[46:49], v[62:65], v[206:209], v[46:49]
	v_mfma_f32_16x16x32_bf16 v[42:45], v[142:145], v[206:209], v[42:45]
	v_mfma_f32_16x16x32_bf16 v[30:33], v[62:65], v[214:217], v[30:33]
	v_mfma_f32_16x16x32_bf16 v[26:29], v[142:145], v[214:217], v[26:29]
	v_mfma_f32_16x16x32_bf16 v[14:17], v[62:65], v[222:225], v[14:17]
	v_mfma_f32_16x16x32_bf16 v[10:13], v[142:145], v[222:225], v[10:13]
	v_mfma_f32_16x16x32_bf16 v[50:53], v[146:149], v[182:185], v[50:53]
	v_mfma_f32_16x16x32_bf16 v[62:65], v[150:153], v[186:189], v[50:53]
	v_mfma_f32_16x16x32_bf16 v[50:53], v[174:177], v[182:185], v[54:57]
	v_mfma_f32_16x16x32_bf16 v[38:41], v[146:149], v[202:205], v[38:41]
	v_mfma_f32_16x16x32_bf16 v[34:37], v[174:177], v[202:205], v[34:37]
	v_mfma_f32_16x16x32_bf16 v[22:25], v[146:149], v[210:213], v[22:25]
	v_mfma_f32_16x16x32_bf16 v[18:21], v[174:177], v[210:213], v[18:21]
	v_mfma_f32_16x16x32_bf16 v[6:9], v[146:149], v[218:221], v[6:9]
	v_mfma_f32_16x16x32_bf16 v[2:5], v[174:177], v[218:221], v[2:5]
	v_mfma_f32_16x16x32_bf16 v[58:61], v[178:181], v[186:189], v[50:53]
	v_mfma_f32_16x16x32_bf16 v[38:41], v[150:153], v[206:209], v[38:41]
	v_mfma_f32_16x16x32_bf16 v[34:37], v[178:181], v[206:209], v[34:37]
	v_mfma_f32_16x16x32_bf16 v[22:25], v[150:153], v[214:217], v[22:25]
	v_mfma_f32_16x16x32_bf16 v[18:21], v[178:181], v[214:217], v[18:21]
	v_mfma_f32_16x16x32_bf16 v[6:9], v[150:153], v[222:225], v[6:9]
	v_mfma_f32_16x16x32_bf16 v[2:5], v[178:181], v[222:225], v[2:5]
	s_barrier
	s_add_i32 s47, s47, 2
	s_add_u32 s16, s16, 0x100
	s_addc_u32 s17, s17, 0
	s_add_u32 s24, s24, 0x100
	s_addc_u32 s25, s25, 0
	s_cmp_gt_u32 s47, 29
	s_cbranch_scc0 .LBB0_1250
	s_setprio 0
	s_and_b64 vcc, exec, s[12:13]
	s_cbranch_vccz .LBB0_1253
	s_barrier

; __device__ __forceinline__ float row_rstd(const float* ss, int row) { return 1.0f / sqrtf(ss[row] * (1.0f / DM) + 1e-6f); }
;     __device__ bool next(int i, Unit& u) const { if (i != 0 || c >= 128) return false; const int t = c >> 2; u.pm = t & 3; u.pn = t >> 2; u.koff = koff_bytes; u.q = c & 3; return true; }
; #define PG8_STAGE(bufoff, gbase, voff) do { _Pragma("unroll") for (int _i = 0; _i < 2; ++_i) \
;         __builtin_amdgcn_global_load_lds((const unsigned*)((const char*)(gbase) + (voff)[_i]), (LAS unsigned*)(lds + (bufoff) + ldsw + _i * 8192), 16, 0, 0); } while (0)
;     __device__ __forceinline__ void operator()(const f32x4 (&acc)[2][2][4][2], const Unit& u, int wr, int wc, int fr, int fq) const {
;     ...
;         const float* bp = bias + (size_t)s * BIAS_N + u.pn * BM + wc * 32 + 8 * fq;
;         const f32x4 ba0 = *(const f32x4*)bp, ba1 = *(const f32x4*)(bp + 4), bb0 = *(const f32x4*)(bp + HALF), bb1 = *(const f32x4*)(bp + HALF + 4);
;         const int lane = fq * 16 + fr;
;         const float rsl0 = row_rstd(ss, u.pm * BM + wr * 64 + lane), rsl1 = row_rstd(ss, u.pm * BM + HALF + wr * 64 + lane);
; template <class Epi, class Sched, bool ALIGN_EPI = false, bool SP2 = false>
; __device__ __forceinline__ void gemm_phase(LAS unsigned char* lds, const Gemm g, const Sched& S, const Epi& E) {
;     ...
;         const bool has_next = S.next(ui + 1, nxt);
;         const char* nA = has_next ? (const char*)g.A + (size_t)nxt.pm * tstep + nxt.koff : cA; const char* nB = has_next ? (const char*)g.Bt + (size_t)nxt.pn * tstep + nxt.koff : cB;
;         for (int t = 0; t < nt; t += 2) {
;             const bool last = (t == nt - 2);
;             const char* a1 = cA + (size_t)(t + 1) * kstep;
;             const char* a2 = last ? nA : cA + (size_t)(t + 2) * kstep; const char* b2 = last ? nB : cB + (size_t)(t + 2) * kstep;
;             const char* a3 = a2 + kstep; const char* b3 = b2 + kstep;
;             if (last && has_next) S.a_ready(nxt);
;             if constexpr (SP2) {
;             PG8_LDB(B0, 0, 0); PG8_LDB(B1, 0, 1); PG8_SCHED; PG8_LDA(At, 0, 0); PG8_STAGE(PG8_SA(1, 1), a1 + hstep, voffA);
;             PG8_WAIT_V(8); PG8_WAIT_L(0); PG8_BAR; PG8_MMA(0, 0, At, B0); PG8_MMA(0, 1, At, B1); PG8_BAR; PG8_SCHED;
;             PG8_LDA(At, 0, 1); PG8_STAGE(PG8_SB(0, 0), b2, voffB); PG8_STAGE(PG8_SB(0, 1), b2 + hstepB, voffB); PG8_STAGE(PG8_SA(0, 0), a2, voffA);
.Lpre_up2l0:
	s_lshl_b64 s[98:99], s[98:99], 2
	s_add_u32 s98, s43, s98
	s_addc_u32 s99, s44, s99
	s_lshl_b32 s100, s0, 8
	s_ashr_i32 s101, s100, 31
	s_lshl_b64 s[100:101], s[100:101], 2
	s_add_u32 s98, s98, s100
	s_addc_u32 s99, s99, s101
	s_add_u32 s98, s98, s50
	s_addc_u32 s99, s99, 0
	s_lshl_b32 s100, s2, 8
	s_add_i32 s100, s100, s42
	v_or_b32_e32 v162, s100, v171
	v_ashrrev_i32_e32 v163, 31, v162
	v_lshl_add_u64 v[162:163], v[162:163], 2, s[64:65]
	v_add_u32_e32 v164, s100, v172
	v_ashrrev_i32_e32 v165, 31, v164
	v_lshl_add_u64 v[164:165], v[164:165], 2, s[64:65]
	global_load_dwordx4 v[234:237], v177, s[98:99] offset:16
	global_load_dwordx4 v[238:241], v177, s[98:99]
	global_load_dwordx4 v[242:245], v177, s[98:99] offset:528
	global_load_dwordx4 v[246:249], v177, s[98:99] offset:512
	global_load_dword v250, v[162:163], off
	global_load_dword v251, v[164:165], off
	v_readfirstlane_b32 s98, v0
	s_nop 3
	s_lshr_b32 s98, s98, 6
	s_cmp_ge_u32 s98, 4
	s_cbranch_scc0 .Lprio_1465
	s_setprio 1
.Lprio_1465:
	ds_read_b128 v[66:69], v174
	ds_read_b128 v[70:73], v174 offset:1024
	ds_read_b128 v[74:77], v174 offset:2048
	ds_read_b128 v[78:81], v174 offset:3072
	ds_read_b128 v[162:165], v175
	ds_read_b128 v[182:185], v175 offset:1024
	ds_read_b128 v[186:189], v175 offset:2048
	ds_read_b128 v[190:193], v175 offset:3072
	s_add_u32 s22, s16, 0xfff80080
	s_addc_u32 s23, s17, -1
	s_cmp_eq_u32 s53, 28
	s_cselect_b32 s41, s3, s23
	s_cselect_b32 s40, s15, s22
	s_cselect_b32 s23, s13, s52
	s_cselect_b32 s22, s24, s25
	v_lshl_add_u64 v[166:167], s[16:17], 0, v[154:155]
	s_add_i32 m0, s33, 0xc000
	ds_read_b128 v[194:197], v176
	ds_read_b128 v[198:201], v176 offset:1024
	ds_read_b128 v[202:205], v176 offset:2048
	ds_read_b128 v[206:209], v176 offset:3072
	ds_read_b128 v[210:213], v176 offset:4096
	ds_read_b128 v[214:217], v176 offset:5120
	ds_read_b128 v[218:221], v176 offset:6144
	ds_read_b128 v[222:225], v176 offset:7168
	global_load_lds_dwordx4 v[166:167], off
	v_lshl_add_u64 v[166:167], s[16:17], 0, v[156:157]
	s_add_i32 m0, s33, 0xe000
	s_nop 0
	global_load_lds_dwordx4 v[166:167], off
	s_waitcnt lgkmcnt(0)
	s_barrier
	s_waitcnt lgkmcnt(0)
	v_mfma_f32_16x16x32_bf16 v[142:145], v[66:69], v[194:197], 0
	v_mfma_f32_16x16x32_bf16 v[138:141], v[74:77], v[194:197], 0
	v_mfma_f32_16x16x32_bf16 v[126:129], v[66:69], v[202:205], 0
	v_mfma_f32_16x16x32_bf16 v[122:125], v[74:77], v[202:205], 0
	v_mfma_f32_16x16x32_bf16 v[110:113], v[66:69], v[210:213], 0
	v_mfma_f32_16x16x32_bf16 v[106:109], v[74:77], v[210:213], 0
	v_mfma_f32_16x16x32_bf16 v[94:97], v[66:69], v[218:221], 0
	v_mfma_f32_16x16x32_bf16 v[90:93], v[74:77], v[218:221], 0
	v_mfma_f32_16x16x32_bf16 v[142:145], v[70:73], v[198:201], v[142:145]
	v_mfma_f32_16x16x32_bf16 v[138:141], v[78:81], v[198:201], v[138:141]
	v_mfma_f32_16x16x32_bf16 v[126:129], v[70:73], v[206:209], v[126:129]
	v_mfma_f32_16x16x32_bf16 v[122:125], v[78:81], v[206:209], v[122:125]
	v_mfma_f32_16x16x32_bf16 v[110:113], v[70:73], v[214:217], v[110:113]
	v_mfma_f32_16x16x32_bf16 v[106:109], v[78:81], v[214:217], v[106:109]
	v_mfma_f32_16x16x32_bf16 v[94:97], v[70:73], v[222:225], v[94:97]
	v_mfma_f32_16x16x32_bf16 v[90:93], v[78:81], v[222:225], v[90:93]
	v_mfma_f32_16x16x32_bf16 v[134:137], v[162:165], v[194:197], 0
	v_mfma_f32_16x16x32_bf16 v[130:133], v[186:189], v[194:197], 0
	v_mfma_f32_16x16x32_bf16 v[118:121], v[162:165], v[202:205], 0
	v_mfma_f32_16x16x32_bf16 v[114:117], v[186:189], v[202:205], 0
	v_mfma_f32_16x16x32_bf16 v[102:105], v[162:165], v[210:213], 0
	v_mfma_f32_16x16x32_bf16 v[98:101], v[186:189], v[210:213], 0
	v_mfma_f32_16x16x32_bf16 v[86:89], v[162:165], v[218:221], 0
	v_mfma_f32_16x16x32_bf16 v[82:85], v[186:189], v[218:221], 0
	v_mfma_f32_16x16x32_bf16 v[134:137], v[182:185], v[198:201], v[134:137]
	v_mfma_f32_16x16x32_bf16 v[130:133], v[190:193], v[198:201], v[130:133]
	v_mfma_f32_16x16x32_bf16 v[118:121], v[182:185], v[206:209], v[118:121]
	v_mfma_f32_16x16x32_bf16 v[114:117], v[190:193], v[206:209], v[114:117]
	v_mfma_f32_16x16x32_bf16 v[102:105], v[182:185], v[214:217], v[102:105]
	v_mfma_f32_16x16x32_bf16 v[98:101], v[190:193], v[214:217], v[98:101]
	v_mfma_f32_16x16x32_bf16 v[86:89], v[182:185], v[222:225], v[86:89]
	v_mfma_f32_16x16x32_bf16 v[82:85], v[190:193], v[222:225], v[82:85]
	s_barrier
	s_add_i32 s54, s47, s29
	v_lshl_add_u64 v[166:167], s[22:23], 0, v[150:151]
	s_mov_b32 m0, s54
	ds_read_b128 v[194:197], v176 offset:16384
	ds_read_b128 v[198:201], v176 offset:17408
	ds_read_b128 v[202:205], v176 offset:18432
	ds_read_b128 v[206:209], v176 offset:19456
	ds_read_b128 v[210:213], v176 offset:20480
	ds_read_b128 v[214:217], v176 offset:21504
	ds_read_b128 v[218:221], v176 offset:22528
	ds_read_b128 v[222:225], v176 offset:23552
	global_load_lds_dwordx4 v[166:167], off
	s_add_i32 m0, s54, 0x2000
	s_add_u32 s54, s22, 0x80000
	v_lshl_add_u64 v[226:227], s[22:23], 0, v[146:147]
	s_addc_u32 s55, s23, 0
	s_add_i32 s56, s48, s29
	global_load_lds_dwordx4 v[226:227], off
	v_lshl_add_u64 v[228:229], s[54:55], 0, v[150:151]
	s_mov_b32 m0, s56
	v_lshl_add_u64 v[230:231], s[40:41], 0, v[148:149]
	global_load_lds_dwordx4 v[228:229], off
	v_lshl_add_u64 v[228:229], s[54:55], 0, v[146:147]
	s_add_i32 m0, s56, 0x2000
	s_nop 0
	global_load_lds_dwordx4 v[228:229], off
	v_lshl_add_u64 v[228:229], s[40:41], 0, v[152:153]
	s_mov_b32 m0, s33
	s_nop 0
	global_load_lds_dwordx4 v[228:229], off
	s_mov_b32 m0, s34
	s_nop 0
	global_load_lds_dwordx4 v[230:231], off
	s_waitcnt lgkmcnt(0)
	s_barrier
; #define PG8_STAGE(bufoff, gbase, voff) do { _Pragma("unroll") for (int _i = 0; _i < 2; ++_i) \
;         __builtin_amdgcn_global_load_lds((const unsigned*)((const char*)(gbase) + (voff)[_i]), (LAS unsigned*)(lds + (bufoff) + ldsw + _i * 8192), 16, 0, 0); } while (0)
; #define PG8_LDA(dst, b, h) do { _Pragma("unroll") for (int m = 0; m < 4; ++m) _Pragma("unroll") for (int k = 0; k < 2; ++k) dst[m][k] = *(const LAS bf16x8*)(lds + PG8_SA(b, h) + aoff + m * 2048 + k * 1024); } while (0)
; #define PG8_LDB(dst, b, h) do { _Pragma("unroll") for (int n = 0; n < 2; ++n) _Pragma("unroll") for (int k = 0; k < 2; ++k) dst[n][k] = *(const LAS bf16x8*)(lds + PG8_SB(b, h) + boff + n * 2048 + k * 1024); } while (0)
; #define PG8_MMA(ai, bj, At, Bt) do { __builtin_amdgcn_s_setprio(1); _Pragma("unroll") for (int m = 0; m < 4; ++m) _Pragma("unroll") for (int n = 0; n < 2; ++n) _Pragma("unroll") for (int k = 0; k < 2; ++k) \
;         acc[ai][bj][m][n] = __builtin_amdgcn_mfma_f32_16x16x32_bf16(Bt[n][k], At[m][k], acc[ai][bj][m][n], 0, 0, 0); __builtin_amdgcn_s_setprio(0); } while (0)
; #define PG8_WAIT_V(n) asm volatile("s_waitcnt vmcnt(" #n ")" ::: "memory")
; #define PG8_WAIT_L(n) asm volatile("s_waitcnt lgkmcnt(" #n ")" ::: "memory")
; #define PG8_BAR __builtin_amdgcn_s_barrier()
; #define PG8_SCHED __builtin_amdgcn_sched_barrier(0)
; template <class Epi, class Sched, bool ALIGN_EPI = false, bool SP2 = false>
; __device__ __forceinline__ void gemm_phase(LAS unsigned char* lds, const Gemm g, const Sched& S, const Epi& E) {
;     ...
;             PG8_WAIT_V(8); PG8_WAIT_L(0); PG8_BAR; PG8_MMA(0, 0, At, B0); PG8_MMA(0, 1, At, B1); PG8_BAR; PG8_SCHED;
;             PG8_LDA(At, 0, 1); PG8_STAGE(PG8_SB(0, 0), b2, voffB); PG8_STAGE(PG8_SB(0, 1), b2 + hstepB, voffB); PG8_STAGE(PG8_SA(0, 0), a2, voffA);
;             PG8_WAIT_V(8); PG8_WAIT_L(0); PG8_BAR; PG8_MMA(1, 0, At, B0); PG8_MMA(1, 1, At, B1); PG8_BAR; PG8_SCHED;
;             PG8_LDB(B0, 1, 0); PG8_LDB(B1, 1, 1); PG8_SCHED; PG8_LDA(At, 1, 0); PG8_STAGE(PG8_SA(0, 1), a2 + hstep, voffA);
;             PG8_WAIT_V(8); PG8_WAIT_L(0); PG8_BAR; PG8_MMA(0, 0, At, B0); PG8_MMA(0, 1, At, B1); PG8_BAR; PG8_SCHED;
	s_waitcnt lgkmcnt(0)
	v_mfma_f32_16x16x32_bf16 v[62:65], v[66:69], v[194:197], 0
	v_mfma_f32_16x16x32_bf16 v[58:61], v[74:77], v[194:197], 0
	v_mfma_f32_16x16x32_bf16 v[46:49], v[66:69], v[202:205], 0
	v_mfma_f32_16x16x32_bf16 v[42:45], v[74:77], v[202:205], 0
	v_mfma_f32_16x16x32_bf16 v[30:33], v[66:69], v[210:213], 0
	v_mfma_f32_16x16x32_bf16 v[26:29], v[74:77], v[210:213], 0
	v_mfma_f32_16x16x32_bf16 v[14:17], v[66:69], v[218:221], 0
	v_mfma_f32_16x16x32_bf16 v[10:13], v[74:77], v[218:221], 0
	v_mfma_f32_16x16x32_bf16 v[62:65], v[70:73], v[198:201], v[62:65]
	v_mfma_f32_16x16x32_bf16 v[58:61], v[78:81], v[198:201], v[58:61]
	v_mfma_f32_16x16x32_bf16 v[46:49], v[70:73], v[206:209], v[46:49]
	v_mfma_f32_16x16x32_bf16 v[42:45], v[78:81], v[206:209], v[42:45]
	v_mfma_f32_16x16x32_bf16 v[30:33], v[70:73], v[214:217], v[30:33]
	v_mfma_f32_16x16x32_bf16 v[26:29], v[78:81], v[214:217], v[26:29]
	v_mfma_f32_16x16x32_bf16 v[14:17], v[70:73], v[222:225], v[14:17]
	v_mfma_f32_16x16x32_bf16 v[10:13], v[78:81], v[222:225], v[10:13]
	v_mfma_f32_16x16x32_bf16 v[54:57], v[162:165], v[194:197], 0
	v_mfma_f32_16x16x32_bf16 v[50:53], v[186:189], v[194:197], 0
	v_mfma_f32_16x16x32_bf16 v[38:41], v[162:165], v[202:205], 0
	v_mfma_f32_16x16x32_bf16 v[34:37], v[186:189], v[202:205], 0
	v_mfma_f32_16x16x32_bf16 v[22:25], v[162:165], v[210:213], 0
	v_mfma_f32_16x16x32_bf16 v[18:21], v[186:189], v[210:213], 0
	v_mfma_f32_16x16x32_bf16 v[6:9], v[162:165], v[218:221], 0
	v_mfma_f32_16x16x32_bf16 v[2:5], v[186:189], v[218:221], 0
	v_mfma_f32_16x16x32_bf16 v[54:57], v[182:185], v[198:201], v[54:57]
	v_mfma_f32_16x16x32_bf16 v[50:53], v[190:193], v[198:201], v[50:53]
	v_mfma_f32_16x16x32_bf16 v[38:41], v[182:185], v[206:209], v[38:41]
	v_mfma_f32_16x16x32_bf16 v[34:37], v[190:193], v[206:209], v[34:37]
	v_mfma_f32_16x16x32_bf16 v[22:25], v[182:185], v[214:217], v[22:25]
	v_mfma_f32_16x16x32_bf16 v[18:21], v[190:193], v[214:217], v[18:21]
	v_mfma_f32_16x16x32_bf16 v[6:9], v[182:185], v[222:225], v[6:9]
	v_mfma_f32_16x16x32_bf16 v[2:5], v[190:193], v[222:225], v[2:5]
	s_barrier
	s_add_i32 s54, 0, 0x18000
	s_add_i32 s55, 0, 0x1c000
	v_add_u32_e32 v78, s54, v170
	v_add_u32_e32 v168, s55, v170
	ds_read_b128 v[66:69], v78
	ds_read_b128 v[70:73], v78 offset:1024
	ds_read_b128 v[74:77], v78 offset:2048
	ds_read_b128 v[78:81], v78 offset:3072
	ds_read_b128 v[162:165], v168
	ds_read_b128 v[182:185], v168 offset:1024
	ds_read_b128 v[186:189], v168 offset:2048
	ds_read_b128 v[190:193], v168 offset:3072
	s_add_u32 s40, s40, 0x80000
	s_addc_u32 s41, s41, 0
	s_mov_b32 m0, s35
	v_lshl_add_u64 v[232:233], s[40:41], 0, v[152:153]
	ds_read_b128 v[194:197], v176 offset:32768
	ds_read_b128 v[198:201], v176 offset:33792
	ds_read_b128 v[202:205], v176 offset:34816
	ds_read_b128 v[206:209], v176 offset:35840
	ds_read_b128 v[210:213], v176 offset:36864
	ds_read_b128 v[214:217], v176 offset:37888
	ds_read_b128 v[218:221], v176 offset:38912
	ds_read_b128 v[222:225], v176 offset:39936
	global_load_lds_dwordx4 v[232:233], off
	v_lshl_add_u64 v[232:233], s[40:41], 0, v[148:149]
	s_mov_b32 m0, s36
	s_nop 0
	global_load_lds_dwordx4 v[232:233], off
	s_waitcnt vmcnt(8)
	s_waitcnt lgkmcnt(0)
	s_barrier
	s_waitcnt lgkmcnt(0)
	v_mfma_f32_16x16x32_bf16 v[142:145], v[66:69], v[194:197], v[142:145]
	v_mfma_f32_16x16x32_bf16 v[138:141], v[74:77], v[194:197], v[138:141]
	v_mfma_f32_16x16x32_bf16 v[126:129], v[66:69], v[202:205], v[126:129]
	v_mfma_f32_16x16x32_bf16 v[122:125], v[74:77], v[202:205], v[122:125]
	v_mfma_f32_16x16x32_bf16 v[110:113], v[66:69], v[210:213], v[110:113]
	v_mfma_f32_16x16x32_bf16 v[106:109], v[74:77], v[210:213], v[106:109]
	v_mfma_f32_16x16x32_bf16 v[94:97], v[66:69], v[218:221], v[94:97]
	v_mfma_f32_16x16x32_bf16 v[90:93], v[74:77], v[218:221], v[90:93]
	v_mfma_f32_16x16x32_bf16 v[142:145], v[70:73], v[198:201], v[142:145]
	v_mfma_f32_16x16x32_bf16 v[138:141], v[78:81], v[198:201], v[138:141]
	v_mfma_f32_16x16x32_bf16 v[126:129], v[70:73], v[206:209], v[126:129]
	v_mfma_f32_16x16x32_bf16 v[122:125], v[78:81], v[206:209], v[122:125]
	v_mfma_f32_16x16x32_bf16 v[110:113], v[70:73], v[214:217], v[110:113]
	v_mfma_f32_16x16x32_bf16 v[106:109], v[78:81], v[214:217], v[106:109]
	v_mfma_f32_16x16x32_bf16 v[94:97], v[70:73], v[222:225], v[94:97]
	v_mfma_f32_16x16x32_bf16 v[90:93], v[78:81], v[222:225], v[90:93]
	v_mfma_f32_16x16x32_bf16 v[134:137], v[162:165], v[194:197], v[134:137]
	v_mfma_f32_16x16x32_bf16 v[130:133], v[186:189], v[194:197], v[130:133]
	v_mfma_f32_16x16x32_bf16 v[118:121], v[162:165], v[202:205], v[118:121]
	v_mfma_f32_16x16x32_bf16 v[114:117], v[186:189], v[202:205], v[114:117]
	v_mfma_f32_16x16x32_bf16 v[102:105], v[162:165], v[210:213], v[102:105]
	v_mfma_f32_16x16x32_bf16 v[98:101], v[186:189], v[210:213], v[98:101]
	v_mfma_f32_16x16x32_bf16 v[86:89], v[162:165], v[218:221], v[86:89]
	v_mfma_f32_16x16x32_bf16 v[82:85], v[186:189], v[218:221], v[82:85]
	v_mfma_f32_16x16x32_bf16 v[134:137], v[182:185], v[198:201], v[134:137]
	v_mfma_f32_16x16x32_bf16 v[130:133], v[190:193], v[198:201], v[130:133]
	v_mfma_f32_16x16x32_bf16 v[118:121], v[182:185], v[206:209], v[118:121]
	v_mfma_f32_16x16x32_bf16 v[114:117], v[190:193], v[206:209], v[114:117]
	v_mfma_f32_16x16x32_bf16 v[102:105], v[182:185], v[214:217], v[102:105]
	v_mfma_f32_16x16x32_bf16 v[98:101], v[190:193], v[214:217], v[98:101]
	v_mfma_f32_16x16x32_bf16 v[86:89], v[182:185], v[222:225], v[86:89]
	v_mfma_f32_16x16x32_bf16 v[82:85], v[190:193], v[222:225], v[82:85]
	s_barrier
; #define PG8_STAGE(bufoff, gbase, voff) do { _Pragma("unroll") for (int _i = 0; _i < 2; ++_i) \
;         __builtin_amdgcn_global_load_lds((const unsigned*)((const char*)(gbase) + (voff)[_i]), (LAS unsigned*)(lds + (bufoff) + ldsw + _i * 8192), 16, 0, 0); } while (0)
; #define PG8_LDA(dst, b, h) do { _Pragma("unroll") for (int m = 0; m < 4; ++m) _Pragma("unroll") for (int k = 0; k < 2; ++k) dst[m][k] = *(const LAS bf16x8*)(lds + PG8_SA(b, h) + aoff + m * 2048 + k * 1024); } while (0)
; #define PG8_LDB(dst, b, h) do { _Pragma("unroll") for (int n = 0; n < 2; ++n) _Pragma("unroll") for (int k = 0; k < 2; ++k) dst[n][k] = *(const LAS bf16x8*)(lds + PG8_SB(b, h) + boff + n * 2048 + k * 1024); } while (0)
; template <class Epi, class Sched, bool ALIGN_EPI = false, bool SP2 = false>
; __device__ __forceinline__ void gemm_phase(LAS unsigned char* lds, const Gemm g, const Sched& S, const Epi& E) {
;     ...
;         for (int t = 0; t < nt; t += 2) {
;             const bool last = (t == nt - 2);
;             const char* a1 = cA + (size_t)(t + 1) * kstep;
;             const char* a2 = last ? nA : cA + (size_t)(t + 2) * kstep; const char* b2 = last ? nB : cB + (size_t)(t + 2) * kstep;
;             const char* a3 = a2 + kstep; const char* b3 = b2 + kstep;
;             if (last && has_next) S.a_ready(nxt);
;             if constexpr (SP2) {
;             PG8_LDB(B0, 0, 0); PG8_LDB(B1, 0, 1); PG8_SCHED; PG8_LDA(At, 0, 0); PG8_STAGE(PG8_SA(1, 1), a1 + hstep, voffA);
;             PG8_WAIT_V(8); PG8_WAIT_L(0); PG8_BAR; PG8_MMA(0, 0, At, B0); PG8_MMA(0, 1, At, B1); PG8_BAR; PG8_SCHED;
;             PG8_LDA(At, 0, 1); PG8_STAGE(PG8_SB(0, 0), b2, voffB); PG8_STAGE(PG8_SB(0, 1), b2 + hstepB, voffB); PG8_STAGE(PG8_SA(0, 0), a2, voffA);
;             PG8_WAIT_V(8); PG8_WAIT_L(0); PG8_BAR; PG8_MMA(1, 0, At, B0); PG8_MMA(1, 1, At, B1); PG8_BAR; PG8_SCHED;
;             PG8_LDB(B0, 1, 0); PG8_LDB(B1, 1, 1); PG8_SCHED; PG8_LDA(At, 1, 0); PG8_STAGE(PG8_SA(0, 1), a2 + hstep, voffA);
;             PG8_WAIT_V(8); PG8_WAIT_L(0); PG8_BAR; PG8_MMA(0, 0, At, B0); PG8_MMA(0, 1, At, B1); PG8_BAR; PG8_SCHED;
;             PG8_LDA(At, 1, 1); PG8_STAGE(PG8_SB(1, 0), b3, voffB); PG8_STAGE(PG8_SB(1, 1), b3 + hstepB, voffB); PG8_STAGE(PG8_SA(1, 0), a3, voffA);
;             PG8_WAIT_V(8); PG8_WAIT_L(0); PG8_BAR; PG8_MMA(1, 0, At, B0); PG8_MMA(1, 1, At, B1); PG8_BAR; PG8_SCHED;
	s_add_i32 s40, s54, s29
	v_lshl_add_u64 v[166:167], v[166:167], 0, s[8:9]
	s_mov_b32 m0, s40
	ds_read_b128 v[194:197], v176 offset:49152
	ds_read_b128 v[198:201], v176 offset:50176
	ds_read_b128 v[202:205], v176 offset:51200
	ds_read_b128 v[206:209], v176 offset:52224
	ds_read_b128 v[210:213], v176 offset:53248
	ds_read_b128 v[214:217], v176 offset:54272
	ds_read_b128 v[218:221], v176 offset:55296
	ds_read_b128 v[222:225], v176 offset:56320
	global_load_lds_dwordx4 v[166:167], off
	s_add_i32 m0, s40, 0x2000
	s_add_u32 s22, s22, 0x80080
	v_lshl_add_u64 v[166:167], v[226:227], 0, s[8:9]
	s_addc_u32 s23, s23, 0
	s_add_i32 s40, s55, s29
	global_load_lds_dwordx4 v[166:167], off
	v_lshl_add_u64 v[166:167], s[22:23], 0, v[150:151]
	s_mov_b32 m0, s40
	s_nop 0
	global_load_lds_dwordx4 v[166:167], off
	v_lshl_add_u64 v[166:167], s[22:23], 0, v[146:147]
	s_add_i32 m0, s40, 0x2000
	s_nop 0
	global_load_lds_dwordx4 v[166:167], off
	v_lshl_add_u64 v[166:167], v[228:229], 0, s[8:9]
	s_mov_b32 m0, s45
	s_nop 0
	global_load_lds_dwordx4 v[166:167], off
	v_lshl_add_u64 v[166:167], v[230:231], 0, s[8:9]
	s_mov_b32 m0, s46
	s_nop 0
	global_load_lds_dwordx4 v[166:167], off
	s_waitcnt vmcnt(8)
	s_waitcnt lgkmcnt(0)
	s_barrier
	s_waitcnt lgkmcnt(0)
	v_mfma_f32_16x16x32_bf16 v[62:65], v[66:69], v[194:197], v[62:65]
	v_mfma_f32_16x16x32_bf16 v[58:61], v[74:77], v[194:197], v[58:61]
	v_mfma_f32_16x16x32_bf16 v[46:49], v[66:69], v[202:205], v[46:49]
	v_mfma_f32_16x16x32_bf16 v[42:45], v[74:77], v[202:205], v[42:45]
	v_mfma_f32_16x16x32_bf16 v[30:33], v[66:69], v[210:213], v[30:33]
	v_mfma_f32_16x16x32_bf16 v[26:29], v[74:77], v[210:213], v[26:29]
	v_mfma_f32_16x16x32_bf16 v[14:17], v[66:69], v[218:221], v[14:17]
	v_mfma_f32_16x16x32_bf16 v[10:13], v[74:77], v[218:221], v[10:13]
	v_mfma_f32_16x16x32_bf16 v[62:65], v[70:73], v[198:201], v[62:65]
	v_mfma_f32_16x16x32_bf16 v[58:61], v[78:81], v[198:201], v[58:61]
	v_mfma_f32_16x16x32_bf16 v[46:49], v[70:73], v[206:209], v[46:49]
	v_mfma_f32_16x16x32_bf16 v[42:45], v[78:81], v[206:209], v[42:45]
	v_mfma_f32_16x16x32_bf16 v[30:33], v[70:73], v[214:217], v[30:33]
	v_mfma_f32_16x16x32_bf16 v[26:29], v[78:81], v[214:217], v[26:29]
	v_mfma_f32_16x16x32_bf16 v[14:17], v[70:73], v[222:225], v[14:17]
	v_mfma_f32_16x16x32_bf16 v[10:13], v[78:81], v[222:225], v[10:13]
	v_mfma_f32_16x16x32_bf16 v[54:57], v[162:165], v[194:197], v[54:57]
	v_mfma_f32_16x16x32_bf16 v[50:53], v[186:189], v[194:197], v[50:53]
	v_mfma_f32_16x16x32_bf16 v[38:41], v[162:165], v[202:205], v[38:41]
	v_mfma_f32_16x16x32_bf16 v[34:37], v[186:189], v[202:205], v[34:37]
	v_mfma_f32_16x16x32_bf16 v[22:25], v[162:165], v[210:213], v[22:25]
	v_mfma_f32_16x16x32_bf16 v[18:21], v[186:189], v[210:213], v[18:21]
	v_mfma_f32_16x16x32_bf16 v[6:9], v[162:165], v[218:221], v[6:9]
	v_mfma_f32_16x16x32_bf16 v[2:5], v[186:189], v[218:221], v[2:5]
	v_mfma_f32_16x16x32_bf16 v[54:57], v[182:185], v[198:201], v[54:57]
	v_mfma_f32_16x16x32_bf16 v[50:53], v[190:193], v[198:201], v[50:53]
	v_mfma_f32_16x16x32_bf16 v[38:41], v[182:185], v[206:209], v[38:41]
	v_mfma_f32_16x16x32_bf16 v[34:37], v[190:193], v[206:209], v[34:37]
	v_mfma_f32_16x16x32_bf16 v[22:25], v[182:185], v[214:217], v[22:25]
	v_mfma_f32_16x16x32_bf16 v[18:21], v[190:193], v[214:217], v[18:21]
	v_mfma_f32_16x16x32_bf16 v[6:9], v[182:185], v[222:225], v[6:9]
	v_mfma_f32_16x16x32_bf16 v[2:5], v[190:193], v[222:225], v[2:5]
	s_barrier
	s_add_i32 s53, s53, 2
	s_add_u32 s16, s16, 0x100
	s_addc_u32 s17, s17, 0
	s_add_u32 s25, s25, 0x100
	s_addc_u32 s52, s52, 0
	s_cmp_gt_u32 s53, 29
.LBB0_1465:
	ds_read_b128 v[66:69], v174
	ds_read_b128 v[70:73], v174 offset:1024
	ds_read_b128 v[74:77], v174 offset:2048
	ds_read_b128 v[78:81], v174 offset:3072
	ds_read_b128 v[162:165], v175
	ds_read_b128 v[182:185], v175 offset:1024
	ds_read_b128 v[186:189], v175 offset:2048
	ds_read_b128 v[190:193], v175 offset:3072
	s_add_u32 s22, s16, 0xfff80080
	s_addc_u32 s23, s17, -1
	s_cmp_eq_u32 s53, 28
	s_cselect_b32 s41, s3, s23
	s_cselect_b32 s40, s15, s22
	s_cselect_b32 s23, s13, s52
	s_cselect_b32 s22, s24, s25
	v_lshl_add_u64 v[166:167], s[16:17], 0, v[154:155]
	s_add_i32 m0, s33, 0xc000
	ds_read_b128 v[194:197], v176
	ds_read_b128 v[198:201], v176 offset:1024
	ds_read_b128 v[202:205], v176 offset:2048
	ds_read_b128 v[206:209], v176 offset:3072
	ds_read_b128 v[210:213], v176 offset:4096
	ds_read_b128 v[214:217], v176 offset:5120
	ds_read_b128 v[218:221], v176 offset:6144
	ds_read_b128 v[222:225], v176 offset:7168
	global_load_lds_dwordx4 v[166:167], off
	v_lshl_add_u64 v[166:167], s[16:17], 0, v[156:157]
	s_add_i32 m0, s33, 0xe000
	s_nop 0
	global_load_lds_dwordx4 v[166:167], off
	s_waitcnt vmcnt(8)
	s_waitcnt lgkmcnt(0)
	s_barrier
; #define PG8_STAGE(bufoff, gbase, voff) do { _Pragma("unroll") for (int _i = 0; _i < 2; ++_i) \
;         __builtin_amdgcn_global_load_lds((const unsigned*)((const char*)(gbase) + (voff)[_i]), (LAS unsigned*)(lds + (bufoff) + ldsw + _i * 8192), 16, 0, 0); } while (0)
; #define PG8_LDA(dst, b, h) do { _Pragma("unroll") for (int m = 0; m < 4; ++m) _Pragma("unroll") for (int k = 0; k < 2; ++k) dst[m][k] = *(const LAS bf16x8*)(lds + PG8_SA(b, h) + aoff + m * 2048 + k * 1024); } while (0)
; #define PG8_LDB(dst, b, h) do { _Pragma("unroll") for (int n = 0; n < 2; ++n) _Pragma("unroll") for (int k = 0; k < 2; ++k) dst[n][k] = *(const LAS bf16x8*)(lds + PG8_SB(b, h) + boff + n * 2048 + k * 1024); } while (0)
; #define PG8_MMA(ai, bj, At, Bt) do { __builtin_amdgcn_s_setprio(1); _Pragma("unroll") for (int m = 0; m < 4; ++m) _Pragma("unroll") for (int n = 0; n < 2; ++n) _Pragma("unroll") for (int k = 0; k < 2; ++k) \
;         acc[ai][bj][m][n] = __builtin_amdgcn_mfma_f32_16x16x32_bf16(Bt[n][k], At[m][k], acc[ai][bj][m][n], 0, 0, 0); __builtin_amdgcn_s_setprio(0); } while (0)
; #define PG8_WAIT_V(n) asm volatile("s_waitcnt vmcnt(" #n ")" ::: "memory")
; #define PG8_WAIT_L(n) asm volatile("s_waitcnt lgkmcnt(" #n ")" ::: "memory")
; #define PG8_BAR __builtin_amdgcn_s_barrier()
; #define PG8_SCHED __builtin_amdgcn_sched_barrier(0)
; template <class Epi, class Sched, bool ALIGN_EPI = false, bool SP2 = false>
; __device__ __forceinline__ void gemm_phase(LAS unsigned char* lds, const Gemm g, const Sched& S, const Epi& E) {
;     ...
;             PG8_LDB(B0, 0, 0); PG8_LDB(B1, 0, 1); PG8_SCHED; PG8_LDA(At, 0, 0); PG8_STAGE(PG8_SA(1, 1), a1 + hstep, voffA);
;             PG8_WAIT_V(8); PG8_WAIT_L(0); PG8_BAR; PG8_MMA(0, 0, At, B0); PG8_MMA(0, 1, At, B1); PG8_BAR; PG8_SCHED;
;             PG8_LDA(At, 0, 1); PG8_STAGE(PG8_SB(0, 0), b2, voffB); PG8_STAGE(PG8_SB(0, 1), b2 + hstepB, voffB); PG8_STAGE(PG8_SA(0, 0), a2, voffA);
;             PG8_WAIT_V(8); PG8_WAIT_L(0); PG8_BAR; PG8_MMA(1, 0, At, B0); PG8_MMA(1, 1, At, B1); PG8_BAR; PG8_SCHED;
;             PG8_LDB(B0, 1, 0); PG8_LDB(B1, 1, 1); PG8_SCHED; PG8_LDA(At, 1, 0); PG8_STAGE(PG8_SA(0, 1), a2 + hstep, voffA);
	s_waitcnt lgkmcnt(0)
	v_mfma_f32_16x16x32_bf16 v[142:145], v[66:69], v[194:197], v[142:145]
	v_mfma_f32_16x16x32_bf16 v[138:141], v[74:77], v[194:197], v[138:141]
	v_mfma_f32_16x16x32_bf16 v[126:129], v[66:69], v[202:205], v[126:129]
	v_mfma_f32_16x16x32_bf16 v[122:125], v[74:77], v[202:205], v[122:125]
	v_mfma_f32_16x16x32_bf16 v[110:113], v[66:69], v[210:213], v[110:113]
	v_mfma_f32_16x16x32_bf16 v[106:109], v[74:77], v[210:213], v[106:109]
	v_mfma_f32_16x16x32_bf16 v[94:97], v[66:69], v[218:221], v[94:97]
	v_mfma_f32_16x16x32_bf16 v[90:93], v[74:77], v[218:221], v[90:93]
	v_mfma_f32_16x16x32_bf16 v[142:145], v[70:73], v[198:201], v[142:145]
	v_mfma_f32_16x16x32_bf16 v[138:141], v[78:81], v[198:201], v[138:141]
	v_mfma_f32_16x16x32_bf16 v[126:129], v[70:73], v[206:209], v[126:129]
	v_mfma_f32_16x16x32_bf16 v[122:125], v[78:81], v[206:209], v[122:125]
	v_mfma_f32_16x16x32_bf16 v[110:113], v[70:73], v[214:217], v[110:113]
	v_mfma_f32_16x16x32_bf16 v[106:109], v[78:81], v[214:217], v[106:109]
	v_mfma_f32_16x16x32_bf16 v[94:97], v[70:73], v[222:225], v[94:97]
	v_mfma_f32_16x16x32_bf16 v[90:93], v[78:81], v[222:225], v[90:93]
	v_mfma_f32_16x16x32_bf16 v[134:137], v[162:165], v[194:197], v[134:137]
	v_mfma_f32_16x16x32_bf16 v[130:133], v[186:189], v[194:197], v[130:133]
	v_mfma_f32_16x16x32_bf16 v[118:121], v[162:165], v[202:205], v[118:121]
	v_mfma_f32_16x16x32_bf16 v[114:117], v[186:189], v[202:205], v[114:117]
	v_mfma_f32_16x16x32_bf16 v[102:105], v[162:165], v[210:213], v[102:105]
	v_mfma_f32_16x16x32_bf16 v[98:101], v[186:189], v[210:213], v[98:101]
	v_mfma_f32_16x16x32_bf16 v[86:89], v[162:165], v[218:221], v[86:89]
	v_mfma_f32_16x16x32_bf16 v[82:85], v[186:189], v[218:221], v[82:85]
	v_mfma_f32_16x16x32_bf16 v[134:137], v[182:185], v[198:201], v[134:137]
	v_mfma_f32_16x16x32_bf16 v[130:133], v[190:193], v[198:201], v[130:133]
	v_mfma_f32_16x16x32_bf16 v[118:121], v[182:185], v[206:209], v[118:121]
	v_mfma_f32_16x16x32_bf16 v[114:117], v[190:193], v[206:209], v[114:117]
	v_mfma_f32_16x16x32_bf16 v[102:105], v[182:185], v[214:217], v[102:105]
	v_mfma_f32_16x16x32_bf16 v[98:101], v[190:193], v[214:217], v[98:101]
	v_mfma_f32_16x16x32_bf16 v[86:89], v[182:185], v[222:225], v[86:89]
	v_mfma_f32_16x16x32_bf16 v[82:85], v[190:193], v[222:225], v[82:85]
	s_barrier
	s_add_i32 s54, s47, s29
	v_lshl_add_u64 v[166:167], s[22:23], 0, v[150:151]
	s_mov_b32 m0, s54
	ds_read_b128 v[194:197], v176 offset:16384
	ds_read_b128 v[198:201], v176 offset:17408
	ds_read_b128 v[202:205], v176 offset:18432
	ds_read_b128 v[206:209], v176 offset:19456
	ds_read_b128 v[210:213], v176 offset:20480
	ds_read_b128 v[214:217], v176 offset:21504
	ds_read_b128 v[218:221], v176 offset:22528
	ds_read_b128 v[222:225], v176 offset:23552
	global_load_lds_dwordx4 v[166:167], off
	s_add_i32 m0, s54, 0x2000
	s_add_u32 s54, s22, 0x80000
	v_lshl_add_u64 v[226:227], s[22:23], 0, v[146:147]
	s_addc_u32 s55, s23, 0
	s_add_i32 s56, s48, s29
	global_load_lds_dwordx4 v[226:227], off
	v_lshl_add_u64 v[228:229], s[54:55], 0, v[150:151]
	s_mov_b32 m0, s56
	v_lshl_add_u64 v[230:231], s[40:41], 0, v[148:149]
	global_load_lds_dwordx4 v[228:229], off
	v_lshl_add_u64 v[228:229], s[54:55], 0, v[146:147]
	s_add_i32 m0, s56, 0x2000
	s_nop 0
	global_load_lds_dwordx4 v[228:229], off
	v_lshl_add_u64 v[228:229], s[40:41], 0, v[152:153]
	s_mov_b32 m0, s33
	s_nop 0
	global_load_lds_dwordx4 v[228:229], off
	s_mov_b32 m0, s34
	s_nop 0
	global_load_lds_dwordx4 v[230:231], off
	s_waitcnt vmcnt(8)
	s_waitcnt lgkmcnt(0)
	s_barrier
	s_waitcnt lgkmcnt(0)
	v_mfma_f32_16x16x32_bf16 v[62:65], v[66:69], v[194:197], v[62:65]
	v_mfma_f32_16x16x32_bf16 v[58:61], v[74:77], v[194:197], v[58:61]
	v_mfma_f32_16x16x32_bf16 v[46:49], v[66:69], v[202:205], v[46:49]
	v_mfma_f32_16x16x32_bf16 v[42:45], v[74:77], v[202:205], v[42:45]
	v_mfma_f32_16x16x32_bf16 v[30:33], v[66:69], v[210:213], v[30:33]
	v_mfma_f32_16x16x32_bf16 v[26:29], v[74:77], v[210:213], v[26:29]
	v_mfma_f32_16x16x32_bf16 v[14:17], v[66:69], v[218:221], v[14:17]
	v_mfma_f32_16x16x32_bf16 v[10:13], v[74:77], v[218:221], v[10:13]
	v_mfma_f32_16x16x32_bf16 v[62:65], v[70:73], v[198:201], v[62:65]
	v_mfma_f32_16x16x32_bf16 v[58:61], v[78:81], v[198:201], v[58:61]
	v_mfma_f32_16x16x32_bf16 v[46:49], v[70:73], v[206:209], v[46:49]
	v_mfma_f32_16x16x32_bf16 v[42:45], v[78:81], v[206:209], v[42:45]
	v_mfma_f32_16x16x32_bf16 v[30:33], v[70:73], v[214:217], v[30:33]
	v_mfma_f32_16x16x32_bf16 v[26:29], v[78:81], v[214:217], v[26:29]
	v_mfma_f32_16x16x32_bf16 v[14:17], v[70:73], v[222:225], v[14:17]
	v_mfma_f32_16x16x32_bf16 v[10:13], v[78:81], v[222:225], v[10:13]
	v_mfma_f32_16x16x32_bf16 v[54:57], v[162:165], v[194:197], v[54:57]
	v_mfma_f32_16x16x32_bf16 v[50:53], v[186:189], v[194:197], v[50:53]
	v_mfma_f32_16x16x32_bf16 v[38:41], v[162:165], v[202:205], v[38:41]
	v_mfma_f32_16x16x32_bf16 v[34:37], v[186:189], v[202:205], v[34:37]
	v_mfma_f32_16x16x32_bf16 v[22:25], v[162:165], v[210:213], v[22:25]
	v_mfma_f32_16x16x32_bf16 v[18:21], v[186:189], v[210:213], v[18:21]
	v_mfma_f32_16x16x32_bf16 v[6:9], v[162:165], v[218:221], v[6:9]
	v_mfma_f32_16x16x32_bf16 v[2:5], v[186:189], v[218:221], v[2:5]
	v_mfma_f32_16x16x32_bf16 v[54:57], v[182:185], v[198:201], v[54:57]
	v_mfma_f32_16x16x32_bf16 v[50:53], v[190:193], v[198:201], v[50:53]
	v_mfma_f32_16x16x32_bf16 v[38:41], v[182:185], v[206:209], v[38:41]
	v_mfma_f32_16x16x32_bf16 v[34:37], v[190:193], v[206:209], v[34:37]
	v_mfma_f32_16x16x32_bf16 v[22:25], v[182:185], v[214:217], v[22:25]
	v_mfma_f32_16x16x32_bf16 v[18:21], v[190:193], v[214:217], v[18:21]
	v_mfma_f32_16x16x32_bf16 v[6:9], v[182:185], v[222:225], v[6:9]
	v_mfma_f32_16x16x32_bf16 v[2:5], v[190:193], v[222:225], v[2:5]
	s_barrier
; #define PG8_STAGE(bufoff, gbase, voff) do { _Pragma("unroll") for (int _i = 0; _i < 2; ++_i) \
;         __builtin_amdgcn_global_load_lds((const unsigned*)((const char*)(gbase) + (voff)[_i]), (LAS unsigned*)(lds + (bufoff) + ldsw + _i * 8192), 16, 0, 0); } while (0)
; #define PG8_LDA(dst, b, h) do { _Pragma("unroll") for (int m = 0; m < 4; ++m) _Pragma("unroll") for (int k = 0; k < 2; ++k) dst[m][k] = *(const LAS bf16x8*)(lds + PG8_SA(b, h) + aoff + m * 2048 + k * 1024); } while (0)
; #define PG8_LDB(dst, b, h) do { _Pragma("unroll") for (int n = 0; n < 2; ++n) _Pragma("unroll") for (int k = 0; k < 2; ++k) dst[n][k] = *(const LAS bf16x8*)(lds + PG8_SB(b, h) + boff + n * 2048 + k * 1024); } while (0)
; #define PG8_MMA(ai, bj, At, Bt) do { __builtin_amdgcn_s_setprio(1); _Pragma("unroll") for (int m = 0; m < 4; ++m) _Pragma("unroll") for (int n = 0; n < 2; ++n) _Pragma("unroll") for (int k = 0; k < 2; ++k) \
;         acc[ai][bj][m][n] = __builtin_amdgcn_mfma_f32_16x16x32_bf16(Bt[n][k], At[m][k], acc[ai][bj][m][n], 0, 0, 0); __builtin_amdgcn_s_setprio(0); } while (0)
; #define PG8_WAIT_V(n) asm volatile("s_waitcnt vmcnt(" #n ")" ::: "memory")
; #define PG8_WAIT_L(n) asm volatile("s_waitcnt lgkmcnt(" #n ")" ::: "memory")
; #define PG8_BAR __builtin_amdgcn_s_barrier()
; #define PG8_SCHED __builtin_amdgcn_sched_barrier(0)
; template <class Epi, class Sched, bool ALIGN_EPI = false, bool SP2 = false>
; __device__ __forceinline__ void gemm_phase(LAS unsigned char* lds, const Gemm g, const Sched& S, const Epi& E) {
;     ...
;             PG8_LDB(B0, 1, 0); PG8_LDB(B1, 1, 1); PG8_SCHED; PG8_LDA(At, 1, 0); PG8_STAGE(PG8_SA(0, 1), a2 + hstep, voffA);
;             PG8_WAIT_V(8); PG8_WAIT_L(0); PG8_BAR; PG8_MMA(0, 0, At, B0); PG8_MMA(0, 1, At, B1); PG8_BAR; PG8_SCHED;
	s_add_i32 s54, 0, 0x18000
	s_add_i32 s55, 0, 0x1c000
	v_add_u32_e32 v78, s54, v170
	v_add_u32_e32 v168, s55, v170
	ds_read_b128 v[66:69], v78
	ds_read_b128 v[70:73], v78 offset:1024
	ds_read_b128 v[74:77], v78 offset:2048
	ds_read_b128 v[78:81], v78 offset:3072
	ds_read_b128 v[162:165], v168
	ds_read_b128 v[182:185], v168 offset:1024
	ds_read_b128 v[186:189], v168 offset:2048
	ds_read_b128 v[190:193], v168 offset:3072
	s_add_u32 s40, s40, 0x80000
	s_addc_u32 s41, s41, 0
	s_mov_b32 m0, s35
	v_lshl_add_u64 v[232:233], s[40:41], 0, v[152:153]
	ds_read_b128 v[194:197], v176 offset:32768
	ds_read_b128 v[198:201], v176 offset:33792
	ds_read_b128 v[202:205], v176 offset:34816
	ds_read_b128 v[206:209], v176 offset:35840
	ds_read_b128 v[210:213], v176 offset:36864
	ds_read_b128 v[214:217], v176 offset:37888
	ds_read_b128 v[218:221], v176 offset:38912
	ds_read_b128 v[222:225], v176 offset:39936
	global_load_lds_dwordx4 v[232:233], off
	v_lshl_add_u64 v[232:233], s[40:41], 0, v[148:149]
	s_mov_b32 m0, s36
	s_nop 0
	global_load_lds_dwordx4 v[232:233], off
	s_waitcnt vmcnt(8)
	s_waitcnt lgkmcnt(0)
	s_barrier
	s_waitcnt lgkmcnt(0)
	v_mfma_f32_16x16x32_bf16 v[142:145], v[66:69], v[194:197], v[142:145]
	v_mfma_f32_16x16x32_bf16 v[138:141], v[74:77], v[194:197], v[138:141]
	v_mfma_f32_16x16x32_bf16 v[126:129], v[66:69], v[202:205], v[126:129]
	v_mfma_f32_16x16x32_bf16 v[122:125], v[74:77], v[202:205], v[122:125]
	v_mfma_f32_16x16x32_bf16 v[110:113], v[66:69], v[210:213], v[110:113]
	v_mfma_f32_16x16x32_bf16 v[106:109], v[74:77], v[210:213], v[106:109]
	v_mfma_f32_16x16x32_bf16 v[94:97], v[66:69], v[218:221], v[94:97]
	v_mfma_f32_16x16x32_bf16 v[90:93], v[74:77], v[218:221], v[90:93]
	v_mfma_f32_16x16x32_bf16 v[142:145], v[70:73], v[198:201], v[142:145]
	v_mfma_f32_16x16x32_bf16 v[138:141], v[78:81], v[198:201], v[138:141]
	v_mfma_f32_16x16x32_bf16 v[126:129], v[70:73], v[206:209], v[126:129]
	v_mfma_f32_16x16x32_bf16 v[122:125], v[78:81], v[206:209], v[122:125]
	v_mfma_f32_16x16x32_bf16 v[110:113], v[70:73], v[214:217], v[110:113]
	v_mfma_f32_16x16x32_bf16 v[106:109], v[78:81], v[214:217], v[106:109]
	v_mfma_f32_16x16x32_bf16 v[94:97], v[70:73], v[222:225], v[94:97]
	v_mfma_f32_16x16x32_bf16 v[90:93], v[78:81], v[222:225], v[90:93]
	v_mfma_f32_16x16x32_bf16 v[134:137], v[162:165], v[194:197], v[134:137]
	v_mfma_f32_16x16x32_bf16 v[130:133], v[186:189], v[194:197], v[130:133]
	v_mfma_f32_16x16x32_bf16 v[118:121], v[162:165], v[202:205], v[118:121]
	v_mfma_f32_16x16x32_bf16 v[114:117], v[186:189], v[202:205], v[114:117]
	v_mfma_f32_16x16x32_bf16 v[102:105], v[162:165], v[210:213], v[102:105]
	v_mfma_f32_16x16x32_bf16 v[98:101], v[186:189], v[210:213], v[98:101]
	v_mfma_f32_16x16x32_bf16 v[86:89], v[162:165], v[218:221], v[86:89]
	v_mfma_f32_16x16x32_bf16 v[82:85], v[186:189], v[218:221], v[82:85]
	v_mfma_f32_16x16x32_bf16 v[134:137], v[182:185], v[198:201], v[134:137]
	v_mfma_f32_16x16x32_bf16 v[130:133], v[190:193], v[198:201], v[130:133]
	v_mfma_f32_16x16x32_bf16 v[118:121], v[182:185], v[206:209], v[118:121]
	v_mfma_f32_16x16x32_bf16 v[114:117], v[190:193], v[206:209], v[114:117]
	v_mfma_f32_16x16x32_bf16 v[102:105], v[182:185], v[214:217], v[102:105]
	v_mfma_f32_16x16x32_bf16 v[98:101], v[190:193], v[214:217], v[98:101]
	v_mfma_f32_16x16x32_bf16 v[86:89], v[182:185], v[222:225], v[86:89]
	v_mfma_f32_16x16x32_bf16 v[82:85], v[190:193], v[222:225], v[82:85]
	s_barrier
; #define PG8_STAGE(bufoff, gbase, voff) do { _Pragma("unroll") for (int _i = 0; _i < 2; ++_i) \
;         __builtin_amdgcn_global_load_lds((const unsigned*)((const char*)(gbase) + (voff)[_i]), (LAS unsigned*)(lds + (bufoff) + ldsw + _i * 8192), 16, 0, 0); } while (0)
; #define PG8_LDA(dst, b, h) do { _Pragma("unroll") for (int m = 0; m < 4; ++m) _Pragma("unroll") for (int k = 0; k < 2; ++k) dst[m][k] = *(const LAS bf16x8*)(lds + PG8_SA(b, h) + aoff + m * 2048 + k * 1024); } while (0)
; #define PG8_WAIT_V(n) asm volatile("s_waitcnt vmcnt(" #n ")" ::: "memory")
; template <class Epi, class Sched, bool ALIGN_EPI = false, bool SP2 = false>
; __device__ __forceinline__ void gemm_phase(LAS unsigned char* lds, const Gemm g, const Sched& S, const Epi& E) {
;     ...
;             PG8_LDA(At, 1, 1); PG8_STAGE(PG8_SB(1, 0), b3, voffB); PG8_STAGE(PG8_SB(1, 1), b3 + hstepB, voffB); PG8_STAGE(PG8_SA(1, 0), a3, voffA);
;             PG8_WAIT_V(8); PG8_WAIT_L(0); PG8_BAR; PG8_MMA(1, 0, At, B0); PG8_MMA(1, 1, At, B1); PG8_BAR; PG8_SCHED;
;             } else {
;             PG8_LDB(B0, 0, 0); PG8_SCHED; PG8_LDA(At, 0, 0); PG8_STAGE(PG8_SA(1, 1), a1 + hstep, voffA);
;             PG8_WAIT_L(8); PG8_BAR; PG8_WAIT_L(0); PG8_MMA(0, 0, At, B0); PG8_BAR; PG8_SCHED;
;             PG8_LDB(B1, 0, 1); PG8_STAGE(PG8_SB(0, 0), b2, voffB);
;             PG8_BAR; PG8_WAIT_L(0); PG8_MMA(0, 1, At, B1); PG8_BAR;
;             PG8_LDA(At, 0, 1); PG8_STAGE(PG8_SA(0, 0), a2, voffA);
;             PG8_BAR; PG8_WAIT_L(0); PG8_MMA(1, 0, At, B0); PG8_BAR; PG8_SCHED;
;             PG8_STAGE(PG8_SB(0, 1), b2 + hstepB, voffB);
;             PG8_WAIT_V(6); PG8_BAR; PG8_MMA(1, 1, At, B1); PG8_BAR;
;             PG8_LDB(B0, 1, 0); PG8_SCHED; PG8_LDA(At, 1, 0); PG8_STAGE(PG8_SA(0, 1), a2 + hstep, voffA);
;             PG8_WAIT_L(8); PG8_BAR; PG8_WAIT_L(0); PG8_MMA(0, 0, At, B0); PG8_BAR; PG8_SCHED;
;             PG8_LDB(B1, 1, 1); PG8_STAGE(PG8_SB(1, 0), b3, voffB);
;             PG8_BAR; PG8_WAIT_L(0); PG8_MMA(0, 1, At, B1); PG8_BAR;
;             PG8_LDA(At, 1, 1); PG8_STAGE(PG8_SA(1, 0), a3, voffA);
;             PG8_BAR; PG8_WAIT_L(0); PG8_MMA(1, 0, At, B0); PG8_BAR; PG8_SCHED;
;             PG8_STAGE(PG8_SB(1, 1), b3 + hstepB, voffB);
;             PG8_WAIT_V(6); PG8_BAR; PG8_MMA(1, 1, At, B1); PG8_BAR;
;             }
;         }
;         if constexpr (ALIGN_EPI) { if (wr == 0) PG8_BAR; }
	s_add_i32 s40, s54, s29
	v_lshl_add_u64 v[166:167], v[166:167], 0, s[8:9]
	s_mov_b32 m0, s40
	ds_read_b128 v[194:197], v176 offset:49152
	ds_read_b128 v[198:201], v176 offset:50176
	ds_read_b128 v[202:205], v176 offset:51200
	ds_read_b128 v[206:209], v176 offset:52224
	ds_read_b128 v[210:213], v176 offset:53248
	ds_read_b128 v[214:217], v176 offset:54272
	ds_read_b128 v[218:221], v176 offset:55296
	ds_read_b128 v[222:225], v176 offset:56320
	global_load_lds_dwordx4 v[166:167], off
	s_add_i32 m0, s40, 0x2000
	s_add_u32 s22, s22, 0x80080
	v_lshl_add_u64 v[166:167], v[226:227], 0, s[8:9]
	s_addc_u32 s23, s23, 0
	s_add_i32 s40, s55, s29
	global_load_lds_dwordx4 v[166:167], off
	v_lshl_add_u64 v[166:167], s[22:23], 0, v[150:151]
	s_mov_b32 m0, s40
	s_nop 0
	global_load_lds_dwordx4 v[166:167], off
	v_lshl_add_u64 v[166:167], s[22:23], 0, v[146:147]
	s_add_i32 m0, s40, 0x2000
	s_nop 0
	global_load_lds_dwordx4 v[166:167], off
	v_lshl_add_u64 v[166:167], v[228:229], 0, s[8:9]
	s_mov_b32 m0, s45
	s_nop 0
	global_load_lds_dwordx4 v[166:167], off
	v_lshl_add_u64 v[166:167], v[230:231], 0, s[8:9]
	s_mov_b32 m0, s46
	s_nop 0
	global_load_lds_dwordx4 v[166:167], off
	s_waitcnt vmcnt(8)
	s_waitcnt lgkmcnt(0)
	s_barrier
	s_waitcnt lgkmcnt(0)
	v_mfma_f32_16x16x32_bf16 v[62:65], v[66:69], v[194:197], v[62:65]
	v_mfma_f32_16x16x32_bf16 v[58:61], v[74:77], v[194:197], v[58:61]
	v_mfma_f32_16x16x32_bf16 v[46:49], v[66:69], v[202:205], v[46:49]
	v_mfma_f32_16x16x32_bf16 v[42:45], v[74:77], v[202:205], v[42:45]
	v_mfma_f32_16x16x32_bf16 v[30:33], v[66:69], v[210:213], v[30:33]
	v_mfma_f32_16x16x32_bf16 v[26:29], v[74:77], v[210:213], v[26:29]
	v_mfma_f32_16x16x32_bf16 v[14:17], v[66:69], v[218:221], v[14:17]
	v_mfma_f32_16x16x32_bf16 v[10:13], v[74:77], v[218:221], v[10:13]
	v_mfma_f32_16x16x32_bf16 v[62:65], v[70:73], v[198:201], v[62:65]
	v_mfma_f32_16x16x32_bf16 v[58:61], v[78:81], v[198:201], v[58:61]
	v_mfma_f32_16x16x32_bf16 v[46:49], v[70:73], v[206:209], v[46:49]
	v_mfma_f32_16x16x32_bf16 v[42:45], v[78:81], v[206:209], v[42:45]
	v_mfma_f32_16x16x32_bf16 v[30:33], v[70:73], v[214:217], v[30:33]
	v_mfma_f32_16x16x32_bf16 v[26:29], v[78:81], v[214:217], v[26:29]
	v_mfma_f32_16x16x32_bf16 v[14:17], v[70:73], v[222:225], v[14:17]
	v_mfma_f32_16x16x32_bf16 v[10:13], v[78:81], v[222:225], v[10:13]
	v_mfma_f32_16x16x32_bf16 v[54:57], v[162:165], v[194:197], v[54:57]
	v_mfma_f32_16x16x32_bf16 v[50:53], v[186:189], v[194:197], v[50:53]
	v_mfma_f32_16x16x32_bf16 v[38:41], v[162:165], v[202:205], v[38:41]
	v_mfma_f32_16x16x32_bf16 v[34:37], v[186:189], v[202:205], v[34:37]
	v_mfma_f32_16x16x32_bf16 v[22:25], v[162:165], v[210:213], v[22:25]
	v_mfma_f32_16x16x32_bf16 v[18:21], v[186:189], v[210:213], v[18:21]
	v_mfma_f32_16x16x32_bf16 v[6:9], v[162:165], v[218:221], v[6:9]
	v_mfma_f32_16x16x32_bf16 v[2:5], v[186:189], v[218:221], v[2:5]
	v_mfma_f32_16x16x32_bf16 v[54:57], v[182:185], v[198:201], v[54:57]
	v_mfma_f32_16x16x32_bf16 v[50:53], v[190:193], v[198:201], v[50:53]
	v_mfma_f32_16x16x32_bf16 v[38:41], v[182:185], v[206:209], v[38:41]
	v_mfma_f32_16x16x32_bf16 v[34:37], v[190:193], v[206:209], v[34:37]
	v_mfma_f32_16x16x32_bf16 v[22:25], v[182:185], v[214:217], v[22:25]
	v_mfma_f32_16x16x32_bf16 v[18:21], v[190:193], v[214:217], v[18:21]
	v_mfma_f32_16x16x32_bf16 v[6:9], v[182:185], v[222:225], v[6:9]
	v_mfma_f32_16x16x32_bf16 v[2:5], v[190:193], v[222:225], v[2:5]
	s_barrier
	s_add_i32 s53, s53, 2
	s_add_u32 s16, s16, 0x100
	s_addc_u32 s17, s17, 0
	s_add_u32 s25, s25, 0x100
	s_addc_u32 s52, s52, 0
	s_cmp_gt_u32 s53, 29
	s_cbranch_scc0 .LBB0_1465
	s_setprio 0
	s_and_b64 vcc, exec, s[10:11]
	s_cbranch_vccz .LBB0_1468
	s_barrier

;     __device__ bool next(int i, Unit& u) const { if (i != 0 || c >= 128) return false; const int t = c >> 2; u.pm = t & 3; u.pn = t >> 2; u.koff = koff_bytes; u.q = c & 3; return true; }
; #define PG8_STAGE(bufoff, gbase, voff) do { _Pragma("unroll") for (int _i = 0; _i < 2; ++_i) \
;         __builtin_amdgcn_global_load_lds((const unsigned*)((const char*)(gbase) + (voff)[_i]), (LAS unsigned*)(lds + (bufoff) + ldsw + _i * 8192), 16, 0, 0); } while (0)
; #define PG8_LDA(dst, b, h) do { _Pragma("unroll") for (int m = 0; m < 4; ++m) _Pragma("unroll") for (int k = 0; k < 2; ++k) dst[m][k] = *(const LAS bf16x8*)(lds + PG8_SA(b, h) + aoff + m * 2048 + k * 1024); } while (0)
; #define PG8_LDB(dst, b, h) do { _Pragma("unroll") for (int n = 0; n < 2; ++n) _Pragma("unroll") for (int k = 0; k < 2; ++k) dst[n][k] = *(const LAS bf16x8*)(lds + PG8_SB(b, h) + boff + n * 2048 + k * 1024); } while (0)
; #define PG8_WAIT_V(n) asm volatile("s_waitcnt vmcnt(" #n ")" ::: "memory")
; #define PG8_WAIT_L(n) asm volatile("s_waitcnt lgkmcnt(" #n ")" ::: "memory")
; #define PG8_BAR __builtin_amdgcn_s_barrier()
; template <class Epi, class Sched, bool ALIGN_EPI = false, bool SP2 = false>
; __device__ __forceinline__ void gemm_phase(LAS unsigned char* lds, const Gemm g, const Sched& S, const Epi& E) {
;     ...
;         const bool has_next = S.next(ui + 1, nxt);
;         const char* nA = has_next ? (const char*)g.A + (size_t)nxt.pm * tstep + nxt.koff : cA; const char* nB = has_next ? (const char*)g.Bt + (size_t)nxt.pn * tstep + nxt.koff : cB;
;         for (int t = 0; t < nt; t += 2) {
;             const bool last = (t == nt - 2);
;             const char* a1 = cA + (size_t)(t + 1) * kstep;
;             const char* a2 = last ? nA : cA + (size_t)(t + 2) * kstep; const char* b2 = last ? nB : cB + (size_t)(t + 2) * kstep;
;             const char* a3 = a2 + kstep; const char* b3 = b2 + kstep;
;             if (last && has_next) S.a_ready(nxt);
;             if constexpr (SP2) {
;             PG8_LDB(B0, 0, 0); PG8_LDB(B1, 0, 1); PG8_SCHED; PG8_LDA(At, 0, 0); PG8_STAGE(PG8_SA(1, 1), a1 + hstep, voffA);
;             PG8_WAIT_V(8); PG8_WAIT_L(0); PG8_BAR; PG8_MMA(0, 0, At, B0); PG8_MMA(0, 1, At, B1); PG8_BAR; PG8_SCHED;
;             PG8_LDA(At, 0, 1); PG8_STAGE(PG8_SB(0, 0), b2, voffB); PG8_STAGE(PG8_SB(0, 1), b2 + hstepB, voffB); PG8_STAGE(PG8_SA(0, 0), a2, voffA);
.LBB0_1594:
	s_add_u32 s9, s20, 0x100
	s_addc_u32 s24, s21, 0
	s_mov_b32 s25, -2
	s_waitcnt vmcnt(0)
	v_readfirstlane_b32 s98, v0
	s_nop 3
	s_lshr_b32 s98, s98, 6
	s_cmp_ge_u32 s98, 4
	s_cbranch_scc0 .Lprio_1595
	s_setprio 1
.Lprio_1595:
	ds_read_b128 v[130:133], v196
	ds_read_b128 v[134:137], v196 offset:1024
	ds_read_b128 v[138:141], v196 offset:2048
	ds_read_b128 v[142:145], v196 offset:3072
	ds_read_b128 v[166:169], v197
	ds_read_b128 v[170:173], v197 offset:1024
	ds_read_b128 v[174:177], v197 offset:2048
	ds_read_b128 v[178:181], v197 offset:3072
	s_add_u32 s20, s16, 0x100
	s_addc_u32 s21, s17, 0
	s_cmpk_eq_i32 s25, 0x54
	s_cselect_b32 s47, s3, s21
	s_cselect_b32 s46, s2, s20
	s_cselect_b32 s23, s19, s24
	s_cselect_b32 s22, s18, s9
	v_lshl_add_u64 v[190:191], s[16:17], 0, v[158:159]
	s_add_i32 m0, s31, 0xc000
	ds_read_b128 v[182:185], v198
	ds_read_b128 v[186:189], v198 offset:1024
	ds_read_b128 v[202:205], v198 offset:2048
	ds_read_b128 v[206:209], v198 offset:3072
	ds_read_b128 v[210:213], v198 offset:4096
	ds_read_b128 v[214:217], v198 offset:5120
	ds_read_b128 v[218:221], v198 offset:6144
	ds_read_b128 v[222:225], v198 offset:7168
	global_load_lds_dwordx4 v[190:191], off
	v_lshl_add_u64 v[190:191], s[16:17], 0, v[160:161]
	s_add_i32 m0, s31, 0xe000
	s_nop 0
	global_load_lds_dwordx4 v[190:191], off
	s_waitcnt lgkmcnt(0)
	s_barrier
	s_waitcnt lgkmcnt(0)
	v_mfma_f32_16x16x32_bf16 v[126:129], v[130:133], v[182:185], 0
	v_mfma_f32_16x16x32_bf16 v[122:125], v[138:141], v[182:185], 0
	v_mfma_f32_16x16x32_bf16 v[110:113], v[130:133], v[202:205], 0
	v_mfma_f32_16x16x32_bf16 v[106:109], v[138:141], v[202:205], 0
	v_mfma_f32_16x16x32_bf16 v[94:97], v[130:133], v[210:213], 0
	v_mfma_f32_16x16x32_bf16 v[90:93], v[138:141], v[210:213], 0
	v_mfma_f32_16x16x32_bf16 v[78:81], v[130:133], v[218:221], 0
	v_mfma_f32_16x16x32_bf16 v[74:77], v[138:141], v[218:221], 0
	v_mfma_f32_16x16x32_bf16 v[126:129], v[134:137], v[186:189], v[126:129]
	v_mfma_f32_16x16x32_bf16 v[122:125], v[142:145], v[186:189], v[122:125]
	v_mfma_f32_16x16x32_bf16 v[110:113], v[134:137], v[206:209], v[110:113]
	v_mfma_f32_16x16x32_bf16 v[106:109], v[142:145], v[206:209], v[106:109]
	v_mfma_f32_16x16x32_bf16 v[94:97], v[134:137], v[214:217], v[94:97]
	v_mfma_f32_16x16x32_bf16 v[90:93], v[142:145], v[214:217], v[90:93]
	v_mfma_f32_16x16x32_bf16 v[78:81], v[134:137], v[222:225], v[78:81]
	v_mfma_f32_16x16x32_bf16 v[74:77], v[142:145], v[222:225], v[74:77]
	v_mfma_f32_16x16x32_bf16 v[118:121], v[166:169], v[182:185], 0
	v_mfma_f32_16x16x32_bf16 v[114:117], v[174:177], v[182:185], 0
	v_mfma_f32_16x16x32_bf16 v[102:105], v[166:169], v[202:205], 0
	v_mfma_f32_16x16x32_bf16 v[98:101], v[174:177], v[202:205], 0
	v_mfma_f32_16x16x32_bf16 v[86:89], v[166:169], v[210:213], 0
	v_mfma_f32_16x16x32_bf16 v[82:85], v[174:177], v[210:213], 0
	v_mfma_f32_16x16x32_bf16 v[70:73], v[166:169], v[218:221], 0
	v_mfma_f32_16x16x32_bf16 v[66:69], v[174:177], v[218:221], 0
	v_mfma_f32_16x16x32_bf16 v[118:121], v[170:173], v[186:189], v[118:121]
	v_mfma_f32_16x16x32_bf16 v[114:117], v[178:181], v[186:189], v[114:117]
	v_mfma_f32_16x16x32_bf16 v[102:105], v[170:173], v[206:209], v[102:105]
	v_mfma_f32_16x16x32_bf16 v[98:101], v[178:181], v[206:209], v[98:101]
	v_mfma_f32_16x16x32_bf16 v[86:89], v[170:173], v[214:217], v[86:89]
	v_mfma_f32_16x16x32_bf16 v[82:85], v[178:181], v[214:217], v[82:85]
	v_mfma_f32_16x16x32_bf16 v[70:73], v[170:173], v[222:225], v[70:73]
	v_mfma_f32_16x16x32_bf16 v[66:69], v[178:181], v[222:225], v[66:69]
	s_barrier
	s_add_i32 s16, s52, s30
	v_lshl_add_u64 v[190:191], s[22:23], 0, v[148:149]
	s_mov_b32 m0, s16
	ds_read_b128 v[182:185], v198 offset:16384
	ds_read_b128 v[186:189], v198 offset:17408
	ds_read_b128 v[202:205], v198 offset:18432
	ds_read_b128 v[206:209], v198 offset:19456
	ds_read_b128 v[210:213], v198 offset:20480
	ds_read_b128 v[214:217], v198 offset:21504
	ds_read_b128 v[218:221], v198 offset:22528
	ds_read_b128 v[222:225], v198 offset:23552
	global_load_lds_dwordx4 v[190:191], off
	s_add_i32 m0, s16, 0x2000
	s_add_u32 s16, s22, 0x58000
	v_lshl_add_u64 v[226:227], s[22:23], 0, v[152:153]
	s_addc_u32 s17, s23, 0
	s_add_i32 s56, s53, s30
	global_load_lds_dwordx4 v[226:227], off
	v_lshl_add_u64 v[228:229], s[16:17], 0, v[148:149]
	s_mov_b32 m0, s56
	v_lshl_add_u64 v[230:231], s[46:47], 0, v[150:151]
	global_load_lds_dwordx4 v[228:229], off
	v_lshl_add_u64 v[228:229], s[16:17], 0, v[152:153]
	s_add_i32 m0, s56, 0x2000
	s_nop 0
	global_load_lds_dwordx4 v[228:229], off
	v_lshl_add_u64 v[228:229], s[46:47], 0, v[146:147]
	s_mov_b32 m0, s31
	s_nop 0
	global_load_lds_dwordx4 v[228:229], off
	s_mov_b32 m0, s33
	s_nop 0
	global_load_lds_dwordx4 v[230:231], off
	s_waitcnt lgkmcnt(0)
	s_barrier
; #define PG8_STAGE(bufoff, gbase, voff) do { _Pragma("unroll") for (int _i = 0; _i < 2; ++_i) \
;         __builtin_amdgcn_global_load_lds((const unsigned*)((const char*)(gbase) + (voff)[_i]), (LAS unsigned*)(lds + (bufoff) + ldsw + _i * 8192), 16, 0, 0); } while (0)
; #define PG8_LDA(dst, b, h) do { _Pragma("unroll") for (int m = 0; m < 4; ++m) _Pragma("unroll") for (int k = 0; k < 2; ++k) dst[m][k] = *(const LAS bf16x8*)(lds + PG8_SA(b, h) + aoff + m * 2048 + k * 1024); } while (0)
; #define PG8_LDB(dst, b, h) do { _Pragma("unroll") for (int n = 0; n < 2; ++n) _Pragma("unroll") for (int k = 0; k < 2; ++k) dst[n][k] = *(const LAS bf16x8*)(lds + PG8_SB(b, h) + boff + n * 2048 + k * 1024); } while (0)
; #define PG8_MMA(ai, bj, At, Bt) do { __builtin_amdgcn_s_setprio(1); _Pragma("unroll") for (int m = 0; m < 4; ++m) _Pragma("unroll") for (int n = 0; n < 2; ++n) _Pragma("unroll") for (int k = 0; k < 2; ++k) \
;         acc[ai][bj][m][n] = __builtin_amdgcn_mfma_f32_16x16x32_bf16(Bt[n][k], At[m][k], acc[ai][bj][m][n], 0, 0, 0); __builtin_amdgcn_s_setprio(0); } while (0)
; #define PG8_WAIT_V(n) asm volatile("s_waitcnt vmcnt(" #n ")" ::: "memory")
; #define PG8_WAIT_L(n) asm volatile("s_waitcnt lgkmcnt(" #n ")" ::: "memory")
; #define PG8_BAR __builtin_amdgcn_s_barrier()
; #define PG8_SCHED __builtin_amdgcn_sched_barrier(0)
; template <class Epi, class Sched, bool ALIGN_EPI = false, bool SP2 = false>
; __device__ __forceinline__ void gemm_phase(LAS unsigned char* lds, const Gemm g, const Sched& S, const Epi& E) {
;     ...
;             PG8_WAIT_V(8); PG8_WAIT_L(0); PG8_BAR; PG8_MMA(0, 0, At, B0); PG8_MMA(0, 1, At, B1); PG8_BAR; PG8_SCHED;
;             PG8_LDA(At, 0, 1); PG8_STAGE(PG8_SB(0, 0), b2, voffB); PG8_STAGE(PG8_SB(0, 1), b2 + hstepB, voffB); PG8_STAGE(PG8_SA(0, 0), a2, voffA);
;             PG8_WAIT_V(8); PG8_WAIT_L(0); PG8_BAR; PG8_MMA(1, 0, At, B0); PG8_MMA(1, 1, At, B1); PG8_BAR; PG8_SCHED;
;             PG8_LDB(B0, 1, 0); PG8_LDB(B1, 1, 1); PG8_SCHED; PG8_LDA(At, 1, 0); PG8_STAGE(PG8_SA(0, 1), a2 + hstep, voffA);
;             PG8_WAIT_V(8); PG8_WAIT_L(0); PG8_BAR; PG8_MMA(0, 0, At, B0); PG8_MMA(0, 1, At, B1); PG8_BAR; PG8_SCHED;
	s_waitcnt lgkmcnt(0)
	v_mfma_f32_16x16x32_bf16 v[62:65], v[130:133], v[182:185], 0
	v_mfma_f32_16x16x32_bf16 v[58:61], v[138:141], v[182:185], 0
	v_mfma_f32_16x16x32_bf16 v[46:49], v[130:133], v[202:205], 0
	v_mfma_f32_16x16x32_bf16 v[42:45], v[138:141], v[202:205], 0
	v_mfma_f32_16x16x32_bf16 v[30:33], v[130:133], v[210:213], 0
	v_mfma_f32_16x16x32_bf16 v[26:29], v[138:141], v[210:213], 0
	v_mfma_f32_16x16x32_bf16 v[14:17], v[130:133], v[218:221], 0
	v_mfma_f32_16x16x32_bf16 v[10:13], v[138:141], v[218:221], 0
	v_mfma_f32_16x16x32_bf16 v[62:65], v[134:137], v[186:189], v[62:65]
	v_mfma_f32_16x16x32_bf16 v[58:61], v[142:145], v[186:189], v[58:61]
	v_mfma_f32_16x16x32_bf16 v[46:49], v[134:137], v[206:209], v[46:49]
	v_mfma_f32_16x16x32_bf16 v[42:45], v[142:145], v[206:209], v[42:45]
	v_mfma_f32_16x16x32_bf16 v[30:33], v[134:137], v[214:217], v[30:33]
	v_mfma_f32_16x16x32_bf16 v[26:29], v[142:145], v[214:217], v[26:29]
	v_mfma_f32_16x16x32_bf16 v[14:17], v[134:137], v[222:225], v[14:17]
	v_mfma_f32_16x16x32_bf16 v[10:13], v[142:145], v[222:225], v[10:13]
	v_mfma_f32_16x16x32_bf16 v[54:57], v[166:169], v[182:185], 0
	v_mfma_f32_16x16x32_bf16 v[50:53], v[174:177], v[182:185], 0
	v_mfma_f32_16x16x32_bf16 v[38:41], v[166:169], v[202:205], 0
	v_mfma_f32_16x16x32_bf16 v[34:37], v[174:177], v[202:205], 0
	v_mfma_f32_16x16x32_bf16 v[22:25], v[166:169], v[210:213], 0
	v_mfma_f32_16x16x32_bf16 v[18:21], v[174:177], v[210:213], 0
	v_mfma_f32_16x16x32_bf16 v[6:9], v[166:169], v[218:221], 0
	v_mfma_f32_16x16x32_bf16 v[2:5], v[174:177], v[218:221], 0
	v_mfma_f32_16x16x32_bf16 v[54:57], v[170:173], v[186:189], v[54:57]
	v_mfma_f32_16x16x32_bf16 v[50:53], v[178:181], v[186:189], v[50:53]
	v_mfma_f32_16x16x32_bf16 v[38:41], v[170:173], v[206:209], v[38:41]
	v_mfma_f32_16x16x32_bf16 v[34:37], v[178:181], v[206:209], v[34:37]
	v_mfma_f32_16x16x32_bf16 v[22:25], v[170:173], v[214:217], v[22:25]
	v_mfma_f32_16x16x32_bf16 v[18:21], v[178:181], v[214:217], v[18:21]
	v_mfma_f32_16x16x32_bf16 v[6:9], v[170:173], v[222:225], v[6:9]
	v_mfma_f32_16x16x32_bf16 v[2:5], v[178:181], v[222:225], v[2:5]
	s_barrier
	s_add_i32 s56, 0, 0x18000
	s_add_i32 s57, 0, 0x1c000
	v_add_u32_e32 v142, s56, v1
	v_add_u32_e32 v154, s57, v1
	ds_read_b128 v[130:133], v142
	ds_read_b128 v[134:137], v142 offset:1024
	ds_read_b128 v[138:141], v142 offset:2048
	ds_read_b128 v[142:145], v142 offset:3072
	ds_read_b128 v[166:169], v154
	ds_read_b128 v[170:173], v154 offset:1024
	ds_read_b128 v[174:177], v154 offset:2048
	ds_read_b128 v[178:181], v154 offset:3072
	s_add_u32 s16, s46, 0x160000
	s_addc_u32 s17, s47, 0
	s_mov_b32 m0, s34
	v_lshl_add_u64 v[232:233], s[16:17], 0, v[146:147]
	ds_read_b128 v[182:185], v198 offset:32768
	ds_read_b128 v[186:189], v198 offset:33792
	ds_read_b128 v[202:205], v198 offset:34816
	ds_read_b128 v[206:209], v198 offset:35840
	ds_read_b128 v[210:213], v198 offset:36864
	ds_read_b128 v[214:217], v198 offset:37888
	ds_read_b128 v[218:221], v198 offset:38912
	ds_read_b128 v[222:225], v198 offset:39936
	global_load_lds_dwordx4 v[232:233], off
	v_lshl_add_u64 v[232:233], s[16:17], 0, v[150:151]
	s_mov_b32 m0, s35
	s_nop 0
	global_load_lds_dwordx4 v[232:233], off
	s_waitcnt vmcnt(8)
	s_waitcnt lgkmcnt(0)
	s_barrier
	s_waitcnt lgkmcnt(0)
	v_mfma_f32_16x16x32_bf16 v[126:129], v[130:133], v[182:185], v[126:129]
	v_mfma_f32_16x16x32_bf16 v[122:125], v[138:141], v[182:185], v[122:125]
	v_mfma_f32_16x16x32_bf16 v[110:113], v[130:133], v[202:205], v[110:113]
	v_mfma_f32_16x16x32_bf16 v[106:109], v[138:141], v[202:205], v[106:109]
	v_mfma_f32_16x16x32_bf16 v[94:97], v[130:133], v[210:213], v[94:97]
	v_mfma_f32_16x16x32_bf16 v[90:93], v[138:141], v[210:213], v[90:93]
	v_mfma_f32_16x16x32_bf16 v[78:81], v[130:133], v[218:221], v[78:81]
	v_mfma_f32_16x16x32_bf16 v[74:77], v[138:141], v[218:221], v[74:77]
	v_mfma_f32_16x16x32_bf16 v[126:129], v[134:137], v[186:189], v[126:129]
	v_mfma_f32_16x16x32_bf16 v[122:125], v[142:145], v[186:189], v[122:125]
	v_mfma_f32_16x16x32_bf16 v[110:113], v[134:137], v[206:209], v[110:113]
	v_mfma_f32_16x16x32_bf16 v[106:109], v[142:145], v[206:209], v[106:109]
	v_mfma_f32_16x16x32_bf16 v[94:97], v[134:137], v[214:217], v[94:97]
	v_mfma_f32_16x16x32_bf16 v[90:93], v[142:145], v[214:217], v[90:93]
	v_mfma_f32_16x16x32_bf16 v[78:81], v[134:137], v[222:225], v[78:81]
	v_mfma_f32_16x16x32_bf16 v[74:77], v[142:145], v[222:225], v[74:77]
	v_mfma_f32_16x16x32_bf16 v[118:121], v[166:169], v[182:185], v[118:121]
	v_mfma_f32_16x16x32_bf16 v[114:117], v[174:177], v[182:185], v[114:117]
	v_mfma_f32_16x16x32_bf16 v[102:105], v[166:169], v[202:205], v[102:105]
	v_mfma_f32_16x16x32_bf16 v[98:101], v[174:177], v[202:205], v[98:101]
	v_mfma_f32_16x16x32_bf16 v[86:89], v[166:169], v[210:213], v[86:89]
	v_mfma_f32_16x16x32_bf16 v[82:85], v[174:177], v[210:213], v[82:85]
	v_mfma_f32_16x16x32_bf16 v[70:73], v[166:169], v[218:221], v[70:73]
	v_mfma_f32_16x16x32_bf16 v[66:69], v[174:177], v[218:221], v[66:69]
	v_mfma_f32_16x16x32_bf16 v[118:121], v[170:173], v[186:189], v[118:121]
	v_mfma_f32_16x16x32_bf16 v[114:117], v[178:181], v[186:189], v[114:117]
	v_mfma_f32_16x16x32_bf16 v[102:105], v[170:173], v[206:209], v[102:105]
	v_mfma_f32_16x16x32_bf16 v[98:101], v[178:181], v[206:209], v[98:101]
	v_mfma_f32_16x16x32_bf16 v[86:89], v[170:173], v[214:217], v[86:89]
	v_mfma_f32_16x16x32_bf16 v[82:85], v[178:181], v[214:217], v[82:85]
	v_mfma_f32_16x16x32_bf16 v[70:73], v[170:173], v[222:225], v[70:73]
	v_mfma_f32_16x16x32_bf16 v[66:69], v[178:181], v[222:225], v[66:69]
	s_barrier
; #define PG8_STAGE(bufoff, gbase, voff) do { _Pragma("unroll") for (int _i = 0; _i < 2; ++_i) \
;         __builtin_amdgcn_global_load_lds((const unsigned*)((const char*)(gbase) + (voff)[_i]), (LAS unsigned*)(lds + (bufoff) + ldsw + _i * 8192), 16, 0, 0); } while (0)
; #define PG8_LDA(dst, b, h) do { _Pragma("unroll") for (int m = 0; m < 4; ++m) _Pragma("unroll") for (int k = 0; k < 2; ++k) dst[m][k] = *(const LAS bf16x8*)(lds + PG8_SA(b, h) + aoff + m * 2048 + k * 1024); } while (0)
; #define PG8_LDB(dst, b, h) do { _Pragma("unroll") for (int n = 0; n < 2; ++n) _Pragma("unroll") for (int k = 0; k < 2; ++k) dst[n][k] = *(const LAS bf16x8*)(lds + PG8_SB(b, h) + boff + n * 2048 + k * 1024); } while (0)
; #define PG8_MMA(ai, bj, At, Bt) do { __builtin_amdgcn_s_setprio(1); _Pragma("unroll") for (int m = 0; m < 4; ++m) _Pragma("unroll") for (int n = 0; n < 2; ++n) _Pragma("unroll") for (int k = 0; k < 2; ++k) \
;         acc[ai][bj][m][n] = __builtin_amdgcn_mfma_f32_16x16x32_bf16(Bt[n][k], At[m][k], acc[ai][bj][m][n], 0, 0, 0); __builtin_amdgcn_s_setprio(0); } while (0)
; #define PG8_WAIT_V(n) asm volatile("s_waitcnt vmcnt(" #n ")" ::: "memory")
; #define PG8_WAIT_L(n) asm volatile("s_waitcnt lgkmcnt(" #n ")" ::: "memory")
; #define PG8_BAR __builtin_amdgcn_s_barrier()
; #define PG8_SCHED __builtin_amdgcn_sched_barrier(0)
; template <class Epi, class Sched, bool ALIGN_EPI = false, bool SP2 = false>
; __device__ __forceinline__ void gemm_phase(LAS unsigned char* lds, const Gemm g, const Sched& S, const Epi& E) {
;     ...
;         for (int t = 0; t < nt; t += 2) {
;             const bool last = (t == nt - 2);
;             const char* a1 = cA + (size_t)(t + 1) * kstep;
;             const char* a2 = last ? nA : cA + (size_t)(t + 2) * kstep; const char* b2 = last ? nB : cB + (size_t)(t + 2) * kstep;
;             const char* a3 = a2 + kstep; const char* b3 = b2 + kstep;
;             if (last && has_next) S.a_ready(nxt);
;             if constexpr (SP2) {
;             PG8_LDB(B0, 0, 0); PG8_LDB(B1, 0, 1); PG8_SCHED; PG8_LDA(At, 0, 0); PG8_STAGE(PG8_SA(1, 1), a1 + hstep, voffA);
;     ...
;             PG8_LDA(At, 1, 1); PG8_STAGE(PG8_SB(1, 0), b3, voffB); PG8_STAGE(PG8_SB(1, 1), b3 + hstepB, voffB); PG8_STAGE(PG8_SA(1, 0), a3, voffA);
;             PG8_WAIT_V(8); PG8_WAIT_L(0); PG8_BAR; PG8_MMA(1, 0, At, B0); PG8_MMA(1, 1, At, B1); PG8_BAR; PG8_SCHED;
	s_add_i32 s16, s56, s30
	v_lshl_add_u64 v[190:191], v[190:191], 0, s[12:13]
	s_mov_b32 m0, s16
	ds_read_b128 v[182:185], v198 offset:49152
	ds_read_b128 v[186:189], v198 offset:50176
	ds_read_b128 v[202:205], v198 offset:51200
	ds_read_b128 v[206:209], v198 offset:52224
	ds_read_b128 v[210:213], v198 offset:53248
	ds_read_b128 v[214:217], v198 offset:54272
	ds_read_b128 v[218:221], v198 offset:55296
	ds_read_b128 v[222:225], v198 offset:56320
	global_load_lds_dwordx4 v[190:191], off
	s_add_i32 m0, s16, 0x2000
	s_add_u32 s16, s22, 0x58080
	v_lshl_add_u64 v[190:191], v[226:227], 0, s[12:13]
	s_addc_u32 s17, s23, 0
	s_add_i32 s22, s57, s30
	global_load_lds_dwordx4 v[190:191], off
	v_lshl_add_u64 v[190:191], s[16:17], 0, v[148:149]
	s_mov_b32 m0, s22
	s_nop 0
	global_load_lds_dwordx4 v[190:191], off
	v_lshl_add_u64 v[190:191], s[16:17], 0, v[152:153]
	s_add_i32 m0, s22, 0x2000
	s_nop 0
	global_load_lds_dwordx4 v[190:191], off
	v_lshl_add_u64 v[190:191], v[228:229], 0, s[12:13]
	s_mov_b32 m0, s49
	s_nop 0
	global_load_lds_dwordx4 v[190:191], off
	v_lshl_add_u64 v[190:191], v[230:231], 0, s[12:13]
	s_mov_b32 m0, s50
	s_nop 0
	global_load_lds_dwordx4 v[190:191], off
	s_waitcnt vmcnt(8)
	s_waitcnt lgkmcnt(0)
	s_barrier
	s_waitcnt lgkmcnt(0)
	v_mfma_f32_16x16x32_bf16 v[62:65], v[130:133], v[182:185], v[62:65]
	v_mfma_f32_16x16x32_bf16 v[58:61], v[138:141], v[182:185], v[58:61]
	v_mfma_f32_16x16x32_bf16 v[46:49], v[130:133], v[202:205], v[46:49]
	v_mfma_f32_16x16x32_bf16 v[42:45], v[138:141], v[202:205], v[42:45]
	v_mfma_f32_16x16x32_bf16 v[30:33], v[130:133], v[210:213], v[30:33]
	v_mfma_f32_16x16x32_bf16 v[26:29], v[138:141], v[210:213], v[26:29]
	v_mfma_f32_16x16x32_bf16 v[14:17], v[130:133], v[218:221], v[14:17]
	v_mfma_f32_16x16x32_bf16 v[10:13], v[138:141], v[218:221], v[10:13]
	v_mfma_f32_16x16x32_bf16 v[62:65], v[134:137], v[186:189], v[62:65]
	v_mfma_f32_16x16x32_bf16 v[58:61], v[142:145], v[186:189], v[58:61]
	v_mfma_f32_16x16x32_bf16 v[46:49], v[134:137], v[206:209], v[46:49]
	v_mfma_f32_16x16x32_bf16 v[42:45], v[142:145], v[206:209], v[42:45]
	v_mfma_f32_16x16x32_bf16 v[30:33], v[134:137], v[214:217], v[30:33]
	v_mfma_f32_16x16x32_bf16 v[26:29], v[142:145], v[214:217], v[26:29]
	v_mfma_f32_16x16x32_bf16 v[14:17], v[134:137], v[222:225], v[14:17]
	v_mfma_f32_16x16x32_bf16 v[10:13], v[142:145], v[222:225], v[10:13]
	v_mfma_f32_16x16x32_bf16 v[54:57], v[166:169], v[182:185], v[54:57]
	v_mfma_f32_16x16x32_bf16 v[50:53], v[174:177], v[182:185], v[50:53]
	v_mfma_f32_16x16x32_bf16 v[38:41], v[166:169], v[202:205], v[38:41]
	v_mfma_f32_16x16x32_bf16 v[34:37], v[174:177], v[202:205], v[34:37]
	v_mfma_f32_16x16x32_bf16 v[22:25], v[166:169], v[210:213], v[22:25]
	v_mfma_f32_16x16x32_bf16 v[18:21], v[174:177], v[210:213], v[18:21]
	v_mfma_f32_16x16x32_bf16 v[6:9], v[166:169], v[218:221], v[6:9]
	v_mfma_f32_16x16x32_bf16 v[2:5], v[174:177], v[218:221], v[2:5]
	v_mfma_f32_16x16x32_bf16 v[54:57], v[170:173], v[186:189], v[54:57]
	v_mfma_f32_16x16x32_bf16 v[50:53], v[178:181], v[186:189], v[50:53]
	v_mfma_f32_16x16x32_bf16 v[38:41], v[170:173], v[206:209], v[38:41]
	v_mfma_f32_16x16x32_bf16 v[34:37], v[178:181], v[206:209], v[34:37]
	v_mfma_f32_16x16x32_bf16 v[22:25], v[170:173], v[214:217], v[22:25]
	v_mfma_f32_16x16x32_bf16 v[18:21], v[178:181], v[214:217], v[18:21]
	v_mfma_f32_16x16x32_bf16 v[6:9], v[170:173], v[222:225], v[6:9]
	v_mfma_f32_16x16x32_bf16 v[2:5], v[178:181], v[222:225], v[2:5]
	s_barrier
	s_add_i32 s25, s25, 2
	s_add_u32 s9, s9, 0x100
	s_addc_u32 s24, s24, 0
	s_cmpk_gt_u32 s25, 0x55
	s_mov_b64 s[16:17], s[20:21]
.LBB0_1595:
	ds_read_b128 v[130:133], v196
	ds_read_b128 v[134:137], v196 offset:1024
	ds_read_b128 v[138:141], v196 offset:2048
	ds_read_b128 v[142:145], v196 offset:3072
	ds_read_b128 v[166:169], v197
	ds_read_b128 v[170:173], v197 offset:1024
	ds_read_b128 v[174:177], v197 offset:2048
	ds_read_b128 v[178:181], v197 offset:3072
	s_add_u32 s20, s16, 0x100
	s_addc_u32 s21, s17, 0
	s_cmpk_eq_i32 s25, 0x54
	s_cselect_b32 s47, s3, s21
	s_cselect_b32 s46, s2, s20
	s_cselect_b32 s23, s19, s24
	s_cselect_b32 s22, s18, s9
	v_lshl_add_u64 v[190:191], s[16:17], 0, v[158:159]
	s_add_i32 m0, s31, 0xc000
	ds_read_b128 v[182:185], v198
	ds_read_b128 v[186:189], v198 offset:1024
	ds_read_b128 v[202:205], v198 offset:2048
	ds_read_b128 v[206:209], v198 offset:3072
	ds_read_b128 v[210:213], v198 offset:4096
	ds_read_b128 v[214:217], v198 offset:5120
	ds_read_b128 v[218:221], v198 offset:6144
	ds_read_b128 v[222:225], v198 offset:7168
	global_load_lds_dwordx4 v[190:191], off
	v_lshl_add_u64 v[190:191], s[16:17], 0, v[160:161]
	s_add_i32 m0, s31, 0xe000
	s_nop 0
	global_load_lds_dwordx4 v[190:191], off
	s_waitcnt vmcnt(8)
	s_waitcnt lgkmcnt(0)
	s_barrier
; #define PG8_STAGE(bufoff, gbase, voff) do { _Pragma("unroll") for (int _i = 0; _i < 2; ++_i) \
;         __builtin_amdgcn_global_load_lds((const unsigned*)((const char*)(gbase) + (voff)[_i]), (LAS unsigned*)(lds + (bufoff) + ldsw + _i * 8192), 16, 0, 0); } while (0)
; #define PG8_LDA(dst, b, h) do { _Pragma("unroll") for (int m = 0; m < 4; ++m) _Pragma("unroll") for (int k = 0; k < 2; ++k) dst[m][k] = *(const LAS bf16x8*)(lds + PG8_SA(b, h) + aoff + m * 2048 + k * 1024); } while (0)
; #define PG8_LDB(dst, b, h) do { _Pragma("unroll") for (int n = 0; n < 2; ++n) _Pragma("unroll") for (int k = 0; k < 2; ++k) dst[n][k] = *(const LAS bf16x8*)(lds + PG8_SB(b, h) + boff + n * 2048 + k * 1024); } while (0)
; #define PG8_MMA(ai, bj, At, Bt) do { __builtin_amdgcn_s_setprio(1); _Pragma("unroll") for (int m = 0; m < 4; ++m) _Pragma("unroll") for (int n = 0; n < 2; ++n) _Pragma("unroll") for (int k = 0; k < 2; ++k) \
;         acc[ai][bj][m][n] = __builtin_amdgcn_mfma_f32_16x16x32_bf16(Bt[n][k], At[m][k], acc[ai][bj][m][n], 0, 0, 0); __builtin_amdgcn_s_setprio(0); } while (0)
; #define PG8_WAIT_V(n) asm volatile("s_waitcnt vmcnt(" #n ")" ::: "memory")
; #define PG8_WAIT_L(n) asm volatile("s_waitcnt lgkmcnt(" #n ")" ::: "memory")
; #define PG8_BAR __builtin_amdgcn_s_barrier()
; #define PG8_SCHED __builtin_amdgcn_sched_barrier(0)
; template <class Epi, class Sched, bool ALIGN_EPI = false, bool SP2 = false>
; __device__ __forceinline__ void gemm_phase(LAS unsigned char* lds, const Gemm g, const Sched& S, const Epi& E) {
;     ...
;             PG8_WAIT_V(8); PG8_WAIT_L(0); PG8_BAR; PG8_MMA(0, 0, At, B0); PG8_MMA(0, 1, At, B1); PG8_BAR; PG8_SCHED;
;             PG8_LDA(At, 0, 1); PG8_STAGE(PG8_SB(0, 0), b2, voffB); PG8_STAGE(PG8_SB(0, 1), b2 + hstepB, voffB); PG8_STAGE(PG8_SA(0, 0), a2, voffA);
;             PG8_WAIT_V(8); PG8_WAIT_L(0); PG8_BAR; PG8_MMA(1, 0, At, B0); PG8_MMA(1, 1, At, B1); PG8_BAR; PG8_SCHED;
;             PG8_LDB(B0, 1, 0); PG8_LDB(B1, 1, 1); PG8_SCHED; PG8_LDA(At, 1, 0); PG8_STAGE(PG8_SA(0, 1), a2 + hstep, voffA);
;             PG8_WAIT_V(8); PG8_WAIT_L(0); PG8_BAR; PG8_MMA(0, 0, At, B0); PG8_MMA(0, 1, At, B1); PG8_BAR; PG8_SCHED;
	s_waitcnt lgkmcnt(0)
	v_mfma_f32_16x16x32_bf16 v[126:129], v[130:133], v[182:185], v[126:129]
	v_mfma_f32_16x16x32_bf16 v[122:125], v[138:141], v[182:185], v[122:125]
	v_mfma_f32_16x16x32_bf16 v[110:113], v[130:133], v[202:205], v[110:113]
	v_mfma_f32_16x16x32_bf16 v[106:109], v[138:141], v[202:205], v[106:109]
	v_mfma_f32_16x16x32_bf16 v[94:97], v[130:133], v[210:213], v[94:97]
	v_mfma_f32_16x16x32_bf16 v[90:93], v[138:141], v[210:213], v[90:93]
	v_mfma_f32_16x16x32_bf16 v[78:81], v[130:133], v[218:221], v[78:81]
	v_mfma_f32_16x16x32_bf16 v[74:77], v[138:141], v[218:221], v[74:77]
	v_mfma_f32_16x16x32_bf16 v[126:129], v[134:137], v[186:189], v[126:129]
	v_mfma_f32_16x16x32_bf16 v[122:125], v[142:145], v[186:189], v[122:125]
	v_mfma_f32_16x16x32_bf16 v[110:113], v[134:137], v[206:209], v[110:113]
	v_mfma_f32_16x16x32_bf16 v[106:109], v[142:145], v[206:209], v[106:109]
	v_mfma_f32_16x16x32_bf16 v[94:97], v[134:137], v[214:217], v[94:97]
	v_mfma_f32_16x16x32_bf16 v[90:93], v[142:145], v[214:217], v[90:93]
	v_mfma_f32_16x16x32_bf16 v[78:81], v[134:137], v[222:225], v[78:81]
	v_mfma_f32_16x16x32_bf16 v[74:77], v[142:145], v[222:225], v[74:77]
	v_mfma_f32_16x16x32_bf16 v[118:121], v[166:169], v[182:185], v[118:121]
	v_mfma_f32_16x16x32_bf16 v[114:117], v[174:177], v[182:185], v[114:117]
	v_mfma_f32_16x16x32_bf16 v[102:105], v[166:169], v[202:205], v[102:105]
	v_mfma_f32_16x16x32_bf16 v[98:101], v[174:177], v[202:205], v[98:101]
	v_mfma_f32_16x16x32_bf16 v[86:89], v[166:169], v[210:213], v[86:89]
	v_mfma_f32_16x16x32_bf16 v[82:85], v[174:177], v[210:213], v[82:85]
	v_mfma_f32_16x16x32_bf16 v[70:73], v[166:169], v[218:221], v[70:73]
	v_mfma_f32_16x16x32_bf16 v[66:69], v[174:177], v[218:221], v[66:69]
	v_mfma_f32_16x16x32_bf16 v[118:121], v[170:173], v[186:189], v[118:121]
	v_mfma_f32_16x16x32_bf16 v[114:117], v[178:181], v[186:189], v[114:117]
	v_mfma_f32_16x16x32_bf16 v[102:105], v[170:173], v[206:209], v[102:105]
	v_mfma_f32_16x16x32_bf16 v[98:101], v[178:181], v[206:209], v[98:101]
	v_mfma_f32_16x16x32_bf16 v[86:89], v[170:173], v[214:217], v[86:89]
	v_mfma_f32_16x16x32_bf16 v[82:85], v[178:181], v[214:217], v[82:85]
	v_mfma_f32_16x16x32_bf16 v[70:73], v[170:173], v[222:225], v[70:73]
	v_mfma_f32_16x16x32_bf16 v[66:69], v[178:181], v[222:225], v[66:69]
	s_barrier
	s_add_i32 s16, s52, s30
	v_lshl_add_u64 v[190:191], s[22:23], 0, v[148:149]
	s_mov_b32 m0, s16
	ds_read_b128 v[182:185], v198 offset:16384
	ds_read_b128 v[186:189], v198 offset:17408
	ds_read_b128 v[202:205], v198 offset:18432
	ds_read_b128 v[206:209], v198 offset:19456
	ds_read_b128 v[210:213], v198 offset:20480
	ds_read_b128 v[214:217], v198 offset:21504
	ds_read_b128 v[218:221], v198 offset:22528
	ds_read_b128 v[222:225], v198 offset:23552
	global_load_lds_dwordx4 v[190:191], off
	s_add_i32 m0, s16, 0x2000
	s_add_u32 s16, s22, 0x58000
	v_lshl_add_u64 v[226:227], s[22:23], 0, v[152:153]
	s_addc_u32 s17, s23, 0
	s_add_i32 s56, s53, s30
	global_load_lds_dwordx4 v[226:227], off
	v_lshl_add_u64 v[228:229], s[16:17], 0, v[148:149]
	s_mov_b32 m0, s56
	v_lshl_add_u64 v[230:231], s[46:47], 0, v[150:151]
	global_load_lds_dwordx4 v[228:229], off
	v_lshl_add_u64 v[228:229], s[16:17], 0, v[152:153]
	s_add_i32 m0, s56, 0x2000
	s_nop 0
	global_load_lds_dwordx4 v[228:229], off
	v_lshl_add_u64 v[228:229], s[46:47], 0, v[146:147]
	s_mov_b32 m0, s31
	s_nop 0
	global_load_lds_dwordx4 v[228:229], off
	s_mov_b32 m0, s33
	s_nop 0
	global_load_lds_dwordx4 v[230:231], off
	s_waitcnt vmcnt(8)
	s_waitcnt lgkmcnt(0)
	s_barrier
	s_waitcnt lgkmcnt(0)
	v_mfma_f32_16x16x32_bf16 v[62:65], v[130:133], v[182:185], v[62:65]
	v_mfma_f32_16x16x32_bf16 v[58:61], v[138:141], v[182:185], v[58:61]
	v_mfma_f32_16x16x32_bf16 v[46:49], v[130:133], v[202:205], v[46:49]
	v_mfma_f32_16x16x32_bf16 v[42:45], v[138:141], v[202:205], v[42:45]
	v_mfma_f32_16x16x32_bf16 v[30:33], v[130:133], v[210:213], v[30:33]
	v_mfma_f32_16x16x32_bf16 v[26:29], v[138:141], v[210:213], v[26:29]
	v_mfma_f32_16x16x32_bf16 v[14:17], v[130:133], v[218:221], v[14:17]
	v_mfma_f32_16x16x32_bf16 v[10:13], v[138:141], v[218:221], v[10:13]
	v_mfma_f32_16x16x32_bf16 v[62:65], v[134:137], v[186:189], v[62:65]
	v_mfma_f32_16x16x32_bf16 v[58:61], v[142:145], v[186:189], v[58:61]
	v_mfma_f32_16x16x32_bf16 v[46:49], v[134:137], v[206:209], v[46:49]
	v_mfma_f32_16x16x32_bf16 v[42:45], v[142:145], v[206:209], v[42:45]
	v_mfma_f32_16x16x32_bf16 v[30:33], v[134:137], v[214:217], v[30:33]
	v_mfma_f32_16x16x32_bf16 v[26:29], v[142:145], v[214:217], v[26:29]
	v_mfma_f32_16x16x32_bf16 v[14:17], v[134:137], v[222:225], v[14:17]
	v_mfma_f32_16x16x32_bf16 v[10:13], v[142:145], v[222:225], v[10:13]
	v_mfma_f32_16x16x32_bf16 v[54:57], v[166:169], v[182:185], v[54:57]
	v_mfma_f32_16x16x32_bf16 v[50:53], v[174:177], v[182:185], v[50:53]
	v_mfma_f32_16x16x32_bf16 v[38:41], v[166:169], v[202:205], v[38:41]
	v_mfma_f32_16x16x32_bf16 v[34:37], v[174:177], v[202:205], v[34:37]
	v_mfma_f32_16x16x32_bf16 v[22:25], v[166:169], v[210:213], v[22:25]
	v_mfma_f32_16x16x32_bf16 v[18:21], v[174:177], v[210:213], v[18:21]
	v_mfma_f32_16x16x32_bf16 v[6:9], v[166:169], v[218:221], v[6:9]
	v_mfma_f32_16x16x32_bf16 v[2:5], v[174:177], v[218:221], v[2:5]
	v_mfma_f32_16x16x32_bf16 v[54:57], v[170:173], v[186:189], v[54:57]
	v_mfma_f32_16x16x32_bf16 v[50:53], v[178:181], v[186:189], v[50:53]
	v_mfma_f32_16x16x32_bf16 v[38:41], v[170:173], v[206:209], v[38:41]
	v_mfma_f32_16x16x32_bf16 v[34:37], v[178:181], v[206:209], v[34:37]
	v_mfma_f32_16x16x32_bf16 v[22:25], v[170:173], v[214:217], v[22:25]
	v_mfma_f32_16x16x32_bf16 v[18:21], v[178:181], v[214:217], v[18:21]
	v_mfma_f32_16x16x32_bf16 v[6:9], v[170:173], v[222:225], v[6:9]
	v_mfma_f32_16x16x32_bf16 v[2:5], v[178:181], v[222:225], v[2:5]
	s_barrier
; #define PG8_STAGE(bufoff, gbase, voff) do { _Pragma("unroll") for (int _i = 0; _i < 2; ++_i) \
;         __builtin_amdgcn_global_load_lds((const unsigned*)((const char*)(gbase) + (voff)[_i]), (LAS unsigned*)(lds + (bufoff) + ldsw + _i * 8192), 16, 0, 0); } while (0)
; #define PG8_LDA(dst, b, h) do { _Pragma("unroll") for (int m = 0; m < 4; ++m) _Pragma("unroll") for (int k = 0; k < 2; ++k) dst[m][k] = *(const LAS bf16x8*)(lds + PG8_SA(b, h) + aoff + m * 2048 + k * 1024); } while (0)
; #define PG8_LDB(dst, b, h) do { _Pragma("unroll") for (int n = 0; n < 2; ++n) _Pragma("unroll") for (int k = 0; k < 2; ++k) dst[n][k] = *(const LAS bf16x8*)(lds + PG8_SB(b, h) + boff + n * 2048 + k * 1024); } while (0)
; #define PG8_MMA(ai, bj, At, Bt) do { __builtin_amdgcn_s_setprio(1); _Pragma("unroll") for (int m = 0; m < 4; ++m) _Pragma("unroll") for (int n = 0; n < 2; ++n) _Pragma("unroll") for (int k = 0; k < 2; ++k) \
;         acc[ai][bj][m][n] = __builtin_amdgcn_mfma_f32_16x16x32_bf16(Bt[n][k], At[m][k], acc[ai][bj][m][n], 0, 0, 0); __builtin_amdgcn_s_setprio(0); } while (0)
; #define PG8_WAIT_V(n) asm volatile("s_waitcnt vmcnt(" #n ")" ::: "memory")
; #define PG8_WAIT_L(n) asm volatile("s_waitcnt lgkmcnt(" #n ")" ::: "memory")
; #define PG8_BAR __builtin_amdgcn_s_barrier()
; #define PG8_SCHED __builtin_amdgcn_sched_barrier(0)
; template <class Epi, class Sched, bool ALIGN_EPI = false, bool SP2 = false>
; __device__ __forceinline__ void gemm_phase(LAS unsigned char* lds, const Gemm g, const Sched& S, const Epi& E) {
;     ...
;             PG8_LDB(B0, 1, 0); PG8_LDB(B1, 1, 1); PG8_SCHED; PG8_LDA(At, 1, 0); PG8_STAGE(PG8_SA(0, 1), a2 + hstep, voffA);
;             PG8_WAIT_V(8); PG8_WAIT_L(0); PG8_BAR; PG8_MMA(0, 0, At, B0); PG8_MMA(0, 1, At, B1); PG8_BAR; PG8_SCHED;
	s_add_i32 s56, 0, 0x18000
	s_add_i32 s57, 0, 0x1c000
	v_add_u32_e32 v142, s56, v1
	v_add_u32_e32 v154, s57, v1
	ds_read_b128 v[130:133], v142
	ds_read_b128 v[134:137], v142 offset:1024
	ds_read_b128 v[138:141], v142 offset:2048
	ds_read_b128 v[142:145], v142 offset:3072
	ds_read_b128 v[166:169], v154
	ds_read_b128 v[170:173], v154 offset:1024
	ds_read_b128 v[174:177], v154 offset:2048
	ds_read_b128 v[178:181], v154 offset:3072
	s_add_u32 s16, s46, 0x160000
	s_addc_u32 s17, s47, 0
	s_mov_b32 m0, s34
	v_lshl_add_u64 v[232:233], s[16:17], 0, v[146:147]
	ds_read_b128 v[182:185], v198 offset:32768
	ds_read_b128 v[186:189], v198 offset:33792
	ds_read_b128 v[202:205], v198 offset:34816
	ds_read_b128 v[206:209], v198 offset:35840
	ds_read_b128 v[210:213], v198 offset:36864
	ds_read_b128 v[214:217], v198 offset:37888
	ds_read_b128 v[218:221], v198 offset:38912
	ds_read_b128 v[222:225], v198 offset:39936
	global_load_lds_dwordx4 v[232:233], off
	v_lshl_add_u64 v[232:233], s[16:17], 0, v[150:151]
	s_mov_b32 m0, s35
	s_nop 0
	global_load_lds_dwordx4 v[232:233], off
	s_waitcnt vmcnt(8)
	s_waitcnt lgkmcnt(0)
	s_barrier
	s_waitcnt lgkmcnt(0)
	v_mfma_f32_16x16x32_bf16 v[126:129], v[130:133], v[182:185], v[126:129]
	v_mfma_f32_16x16x32_bf16 v[122:125], v[138:141], v[182:185], v[122:125]
	v_mfma_f32_16x16x32_bf16 v[110:113], v[130:133], v[202:205], v[110:113]
	v_mfma_f32_16x16x32_bf16 v[106:109], v[138:141], v[202:205], v[106:109]
	v_mfma_f32_16x16x32_bf16 v[94:97], v[130:133], v[210:213], v[94:97]
	v_mfma_f32_16x16x32_bf16 v[90:93], v[138:141], v[210:213], v[90:93]
	v_mfma_f32_16x16x32_bf16 v[78:81], v[130:133], v[218:221], v[78:81]
	v_mfma_f32_16x16x32_bf16 v[74:77], v[138:141], v[218:221], v[74:77]
	v_mfma_f32_16x16x32_bf16 v[126:129], v[134:137], v[186:189], v[126:129]
	v_mfma_f32_16x16x32_bf16 v[122:125], v[142:145], v[186:189], v[122:125]
	v_mfma_f32_16x16x32_bf16 v[110:113], v[134:137], v[206:209], v[110:113]
	v_mfma_f32_16x16x32_bf16 v[106:109], v[142:145], v[206:209], v[106:109]
	v_mfma_f32_16x16x32_bf16 v[94:97], v[134:137], v[214:217], v[94:97]
	v_mfma_f32_16x16x32_bf16 v[90:93], v[142:145], v[214:217], v[90:93]
	v_mfma_f32_16x16x32_bf16 v[78:81], v[134:137], v[222:225], v[78:81]
	v_mfma_f32_16x16x32_bf16 v[74:77], v[142:145], v[222:225], v[74:77]
	v_mfma_f32_16x16x32_bf16 v[118:121], v[166:169], v[182:185], v[118:121]
	v_mfma_f32_16x16x32_bf16 v[114:117], v[174:177], v[182:185], v[114:117]
	v_mfma_f32_16x16x32_bf16 v[102:105], v[166:169], v[202:205], v[102:105]
	v_mfma_f32_16x16x32_bf16 v[98:101], v[174:177], v[202:205], v[98:101]
	v_mfma_f32_16x16x32_bf16 v[86:89], v[166:169], v[210:213], v[86:89]
	v_mfma_f32_16x16x32_bf16 v[82:85], v[174:177], v[210:213], v[82:85]
	v_mfma_f32_16x16x32_bf16 v[70:73], v[166:169], v[218:221], v[70:73]
	v_mfma_f32_16x16x32_bf16 v[66:69], v[174:177], v[218:221], v[66:69]
	v_mfma_f32_16x16x32_bf16 v[118:121], v[170:173], v[186:189], v[118:121]
	v_mfma_f32_16x16x32_bf16 v[114:117], v[178:181], v[186:189], v[114:117]
	v_mfma_f32_16x16x32_bf16 v[102:105], v[170:173], v[206:209], v[102:105]
	v_mfma_f32_16x16x32_bf16 v[98:101], v[178:181], v[206:209], v[98:101]
	v_mfma_f32_16x16x32_bf16 v[86:89], v[170:173], v[214:217], v[86:89]
	v_mfma_f32_16x16x32_bf16 v[82:85], v[178:181], v[214:217], v[82:85]
	v_mfma_f32_16x16x32_bf16 v[70:73], v[170:173], v[222:225], v[70:73]
	v_mfma_f32_16x16x32_bf16 v[66:69], v[178:181], v[222:225], v[66:69]
	s_barrier
; #define PG8_STAGE(bufoff, gbase, voff) do { _Pragma("unroll") for (int _i = 0; _i < 2; ++_i) \
;         __builtin_amdgcn_global_load_lds((const unsigned*)((const char*)(gbase) + (voff)[_i]), (LAS unsigned*)(lds + (bufoff) + ldsw + _i * 8192), 16, 0, 0); } while (0)
; #define PG8_LDA(dst, b, h) do { _Pragma("unroll") for (int m = 0; m < 4; ++m) _Pragma("unroll") for (int k = 0; k < 2; ++k) dst[m][k] = *(const LAS bf16x8*)(lds + PG8_SA(b, h) + aoff + m * 2048 + k * 1024); } while (0)
; #define PG8_MMA(ai, bj, At, Bt) do { __builtin_amdgcn_s_setprio(1); _Pragma("unroll") for (int m = 0; m < 4; ++m) _Pragma("unroll") for (int n = 0; n < 2; ++n) _Pragma("unroll") for (int k = 0; k < 2; ++k) \
;         acc[ai][bj][m][n] = __builtin_amdgcn_mfma_f32_16x16x32_bf16(Bt[n][k], At[m][k], acc[ai][bj][m][n], 0, 0, 0); __builtin_amdgcn_s_setprio(0); } while (0)
; #define PG8_WAIT_V(n) asm volatile("s_waitcnt vmcnt(" #n ")" ::: "memory")
; #define PG8_WAIT_L(n) asm volatile("s_waitcnt lgkmcnt(" #n ")" ::: "memory")
; #define PG8_BAR __builtin_amdgcn_s_barrier()
; #define PG8_SCHED __builtin_amdgcn_sched_barrier(0)
; template <class Epi, class Sched, bool ALIGN_EPI = false, bool SP2 = false>
; __device__ __forceinline__ void gemm_phase(LAS unsigned char* lds, const Gemm g, const Sched& S, const Epi& E) {
;     ...
;             PG8_LDA(At, 1, 1); PG8_STAGE(PG8_SB(1, 0), b3, voffB); PG8_STAGE(PG8_SB(1, 1), b3 + hstepB, voffB); PG8_STAGE(PG8_SA(1, 0), a3, voffA);
;             PG8_WAIT_V(8); PG8_WAIT_L(0); PG8_BAR; PG8_MMA(1, 0, At, B0); PG8_MMA(1, 1, At, B1); PG8_BAR; PG8_SCHED;
;     ...
;         if constexpr (ALIGN_EPI) { if (wr == 0) PG8_BAR; }
	s_add_i32 s16, s56, s30
	v_lshl_add_u64 v[190:191], v[190:191], 0, s[12:13]
	s_mov_b32 m0, s16
	ds_read_b128 v[182:185], v198 offset:49152
	ds_read_b128 v[186:189], v198 offset:50176
	ds_read_b128 v[202:205], v198 offset:51200
	ds_read_b128 v[206:209], v198 offset:52224
	ds_read_b128 v[210:213], v198 offset:53248
	ds_read_b128 v[214:217], v198 offset:54272
	ds_read_b128 v[218:221], v198 offset:55296
	ds_read_b128 v[222:225], v198 offset:56320
	global_load_lds_dwordx4 v[190:191], off
	s_add_i32 m0, s16, 0x2000
	s_add_u32 s16, s22, 0x58080
	v_lshl_add_u64 v[190:191], v[226:227], 0, s[12:13]
	s_addc_u32 s17, s23, 0
	s_add_i32 s22, s57, s30
	global_load_lds_dwordx4 v[190:191], off
	v_lshl_add_u64 v[190:191], s[16:17], 0, v[148:149]
	s_mov_b32 m0, s22
	s_nop 0
	global_load_lds_dwordx4 v[190:191], off
	v_lshl_add_u64 v[190:191], s[16:17], 0, v[152:153]
	s_add_i32 m0, s22, 0x2000
	s_nop 0
	global_load_lds_dwordx4 v[190:191], off
	v_lshl_add_u64 v[190:191], v[228:229], 0, s[12:13]
	s_mov_b32 m0, s49
	s_nop 0
	global_load_lds_dwordx4 v[190:191], off
	v_lshl_add_u64 v[190:191], v[230:231], 0, s[12:13]
	s_mov_b32 m0, s50
	s_nop 0
	global_load_lds_dwordx4 v[190:191], off
	s_waitcnt vmcnt(8)
	s_waitcnt lgkmcnt(0)
	s_barrier
	s_waitcnt lgkmcnt(0)
	v_mfma_f32_16x16x32_bf16 v[62:65], v[130:133], v[182:185], v[62:65]
	v_mfma_f32_16x16x32_bf16 v[58:61], v[138:141], v[182:185], v[58:61]
	v_mfma_f32_16x16x32_bf16 v[46:49], v[130:133], v[202:205], v[46:49]
	v_mfma_f32_16x16x32_bf16 v[42:45], v[138:141], v[202:205], v[42:45]
	v_mfma_f32_16x16x32_bf16 v[30:33], v[130:133], v[210:213], v[30:33]
	v_mfma_f32_16x16x32_bf16 v[26:29], v[138:141], v[210:213], v[26:29]
	v_mfma_f32_16x16x32_bf16 v[14:17], v[130:133], v[218:221], v[14:17]
	v_mfma_f32_16x16x32_bf16 v[10:13], v[138:141], v[218:221], v[10:13]
	v_mfma_f32_16x16x32_bf16 v[62:65], v[134:137], v[186:189], v[62:65]
	v_mfma_f32_16x16x32_bf16 v[58:61], v[142:145], v[186:189], v[58:61]
	v_mfma_f32_16x16x32_bf16 v[46:49], v[134:137], v[206:209], v[46:49]
	v_mfma_f32_16x16x32_bf16 v[42:45], v[142:145], v[206:209], v[42:45]
	v_mfma_f32_16x16x32_bf16 v[30:33], v[134:137], v[214:217], v[30:33]
	v_mfma_f32_16x16x32_bf16 v[26:29], v[142:145], v[214:217], v[26:29]
	v_mfma_f32_16x16x32_bf16 v[14:17], v[134:137], v[222:225], v[14:17]
	v_mfma_f32_16x16x32_bf16 v[10:13], v[142:145], v[222:225], v[10:13]
	v_mfma_f32_16x16x32_bf16 v[54:57], v[166:169], v[182:185], v[54:57]
	v_mfma_f32_16x16x32_bf16 v[50:53], v[174:177], v[182:185], v[50:53]
	v_mfma_f32_16x16x32_bf16 v[38:41], v[166:169], v[202:205], v[38:41]
	v_mfma_f32_16x16x32_bf16 v[34:37], v[174:177], v[202:205], v[34:37]
	v_mfma_f32_16x16x32_bf16 v[22:25], v[166:169], v[210:213], v[22:25]
	v_mfma_f32_16x16x32_bf16 v[18:21], v[174:177], v[210:213], v[18:21]
	v_mfma_f32_16x16x32_bf16 v[6:9], v[166:169], v[218:221], v[6:9]
	v_mfma_f32_16x16x32_bf16 v[2:5], v[174:177], v[218:221], v[2:5]
	v_mfma_f32_16x16x32_bf16 v[54:57], v[170:173], v[186:189], v[54:57]
	v_mfma_f32_16x16x32_bf16 v[50:53], v[178:181], v[186:189], v[50:53]
	v_mfma_f32_16x16x32_bf16 v[38:41], v[170:173], v[206:209], v[38:41]
	v_mfma_f32_16x16x32_bf16 v[34:37], v[178:181], v[206:209], v[34:37]
	v_mfma_f32_16x16x32_bf16 v[22:25], v[170:173], v[214:217], v[22:25]
	v_mfma_f32_16x16x32_bf16 v[18:21], v[178:181], v[214:217], v[18:21]
	v_mfma_f32_16x16x32_bf16 v[6:9], v[170:173], v[222:225], v[6:9]
	v_mfma_f32_16x16x32_bf16 v[2:5], v[178:181], v[222:225], v[2:5]
	s_barrier
	s_add_i32 s25, s25, 2
	s_add_u32 s9, s9, 0x100
	s_addc_u32 s24, s24, 0
	s_cmpk_gt_u32 s25, 0x55
	s_mov_b64 s[16:17], s[20:21]
	s_cbranch_scc0 .LBB0_1595
	s_setprio 0
	s_and_b64 vcc, exec, s[14:15]
	s_cbranch_vccz .LBB0_1598
	s_barrier

; __device__ __forceinline__ float row_rstd(const float* ss, int row) { return 1.0f / sqrtf(ss[row] * (1.0f / DM) + 1e-6f); }
; #define PG8_STAGE(bufoff, gbase, voff) do { _Pragma("unroll") for (int _i = 0; _i < 2; ++_i) \
;         __builtin_amdgcn_global_load_lds((const unsigned*)((const char*)(gbase) + (voff)[_i]), (LAS unsigned*)(lds + (bufoff) + ldsw + _i * 8192), 16, 0, 0); } while (0)
; #define PG8_LDA(dst, b, h) do { _Pragma("unroll") for (int m = 0; m < 4; ++m) _Pragma("unroll") for (int k = 0; k < 2; ++k) dst[m][k] = *(const LAS bf16x8*)(lds + PG8_SA(b, h) + aoff + m * 2048 + k * 1024); } while (0)
; #define PG8_LDB(dst, b, h) do { _Pragma("unroll") for (int n = 0; n < 2; ++n) _Pragma("unroll") for (int k = 0; k < 2; ++k) dst[n][k] = *(const LAS bf16x8*)(lds + PG8_SB(b, h) + boff + n * 2048 + k * 1024); } while (0)
; #define PG8_WAIT_V(n) asm volatile("s_waitcnt vmcnt(" #n ")" ::: "memory")
; #define PG8_WAIT_L(n) asm volatile("s_waitcnt lgkmcnt(" #n ")" ::: "memory")
; #define PG8_BAR __builtin_amdgcn_s_barrier()
; #define PG8_SCHED __builtin_amdgcn_sched_barrier(0)
;     __device__ __forceinline__ void operator()(const f32x4 (&acc)[2][2][4][2], const Unit& u, int wr, int wc, int fr, int fq) const {
;     ...
;         const float* bp = bias + (size_t)s * BIAS_N + u.pn * BM + wc * 32 + 8 * fq;
;         const f32x4 ba0 = *(const f32x4*)bp, ba1 = *(const f32x4*)(bp + 4), bb0 = *(const f32x4*)(bp + HALF), bb1 = *(const f32x4*)(bp + HALF + 4);
;         const int lane = fq * 16 + fr;
;         const float rsl0 = row_rstd(ss, u.pm * BM + wr * 64 + lane), rsl1 = row_rstd(ss, u.pm * BM + HALF + wr * 64 + lane);
; template <class Epi, class Sched, bool ALIGN_EPI = false, bool SP2 = false>
; __device__ __forceinline__ void gemm_phase(LAS unsigned char* lds, const Gemm g, const Sched& S, const Epi& E) {
;     ...
;             if constexpr (SP2) {
;             PG8_LDB(B0, 0, 0); PG8_LDB(B1, 0, 1); PG8_SCHED; PG8_LDA(At, 0, 0); PG8_STAGE(PG8_SA(1, 1), a1 + hstep, voffA);
;             PG8_WAIT_V(8); PG8_WAIT_L(0); PG8_BAR; PG8_MMA(0, 0, At, B0); PG8_MMA(0, 1, At, B1); PG8_BAR; PG8_SCHED;
;             PG8_LDA(At, 0, 1); PG8_STAGE(PG8_SB(0, 0), b2, voffB); PG8_STAGE(PG8_SB(0, 1), b2 + hstepB, voffB); PG8_STAGE(PG8_SA(0, 0), a2, voffA);
;             PG8_WAIT_V(8); PG8_WAIT_L(0); PG8_BAR; PG8_MMA(1, 0, At, B0); PG8_MMA(1, 1, At, B1); PG8_BAR; PG8_SCHED;
.Lpre_up1l1:
	s_lshl_b64 s[98:99], s[98:99], 2
	s_add_u32 s98, s36, s98
	s_addc_u32 s99, s37, s99
	s_lshl_b32 s100, s0, 8
	s_ashr_i32 s101, s100, 31
	s_lshl_b64 s[100:101], s[100:101], 2
	s_add_u32 s98, s98, s100
	s_addc_u32 s99, s99, s101
	s_add_u32 s98, s98, s47
	s_addc_u32 s99, s99, 0
	s_lshl_b32 s100, s2, 8
	s_add_i32 s100, s100, s35
	v_or_b32_e32 v162, s100, v170
	v_ashrrev_i32_e32 v163, 31, v162
	v_lshl_add_u64 v[162:163], v[162:163], 2, s[6:7]
	v_add_u32_e32 v164, s100, v171
	v_ashrrev_i32_e32 v165, 31, v164
	v_lshl_add_u64 v[164:165], v[164:165], 2, s[6:7]
	global_load_dwordx4 v[234:237], v176, s[98:99] offset:16
	global_load_dwordx4 v[238:241], v176, s[98:99]
	global_load_dwordx4 v[242:245], v176, s[98:99] offset:528
	global_load_dwordx4 v[246:249], v176, s[98:99] offset:512
	global_load_dword v250, v[162:163], off
	global_load_dword v251, v[164:165], off
	v_readfirstlane_b32 s98, v0
	s_nop 3
	s_lshr_b32 s98, s98, 6
	s_cmp_ge_u32 s98, 4
	s_cbranch_scc0 .Lprio_1822
	s_setprio 1
.Lprio_1822:
	ds_read_b128 v[66:69], v173
	ds_read_b128 v[70:73], v173 offset:1024
	ds_read_b128 v[74:77], v173 offset:2048
	ds_read_b128 v[78:81], v173 offset:3072
	ds_read_b128 v[162:165], v174
	ds_read_b128 v[180:183], v174 offset:1024
	ds_read_b128 v[184:187], v174 offset:2048
	ds_read_b128 v[188:191], v174 offset:3072
	s_add_u32 s22, s16, 0xfff80080
	s_addc_u32 s23, s17, -1
	s_cmp_eq_u32 s50, 28
	s_cselect_b32 s41, s3, s23
	s_cselect_b32 s40, s15, s22
	s_cselect_b32 s23, s13, s49
	s_cselect_b32 s22, s24, s25
	v_lshl_add_u64 v[166:167], s[16:17], 0, v[156:157]
	s_add_i32 m0, s29, 0xc000
	ds_read_b128 v[192:195], v175
	ds_read_b128 v[196:199], v175 offset:1024
	ds_read_b128 v[200:203], v175 offset:2048
	ds_read_b128 v[204:207], v175 offset:3072
	ds_read_b128 v[208:211], v175 offset:4096
	ds_read_b128 v[212:215], v175 offset:5120
	ds_read_b128 v[216:219], v175 offset:6144
	ds_read_b128 v[220:223], v175 offset:7168
	global_load_lds_dwordx4 v[166:167], off
	v_lshl_add_u64 v[166:167], s[16:17], 0, v[154:155]
	s_add_i32 m0, s29, 0xe000
	s_nop 0
	global_load_lds_dwordx4 v[166:167], off
	s_waitcnt lgkmcnt(0)
	s_barrier
	s_waitcnt lgkmcnt(0)
	v_mfma_f32_16x16x32_bf16 v[142:145], v[66:69], v[192:195], 0
	v_mfma_f32_16x16x32_bf16 v[138:141], v[74:77], v[192:195], 0
	v_mfma_f32_16x16x32_bf16 v[126:129], v[66:69], v[200:203], 0
	v_mfma_f32_16x16x32_bf16 v[122:125], v[74:77], v[200:203], 0
	v_mfma_f32_16x16x32_bf16 v[110:113], v[66:69], v[208:211], 0
	v_mfma_f32_16x16x32_bf16 v[106:109], v[74:77], v[208:211], 0
	v_mfma_f32_16x16x32_bf16 v[94:97], v[66:69], v[216:219], 0
	v_mfma_f32_16x16x32_bf16 v[90:93], v[74:77], v[216:219], 0
	v_mfma_f32_16x16x32_bf16 v[142:145], v[70:73], v[196:199], v[142:145]
	v_mfma_f32_16x16x32_bf16 v[138:141], v[78:81], v[196:199], v[138:141]
	v_mfma_f32_16x16x32_bf16 v[126:129], v[70:73], v[204:207], v[126:129]
	v_mfma_f32_16x16x32_bf16 v[122:125], v[78:81], v[204:207], v[122:125]
	v_mfma_f32_16x16x32_bf16 v[110:113], v[70:73], v[212:215], v[110:113]
	v_mfma_f32_16x16x32_bf16 v[106:109], v[78:81], v[212:215], v[106:109]
	v_mfma_f32_16x16x32_bf16 v[94:97], v[70:73], v[220:223], v[94:97]
	v_mfma_f32_16x16x32_bf16 v[90:93], v[78:81], v[220:223], v[90:93]
	v_mfma_f32_16x16x32_bf16 v[134:137], v[162:165], v[192:195], 0
	v_mfma_f32_16x16x32_bf16 v[130:133], v[184:187], v[192:195], 0
	v_mfma_f32_16x16x32_bf16 v[118:121], v[162:165], v[200:203], 0
	v_mfma_f32_16x16x32_bf16 v[114:117], v[184:187], v[200:203], 0
	v_mfma_f32_16x16x32_bf16 v[102:105], v[162:165], v[208:211], 0
	v_mfma_f32_16x16x32_bf16 v[98:101], v[184:187], v[208:211], 0
	v_mfma_f32_16x16x32_bf16 v[86:89], v[162:165], v[216:219], 0
	v_mfma_f32_16x16x32_bf16 v[82:85], v[184:187], v[216:219], 0
	v_mfma_f32_16x16x32_bf16 v[134:137], v[180:183], v[196:199], v[134:137]
	v_mfma_f32_16x16x32_bf16 v[130:133], v[188:191], v[196:199], v[130:133]
	v_mfma_f32_16x16x32_bf16 v[118:121], v[180:183], v[204:207], v[118:121]
	v_mfma_f32_16x16x32_bf16 v[114:117], v[188:191], v[204:207], v[114:117]
	v_mfma_f32_16x16x32_bf16 v[102:105], v[180:183], v[212:215], v[102:105]
	v_mfma_f32_16x16x32_bf16 v[98:101], v[188:191], v[212:215], v[98:101]
	v_mfma_f32_16x16x32_bf16 v[86:89], v[180:183], v[220:223], v[86:89]
	v_mfma_f32_16x16x32_bf16 v[82:85], v[188:191], v[220:223], v[82:85]
	s_barrier
	s_add_i32 s51, s44, s26
	v_lshl_add_u64 v[166:167], s[22:23], 0, v[150:151]
	s_mov_b32 m0, s51
	ds_read_b128 v[192:195], v175 offset:16384
	ds_read_b128 v[196:199], v175 offset:17408
	ds_read_b128 v[200:203], v175 offset:18432
	ds_read_b128 v[204:207], v175 offset:19456
	ds_read_b128 v[208:211], v175 offset:20480
	ds_read_b128 v[212:215], v175 offset:21504
	ds_read_b128 v[216:219], v175 offset:22528
	ds_read_b128 v[220:223], v175 offset:23552
	global_load_lds_dwordx4 v[166:167], off
	s_add_i32 m0, s51, 0x2000
	s_add_u32 s52, s22, 0x80000
	v_lshl_add_u64 v[224:225], s[22:23], 0, v[146:147]
	s_addc_u32 s53, s23, 0
	s_add_i32 s51, s45, s26
	global_load_lds_dwordx4 v[224:225], off
	v_lshl_add_u64 v[226:227], s[52:53], 0, v[150:151]
	s_mov_b32 m0, s51
	v_lshl_add_u64 v[228:229], s[40:41], 0, v[148:149]
	global_load_lds_dwordx4 v[226:227], off
	v_lshl_add_u64 v[226:227], s[52:53], 0, v[146:147]
	s_add_i32 m0, s51, 0x2000
	s_nop 0
	global_load_lds_dwordx4 v[226:227], off
	v_lshl_add_u64 v[226:227], s[40:41], 0, v[152:153]
	s_mov_b32 m0, s29
	s_nop 0
	global_load_lds_dwordx4 v[226:227], off
	s_mov_b32 m0, s30
	s_nop 0
	global_load_lds_dwordx4 v[228:229], off
	s_waitcnt lgkmcnt(0)
	s_barrier
; #define PG8_STAGE(bufoff, gbase, voff) do { _Pragma("unroll") for (int _i = 0; _i < 2; ++_i) \
;         __builtin_amdgcn_global_load_lds((const unsigned*)((const char*)(gbase) + (voff)[_i]), (LAS unsigned*)(lds + (bufoff) + ldsw + _i * 8192), 16, 0, 0); } while (0)
; #define PG8_LDA(dst, b, h) do { _Pragma("unroll") for (int m = 0; m < 4; ++m) _Pragma("unroll") for (int k = 0; k < 2; ++k) dst[m][k] = *(const LAS bf16x8*)(lds + PG8_SA(b, h) + aoff + m * 2048 + k * 1024); } while (0)
; #define PG8_LDB(dst, b, h) do { _Pragma("unroll") for (int n = 0; n < 2; ++n) _Pragma("unroll") for (int k = 0; k < 2; ++k) dst[n][k] = *(const LAS bf16x8*)(lds + PG8_SB(b, h) + boff + n * 2048 + k * 1024); } while (0)
; #define PG8_MMA(ai, bj, At, Bt) do { __builtin_amdgcn_s_setprio(1); _Pragma("unroll") for (int m = 0; m < 4; ++m) _Pragma("unroll") for (int n = 0; n < 2; ++n) _Pragma("unroll") for (int k = 0; k < 2; ++k) \
;         acc[ai][bj][m][n] = __builtin_amdgcn_mfma_f32_16x16x32_bf16(Bt[n][k], At[m][k], acc[ai][bj][m][n], 0, 0, 0); __builtin_amdgcn_s_setprio(0); } while (0)
; #define PG8_WAIT_V(n) asm volatile("s_waitcnt vmcnt(" #n ")" ::: "memory")
; #define PG8_WAIT_L(n) asm volatile("s_waitcnt lgkmcnt(" #n ")" ::: "memory")
; #define PG8_BAR __builtin_amdgcn_s_barrier()
; #define PG8_SCHED __builtin_amdgcn_sched_barrier(0)
; template <class Epi, class Sched, bool ALIGN_EPI = false, bool SP2 = false>
; __device__ __forceinline__ void gemm_phase(LAS unsigned char* lds, const Gemm g, const Sched& S, const Epi& E) {
;     ...
;             PG8_WAIT_V(8); PG8_WAIT_L(0); PG8_BAR; PG8_MMA(1, 0, At, B0); PG8_MMA(1, 1, At, B1); PG8_BAR; PG8_SCHED;
;             PG8_LDB(B0, 1, 0); PG8_LDB(B1, 1, 1); PG8_SCHED; PG8_LDA(At, 1, 0); PG8_STAGE(PG8_SA(0, 1), a2 + hstep, voffA);
;             PG8_WAIT_V(8); PG8_WAIT_L(0); PG8_BAR; PG8_MMA(0, 0, At, B0); PG8_MMA(0, 1, At, B1); PG8_BAR; PG8_SCHED;
	s_waitcnt lgkmcnt(0)
	v_mfma_f32_16x16x32_bf16 v[62:65], v[66:69], v[192:195], 0
	v_mfma_f32_16x16x32_bf16 v[58:61], v[74:77], v[192:195], 0
	v_mfma_f32_16x16x32_bf16 v[46:49], v[66:69], v[200:203], 0
	v_mfma_f32_16x16x32_bf16 v[42:45], v[74:77], v[200:203], 0
	v_mfma_f32_16x16x32_bf16 v[30:33], v[66:69], v[208:211], 0
	v_mfma_f32_16x16x32_bf16 v[26:29], v[74:77], v[208:211], 0
	v_mfma_f32_16x16x32_bf16 v[14:17], v[66:69], v[216:219], 0
	v_mfma_f32_16x16x32_bf16 v[10:13], v[74:77], v[216:219], 0
	v_mfma_f32_16x16x32_bf16 v[62:65], v[70:73], v[196:199], v[62:65]
	v_mfma_f32_16x16x32_bf16 v[58:61], v[78:81], v[196:199], v[58:61]
	v_mfma_f32_16x16x32_bf16 v[46:49], v[70:73], v[204:207], v[46:49]
	v_mfma_f32_16x16x32_bf16 v[42:45], v[78:81], v[204:207], v[42:45]
	v_mfma_f32_16x16x32_bf16 v[30:33], v[70:73], v[212:215], v[30:33]
	v_mfma_f32_16x16x32_bf16 v[26:29], v[78:81], v[212:215], v[26:29]
	v_mfma_f32_16x16x32_bf16 v[14:17], v[70:73], v[220:223], v[14:17]
	v_mfma_f32_16x16x32_bf16 v[10:13], v[78:81], v[220:223], v[10:13]
	v_mfma_f32_16x16x32_bf16 v[54:57], v[162:165], v[192:195], 0
	v_mfma_f32_16x16x32_bf16 v[50:53], v[184:187], v[192:195], 0
	v_mfma_f32_16x16x32_bf16 v[38:41], v[162:165], v[200:203], 0
	v_mfma_f32_16x16x32_bf16 v[34:37], v[184:187], v[200:203], 0
	v_mfma_f32_16x16x32_bf16 v[22:25], v[162:165], v[208:211], 0
	v_mfma_f32_16x16x32_bf16 v[18:21], v[184:187], v[208:211], 0
	v_mfma_f32_16x16x32_bf16 v[6:9], v[162:165], v[216:219], 0
	v_mfma_f32_16x16x32_bf16 v[2:5], v[184:187], v[216:219], 0
	v_mfma_f32_16x16x32_bf16 v[54:57], v[180:183], v[196:199], v[54:57]
	v_mfma_f32_16x16x32_bf16 v[50:53], v[188:191], v[196:199], v[50:53]
	v_mfma_f32_16x16x32_bf16 v[38:41], v[180:183], v[204:207], v[38:41]
	v_mfma_f32_16x16x32_bf16 v[34:37], v[188:191], v[204:207], v[34:37]
	v_mfma_f32_16x16x32_bf16 v[22:25], v[180:183], v[212:215], v[22:25]
	v_mfma_f32_16x16x32_bf16 v[18:21], v[188:191], v[212:215], v[18:21]
	v_mfma_f32_16x16x32_bf16 v[6:9], v[180:183], v[220:223], v[6:9]
	v_mfma_f32_16x16x32_bf16 v[2:5], v[188:191], v[220:223], v[2:5]
	s_barrier
	s_add_i32 s51, 0, 0x18000
	s_add_i32 s52, 0, 0x1c000
	v_add_u32_e32 v78, s51, v169
	v_add_u32_e32 v168, s52, v169
	ds_read_b128 v[66:69], v78
	ds_read_b128 v[70:73], v78 offset:1024
	ds_read_b128 v[74:77], v78 offset:2048
	ds_read_b128 v[78:81], v78 offset:3072
	ds_read_b128 v[162:165], v168
	ds_read_b128 v[180:183], v168 offset:1024
	ds_read_b128 v[184:187], v168 offset:2048
	ds_read_b128 v[188:191], v168 offset:3072
	s_add_u32 s40, s40, 0x80000
	s_addc_u32 s41, s41, 0
	s_mov_b32 m0, s31
	v_lshl_add_u64 v[230:231], s[40:41], 0, v[152:153]
	ds_read_b128 v[192:195], v175 offset:32768
	ds_read_b128 v[196:199], v175 offset:33792
	ds_read_b128 v[200:203], v175 offset:34816
	ds_read_b128 v[204:207], v175 offset:35840
	ds_read_b128 v[208:211], v175 offset:36864
	ds_read_b128 v[212:215], v175 offset:37888
	ds_read_b128 v[216:219], v175 offset:38912
	ds_read_b128 v[220:223], v175 offset:39936
	global_load_lds_dwordx4 v[230:231], off
	v_lshl_add_u64 v[230:231], s[40:41], 0, v[148:149]
	s_mov_b32 m0, s33
	s_nop 0
	global_load_lds_dwordx4 v[230:231], off
	s_waitcnt vmcnt(8)
	s_waitcnt lgkmcnt(0)
	s_barrier
	s_waitcnt lgkmcnt(0)
	v_mfma_f32_16x16x32_bf16 v[142:145], v[66:69], v[192:195], v[142:145]
	v_mfma_f32_16x16x32_bf16 v[138:141], v[74:77], v[192:195], v[138:141]
	v_mfma_f32_16x16x32_bf16 v[126:129], v[66:69], v[200:203], v[126:129]
	v_mfma_f32_16x16x32_bf16 v[122:125], v[74:77], v[200:203], v[122:125]
	v_mfma_f32_16x16x32_bf16 v[110:113], v[66:69], v[208:211], v[110:113]
	v_mfma_f32_16x16x32_bf16 v[106:109], v[74:77], v[208:211], v[106:109]
	v_mfma_f32_16x16x32_bf16 v[94:97], v[66:69], v[216:219], v[94:97]
	v_mfma_f32_16x16x32_bf16 v[90:93], v[74:77], v[216:219], v[90:93]
	v_mfma_f32_16x16x32_bf16 v[142:145], v[70:73], v[196:199], v[142:145]
	v_mfma_f32_16x16x32_bf16 v[138:141], v[78:81], v[196:199], v[138:141]
	v_mfma_f32_16x16x32_bf16 v[126:129], v[70:73], v[204:207], v[126:129]
	v_mfma_f32_16x16x32_bf16 v[122:125], v[78:81], v[204:207], v[122:125]
	v_mfma_f32_16x16x32_bf16 v[110:113], v[70:73], v[212:215], v[110:113]
	v_mfma_f32_16x16x32_bf16 v[106:109], v[78:81], v[212:215], v[106:109]
	v_mfma_f32_16x16x32_bf16 v[94:97], v[70:73], v[220:223], v[94:97]
	v_mfma_f32_16x16x32_bf16 v[90:93], v[78:81], v[220:223], v[90:93]
	v_mfma_f32_16x16x32_bf16 v[134:137], v[162:165], v[192:195], v[134:137]
	v_mfma_f32_16x16x32_bf16 v[130:133], v[184:187], v[192:195], v[130:133]
	v_mfma_f32_16x16x32_bf16 v[118:121], v[162:165], v[200:203], v[118:121]
	v_mfma_f32_16x16x32_bf16 v[114:117], v[184:187], v[200:203], v[114:117]
	v_mfma_f32_16x16x32_bf16 v[102:105], v[162:165], v[208:211], v[102:105]
	v_mfma_f32_16x16x32_bf16 v[98:101], v[184:187], v[208:211], v[98:101]
	v_mfma_f32_16x16x32_bf16 v[86:89], v[162:165], v[216:219], v[86:89]
	v_mfma_f32_16x16x32_bf16 v[82:85], v[184:187], v[216:219], v[82:85]
	v_mfma_f32_16x16x32_bf16 v[134:137], v[180:183], v[196:199], v[134:137]
	v_mfma_f32_16x16x32_bf16 v[130:133], v[188:191], v[196:199], v[130:133]
	v_mfma_f32_16x16x32_bf16 v[118:121], v[180:183], v[204:207], v[118:121]
	v_mfma_f32_16x16x32_bf16 v[114:117], v[188:191], v[204:207], v[114:117]
	v_mfma_f32_16x16x32_bf16 v[102:105], v[180:183], v[212:215], v[102:105]
	v_mfma_f32_16x16x32_bf16 v[98:101], v[188:191], v[212:215], v[98:101]
	v_mfma_f32_16x16x32_bf16 v[86:89], v[180:183], v[220:223], v[86:89]
	v_mfma_f32_16x16x32_bf16 v[82:85], v[188:191], v[220:223], v[82:85]
	s_barrier
; #define PG8_STAGE(bufoff, gbase, voff) do { _Pragma("unroll") for (int _i = 0; _i < 2; ++_i) \
;         __builtin_amdgcn_global_load_lds((const unsigned*)((const char*)(gbase) + (voff)[_i]), (LAS unsigned*)(lds + (bufoff) + ldsw + _i * 8192), 16, 0, 0); } while (0)
; #define PG8_LDA(dst, b, h) do { _Pragma("unroll") for (int m = 0; m < 4; ++m) _Pragma("unroll") for (int k = 0; k < 2; ++k) dst[m][k] = *(const LAS bf16x8*)(lds + PG8_SA(b, h) + aoff + m * 2048 + k * 1024); } while (0)
; #define PG8_LDB(dst, b, h) do { _Pragma("unroll") for (int n = 0; n < 2; ++n) _Pragma("unroll") for (int k = 0; k < 2; ++k) dst[n][k] = *(const LAS bf16x8*)(lds + PG8_SB(b, h) + boff + n * 2048 + k * 1024); } while (0)
; #define PG8_MMA(ai, bj, At, Bt) do { __builtin_amdgcn_s_setprio(1); _Pragma("unroll") for (int m = 0; m < 4; ++m) _Pragma("unroll") for (int n = 0; n < 2; ++n) _Pragma("unroll") for (int k = 0; k < 2; ++k) \
;         acc[ai][bj][m][n] = __builtin_amdgcn_mfma_f32_16x16x32_bf16(Bt[n][k], At[m][k], acc[ai][bj][m][n], 0, 0, 0); __builtin_amdgcn_s_setprio(0); } while (0)
; #define PG8_WAIT_V(n) asm volatile("s_waitcnt vmcnt(" #n ")" ::: "memory")
; #define PG8_WAIT_L(n) asm volatile("s_waitcnt lgkmcnt(" #n ")" ::: "memory")
; #define PG8_BAR __builtin_amdgcn_s_barrier()
; #define PG8_SCHED __builtin_amdgcn_sched_barrier(0)
; template <class Epi, class Sched, bool ALIGN_EPI = false, bool SP2 = false>
; __device__ __forceinline__ void gemm_phase(LAS unsigned char* lds, const Gemm g, const Sched& S, const Epi& E) {
;     ...
;         for (int t = 0; t < nt; t += 2) {
;             const bool last = (t == nt - 2);
;             const char* a1 = cA + (size_t)(t + 1) * kstep;
;             const char* a2 = last ? nA : cA + (size_t)(t + 2) * kstep; const char* b2 = last ? nB : cB + (size_t)(t + 2) * kstep;
;             const char* a3 = a2 + kstep; const char* b3 = b2 + kstep;
;             if (last && has_next) S.a_ready(nxt);
;             if constexpr (SP2) {
;             PG8_LDB(B0, 0, 0); PG8_LDB(B1, 0, 1); PG8_SCHED; PG8_LDA(At, 0, 0); PG8_STAGE(PG8_SA(1, 1), a1 + hstep, voffA);
;     ...
;             PG8_LDA(At, 1, 1); PG8_STAGE(PG8_SB(1, 0), b3, voffB); PG8_STAGE(PG8_SB(1, 1), b3 + hstepB, voffB); PG8_STAGE(PG8_SA(1, 0), a3, voffA);
;             PG8_WAIT_V(8); PG8_WAIT_L(0); PG8_BAR; PG8_MMA(1, 0, At, B0); PG8_MMA(1, 1, At, B1); PG8_BAR; PG8_SCHED;
	s_add_i32 s40, s51, s26
	v_lshl_add_u64 v[166:167], v[166:167], 0, s[8:9]
	s_mov_b32 m0, s40
	ds_read_b128 v[192:195], v175 offset:49152
	ds_read_b128 v[196:199], v175 offset:50176
	ds_read_b128 v[200:203], v175 offset:51200
	ds_read_b128 v[204:207], v175 offset:52224
	ds_read_b128 v[208:211], v175 offset:53248
	ds_read_b128 v[212:215], v175 offset:54272
	ds_read_b128 v[216:219], v175 offset:55296
	ds_read_b128 v[220:223], v175 offset:56320
	global_load_lds_dwordx4 v[166:167], off
	s_add_i32 m0, s40, 0x2000
	s_add_u32 s22, s22, 0x80080
	v_lshl_add_u64 v[166:167], v[224:225], 0, s[8:9]
	s_addc_u32 s23, s23, 0
	s_add_i32 s40, s52, s26
	global_load_lds_dwordx4 v[166:167], off
	v_lshl_add_u64 v[166:167], s[22:23], 0, v[150:151]
	s_mov_b32 m0, s40
	s_nop 0
	global_load_lds_dwordx4 v[166:167], off
	v_lshl_add_u64 v[166:167], s[22:23], 0, v[146:147]
	s_add_i32 m0, s40, 0x2000
	s_nop 0
	global_load_lds_dwordx4 v[166:167], off
	v_lshl_add_u64 v[166:167], v[226:227], 0, s[8:9]
	s_mov_b32 m0, s42
	s_nop 0
	global_load_lds_dwordx4 v[166:167], off
	v_lshl_add_u64 v[166:167], v[228:229], 0, s[8:9]
	s_mov_b32 m0, s43
	s_nop 0
	global_load_lds_dwordx4 v[166:167], off
	s_waitcnt vmcnt(8)
	s_waitcnt lgkmcnt(0)
	s_barrier
	s_waitcnt lgkmcnt(0)
	v_mfma_f32_16x16x32_bf16 v[62:65], v[66:69], v[192:195], v[62:65]
	v_mfma_f32_16x16x32_bf16 v[58:61], v[74:77], v[192:195], v[58:61]
	v_mfma_f32_16x16x32_bf16 v[46:49], v[66:69], v[200:203], v[46:49]
	v_mfma_f32_16x16x32_bf16 v[42:45], v[74:77], v[200:203], v[42:45]
	v_mfma_f32_16x16x32_bf16 v[30:33], v[66:69], v[208:211], v[30:33]
	v_mfma_f32_16x16x32_bf16 v[26:29], v[74:77], v[208:211], v[26:29]
	v_mfma_f32_16x16x32_bf16 v[14:17], v[66:69], v[216:219], v[14:17]
	v_mfma_f32_16x16x32_bf16 v[10:13], v[74:77], v[216:219], v[10:13]
	v_mfma_f32_16x16x32_bf16 v[62:65], v[70:73], v[196:199], v[62:65]
	v_mfma_f32_16x16x32_bf16 v[58:61], v[78:81], v[196:199], v[58:61]
	v_mfma_f32_16x16x32_bf16 v[46:49], v[70:73], v[204:207], v[46:49]
	v_mfma_f32_16x16x32_bf16 v[42:45], v[78:81], v[204:207], v[42:45]
	v_mfma_f32_16x16x32_bf16 v[30:33], v[70:73], v[212:215], v[30:33]
	v_mfma_f32_16x16x32_bf16 v[26:29], v[78:81], v[212:215], v[26:29]
	v_mfma_f32_16x16x32_bf16 v[14:17], v[70:73], v[220:223], v[14:17]
	v_mfma_f32_16x16x32_bf16 v[10:13], v[78:81], v[220:223], v[10:13]
	v_mfma_f32_16x16x32_bf16 v[54:57], v[162:165], v[192:195], v[54:57]
	v_mfma_f32_16x16x32_bf16 v[50:53], v[184:187], v[192:195], v[50:53]
	v_mfma_f32_16x16x32_bf16 v[38:41], v[162:165], v[200:203], v[38:41]
	v_mfma_f32_16x16x32_bf16 v[34:37], v[184:187], v[200:203], v[34:37]
	v_mfma_f32_16x16x32_bf16 v[22:25], v[162:165], v[208:211], v[22:25]
	v_mfma_f32_16x16x32_bf16 v[18:21], v[184:187], v[208:211], v[18:21]
	v_mfma_f32_16x16x32_bf16 v[6:9], v[162:165], v[216:219], v[6:9]
	v_mfma_f32_16x16x32_bf16 v[2:5], v[184:187], v[216:219], v[2:5]
	v_mfma_f32_16x16x32_bf16 v[54:57], v[180:183], v[196:199], v[54:57]
	v_mfma_f32_16x16x32_bf16 v[50:53], v[188:191], v[196:199], v[50:53]
	v_mfma_f32_16x16x32_bf16 v[38:41], v[180:183], v[204:207], v[38:41]
	v_mfma_f32_16x16x32_bf16 v[34:37], v[188:191], v[204:207], v[34:37]
	v_mfma_f32_16x16x32_bf16 v[22:25], v[180:183], v[212:215], v[22:25]
	v_mfma_f32_16x16x32_bf16 v[18:21], v[188:191], v[212:215], v[18:21]
	v_mfma_f32_16x16x32_bf16 v[6:9], v[180:183], v[220:223], v[6:9]
	v_mfma_f32_16x16x32_bf16 v[2:5], v[188:191], v[220:223], v[2:5]
	s_barrier
	s_add_i32 s50, s50, 2
	s_add_u32 s25, s25, 0x100
	s_addc_u32 s49, s49, 0
	s_add_u32 s16, s16, 0x100
	s_addc_u32 s17, s17, 0
	s_cmp_lt_u32 s50, 30
.LBB0_1822:
	ds_read_b128 v[66:69], v173
	ds_read_b128 v[70:73], v173 offset:1024
	ds_read_b128 v[74:77], v173 offset:2048
	ds_read_b128 v[78:81], v173 offset:3072
	ds_read_b128 v[162:165], v174
	ds_read_b128 v[180:183], v174 offset:1024
	ds_read_b128 v[184:187], v174 offset:2048
	ds_read_b128 v[188:191], v174 offset:3072
	s_add_u32 s22, s16, 0xfff80080
	s_addc_u32 s23, s17, -1
	s_cmp_eq_u32 s50, 28
	s_cselect_b32 s41, s3, s23
	s_cselect_b32 s40, s15, s22
	s_cselect_b32 s23, s13, s49
	s_cselect_b32 s22, s24, s25
	v_lshl_add_u64 v[166:167], s[16:17], 0, v[156:157]
	s_add_i32 m0, s29, 0xc000
	ds_read_b128 v[192:195], v175
	ds_read_b128 v[196:199], v175 offset:1024
	ds_read_b128 v[200:203], v175 offset:2048
	ds_read_b128 v[204:207], v175 offset:3072
	ds_read_b128 v[208:211], v175 offset:4096
	ds_read_b128 v[212:215], v175 offset:5120
	ds_read_b128 v[216:219], v175 offset:6144
	ds_read_b128 v[220:223], v175 offset:7168
	global_load_lds_dwordx4 v[166:167], off
	v_lshl_add_u64 v[166:167], s[16:17], 0, v[154:155]
	s_add_i32 m0, s29, 0xe000
	s_nop 0
	global_load_lds_dwordx4 v[166:167], off
	s_waitcnt vmcnt(8)
	s_waitcnt lgkmcnt(0)
	s_barrier
; #define PG8_STAGE(bufoff, gbase, voff) do { _Pragma("unroll") for (int _i = 0; _i < 2; ++_i) \
;         __builtin_amdgcn_global_load_lds((const unsigned*)((const char*)(gbase) + (voff)[_i]), (LAS unsigned*)(lds + (bufoff) + ldsw + _i * 8192), 16, 0, 0); } while (0)
; #define PG8_LDA(dst, b, h) do { _Pragma("unroll") for (int m = 0; m < 4; ++m) _Pragma("unroll") for (int k = 0; k < 2; ++k) dst[m][k] = *(const LAS bf16x8*)(lds + PG8_SA(b, h) + aoff + m * 2048 + k * 1024); } while (0)
; #define PG8_LDB(dst, b, h) do { _Pragma("unroll") for (int n = 0; n < 2; ++n) _Pragma("unroll") for (int k = 0; k < 2; ++k) dst[n][k] = *(const LAS bf16x8*)(lds + PG8_SB(b, h) + boff + n * 2048 + k * 1024); } while (0)
; #define PG8_MMA(ai, bj, At, Bt) do { __builtin_amdgcn_s_setprio(1); _Pragma("unroll") for (int m = 0; m < 4; ++m) _Pragma("unroll") for (int n = 0; n < 2; ++n) _Pragma("unroll") for (int k = 0; k < 2; ++k) \
;         acc[ai][bj][m][n] = __builtin_amdgcn_mfma_f32_16x16x32_bf16(Bt[n][k], At[m][k], acc[ai][bj][m][n], 0, 0, 0); __builtin_amdgcn_s_setprio(0); } while (0)
; #define PG8_WAIT_V(n) asm volatile("s_waitcnt vmcnt(" #n ")" ::: "memory")
; #define PG8_WAIT_L(n) asm volatile("s_waitcnt lgkmcnt(" #n ")" ::: "memory")
; #define PG8_BAR __builtin_amdgcn_s_barrier()
; #define PG8_SCHED __builtin_amdgcn_sched_barrier(0)
; template <class Epi, class Sched, bool ALIGN_EPI = false, bool SP2 = false>
; __device__ __forceinline__ void gemm_phase(LAS unsigned char* lds, const Gemm g, const Sched& S, const Epi& E) {
;     ...
;             PG8_WAIT_V(8); PG8_WAIT_L(0); PG8_BAR; PG8_MMA(0, 0, At, B0); PG8_MMA(0, 1, At, B1); PG8_BAR; PG8_SCHED;
;             PG8_LDA(At, 0, 1); PG8_STAGE(PG8_SB(0, 0), b2, voffB); PG8_STAGE(PG8_SB(0, 1), b2 + hstepB, voffB); PG8_STAGE(PG8_SA(0, 0), a2, voffA);
;             PG8_WAIT_V(8); PG8_WAIT_L(0); PG8_BAR; PG8_MMA(1, 0, At, B0); PG8_MMA(1, 1, At, B1); PG8_BAR; PG8_SCHED;
;             PG8_LDB(B0, 1, 0); PG8_LDB(B1, 1, 1); PG8_SCHED; PG8_LDA(At, 1, 0); PG8_STAGE(PG8_SA(0, 1), a2 + hstep, voffA);
;             PG8_WAIT_V(8); PG8_WAIT_L(0); PG8_BAR; PG8_MMA(0, 0, At, B0); PG8_MMA(0, 1, At, B1); PG8_BAR; PG8_SCHED;
	s_waitcnt lgkmcnt(0)
	v_mfma_f32_16x16x32_bf16 v[142:145], v[66:69], v[192:195], v[142:145]
	v_mfma_f32_16x16x32_bf16 v[138:141], v[74:77], v[192:195], v[138:141]
	v_mfma_f32_16x16x32_bf16 v[126:129], v[66:69], v[200:203], v[126:129]
	v_mfma_f32_16x16x32_bf16 v[122:125], v[74:77], v[200:203], v[122:125]
	v_mfma_f32_16x16x32_bf16 v[110:113], v[66:69], v[208:211], v[110:113]
	v_mfma_f32_16x16x32_bf16 v[106:109], v[74:77], v[208:211], v[106:109]
	v_mfma_f32_16x16x32_bf16 v[94:97], v[66:69], v[216:219], v[94:97]
	v_mfma_f32_16x16x32_bf16 v[90:93], v[74:77], v[216:219], v[90:93]
	v_mfma_f32_16x16x32_bf16 v[142:145], v[70:73], v[196:199], v[142:145]
	v_mfma_f32_16x16x32_bf16 v[138:141], v[78:81], v[196:199], v[138:141]
	v_mfma_f32_16x16x32_bf16 v[126:129], v[70:73], v[204:207], v[126:129]
	v_mfma_f32_16x16x32_bf16 v[122:125], v[78:81], v[204:207], v[122:125]
	v_mfma_f32_16x16x32_bf16 v[110:113], v[70:73], v[212:215], v[110:113]
	v_mfma_f32_16x16x32_bf16 v[106:109], v[78:81], v[212:215], v[106:109]
	v_mfma_f32_16x16x32_bf16 v[94:97], v[70:73], v[220:223], v[94:97]
	v_mfma_f32_16x16x32_bf16 v[90:93], v[78:81], v[220:223], v[90:93]
	v_mfma_f32_16x16x32_bf16 v[134:137], v[162:165], v[192:195], v[134:137]
	v_mfma_f32_16x16x32_bf16 v[130:133], v[184:187], v[192:195], v[130:133]
	v_mfma_f32_16x16x32_bf16 v[118:121], v[162:165], v[200:203], v[118:121]
	v_mfma_f32_16x16x32_bf16 v[114:117], v[184:187], v[200:203], v[114:117]
	v_mfma_f32_16x16x32_bf16 v[102:105], v[162:165], v[208:211], v[102:105]
	v_mfma_f32_16x16x32_bf16 v[98:101], v[184:187], v[208:211], v[98:101]
	v_mfma_f32_16x16x32_bf16 v[86:89], v[162:165], v[216:219], v[86:89]
	v_mfma_f32_16x16x32_bf16 v[82:85], v[184:187], v[216:219], v[82:85]
	v_mfma_f32_16x16x32_bf16 v[134:137], v[180:183], v[196:199], v[134:137]
	v_mfma_f32_16x16x32_bf16 v[130:133], v[188:191], v[196:199], v[130:133]
	v_mfma_f32_16x16x32_bf16 v[118:121], v[180:183], v[204:207], v[118:121]
	v_mfma_f32_16x16x32_bf16 v[114:117], v[188:191], v[204:207], v[114:117]
	v_mfma_f32_16x16x32_bf16 v[102:105], v[180:183], v[212:215], v[102:105]
	v_mfma_f32_16x16x32_bf16 v[98:101], v[188:191], v[212:215], v[98:101]
	v_mfma_f32_16x16x32_bf16 v[86:89], v[180:183], v[220:223], v[86:89]
	v_mfma_f32_16x16x32_bf16 v[82:85], v[188:191], v[220:223], v[82:85]
	s_barrier
	s_add_i32 s51, s44, s26
	v_lshl_add_u64 v[166:167], s[22:23], 0, v[150:151]
	s_mov_b32 m0, s51
	ds_read_b128 v[192:195], v175 offset:16384
	ds_read_b128 v[196:199], v175 offset:17408
	ds_read_b128 v[200:203], v175 offset:18432
	ds_read_b128 v[204:207], v175 offset:19456
	ds_read_b128 v[208:211], v175 offset:20480
	ds_read_b128 v[212:215], v175 offset:21504
	ds_read_b128 v[216:219], v175 offset:22528
	ds_read_b128 v[220:223], v175 offset:23552
	global_load_lds_dwordx4 v[166:167], off
	s_add_i32 m0, s51, 0x2000
	s_add_u32 s52, s22, 0x80000
	v_lshl_add_u64 v[224:225], s[22:23], 0, v[146:147]
	s_addc_u32 s53, s23, 0
	s_add_i32 s51, s45, s26
	global_load_lds_dwordx4 v[224:225], off
	v_lshl_add_u64 v[226:227], s[52:53], 0, v[150:151]
	s_mov_b32 m0, s51
	v_lshl_add_u64 v[228:229], s[40:41], 0, v[148:149]
	global_load_lds_dwordx4 v[226:227], off
	v_lshl_add_u64 v[226:227], s[52:53], 0, v[146:147]
	s_add_i32 m0, s51, 0x2000
	s_nop 0
	global_load_lds_dwordx4 v[226:227], off
	v_lshl_add_u64 v[226:227], s[40:41], 0, v[152:153]
	s_mov_b32 m0, s29
	s_nop 0
	global_load_lds_dwordx4 v[226:227], off
	s_mov_b32 m0, s30
	s_nop 0
	global_load_lds_dwordx4 v[228:229], off
	s_waitcnt vmcnt(8)
	s_waitcnt lgkmcnt(0)
	s_barrier
	s_waitcnt lgkmcnt(0)
	v_mfma_f32_16x16x32_bf16 v[62:65], v[66:69], v[192:195], v[62:65]
	v_mfma_f32_16x16x32_bf16 v[58:61], v[74:77], v[192:195], v[58:61]
	v_mfma_f32_16x16x32_bf16 v[46:49], v[66:69], v[200:203], v[46:49]
	v_mfma_f32_16x16x32_bf16 v[42:45], v[74:77], v[200:203], v[42:45]
	v_mfma_f32_16x16x32_bf16 v[30:33], v[66:69], v[208:211], v[30:33]
	v_mfma_f32_16x16x32_bf16 v[26:29], v[74:77], v[208:211], v[26:29]
	v_mfma_f32_16x16x32_bf16 v[14:17], v[66:69], v[216:219], v[14:17]
	v_mfma_f32_16x16x32_bf16 v[10:13], v[74:77], v[216:219], v[10:13]
	v_mfma_f32_16x16x32_bf16 v[62:65], v[70:73], v[196:199], v[62:65]
	v_mfma_f32_16x16x32_bf16 v[58:61], v[78:81], v[196:199], v[58:61]
	v_mfma_f32_16x16x32_bf16 v[46:49], v[70:73], v[204:207], v[46:49]
	v_mfma_f32_16x16x32_bf16 v[42:45], v[78:81], v[204:207], v[42:45]
	v_mfma_f32_16x16x32_bf16 v[30:33], v[70:73], v[212:215], v[30:33]
	v_mfma_f32_16x16x32_bf16 v[26:29], v[78:81], v[212:215], v[26:29]
	v_mfma_f32_16x16x32_bf16 v[14:17], v[70:73], v[220:223], v[14:17]
	v_mfma_f32_16x16x32_bf16 v[10:13], v[78:81], v[220:223], v[10:13]
	v_mfma_f32_16x16x32_bf16 v[54:57], v[162:165], v[192:195], v[54:57]
	v_mfma_f32_16x16x32_bf16 v[50:53], v[184:187], v[192:195], v[50:53]
	v_mfma_f32_16x16x32_bf16 v[38:41], v[162:165], v[200:203], v[38:41]
	v_mfma_f32_16x16x32_bf16 v[34:37], v[184:187], v[200:203], v[34:37]
	v_mfma_f32_16x16x32_bf16 v[22:25], v[162:165], v[208:211], v[22:25]
	v_mfma_f32_16x16x32_bf16 v[18:21], v[184:187], v[208:211], v[18:21]
	v_mfma_f32_16x16x32_bf16 v[6:9], v[162:165], v[216:219], v[6:9]
	v_mfma_f32_16x16x32_bf16 v[2:5], v[184:187], v[216:219], v[2:5]
	v_mfma_f32_16x16x32_bf16 v[54:57], v[180:183], v[196:199], v[54:57]
	v_mfma_f32_16x16x32_bf16 v[50:53], v[188:191], v[196:199], v[50:53]
	v_mfma_f32_16x16x32_bf16 v[38:41], v[180:183], v[204:207], v[38:41]
	v_mfma_f32_16x16x32_bf16 v[34:37], v[188:191], v[204:207], v[34:37]
	v_mfma_f32_16x16x32_bf16 v[22:25], v[180:183], v[212:215], v[22:25]
	v_mfma_f32_16x16x32_bf16 v[18:21], v[188:191], v[212:215], v[18:21]
	v_mfma_f32_16x16x32_bf16 v[6:9], v[180:183], v[220:223], v[6:9]
	v_mfma_f32_16x16x32_bf16 v[2:5], v[188:191], v[220:223], v[2:5]
	s_barrier
; #define PG8_STAGE(bufoff, gbase, voff) do { _Pragma("unroll") for (int _i = 0; _i < 2; ++_i) \
;         __builtin_amdgcn_global_load_lds((const unsigned*)((const char*)(gbase) + (voff)[_i]), (LAS unsigned*)(lds + (bufoff) + ldsw + _i * 8192), 16, 0, 0); } while (0)
; #define PG8_LDA(dst, b, h) do { _Pragma("unroll") for (int m = 0; m < 4; ++m) _Pragma("unroll") for (int k = 0; k < 2; ++k) dst[m][k] = *(const LAS bf16x8*)(lds + PG8_SA(b, h) + aoff + m * 2048 + k * 1024); } while (0)
; #define PG8_LDB(dst, b, h) do { _Pragma("unroll") for (int n = 0; n < 2; ++n) _Pragma("unroll") for (int k = 0; k < 2; ++k) dst[n][k] = *(const LAS bf16x8*)(lds + PG8_SB(b, h) + boff + n * 2048 + k * 1024); } while (0)
; #define PG8_MMA(ai, bj, At, Bt) do { __builtin_amdgcn_s_setprio(1); _Pragma("unroll") for (int m = 0; m < 4; ++m) _Pragma("unroll") for (int n = 0; n < 2; ++n) _Pragma("unroll") for (int k = 0; k < 2; ++k) \
;         acc[ai][bj][m][n] = __builtin_amdgcn_mfma_f32_16x16x32_bf16(Bt[n][k], At[m][k], acc[ai][bj][m][n], 0, 0, 0); __builtin_amdgcn_s_setprio(0); } while (0)
; #define PG8_WAIT_V(n) asm volatile("s_waitcnt vmcnt(" #n ")" ::: "memory")
; #define PG8_WAIT_L(n) asm volatile("s_waitcnt lgkmcnt(" #n ")" ::: "memory")
; #define PG8_BAR __builtin_amdgcn_s_barrier()
; #define PG8_SCHED __builtin_amdgcn_sched_barrier(0)
; template <class Epi, class Sched, bool ALIGN_EPI = false, bool SP2 = false>
; __device__ __forceinline__ void gemm_phase(LAS unsigned char* lds, const Gemm g, const Sched& S, const Epi& E) {
;     ...
;             PG8_LDB(B0, 1, 0); PG8_LDB(B1, 1, 1); PG8_SCHED; PG8_LDA(At, 1, 0); PG8_STAGE(PG8_SA(0, 1), a2 + hstep, voffA);
;             PG8_WAIT_V(8); PG8_WAIT_L(0); PG8_BAR; PG8_MMA(0, 0, At, B0); PG8_MMA(0, 1, At, B1); PG8_BAR; PG8_SCHED;
	s_add_i32 s51, 0, 0x18000
	s_add_i32 s52, 0, 0x1c000
	v_add_u32_e32 v78, s51, v169
	v_add_u32_e32 v168, s52, v169
	ds_read_b128 v[66:69], v78
	ds_read_b128 v[70:73], v78 offset:1024
	ds_read_b128 v[74:77], v78 offset:2048
	ds_read_b128 v[78:81], v78 offset:3072
	ds_read_b128 v[162:165], v168
	ds_read_b128 v[180:183], v168 offset:1024
	ds_read_b128 v[184:187], v168 offset:2048
	ds_read_b128 v[188:191], v168 offset:3072
	s_add_u32 s40, s40, 0x80000
	s_addc_u32 s41, s41, 0
	s_mov_b32 m0, s31
	v_lshl_add_u64 v[230:231], s[40:41], 0, v[152:153]
	ds_read_b128 v[192:195], v175 offset:32768
	ds_read_b128 v[196:199], v175 offset:33792
	ds_read_b128 v[200:203], v175 offset:34816
	ds_read_b128 v[204:207], v175 offset:35840
	ds_read_b128 v[208:211], v175 offset:36864
	ds_read_b128 v[212:215], v175 offset:37888
	ds_read_b128 v[216:219], v175 offset:38912
	ds_read_b128 v[220:223], v175 offset:39936
	global_load_lds_dwordx4 v[230:231], off
	v_lshl_add_u64 v[230:231], s[40:41], 0, v[148:149]
	s_mov_b32 m0, s33
	s_nop 0
	global_load_lds_dwordx4 v[230:231], off
	s_waitcnt vmcnt(8)
	s_waitcnt lgkmcnt(0)
	s_barrier
	s_waitcnt lgkmcnt(0)
	v_mfma_f32_16x16x32_bf16 v[142:145], v[66:69], v[192:195], v[142:145]
	v_mfma_f32_16x16x32_bf16 v[138:141], v[74:77], v[192:195], v[138:141]
	v_mfma_f32_16x16x32_bf16 v[126:129], v[66:69], v[200:203], v[126:129]
	v_mfma_f32_16x16x32_bf16 v[122:125], v[74:77], v[200:203], v[122:125]
	v_mfma_f32_16x16x32_bf16 v[110:113], v[66:69], v[208:211], v[110:113]
	v_mfma_f32_16x16x32_bf16 v[106:109], v[74:77], v[208:211], v[106:109]
	v_mfma_f32_16x16x32_bf16 v[94:97], v[66:69], v[216:219], v[94:97]
	v_mfma_f32_16x16x32_bf16 v[90:93], v[74:77], v[216:219], v[90:93]
	v_mfma_f32_16x16x32_bf16 v[142:145], v[70:73], v[196:199], v[142:145]
	v_mfma_f32_16x16x32_bf16 v[138:141], v[78:81], v[196:199], v[138:141]
	v_mfma_f32_16x16x32_bf16 v[126:129], v[70:73], v[204:207], v[126:129]
	v_mfma_f32_16x16x32_bf16 v[122:125], v[78:81], v[204:207], v[122:125]
	v_mfma_f32_16x16x32_bf16 v[110:113], v[70:73], v[212:215], v[110:113]
	v_mfma_f32_16x16x32_bf16 v[106:109], v[78:81], v[212:215], v[106:109]
	v_mfma_f32_16x16x32_bf16 v[94:97], v[70:73], v[220:223], v[94:97]
	v_mfma_f32_16x16x32_bf16 v[90:93], v[78:81], v[220:223], v[90:93]
	v_mfma_f32_16x16x32_bf16 v[134:137], v[162:165], v[192:195], v[134:137]
	v_mfma_f32_16x16x32_bf16 v[130:133], v[184:187], v[192:195], v[130:133]
	v_mfma_f32_16x16x32_bf16 v[118:121], v[162:165], v[200:203], v[118:121]
	v_mfma_f32_16x16x32_bf16 v[114:117], v[184:187], v[200:203], v[114:117]
	v_mfma_f32_16x16x32_bf16 v[102:105], v[162:165], v[208:211], v[102:105]
	v_mfma_f32_16x16x32_bf16 v[98:101], v[184:187], v[208:211], v[98:101]
	v_mfma_f32_16x16x32_bf16 v[86:89], v[162:165], v[216:219], v[86:89]
	v_mfma_f32_16x16x32_bf16 v[82:85], v[184:187], v[216:219], v[82:85]
	v_mfma_f32_16x16x32_bf16 v[134:137], v[180:183], v[196:199], v[134:137]
	v_mfma_f32_16x16x32_bf16 v[130:133], v[188:191], v[196:199], v[130:133]
	v_mfma_f32_16x16x32_bf16 v[118:121], v[180:183], v[204:207], v[118:121]
	v_mfma_f32_16x16x32_bf16 v[114:117], v[188:191], v[204:207], v[114:117]
	v_mfma_f32_16x16x32_bf16 v[102:105], v[180:183], v[212:215], v[102:105]
	v_mfma_f32_16x16x32_bf16 v[98:101], v[188:191], v[212:215], v[98:101]
	v_mfma_f32_16x16x32_bf16 v[86:89], v[180:183], v[220:223], v[86:89]
	v_mfma_f32_16x16x32_bf16 v[82:85], v[188:191], v[220:223], v[82:85]
	s_barrier
; #define PG8_STAGE(bufoff, gbase, voff) do { _Pragma("unroll") for (int _i = 0; _i < 2; ++_i) \
;         __builtin_amdgcn_global_load_lds((const unsigned*)((const char*)(gbase) + (voff)[_i]), (LAS unsigned*)(lds + (bufoff) + ldsw + _i * 8192), 16, 0, 0); } while (0)
; #define PG8_LDA(dst, b, h) do { _Pragma("unroll") for (int m = 0; m < 4; ++m) _Pragma("unroll") for (int k = 0; k < 2; ++k) dst[m][k] = *(const LAS bf16x8*)(lds + PG8_SA(b, h) + aoff + m * 2048 + k * 1024); } while (0)
; #define PG8_MMA(ai, bj, At, Bt) do { __builtin_amdgcn_s_setprio(1); _Pragma("unroll") for (int m = 0; m < 4; ++m) _Pragma("unroll") for (int n = 0; n < 2; ++n) _Pragma("unroll") for (int k = 0; k < 2; ++k) \
;         acc[ai][bj][m][n] = __builtin_amdgcn_mfma_f32_16x16x32_bf16(Bt[n][k], At[m][k], acc[ai][bj][m][n], 0, 0, 0); __builtin_amdgcn_s_setprio(0); } while (0)
; #define PG8_WAIT_V(n) asm volatile("s_waitcnt vmcnt(" #n ")" ::: "memory")
; #define PG8_WAIT_L(n) asm volatile("s_waitcnt lgkmcnt(" #n ")" ::: "memory")
; #define PG8_BAR __builtin_amdgcn_s_barrier()
; #define PG8_SCHED __builtin_amdgcn_sched_barrier(0)
; template <class Epi, class Sched, bool ALIGN_EPI = false, bool SP2 = false>
; __device__ __forceinline__ void gemm_phase(LAS unsigned char* lds, const Gemm g, const Sched& S, const Epi& E) {
;     ...
;             PG8_LDA(At, 1, 1); PG8_STAGE(PG8_SB(1, 0), b3, voffB); PG8_STAGE(PG8_SB(1, 1), b3 + hstepB, voffB); PG8_STAGE(PG8_SA(1, 0), a3, voffA);
;             PG8_WAIT_V(8); PG8_WAIT_L(0); PG8_BAR; PG8_MMA(1, 0, At, B0); PG8_MMA(1, 1, At, B1); PG8_BAR; PG8_SCHED;
;     ...
;         if constexpr (ALIGN_EPI) { if (wr == 0) PG8_BAR; }
	s_add_i32 s40, s51, s26
	v_lshl_add_u64 v[166:167], v[166:167], 0, s[8:9]
	s_mov_b32 m0, s40
	ds_read_b128 v[192:195], v175 offset:49152
	ds_read_b128 v[196:199], v175 offset:50176
	ds_read_b128 v[200:203], v175 offset:51200
	ds_read_b128 v[204:207], v175 offset:52224
	ds_read_b128 v[208:211], v175 offset:53248
	ds_read_b128 v[212:215], v175 offset:54272
	ds_read_b128 v[216:219], v175 offset:55296
	ds_read_b128 v[220:223], v175 offset:56320
	global_load_lds_dwordx4 v[166:167], off
	s_add_i32 m0, s40, 0x2000
	s_add_u32 s22, s22, 0x80080
	v_lshl_add_u64 v[166:167], v[224:225], 0, s[8:9]
	s_addc_u32 s23, s23, 0
	s_add_i32 s40, s52, s26
	global_load_lds_dwordx4 v[166:167], off
	v_lshl_add_u64 v[166:167], s[22:23], 0, v[150:151]
	s_mov_b32 m0, s40
	s_nop 0
	global_load_lds_dwordx4 v[166:167], off
	v_lshl_add_u64 v[166:167], s[22:23], 0, v[146:147]
	s_add_i32 m0, s40, 0x2000
	s_nop 0
	global_load_lds_dwordx4 v[166:167], off
	v_lshl_add_u64 v[166:167], v[226:227], 0, s[8:9]
	s_mov_b32 m0, s42
	s_nop 0
	global_load_lds_dwordx4 v[166:167], off
	v_lshl_add_u64 v[166:167], v[228:229], 0, s[8:9]
	s_mov_b32 m0, s43
	s_nop 0
	global_load_lds_dwordx4 v[166:167], off
	s_waitcnt vmcnt(8)
	s_waitcnt lgkmcnt(0)
	s_barrier
	s_waitcnt lgkmcnt(0)
	v_mfma_f32_16x16x32_bf16 v[62:65], v[66:69], v[192:195], v[62:65]
	v_mfma_f32_16x16x32_bf16 v[58:61], v[74:77], v[192:195], v[58:61]
	v_mfma_f32_16x16x32_bf16 v[46:49], v[66:69], v[200:203], v[46:49]
	v_mfma_f32_16x16x32_bf16 v[42:45], v[74:77], v[200:203], v[42:45]
	v_mfma_f32_16x16x32_bf16 v[30:33], v[66:69], v[208:211], v[30:33]
	v_mfma_f32_16x16x32_bf16 v[26:29], v[74:77], v[208:211], v[26:29]
	v_mfma_f32_16x16x32_bf16 v[14:17], v[66:69], v[216:219], v[14:17]
	v_mfma_f32_16x16x32_bf16 v[10:13], v[74:77], v[216:219], v[10:13]
	v_mfma_f32_16x16x32_bf16 v[62:65], v[70:73], v[196:199], v[62:65]
	v_mfma_f32_16x16x32_bf16 v[58:61], v[78:81], v[196:199], v[58:61]
	v_mfma_f32_16x16x32_bf16 v[46:49], v[70:73], v[204:207], v[46:49]
	v_mfma_f32_16x16x32_bf16 v[42:45], v[78:81], v[204:207], v[42:45]
	v_mfma_f32_16x16x32_bf16 v[30:33], v[70:73], v[212:215], v[30:33]
	v_mfma_f32_16x16x32_bf16 v[26:29], v[78:81], v[212:215], v[26:29]
	v_mfma_f32_16x16x32_bf16 v[14:17], v[70:73], v[220:223], v[14:17]
	v_mfma_f32_16x16x32_bf16 v[10:13], v[78:81], v[220:223], v[10:13]
	v_mfma_f32_16x16x32_bf16 v[54:57], v[162:165], v[192:195], v[54:57]
	v_mfma_f32_16x16x32_bf16 v[50:53], v[184:187], v[192:195], v[50:53]
	v_mfma_f32_16x16x32_bf16 v[38:41], v[162:165], v[200:203], v[38:41]
	v_mfma_f32_16x16x32_bf16 v[34:37], v[184:187], v[200:203], v[34:37]
	v_mfma_f32_16x16x32_bf16 v[22:25], v[162:165], v[208:211], v[22:25]
	v_mfma_f32_16x16x32_bf16 v[18:21], v[184:187], v[208:211], v[18:21]
	v_mfma_f32_16x16x32_bf16 v[6:9], v[162:165], v[216:219], v[6:9]
	v_mfma_f32_16x16x32_bf16 v[2:5], v[184:187], v[216:219], v[2:5]
	v_mfma_f32_16x16x32_bf16 v[54:57], v[180:183], v[196:199], v[54:57]
	v_mfma_f32_16x16x32_bf16 v[50:53], v[188:191], v[196:199], v[50:53]
	v_mfma_f32_16x16x32_bf16 v[38:41], v[180:183], v[204:207], v[38:41]
	v_mfma_f32_16x16x32_bf16 v[34:37], v[188:191], v[204:207], v[34:37]
	v_mfma_f32_16x16x32_bf16 v[22:25], v[180:183], v[212:215], v[22:25]
	v_mfma_f32_16x16x32_bf16 v[18:21], v[188:191], v[212:215], v[18:21]
	v_mfma_f32_16x16x32_bf16 v[6:9], v[180:183], v[220:223], v[6:9]
	v_mfma_f32_16x16x32_bf16 v[2:5], v[188:191], v[220:223], v[2:5]
	s_barrier
	s_add_i32 s50, s50, 2
	s_add_u32 s25, s25, 0x100
	s_addc_u32 s49, s49, 0
	s_add_u32 s16, s16, 0x100
	s_addc_u32 s17, s17, 0
	s_cmp_lt_u32 s50, 30
	s_cbranch_scc1 .LBB0_1822
	s_setprio 0
	s_andn2_b64 vcc, exec, s[10:11]
	s_cbranch_vccnz .LBB0_1825
	s_barrier

;     __device__ bool next(int i, Unit& u) const { if (i != 0 || c >= 128) return false; const int t = c >> 2; u.pm = t & 3; u.pn = t >> 2; u.koff = koff_bytes; u.q = c & 3; return true; }
; #define PG8_STAGE(bufoff, gbase, voff) do { _Pragma("unroll") for (int _i = 0; _i < 2; ++_i) \
;         __builtin_amdgcn_global_load_lds((const unsigned*)((const char*)(gbase) + (voff)[_i]), (LAS unsigned*)(lds + (bufoff) + ldsw + _i * 8192), 16, 0, 0); } while (0)
; #define PG8_LDA(dst, b, h) do { _Pragma("unroll") for (int m = 0; m < 4; ++m) _Pragma("unroll") for (int k = 0; k < 2; ++k) dst[m][k] = *(const LAS bf16x8*)(lds + PG8_SA(b, h) + aoff + m * 2048 + k * 1024); } while (0)
; #define PG8_LDB(dst, b, h) do { _Pragma("unroll") for (int n = 0; n < 2; ++n) _Pragma("unroll") for (int k = 0; k < 2; ++k) dst[n][k] = *(const LAS bf16x8*)(lds + PG8_SB(b, h) + boff + n * 2048 + k * 1024); } while (0)
; #define PG8_MMA(ai, bj, At, Bt) do { __builtin_amdgcn_s_setprio(1); _Pragma("unroll") for (int m = 0; m < 4; ++m) _Pragma("unroll") for (int n = 0; n < 2; ++n) _Pragma("unroll") for (int k = 0; k < 2; ++k) \
;         acc[ai][bj][m][n] = __builtin_amdgcn_mfma_f32_16x16x32_bf16(Bt[n][k], At[m][k], acc[ai][bj][m][n], 0, 0, 0); __builtin_amdgcn_s_setprio(0); } while (0)
; #define PG8_WAIT_V(n) asm volatile("s_waitcnt vmcnt(" #n ")" ::: "memory")
; #define PG8_BAR __builtin_amdgcn_s_barrier()
; template <class Epi, class Sched, bool ALIGN_EPI = false, bool SP2 = false>
; __device__ __forceinline__ void gemm_phase(LAS unsigned char* lds, const Gemm g, const Sched& S, const Epi& E) {
;     ...
;         const bool has_next = S.next(ui + 1, nxt);
;         const char* nA = has_next ? (const char*)g.A + (size_t)nxt.pm * tstep + nxt.koff : cA; const char* nB = has_next ? (const char*)g.Bt + (size_t)nxt.pn * tstep + nxt.koff : cB;
;     ...
;             if constexpr (SP2) {
;             PG8_LDB(B0, 0, 0); PG8_LDB(B1, 0, 1); PG8_SCHED; PG8_LDA(At, 0, 0); PG8_STAGE(PG8_SA(1, 1), a1 + hstep, voffA);
;             PG8_WAIT_V(8); PG8_WAIT_L(0); PG8_BAR; PG8_MMA(0, 0, At, B0); PG8_MMA(0, 1, At, B1); PG8_BAR; PG8_SCHED;
;             PG8_LDA(At, 0, 1); PG8_STAGE(PG8_SB(0, 0), b2, voffB); PG8_STAGE(PG8_SB(0, 1), b2 + hstepB, voffB); PG8_STAGE(PG8_SA(0, 0), a2, voffA);
;             PG8_WAIT_V(8); PG8_WAIT_L(0); PG8_BAR; PG8_MMA(1, 0, At, B0); PG8_MMA(1, 1, At, B1); PG8_BAR; PG8_SCHED;
.LBB0_1925:
	s_add_u32 s5, s20, 0x100
	s_addc_u32 s24, s21, 0
	s_mov_b32 s25, -2
	s_waitcnt vmcnt(0)
	v_readfirstlane_b32 s98, v0
	s_nop 3
	s_lshr_b32 s98, s98, 6
	s_cmp_ge_u32 s98, 4
	s_cbranch_scc0 .Lprio_1926
	s_setprio 1
.Lprio_1926:
	ds_read_b128 v[130:133], v196
	ds_read_b128 v[134:137], v196 offset:1024
	ds_read_b128 v[138:141], v196 offset:2048
	ds_read_b128 v[142:145], v196 offset:3072
	ds_read_b128 v[166:169], v197
	ds_read_b128 v[170:173], v197 offset:1024
	ds_read_b128 v[174:177], v197 offset:2048
	ds_read_b128 v[178:181], v197 offset:3072
	s_add_u32 s20, s18, 0x100
	s_addc_u32 s21, s19, 0
	s_cmpk_eq_i32 s25, 0x54
	s_cselect_b32 s47, s17, s21
	s_cselect_b32 s46, s16, s20
	s_cselect_b32 s23, s3, s24
	s_cselect_b32 s22, s2, s5
	v_lshl_add_u64 v[190:191], s[18:19], 0, v[160:161]
	s_add_i32 m0, s27, 0xc000
	ds_read_b128 v[182:185], v198
	ds_read_b128 v[186:189], v198 offset:1024
	ds_read_b128 v[202:205], v198 offset:2048
	ds_read_b128 v[206:209], v198 offset:3072
	ds_read_b128 v[210:213], v198 offset:4096
	ds_read_b128 v[214:217], v198 offset:5120
	ds_read_b128 v[218:221], v198 offset:6144
	ds_read_b128 v[222:225], v198 offset:7168
	global_load_lds_dwordx4 v[190:191], off
	v_lshl_add_u64 v[190:191], s[18:19], 0, v[158:159]
	s_add_i32 m0, s27, 0xe000
	s_nop 0
	global_load_lds_dwordx4 v[190:191], off
	s_waitcnt lgkmcnt(0)
	s_barrier
	s_waitcnt lgkmcnt(0)
	v_mfma_f32_16x16x32_bf16 v[126:129], v[130:133], v[182:185], 0
	v_mfma_f32_16x16x32_bf16 v[122:125], v[138:141], v[182:185], 0
	v_mfma_f32_16x16x32_bf16 v[110:113], v[130:133], v[202:205], 0
	v_mfma_f32_16x16x32_bf16 v[106:109], v[138:141], v[202:205], 0
	v_mfma_f32_16x16x32_bf16 v[94:97], v[130:133], v[210:213], 0
	v_mfma_f32_16x16x32_bf16 v[90:93], v[138:141], v[210:213], 0
	v_mfma_f32_16x16x32_bf16 v[78:81], v[130:133], v[218:221], 0
	v_mfma_f32_16x16x32_bf16 v[74:77], v[138:141], v[218:221], 0
	v_mfma_f32_16x16x32_bf16 v[126:129], v[134:137], v[186:189], v[126:129]
	v_mfma_f32_16x16x32_bf16 v[122:125], v[142:145], v[186:189], v[122:125]
	v_mfma_f32_16x16x32_bf16 v[110:113], v[134:137], v[206:209], v[110:113]
	v_mfma_f32_16x16x32_bf16 v[106:109], v[142:145], v[206:209], v[106:109]
	v_mfma_f32_16x16x32_bf16 v[94:97], v[134:137], v[214:217], v[94:97]
	v_mfma_f32_16x16x32_bf16 v[90:93], v[142:145], v[214:217], v[90:93]
	v_mfma_f32_16x16x32_bf16 v[78:81], v[134:137], v[222:225], v[78:81]
	v_mfma_f32_16x16x32_bf16 v[74:77], v[142:145], v[222:225], v[74:77]
	v_mfma_f32_16x16x32_bf16 v[118:121], v[166:169], v[182:185], 0
	v_mfma_f32_16x16x32_bf16 v[114:117], v[174:177], v[182:185], 0
	v_mfma_f32_16x16x32_bf16 v[102:105], v[166:169], v[202:205], 0
	v_mfma_f32_16x16x32_bf16 v[98:101], v[174:177], v[202:205], 0
	v_mfma_f32_16x16x32_bf16 v[86:89], v[166:169], v[210:213], 0
	v_mfma_f32_16x16x32_bf16 v[82:85], v[174:177], v[210:213], 0
	v_mfma_f32_16x16x32_bf16 v[70:73], v[166:169], v[218:221], 0
	v_mfma_f32_16x16x32_bf16 v[66:69], v[174:177], v[218:221], 0
	v_mfma_f32_16x16x32_bf16 v[118:121], v[170:173], v[186:189], v[118:121]
	v_mfma_f32_16x16x32_bf16 v[114:117], v[178:181], v[186:189], v[114:117]
	v_mfma_f32_16x16x32_bf16 v[102:105], v[170:173], v[206:209], v[102:105]
	v_mfma_f32_16x16x32_bf16 v[98:101], v[178:181], v[206:209], v[98:101]
	v_mfma_f32_16x16x32_bf16 v[86:89], v[170:173], v[214:217], v[86:89]
	v_mfma_f32_16x16x32_bf16 v[82:85], v[178:181], v[214:217], v[82:85]
	v_mfma_f32_16x16x32_bf16 v[70:73], v[170:173], v[222:225], v[70:73]
	v_mfma_f32_16x16x32_bf16 v[66:69], v[178:181], v[222:225], v[66:69]
	s_barrier
	s_add_i32 s18, s50, s26
	v_lshl_add_u64 v[190:191], s[22:23], 0, v[148:149]
	s_mov_b32 m0, s18
	ds_read_b128 v[182:185], v198 offset:16384
	ds_read_b128 v[186:189], v198 offset:17408
	ds_read_b128 v[202:205], v198 offset:18432
	ds_read_b128 v[206:209], v198 offset:19456
	ds_read_b128 v[210:213], v198 offset:20480
	ds_read_b128 v[214:217], v198 offset:21504
	ds_read_b128 v[218:221], v198 offset:22528
	ds_read_b128 v[222:225], v198 offset:23552
	global_load_lds_dwordx4 v[190:191], off
	s_add_i32 m0, s18, 0x2000
	s_add_u32 s18, s22, 0x58000
	v_lshl_add_u64 v[226:227], s[22:23], 0, v[152:153]
	s_addc_u32 s19, s23, 0
	s_add_i32 s54, s51, s26
	global_load_lds_dwordx4 v[226:227], off
	v_lshl_add_u64 v[228:229], s[18:19], 0, v[148:149]
	s_mov_b32 m0, s54
	v_lshl_add_u64 v[230:231], s[46:47], 0, v[150:151]
	global_load_lds_dwordx4 v[228:229], off
	v_lshl_add_u64 v[228:229], s[18:19], 0, v[152:153]
	s_add_i32 m0, s54, 0x2000
	s_nop 0
	global_load_lds_dwordx4 v[228:229], off
	v_lshl_add_u64 v[228:229], s[46:47], 0, v[146:147]
	s_mov_b32 m0, s27
	s_nop 0
	global_load_lds_dwordx4 v[228:229], off
	s_mov_b32 m0, s28
	s_nop 0
	global_load_lds_dwordx4 v[230:231], off
	s_waitcnt lgkmcnt(0)
	s_barrier
; #define PG8_STAGE(bufoff, gbase, voff) do { _Pragma("unroll") for (int _i = 0; _i < 2; ++_i) \
;         __builtin_amdgcn_global_load_lds((const unsigned*)((const char*)(gbase) + (voff)[_i]), (LAS unsigned*)(lds + (bufoff) + ldsw + _i * 8192), 16, 0, 0); } while (0)
; #define PG8_LDA(dst, b, h) do { _Pragma("unroll") for (int m = 0; m < 4; ++m) _Pragma("unroll") for (int k = 0; k < 2; ++k) dst[m][k] = *(const LAS bf16x8*)(lds + PG8_SA(b, h) + aoff + m * 2048 + k * 1024); } while (0)
; #define PG8_LDB(dst, b, h) do { _Pragma("unroll") for (int n = 0; n < 2; ++n) _Pragma("unroll") for (int k = 0; k < 2; ++k) dst[n][k] = *(const LAS bf16x8*)(lds + PG8_SB(b, h) + boff + n * 2048 + k * 1024); } while (0)
; #define PG8_MMA(ai, bj, At, Bt) do { __builtin_amdgcn_s_setprio(1); _Pragma("unroll") for (int m = 0; m < 4; ++m) _Pragma("unroll") for (int n = 0; n < 2; ++n) _Pragma("unroll") for (int k = 0; k < 2; ++k) \
;         acc[ai][bj][m][n] = __builtin_amdgcn_mfma_f32_16x16x32_bf16(Bt[n][k], At[m][k], acc[ai][bj][m][n], 0, 0, 0); __builtin_amdgcn_s_setprio(0); } while (0)
; #define PG8_WAIT_V(n) asm volatile("s_waitcnt vmcnt(" #n ")" ::: "memory")
; #define PG8_WAIT_L(n) asm volatile("s_waitcnt lgkmcnt(" #n ")" ::: "memory")
; #define PG8_BAR __builtin_amdgcn_s_barrier()
; #define PG8_SCHED __builtin_amdgcn_sched_barrier(0)
; template <class Epi, class Sched, bool ALIGN_EPI = false, bool SP2 = false>
; __device__ __forceinline__ void gemm_phase(LAS unsigned char* lds, const Gemm g, const Sched& S, const Epi& E) {
;     ...
;             PG8_WAIT_V(8); PG8_WAIT_L(0); PG8_BAR; PG8_MMA(1, 0, At, B0); PG8_MMA(1, 1, At, B1); PG8_BAR; PG8_SCHED;
;             PG8_LDB(B0, 1, 0); PG8_LDB(B1, 1, 1); PG8_SCHED; PG8_LDA(At, 1, 0); PG8_STAGE(PG8_SA(0, 1), a2 + hstep, voffA);
;             PG8_WAIT_V(8); PG8_WAIT_L(0); PG8_BAR; PG8_MMA(0, 0, At, B0); PG8_MMA(0, 1, At, B1); PG8_BAR; PG8_SCHED;
	s_waitcnt lgkmcnt(0)
	v_mfma_f32_16x16x32_bf16 v[62:65], v[130:133], v[182:185], 0
	v_mfma_f32_16x16x32_bf16 v[58:61], v[138:141], v[182:185], 0
	v_mfma_f32_16x16x32_bf16 v[46:49], v[130:133], v[202:205], 0
	v_mfma_f32_16x16x32_bf16 v[42:45], v[138:141], v[202:205], 0
	v_mfma_f32_16x16x32_bf16 v[30:33], v[130:133], v[210:213], 0
	v_mfma_f32_16x16x32_bf16 v[26:29], v[138:141], v[210:213], 0
	v_mfma_f32_16x16x32_bf16 v[14:17], v[130:133], v[218:221], 0
	v_mfma_f32_16x16x32_bf16 v[10:13], v[138:141], v[218:221], 0
	v_mfma_f32_16x16x32_bf16 v[62:65], v[134:137], v[186:189], v[62:65]
	v_mfma_f32_16x16x32_bf16 v[58:61], v[142:145], v[186:189], v[58:61]
	v_mfma_f32_16x16x32_bf16 v[46:49], v[134:137], v[206:209], v[46:49]
	v_mfma_f32_16x16x32_bf16 v[42:45], v[142:145], v[206:209], v[42:45]
	v_mfma_f32_16x16x32_bf16 v[30:33], v[134:137], v[214:217], v[30:33]
	v_mfma_f32_16x16x32_bf16 v[26:29], v[142:145], v[214:217], v[26:29]
	v_mfma_f32_16x16x32_bf16 v[14:17], v[134:137], v[222:225], v[14:17]
	v_mfma_f32_16x16x32_bf16 v[10:13], v[142:145], v[222:225], v[10:13]
	v_mfma_f32_16x16x32_bf16 v[54:57], v[166:169], v[182:185], 0
	v_mfma_f32_16x16x32_bf16 v[50:53], v[174:177], v[182:185], 0
	v_mfma_f32_16x16x32_bf16 v[38:41], v[166:169], v[202:205], 0
	v_mfma_f32_16x16x32_bf16 v[34:37], v[174:177], v[202:205], 0
	v_mfma_f32_16x16x32_bf16 v[22:25], v[166:169], v[210:213], 0
	v_mfma_f32_16x16x32_bf16 v[18:21], v[174:177], v[210:213], 0
	v_mfma_f32_16x16x32_bf16 v[6:9], v[166:169], v[218:221], 0
	v_mfma_f32_16x16x32_bf16 v[2:5], v[174:177], v[218:221], 0
	v_mfma_f32_16x16x32_bf16 v[54:57], v[170:173], v[186:189], v[54:57]
	v_mfma_f32_16x16x32_bf16 v[50:53], v[178:181], v[186:189], v[50:53]
	v_mfma_f32_16x16x32_bf16 v[38:41], v[170:173], v[206:209], v[38:41]
	v_mfma_f32_16x16x32_bf16 v[34:37], v[178:181], v[206:209], v[34:37]
	v_mfma_f32_16x16x32_bf16 v[22:25], v[170:173], v[214:217], v[22:25]
	v_mfma_f32_16x16x32_bf16 v[18:21], v[178:181], v[214:217], v[18:21]
	v_mfma_f32_16x16x32_bf16 v[6:9], v[170:173], v[222:225], v[6:9]
	v_mfma_f32_16x16x32_bf16 v[2:5], v[178:181], v[222:225], v[2:5]
	s_barrier
	s_add_i32 s54, 0, 0x18000
	s_add_i32 s55, 0, 0x1c000
	v_add_u32_e32 v142, s54, v1
	v_add_u32_e32 v154, s55, v1
	ds_read_b128 v[130:133], v142
	ds_read_b128 v[134:137], v142 offset:1024
	ds_read_b128 v[138:141], v142 offset:2048
	ds_read_b128 v[142:145], v142 offset:3072
	ds_read_b128 v[166:169], v154
	ds_read_b128 v[170:173], v154 offset:1024
	ds_read_b128 v[174:177], v154 offset:2048
	ds_read_b128 v[178:181], v154 offset:3072
	s_add_u32 s18, s46, 0x160000
	s_addc_u32 s19, s47, 0
	s_mov_b32 m0, s29
	v_lshl_add_u64 v[232:233], s[18:19], 0, v[146:147]
	ds_read_b128 v[182:185], v198 offset:32768
	ds_read_b128 v[186:189], v198 offset:33792
	ds_read_b128 v[202:205], v198 offset:34816
	ds_read_b128 v[206:209], v198 offset:35840
	ds_read_b128 v[210:213], v198 offset:36864
	ds_read_b128 v[214:217], v198 offset:37888
	ds_read_b128 v[218:221], v198 offset:38912
	ds_read_b128 v[222:225], v198 offset:39936
	global_load_lds_dwordx4 v[232:233], off
	v_lshl_add_u64 v[232:233], s[18:19], 0, v[150:151]
	s_mov_b32 m0, s30
	s_nop 0
	global_load_lds_dwordx4 v[232:233], off
	s_waitcnt vmcnt(8)
	s_waitcnt lgkmcnt(0)
	s_barrier
	s_waitcnt lgkmcnt(0)
	v_mfma_f32_16x16x32_bf16 v[126:129], v[130:133], v[182:185], v[126:129]
	v_mfma_f32_16x16x32_bf16 v[122:125], v[138:141], v[182:185], v[122:125]
	v_mfma_f32_16x16x32_bf16 v[110:113], v[130:133], v[202:205], v[110:113]
	v_mfma_f32_16x16x32_bf16 v[106:109], v[138:141], v[202:205], v[106:109]
	v_mfma_f32_16x16x32_bf16 v[94:97], v[130:133], v[210:213], v[94:97]
	v_mfma_f32_16x16x32_bf16 v[90:93], v[138:141], v[210:213], v[90:93]
	v_mfma_f32_16x16x32_bf16 v[78:81], v[130:133], v[218:221], v[78:81]
	v_mfma_f32_16x16x32_bf16 v[74:77], v[138:141], v[218:221], v[74:77]
	v_mfma_f32_16x16x32_bf16 v[126:129], v[134:137], v[186:189], v[126:129]
	v_mfma_f32_16x16x32_bf16 v[122:125], v[142:145], v[186:189], v[122:125]
	v_mfma_f32_16x16x32_bf16 v[110:113], v[134:137], v[206:209], v[110:113]
	v_mfma_f32_16x16x32_bf16 v[106:109], v[142:145], v[206:209], v[106:109]
	v_mfma_f32_16x16x32_bf16 v[94:97], v[134:137], v[214:217], v[94:97]
	v_mfma_f32_16x16x32_bf16 v[90:93], v[142:145], v[214:217], v[90:93]
	v_mfma_f32_16x16x32_bf16 v[78:81], v[134:137], v[222:225], v[78:81]
	v_mfma_f32_16x16x32_bf16 v[74:77], v[142:145], v[222:225], v[74:77]
	v_mfma_f32_16x16x32_bf16 v[118:121], v[166:169], v[182:185], v[118:121]
	v_mfma_f32_16x16x32_bf16 v[114:117], v[174:177], v[182:185], v[114:117]
	v_mfma_f32_16x16x32_bf16 v[102:105], v[166:169], v[202:205], v[102:105]
	v_mfma_f32_16x16x32_bf16 v[98:101], v[174:177], v[202:205], v[98:101]
	v_mfma_f32_16x16x32_bf16 v[86:89], v[166:169], v[210:213], v[86:89]
	v_mfma_f32_16x16x32_bf16 v[82:85], v[174:177], v[210:213], v[82:85]
	v_mfma_f32_16x16x32_bf16 v[70:73], v[166:169], v[218:221], v[70:73]
	v_mfma_f32_16x16x32_bf16 v[66:69], v[174:177], v[218:221], v[66:69]
	v_mfma_f32_16x16x32_bf16 v[118:121], v[170:173], v[186:189], v[118:121]
	v_mfma_f32_16x16x32_bf16 v[114:117], v[178:181], v[186:189], v[114:117]
	v_mfma_f32_16x16x32_bf16 v[102:105], v[170:173], v[206:209], v[102:105]
	v_mfma_f32_16x16x32_bf16 v[98:101], v[178:181], v[206:209], v[98:101]
	v_mfma_f32_16x16x32_bf16 v[86:89], v[170:173], v[214:217], v[86:89]
	v_mfma_f32_16x16x32_bf16 v[82:85], v[178:181], v[214:217], v[82:85]
	v_mfma_f32_16x16x32_bf16 v[70:73], v[170:173], v[222:225], v[70:73]
	v_mfma_f32_16x16x32_bf16 v[66:69], v[178:181], v[222:225], v[66:69]
	s_barrier
; #define PG8_STAGE(bufoff, gbase, voff) do { _Pragma("unroll") for (int _i = 0; _i < 2; ++_i) \
;         __builtin_amdgcn_global_load_lds((const unsigned*)((const char*)(gbase) + (voff)[_i]), (LAS unsigned*)(lds + (bufoff) + ldsw + _i * 8192), 16, 0, 0); } while (0)
; #define PG8_LDA(dst, b, h) do { _Pragma("unroll") for (int m = 0; m < 4; ++m) _Pragma("unroll") for (int k = 0; k < 2; ++k) dst[m][k] = *(const LAS bf16x8*)(lds + PG8_SA(b, h) + aoff + m * 2048 + k * 1024); } while (0)
; #define PG8_LDB(dst, b, h) do { _Pragma("unroll") for (int n = 0; n < 2; ++n) _Pragma("unroll") for (int k = 0; k < 2; ++k) dst[n][k] = *(const LAS bf16x8*)(lds + PG8_SB(b, h) + boff + n * 2048 + k * 1024); } while (0)
; #define PG8_MMA(ai, bj, At, Bt) do { __builtin_amdgcn_s_setprio(1); _Pragma("unroll") for (int m = 0; m < 4; ++m) _Pragma("unroll") for (int n = 0; n < 2; ++n) _Pragma("unroll") for (int k = 0; k < 2; ++k) \
;         acc[ai][bj][m][n] = __builtin_amdgcn_mfma_f32_16x16x32_bf16(Bt[n][k], At[m][k], acc[ai][bj][m][n], 0, 0, 0); __builtin_amdgcn_s_setprio(0); } while (0)
; #define PG8_WAIT_V(n) asm volatile("s_waitcnt vmcnt(" #n ")" ::: "memory")
; #define PG8_WAIT_L(n) asm volatile("s_waitcnt lgkmcnt(" #n ")" ::: "memory")
; #define PG8_BAR __builtin_amdgcn_s_barrier()
; #define PG8_SCHED __builtin_amdgcn_sched_barrier(0)
; template <class Epi, class Sched, bool ALIGN_EPI = false, bool SP2 = false>
; __device__ __forceinline__ void gemm_phase(LAS unsigned char* lds, const Gemm g, const Sched& S, const Epi& E) {
;     ...
;         for (int t = 0; t < nt; t += 2) {
;             const bool last = (t == nt - 2);
;             const char* a1 = cA + (size_t)(t + 1) * kstep;
;             const char* a2 = last ? nA : cA + (size_t)(t + 2) * kstep; const char* b2 = last ? nB : cB + (size_t)(t + 2) * kstep;
;             const char* a3 = a2 + kstep; const char* b3 = b2 + kstep;
;             if (last && has_next) S.a_ready(nxt);
;             if constexpr (SP2) {
;             PG8_LDB(B0, 0, 0); PG8_LDB(B1, 0, 1); PG8_SCHED; PG8_LDA(At, 0, 0); PG8_STAGE(PG8_SA(1, 1), a1 + hstep, voffA);
;     ...
;             PG8_LDA(At, 1, 1); PG8_STAGE(PG8_SB(1, 0), b3, voffB); PG8_STAGE(PG8_SB(1, 1), b3 + hstepB, voffB); PG8_STAGE(PG8_SA(1, 0), a3, voffA);
;             PG8_WAIT_V(8); PG8_WAIT_L(0); PG8_BAR; PG8_MMA(1, 0, At, B0); PG8_MMA(1, 1, At, B1); PG8_BAR; PG8_SCHED;
	s_add_i32 s18, s54, s26
	v_lshl_add_u64 v[190:191], v[190:191], 0, s[12:13]
	s_mov_b32 m0, s18
	ds_read_b128 v[182:185], v198 offset:49152
	ds_read_b128 v[186:189], v198 offset:50176
	ds_read_b128 v[202:205], v198 offset:51200
	ds_read_b128 v[206:209], v198 offset:52224
	ds_read_b128 v[210:213], v198 offset:53248
	ds_read_b128 v[214:217], v198 offset:54272
	ds_read_b128 v[218:221], v198 offset:55296
	ds_read_b128 v[222:225], v198 offset:56320
	global_load_lds_dwordx4 v[190:191], off
	s_add_i32 m0, s18, 0x2000
	s_add_u32 s18, s22, 0x58080
	v_lshl_add_u64 v[190:191], v[226:227], 0, s[12:13]
	s_addc_u32 s19, s23, 0
	s_add_i32 s22, s55, s26
	global_load_lds_dwordx4 v[190:191], off
	v_lshl_add_u64 v[190:191], s[18:19], 0, v[148:149]
	s_mov_b32 m0, s22
	s_nop 0
	global_load_lds_dwordx4 v[190:191], off
	v_lshl_add_u64 v[190:191], s[18:19], 0, v[152:153]
	s_add_i32 m0, s22, 0x2000
	s_nop 0
	global_load_lds_dwordx4 v[190:191], off
	v_lshl_add_u64 v[190:191], v[228:229], 0, s[12:13]
	s_mov_b32 m0, s37
	s_nop 0
	global_load_lds_dwordx4 v[190:191], off
	v_lshl_add_u64 v[190:191], v[230:231], 0, s[12:13]
	s_mov_b32 m0, s48
	s_nop 0
	global_load_lds_dwordx4 v[190:191], off
	s_waitcnt vmcnt(8)
	s_waitcnt lgkmcnt(0)
	s_barrier
	s_waitcnt lgkmcnt(0)
	v_mfma_f32_16x16x32_bf16 v[62:65], v[130:133], v[182:185], v[62:65]
	v_mfma_f32_16x16x32_bf16 v[58:61], v[138:141], v[182:185], v[58:61]
	v_mfma_f32_16x16x32_bf16 v[46:49], v[130:133], v[202:205], v[46:49]
	v_mfma_f32_16x16x32_bf16 v[42:45], v[138:141], v[202:205], v[42:45]
	v_mfma_f32_16x16x32_bf16 v[30:33], v[130:133], v[210:213], v[30:33]
	v_mfma_f32_16x16x32_bf16 v[26:29], v[138:141], v[210:213], v[26:29]
	v_mfma_f32_16x16x32_bf16 v[14:17], v[130:133], v[218:221], v[14:17]
	v_mfma_f32_16x16x32_bf16 v[10:13], v[138:141], v[218:221], v[10:13]
	v_mfma_f32_16x16x32_bf16 v[62:65], v[134:137], v[186:189], v[62:65]
	v_mfma_f32_16x16x32_bf16 v[58:61], v[142:145], v[186:189], v[58:61]
	v_mfma_f32_16x16x32_bf16 v[46:49], v[134:137], v[206:209], v[46:49]
	v_mfma_f32_16x16x32_bf16 v[42:45], v[142:145], v[206:209], v[42:45]
	v_mfma_f32_16x16x32_bf16 v[30:33], v[134:137], v[214:217], v[30:33]
	v_mfma_f32_16x16x32_bf16 v[26:29], v[142:145], v[214:217], v[26:29]
	v_mfma_f32_16x16x32_bf16 v[14:17], v[134:137], v[222:225], v[14:17]
	v_mfma_f32_16x16x32_bf16 v[10:13], v[142:145], v[222:225], v[10:13]
	v_mfma_f32_16x16x32_bf16 v[54:57], v[166:169], v[182:185], v[54:57]
	v_mfma_f32_16x16x32_bf16 v[50:53], v[174:177], v[182:185], v[50:53]
	v_mfma_f32_16x16x32_bf16 v[38:41], v[166:169], v[202:205], v[38:41]
	v_mfma_f32_16x16x32_bf16 v[34:37], v[174:177], v[202:205], v[34:37]
	v_mfma_f32_16x16x32_bf16 v[22:25], v[166:169], v[210:213], v[22:25]
	v_mfma_f32_16x16x32_bf16 v[18:21], v[174:177], v[210:213], v[18:21]
	v_mfma_f32_16x16x32_bf16 v[6:9], v[166:169], v[218:221], v[6:9]
	v_mfma_f32_16x16x32_bf16 v[2:5], v[174:177], v[218:221], v[2:5]
	v_mfma_f32_16x16x32_bf16 v[54:57], v[170:173], v[186:189], v[54:57]
	v_mfma_f32_16x16x32_bf16 v[50:53], v[178:181], v[186:189], v[50:53]
	v_mfma_f32_16x16x32_bf16 v[38:41], v[170:173], v[206:209], v[38:41]
	v_mfma_f32_16x16x32_bf16 v[34:37], v[178:181], v[206:209], v[34:37]
	v_mfma_f32_16x16x32_bf16 v[22:25], v[170:173], v[214:217], v[22:25]
	v_mfma_f32_16x16x32_bf16 v[18:21], v[178:181], v[214:217], v[18:21]
	v_mfma_f32_16x16x32_bf16 v[6:9], v[170:173], v[222:225], v[6:9]
	v_mfma_f32_16x16x32_bf16 v[2:5], v[178:181], v[222:225], v[2:5]
	s_barrier
	s_add_i32 s25, s25, 2
	s_add_u32 s5, s5, 0x100
	s_addc_u32 s24, s24, 0
	s_cmpk_lt_u32 s25, 0x56
	s_mov_b64 s[18:19], s[20:21]
.LBB0_1926:
	ds_read_b128 v[130:133], v196
	ds_read_b128 v[134:137], v196 offset:1024
	ds_read_b128 v[138:141], v196 offset:2048
	ds_read_b128 v[142:145], v196 offset:3072
	ds_read_b128 v[166:169], v197
	ds_read_b128 v[170:173], v197 offset:1024
	ds_read_b128 v[174:177], v197 offset:2048
	ds_read_b128 v[178:181], v197 offset:3072
	s_add_u32 s20, s18, 0x100
	s_addc_u32 s21, s19, 0
	s_cmpk_eq_i32 s25, 0x54
	s_cselect_b32 s47, s17, s21
	s_cselect_b32 s46, s16, s20
	s_cselect_b32 s23, s3, s24
	s_cselect_b32 s22, s2, s5
	v_lshl_add_u64 v[190:191], s[18:19], 0, v[160:161]
	s_add_i32 m0, s27, 0xc000
	ds_read_b128 v[182:185], v198
	ds_read_b128 v[186:189], v198 offset:1024
	ds_read_b128 v[202:205], v198 offset:2048
	ds_read_b128 v[206:209], v198 offset:3072
	ds_read_b128 v[210:213], v198 offset:4096
	ds_read_b128 v[214:217], v198 offset:5120
	ds_read_b128 v[218:221], v198 offset:6144
	ds_read_b128 v[222:225], v198 offset:7168
	global_load_lds_dwordx4 v[190:191], off
	v_lshl_add_u64 v[190:191], s[18:19], 0, v[158:159]
	s_add_i32 m0, s27, 0xe000
	s_nop 0
	global_load_lds_dwordx4 v[190:191], off
	s_waitcnt vmcnt(8)
	s_waitcnt lgkmcnt(0)
	s_barrier
; #define PG8_STAGE(bufoff, gbase, voff) do { _Pragma("unroll") for (int _i = 0; _i < 2; ++_i) \
;         __builtin_amdgcn_global_load_lds((const unsigned*)((const char*)(gbase) + (voff)[_i]), (LAS unsigned*)(lds + (bufoff) + ldsw + _i * 8192), 16, 0, 0); } while (0)
; #define PG8_LDA(dst, b, h) do { _Pragma("unroll") for (int m = 0; m < 4; ++m) _Pragma("unroll") for (int k = 0; k < 2; ++k) dst[m][k] = *(const LAS bf16x8*)(lds + PG8_SA(b, h) + aoff + m * 2048 + k * 1024); } while (0)
; #define PG8_LDB(dst, b, h) do { _Pragma("unroll") for (int n = 0; n < 2; ++n) _Pragma("unroll") for (int k = 0; k < 2; ++k) dst[n][k] = *(const LAS bf16x8*)(lds + PG8_SB(b, h) + boff + n * 2048 + k * 1024); } while (0)
; #define PG8_MMA(ai, bj, At, Bt) do { __builtin_amdgcn_s_setprio(1); _Pragma("unroll") for (int m = 0; m < 4; ++m) _Pragma("unroll") for (int n = 0; n < 2; ++n) _Pragma("unroll") for (int k = 0; k < 2; ++k) \
;         acc[ai][bj][m][n] = __builtin_amdgcn_mfma_f32_16x16x32_bf16(Bt[n][k], At[m][k], acc[ai][bj][m][n], 0, 0, 0); __builtin_amdgcn_s_setprio(0); } while (0)
; #define PG8_WAIT_V(n) asm volatile("s_waitcnt vmcnt(" #n ")" ::: "memory")
; #define PG8_WAIT_L(n) asm volatile("s_waitcnt lgkmcnt(" #n ")" ::: "memory")
; #define PG8_BAR __builtin_amdgcn_s_barrier()
; #define PG8_SCHED __builtin_amdgcn_sched_barrier(0)
; template <class Epi, class Sched, bool ALIGN_EPI = false, bool SP2 = false>
; __device__ __forceinline__ void gemm_phase(LAS unsigned char* lds, const Gemm g, const Sched& S, const Epi& E) {
;     ...
;             PG8_WAIT_V(8); PG8_WAIT_L(0); PG8_BAR; PG8_MMA(0, 0, At, B0); PG8_MMA(0, 1, At, B1); PG8_BAR; PG8_SCHED;
;             PG8_LDA(At, 0, 1); PG8_STAGE(PG8_SB(0, 0), b2, voffB); PG8_STAGE(PG8_SB(0, 1), b2 + hstepB, voffB); PG8_STAGE(PG8_SA(0, 0), a2, voffA);
;             PG8_WAIT_V(8); PG8_WAIT_L(0); PG8_BAR; PG8_MMA(1, 0, At, B0); PG8_MMA(1, 1, At, B1); PG8_BAR; PG8_SCHED;
;             PG8_LDB(B0, 1, 0); PG8_LDB(B1, 1, 1); PG8_SCHED; PG8_LDA(At, 1, 0); PG8_STAGE(PG8_SA(0, 1), a2 + hstep, voffA);
;             PG8_WAIT_V(8); PG8_WAIT_L(0); PG8_BAR; PG8_MMA(0, 0, At, B0); PG8_MMA(0, 1, At, B1); PG8_BAR; PG8_SCHED;
	s_waitcnt lgkmcnt(0)
	v_mfma_f32_16x16x32_bf16 v[126:129], v[130:133], v[182:185], v[126:129]
	v_mfma_f32_16x16x32_bf16 v[122:125], v[138:141], v[182:185], v[122:125]
	v_mfma_f32_16x16x32_bf16 v[110:113], v[130:133], v[202:205], v[110:113]
	v_mfma_f32_16x16x32_bf16 v[106:109], v[138:141], v[202:205], v[106:109]
	v_mfma_f32_16x16x32_bf16 v[94:97], v[130:133], v[210:213], v[94:97]
	v_mfma_f32_16x16x32_bf16 v[90:93], v[138:141], v[210:213], v[90:93]
	v_mfma_f32_16x16x32_bf16 v[78:81], v[130:133], v[218:221], v[78:81]
	v_mfma_f32_16x16x32_bf16 v[74:77], v[138:141], v[218:221], v[74:77]
	v_mfma_f32_16x16x32_bf16 v[126:129], v[134:137], v[186:189], v[126:129]
	v_mfma_f32_16x16x32_bf16 v[122:125], v[142:145], v[186:189], v[122:125]
	v_mfma_f32_16x16x32_bf16 v[110:113], v[134:137], v[206:209], v[110:113]
	v_mfma_f32_16x16x32_bf16 v[106:109], v[142:145], v[206:209], v[106:109]
	v_mfma_f32_16x16x32_bf16 v[94:97], v[134:137], v[214:217], v[94:97]
	v_mfma_f32_16x16x32_bf16 v[90:93], v[142:145], v[214:217], v[90:93]
	v_mfma_f32_16x16x32_bf16 v[78:81], v[134:137], v[222:225], v[78:81]
	v_mfma_f32_16x16x32_bf16 v[74:77], v[142:145], v[222:225], v[74:77]
	v_mfma_f32_16x16x32_bf16 v[118:121], v[166:169], v[182:185], v[118:121]
	v_mfma_f32_16x16x32_bf16 v[114:117], v[174:177], v[182:185], v[114:117]
	v_mfma_f32_16x16x32_bf16 v[102:105], v[166:169], v[202:205], v[102:105]
	v_mfma_f32_16x16x32_bf16 v[98:101], v[174:177], v[202:205], v[98:101]
	v_mfma_f32_16x16x32_bf16 v[86:89], v[166:169], v[210:213], v[86:89]
	v_mfma_f32_16x16x32_bf16 v[82:85], v[174:177], v[210:213], v[82:85]
	v_mfma_f32_16x16x32_bf16 v[70:73], v[166:169], v[218:221], v[70:73]
	v_mfma_f32_16x16x32_bf16 v[66:69], v[174:177], v[218:221], v[66:69]
	v_mfma_f32_16x16x32_bf16 v[118:121], v[170:173], v[186:189], v[118:121]
	v_mfma_f32_16x16x32_bf16 v[114:117], v[178:181], v[186:189], v[114:117]
	v_mfma_f32_16x16x32_bf16 v[102:105], v[170:173], v[206:209], v[102:105]
	v_mfma_f32_16x16x32_bf16 v[98:101], v[178:181], v[206:209], v[98:101]
	v_mfma_f32_16x16x32_bf16 v[86:89], v[170:173], v[214:217], v[86:89]
	v_mfma_f32_16x16x32_bf16 v[82:85], v[178:181], v[214:217], v[82:85]
	v_mfma_f32_16x16x32_bf16 v[70:73], v[170:173], v[222:225], v[70:73]
	v_mfma_f32_16x16x32_bf16 v[66:69], v[178:181], v[222:225], v[66:69]
	s_barrier
	s_add_i32 s18, s50, s26
	v_lshl_add_u64 v[190:191], s[22:23], 0, v[148:149]
	s_mov_b32 m0, s18
	ds_read_b128 v[182:185], v198 offset:16384
	ds_read_b128 v[186:189], v198 offset:17408
	ds_read_b128 v[202:205], v198 offset:18432
	ds_read_b128 v[206:209], v198 offset:19456
	ds_read_b128 v[210:213], v198 offset:20480
	ds_read_b128 v[214:217], v198 offset:21504
	ds_read_b128 v[218:221], v198 offset:22528
	ds_read_b128 v[222:225], v198 offset:23552
	global_load_lds_dwordx4 v[190:191], off
	s_add_i32 m0, s18, 0x2000
	s_add_u32 s18, s22, 0x58000
	v_lshl_add_u64 v[226:227], s[22:23], 0, v[152:153]
	s_addc_u32 s19, s23, 0
	s_add_i32 s54, s51, s26
	global_load_lds_dwordx4 v[226:227], off
	v_lshl_add_u64 v[228:229], s[18:19], 0, v[148:149]
	s_mov_b32 m0, s54
	v_lshl_add_u64 v[230:231], s[46:47], 0, v[150:151]
	global_load_lds_dwordx4 v[228:229], off
	v_lshl_add_u64 v[228:229], s[18:19], 0, v[152:153]
	s_add_i32 m0, s54, 0x2000
	s_nop 0
	global_load_lds_dwordx4 v[228:229], off
	v_lshl_add_u64 v[228:229], s[46:47], 0, v[146:147]
	s_mov_b32 m0, s27
	s_nop 0
	global_load_lds_dwordx4 v[228:229], off
	s_mov_b32 m0, s28
	s_nop 0
	global_load_lds_dwordx4 v[230:231], off
	s_waitcnt vmcnt(8)
	s_waitcnt lgkmcnt(0)
	s_barrier
	s_waitcnt lgkmcnt(0)
	v_mfma_f32_16x16x32_bf16 v[62:65], v[130:133], v[182:185], v[62:65]
	v_mfma_f32_16x16x32_bf16 v[58:61], v[138:141], v[182:185], v[58:61]
	v_mfma_f32_16x16x32_bf16 v[46:49], v[130:133], v[202:205], v[46:49]
	v_mfma_f32_16x16x32_bf16 v[42:45], v[138:141], v[202:205], v[42:45]
	v_mfma_f32_16x16x32_bf16 v[30:33], v[130:133], v[210:213], v[30:33]
	v_mfma_f32_16x16x32_bf16 v[26:29], v[138:141], v[210:213], v[26:29]
	v_mfma_f32_16x16x32_bf16 v[14:17], v[130:133], v[218:221], v[14:17]
	v_mfma_f32_16x16x32_bf16 v[10:13], v[138:141], v[218:221], v[10:13]
	v_mfma_f32_16x16x32_bf16 v[62:65], v[134:137], v[186:189], v[62:65]
	v_mfma_f32_16x16x32_bf16 v[58:61], v[142:145], v[186:189], v[58:61]
	v_mfma_f32_16x16x32_bf16 v[46:49], v[134:137], v[206:209], v[46:49]
	v_mfma_f32_16x16x32_bf16 v[42:45], v[142:145], v[206:209], v[42:45]
	v_mfma_f32_16x16x32_bf16 v[30:33], v[134:137], v[214:217], v[30:33]
	v_mfma_f32_16x16x32_bf16 v[26:29], v[142:145], v[214:217], v[26:29]
	v_mfma_f32_16x16x32_bf16 v[14:17], v[134:137], v[222:225], v[14:17]
	v_mfma_f32_16x16x32_bf16 v[10:13], v[142:145], v[222:225], v[10:13]
	v_mfma_f32_16x16x32_bf16 v[54:57], v[166:169], v[182:185], v[54:57]
	v_mfma_f32_16x16x32_bf16 v[50:53], v[174:177], v[182:185], v[50:53]
	v_mfma_f32_16x16x32_bf16 v[38:41], v[166:169], v[202:205], v[38:41]
	v_mfma_f32_16x16x32_bf16 v[34:37], v[174:177], v[202:205], v[34:37]
	v_mfma_f32_16x16x32_bf16 v[22:25], v[166:169], v[210:213], v[22:25]
	v_mfma_f32_16x16x32_bf16 v[18:21], v[174:177], v[210:213], v[18:21]
	v_mfma_f32_16x16x32_bf16 v[6:9], v[166:169], v[218:221], v[6:9]
	v_mfma_f32_16x16x32_bf16 v[2:5], v[174:177], v[218:221], v[2:5]
	v_mfma_f32_16x16x32_bf16 v[54:57], v[170:173], v[186:189], v[54:57]
	v_mfma_f32_16x16x32_bf16 v[50:53], v[178:181], v[186:189], v[50:53]
	v_mfma_f32_16x16x32_bf16 v[38:41], v[170:173], v[206:209], v[38:41]
	v_mfma_f32_16x16x32_bf16 v[34:37], v[178:181], v[206:209], v[34:37]
	v_mfma_f32_16x16x32_bf16 v[22:25], v[170:173], v[214:217], v[22:25]
	v_mfma_f32_16x16x32_bf16 v[18:21], v[178:181], v[214:217], v[18:21]
	v_mfma_f32_16x16x32_bf16 v[6:9], v[170:173], v[222:225], v[6:9]
	v_mfma_f32_16x16x32_bf16 v[2:5], v[178:181], v[222:225], v[2:5]
	s_barrier
; #define PG8_STAGE(bufoff, gbase, voff) do { _Pragma("unroll") for (int _i = 0; _i < 2; ++_i) \
;         __builtin_amdgcn_global_load_lds((const unsigned*)((const char*)(gbase) + (voff)[_i]), (LAS unsigned*)(lds + (bufoff) + ldsw + _i * 8192), 16, 0, 0); } while (0)
; #define PG8_LDA(dst, b, h) do { _Pragma("unroll") for (int m = 0; m < 4; ++m) _Pragma("unroll") for (int k = 0; k < 2; ++k) dst[m][k] = *(const LAS bf16x8*)(lds + PG8_SA(b, h) + aoff + m * 2048 + k * 1024); } while (0)
; #define PG8_LDB(dst, b, h) do { _Pragma("unroll") for (int n = 0; n < 2; ++n) _Pragma("unroll") for (int k = 0; k < 2; ++k) dst[n][k] = *(const LAS bf16x8*)(lds + PG8_SB(b, h) + boff + n * 2048 + k * 1024); } while (0)
; #define PG8_MMA(ai, bj, At, Bt) do { __builtin_amdgcn_s_setprio(1); _Pragma("unroll") for (int m = 0; m < 4; ++m) _Pragma("unroll") for (int n = 0; n < 2; ++n) _Pragma("unroll") for (int k = 0; k < 2; ++k) \
;         acc[ai][bj][m][n] = __builtin_amdgcn_mfma_f32_16x16x32_bf16(Bt[n][k], At[m][k], acc[ai][bj][m][n], 0, 0, 0); __builtin_amdgcn_s_setprio(0); } while (0)
; #define PG8_WAIT_V(n) asm volatile("s_waitcnt vmcnt(" #n ")" ::: "memory")
; #define PG8_WAIT_L(n) asm volatile("s_waitcnt lgkmcnt(" #n ")" ::: "memory")
; #define PG8_BAR __builtin_amdgcn_s_barrier()
; #define PG8_SCHED __builtin_amdgcn_sched_barrier(0)
; template <class Epi, class Sched, bool ALIGN_EPI = false, bool SP2 = false>
; __device__ __forceinline__ void gemm_phase(LAS unsigned char* lds, const Gemm g, const Sched& S, const Epi& E) {
;     ...
;             PG8_LDB(B0, 1, 0); PG8_LDB(B1, 1, 1); PG8_SCHED; PG8_LDA(At, 1, 0); PG8_STAGE(PG8_SA(0, 1), a2 + hstep, voffA);
;             PG8_WAIT_V(8); PG8_WAIT_L(0); PG8_BAR; PG8_MMA(0, 0, At, B0); PG8_MMA(0, 1, At, B1); PG8_BAR; PG8_SCHED;
	s_add_i32 s54, 0, 0x18000
	s_add_i32 s55, 0, 0x1c000
	v_add_u32_e32 v142, s54, v1
	v_add_u32_e32 v154, s55, v1
	ds_read_b128 v[130:133], v142
	ds_read_b128 v[134:137], v142 offset:1024
	ds_read_b128 v[138:141], v142 offset:2048
	ds_read_b128 v[142:145], v142 offset:3072
	ds_read_b128 v[166:169], v154
	ds_read_b128 v[170:173], v154 offset:1024
	ds_read_b128 v[174:177], v154 offset:2048
	ds_read_b128 v[178:181], v154 offset:3072
	s_add_u32 s18, s46, 0x160000
	s_addc_u32 s19, s47, 0
	s_mov_b32 m0, s29
	v_lshl_add_u64 v[232:233], s[18:19], 0, v[146:147]
	ds_read_b128 v[182:185], v198 offset:32768
	ds_read_b128 v[186:189], v198 offset:33792
	ds_read_b128 v[202:205], v198 offset:34816
	ds_read_b128 v[206:209], v198 offset:35840
	ds_read_b128 v[210:213], v198 offset:36864
	ds_read_b128 v[214:217], v198 offset:37888
	ds_read_b128 v[218:221], v198 offset:38912
	ds_read_b128 v[222:225], v198 offset:39936
	global_load_lds_dwordx4 v[232:233], off
	v_lshl_add_u64 v[232:233], s[18:19], 0, v[150:151]
	s_mov_b32 m0, s30
	s_nop 0
	global_load_lds_dwordx4 v[232:233], off
	s_waitcnt vmcnt(8)
	s_waitcnt lgkmcnt(0)
	s_barrier
	s_waitcnt lgkmcnt(0)
	v_mfma_f32_16x16x32_bf16 v[126:129], v[130:133], v[182:185], v[126:129]
	v_mfma_f32_16x16x32_bf16 v[122:125], v[138:141], v[182:185], v[122:125]
	v_mfma_f32_16x16x32_bf16 v[110:113], v[130:133], v[202:205], v[110:113]
	v_mfma_f32_16x16x32_bf16 v[106:109], v[138:141], v[202:205], v[106:109]
	v_mfma_f32_16x16x32_bf16 v[94:97], v[130:133], v[210:213], v[94:97]
	v_mfma_f32_16x16x32_bf16 v[90:93], v[138:141], v[210:213], v[90:93]
	v_mfma_f32_16x16x32_bf16 v[78:81], v[130:133], v[218:221], v[78:81]
	v_mfma_f32_16x16x32_bf16 v[74:77], v[138:141], v[218:221], v[74:77]
	v_mfma_f32_16x16x32_bf16 v[126:129], v[134:137], v[186:189], v[126:129]
	v_mfma_f32_16x16x32_bf16 v[122:125], v[142:145], v[186:189], v[122:125]
	v_mfma_f32_16x16x32_bf16 v[110:113], v[134:137], v[206:209], v[110:113]
	v_mfma_f32_16x16x32_bf16 v[106:109], v[142:145], v[206:209], v[106:109]
	v_mfma_f32_16x16x32_bf16 v[94:97], v[134:137], v[214:217], v[94:97]
	v_mfma_f32_16x16x32_bf16 v[90:93], v[142:145], v[214:217], v[90:93]
	v_mfma_f32_16x16x32_bf16 v[78:81], v[134:137], v[222:225], v[78:81]
	v_mfma_f32_16x16x32_bf16 v[74:77], v[142:145], v[222:225], v[74:77]
	v_mfma_f32_16x16x32_bf16 v[118:121], v[166:169], v[182:185], v[118:121]
	v_mfma_f32_16x16x32_bf16 v[114:117], v[174:177], v[182:185], v[114:117]
	v_mfma_f32_16x16x32_bf16 v[102:105], v[166:169], v[202:205], v[102:105]
	v_mfma_f32_16x16x32_bf16 v[98:101], v[174:177], v[202:205], v[98:101]
	v_mfma_f32_16x16x32_bf16 v[86:89], v[166:169], v[210:213], v[86:89]
	v_mfma_f32_16x16x32_bf16 v[82:85], v[174:177], v[210:213], v[82:85]
	v_mfma_f32_16x16x32_bf16 v[70:73], v[166:169], v[218:221], v[70:73]
	v_mfma_f32_16x16x32_bf16 v[66:69], v[174:177], v[218:221], v[66:69]
	v_mfma_f32_16x16x32_bf16 v[118:121], v[170:173], v[186:189], v[118:121]
	v_mfma_f32_16x16x32_bf16 v[114:117], v[178:181], v[186:189], v[114:117]
	v_mfma_f32_16x16x32_bf16 v[102:105], v[170:173], v[206:209], v[102:105]
	v_mfma_f32_16x16x32_bf16 v[98:101], v[178:181], v[206:209], v[98:101]
	v_mfma_f32_16x16x32_bf16 v[86:89], v[170:173], v[214:217], v[86:89]
	v_mfma_f32_16x16x32_bf16 v[82:85], v[178:181], v[214:217], v[82:85]
	v_mfma_f32_16x16x32_bf16 v[70:73], v[170:173], v[222:225], v[70:73]
	v_mfma_f32_16x16x32_bf16 v[66:69], v[178:181], v[222:225], v[66:69]
	s_barrier
; #define PG8_STAGE(bufoff, gbase, voff) do { _Pragma("unroll") for (int _i = 0; _i < 2; ++_i) \
;         __builtin_amdgcn_global_load_lds((const unsigned*)((const char*)(gbase) + (voff)[_i]), (LAS unsigned*)(lds + (bufoff) + ldsw + _i * 8192), 16, 0, 0); } while (0)
; #define PG8_LDA(dst, b, h) do { _Pragma("unroll") for (int m = 0; m < 4; ++m) _Pragma("unroll") for (int k = 0; k < 2; ++k) dst[m][k] = *(const LAS bf16x8*)(lds + PG8_SA(b, h) + aoff + m * 2048 + k * 1024); } while (0)
; #define PG8_MMA(ai, bj, At, Bt) do { __builtin_amdgcn_s_setprio(1); _Pragma("unroll") for (int m = 0; m < 4; ++m) _Pragma("unroll") for (int n = 0; n < 2; ++n) _Pragma("unroll") for (int k = 0; k < 2; ++k) \
;         acc[ai][bj][m][n] = __builtin_amdgcn_mfma_f32_16x16x32_bf16(Bt[n][k], At[m][k], acc[ai][bj][m][n], 0, 0, 0); __builtin_amdgcn_s_setprio(0); } while (0)
; #define PG8_WAIT_V(n) asm volatile("s_waitcnt vmcnt(" #n ")" ::: "memory")
; #define PG8_WAIT_L(n) asm volatile("s_waitcnt lgkmcnt(" #n ")" ::: "memory")
; #define PG8_BAR __builtin_amdgcn_s_barrier()
; #define PG8_SCHED __builtin_amdgcn_sched_barrier(0)
; template <class Epi, class Sched, bool ALIGN_EPI = false, bool SP2 = false>
; __device__ __forceinline__ void gemm_phase(LAS unsigned char* lds, const Gemm g, const Sched& S, const Epi& E) {
;     ...
;             PG8_LDA(At, 1, 1); PG8_STAGE(PG8_SB(1, 0), b3, voffB); PG8_STAGE(PG8_SB(1, 1), b3 + hstepB, voffB); PG8_STAGE(PG8_SA(1, 0), a3, voffA);
;             PG8_WAIT_V(8); PG8_WAIT_L(0); PG8_BAR; PG8_MMA(1, 0, At, B0); PG8_MMA(1, 1, At, B1); PG8_BAR; PG8_SCHED;
;     ...
;         if constexpr (ALIGN_EPI) { if (wr == 0) PG8_BAR; }
	s_add_i32 s18, s54, s26
	v_lshl_add_u64 v[190:191], v[190:191], 0, s[12:13]
	s_mov_b32 m0, s18
	ds_read_b128 v[182:185], v198 offset:49152
	ds_read_b128 v[186:189], v198 offset:50176
	ds_read_b128 v[202:205], v198 offset:51200
	ds_read_b128 v[206:209], v198 offset:52224
	ds_read_b128 v[210:213], v198 offset:53248
	ds_read_b128 v[214:217], v198 offset:54272
	ds_read_b128 v[218:221], v198 offset:55296
	ds_read_b128 v[222:225], v198 offset:56320
	global_load_lds_dwordx4 v[190:191], off
	s_add_i32 m0, s18, 0x2000
	s_add_u32 s18, s22, 0x58080
	v_lshl_add_u64 v[190:191], v[226:227], 0, s[12:13]
	s_addc_u32 s19, s23, 0
	s_add_i32 s22, s55, s26
	global_load_lds_dwordx4 v[190:191], off
	v_lshl_add_u64 v[190:191], s[18:19], 0, v[148:149]
	s_mov_b32 m0, s22
	s_nop 0
	global_load_lds_dwordx4 v[190:191], off
	v_lshl_add_u64 v[190:191], s[18:19], 0, v[152:153]
	s_add_i32 m0, s22, 0x2000
	s_nop 0
	global_load_lds_dwordx4 v[190:191], off
	v_lshl_add_u64 v[190:191], v[228:229], 0, s[12:13]
	s_mov_b32 m0, s37
	s_nop 0
	global_load_lds_dwordx4 v[190:191], off
	v_lshl_add_u64 v[190:191], v[230:231], 0, s[12:13]
	s_mov_b32 m0, s48
	s_nop 0
	global_load_lds_dwordx4 v[190:191], off
	s_waitcnt vmcnt(8)
	s_waitcnt lgkmcnt(0)
	s_barrier
	s_waitcnt lgkmcnt(0)
	v_mfma_f32_16x16x32_bf16 v[62:65], v[130:133], v[182:185], v[62:65]
	v_mfma_f32_16x16x32_bf16 v[58:61], v[138:141], v[182:185], v[58:61]
	v_mfma_f32_16x16x32_bf16 v[46:49], v[130:133], v[202:205], v[46:49]
	v_mfma_f32_16x16x32_bf16 v[42:45], v[138:141], v[202:205], v[42:45]
	v_mfma_f32_16x16x32_bf16 v[30:33], v[130:133], v[210:213], v[30:33]
	v_mfma_f32_16x16x32_bf16 v[26:29], v[138:141], v[210:213], v[26:29]
	v_mfma_f32_16x16x32_bf16 v[14:17], v[130:133], v[218:221], v[14:17]
	v_mfma_f32_16x16x32_bf16 v[10:13], v[138:141], v[218:221], v[10:13]
	v_mfma_f32_16x16x32_bf16 v[62:65], v[134:137], v[186:189], v[62:65]
	v_mfma_f32_16x16x32_bf16 v[58:61], v[142:145], v[186:189], v[58:61]
	v_mfma_f32_16x16x32_bf16 v[46:49], v[134:137], v[206:209], v[46:49]
	v_mfma_f32_16x16x32_bf16 v[42:45], v[142:145], v[206:209], v[42:45]
	v_mfma_f32_16x16x32_bf16 v[30:33], v[134:137], v[214:217], v[30:33]
	v_mfma_f32_16x16x32_bf16 v[26:29], v[142:145], v[214:217], v[26:29]
	v_mfma_f32_16x16x32_bf16 v[14:17], v[134:137], v[222:225], v[14:17]
	v_mfma_f32_16x16x32_bf16 v[10:13], v[142:145], v[222:225], v[10:13]
	v_mfma_f32_16x16x32_bf16 v[54:57], v[166:169], v[182:185], v[54:57]
	v_mfma_f32_16x16x32_bf16 v[50:53], v[174:177], v[182:185], v[50:53]
	v_mfma_f32_16x16x32_bf16 v[38:41], v[166:169], v[202:205], v[38:41]
	v_mfma_f32_16x16x32_bf16 v[34:37], v[174:177], v[202:205], v[34:37]
	v_mfma_f32_16x16x32_bf16 v[22:25], v[166:169], v[210:213], v[22:25]
	v_mfma_f32_16x16x32_bf16 v[18:21], v[174:177], v[210:213], v[18:21]
	v_mfma_f32_16x16x32_bf16 v[6:9], v[166:169], v[218:221], v[6:9]
	v_mfma_f32_16x16x32_bf16 v[2:5], v[174:177], v[218:221], v[2:5]
	v_mfma_f32_16x16x32_bf16 v[54:57], v[170:173], v[186:189], v[54:57]
	v_mfma_f32_16x16x32_bf16 v[50:53], v[178:181], v[186:189], v[50:53]
	v_mfma_f32_16x16x32_bf16 v[38:41], v[170:173], v[206:209], v[38:41]
	v_mfma_f32_16x16x32_bf16 v[34:37], v[178:181], v[206:209], v[34:37]
	v_mfma_f32_16x16x32_bf16 v[22:25], v[170:173], v[214:217], v[22:25]
	v_mfma_f32_16x16x32_bf16 v[18:21], v[178:181], v[214:217], v[18:21]
	v_mfma_f32_16x16x32_bf16 v[6:9], v[170:173], v[222:225], v[6:9]
	v_mfma_f32_16x16x32_bf16 v[2:5], v[178:181], v[222:225], v[2:5]
	s_barrier
	s_add_i32 s25, s25, 2
	s_add_u32 s5, s5, 0x100
	s_addc_u32 s24, s24, 0
	s_cmpk_lt_u32 s25, 0x56
	s_mov_b64 s[18:19], s[20:21]
	s_cbranch_scc1 .LBB0_1926
	s_setprio 0
	s_andn2_b64 vcc, exec, s[14:15]
	s_cbranch_vccnz .LBB0_1929
	s_barrier

;     __device__ bool next(int i, Unit& u) const { if (i != 0 || c >= 128) return false; const int t = c >> 2; u.pm = t & 3; u.pn = t >> 2; u.koff = koff_bytes; u.q = c & 3; return true; }
; #define PG8_STAGE(bufoff, gbase, voff) do { _Pragma("unroll") for (int _i = 0; _i < 2; ++_i) \
;         __builtin_amdgcn_global_load_lds((const unsigned*)((const char*)(gbase) + (voff)[_i]), (LAS unsigned*)(lds + (bufoff) + ldsw + _i * 8192), 16, 0, 0); } while (0)
; #define PG8_LDA(dst, b, h) do { _Pragma("unroll") for (int m = 0; m < 4; ++m) _Pragma("unroll") for (int k = 0; k < 2; ++k) dst[m][k] = *(const LAS bf16x8*)(lds + PG8_SA(b, h) + aoff + m * 2048 + k * 1024); } while (0)
; #define PG8_LDB(dst, b, h) do { _Pragma("unroll") for (int n = 0; n < 2; ++n) _Pragma("unroll") for (int k = 0; k < 2; ++k) dst[n][k] = *(const LAS bf16x8*)(lds + PG8_SB(b, h) + boff + n * 2048 + k * 1024); } while (0)
; #define PG8_MMA(ai, bj, At, Bt) do { __builtin_amdgcn_s_setprio(1); _Pragma("unroll") for (int m = 0; m < 4; ++m) _Pragma("unroll") for (int n = 0; n < 2; ++n) _Pragma("unroll") for (int k = 0; k < 2; ++k) \
;         acc[ai][bj][m][n] = __builtin_amdgcn_mfma_f32_16x16x32_bf16(Bt[n][k], At[m][k], acc[ai][bj][m][n], 0, 0, 0); __builtin_amdgcn_s_setprio(0); } while (0)
; #define PG8_WAIT_V(n) asm volatile("s_waitcnt vmcnt(" #n ")" ::: "memory")
; #define PG8_BAR __builtin_amdgcn_s_barrier()
; template <class Epi, class Sched, bool ALIGN_EPI = false, bool SP2 = false>
; __device__ __forceinline__ void gemm_phase(LAS unsigned char* lds, const Gemm g, const Sched& S, const Epi& E) {
;     ...
;         const bool has_next = S.next(ui + 1, nxt);
;         const char* nA = has_next ? (const char*)g.A + (size_t)nxt.pm * tstep + nxt.koff : cA; const char* nB = has_next ? (const char*)g.Bt + (size_t)nxt.pn * tstep + nxt.koff : cB;
;     ...
;             if constexpr (SP2) {
;             PG8_LDB(B0, 0, 0); PG8_LDB(B1, 0, 1); PG8_SCHED; PG8_LDA(At, 0, 0); PG8_STAGE(PG8_SA(1, 1), a1 + hstep, voffA);
;             PG8_WAIT_V(8); PG8_WAIT_L(0); PG8_BAR; PG8_MMA(0, 0, At, B0); PG8_MMA(0, 1, At, B1); PG8_BAR; PG8_SCHED;
;             PG8_LDA(At, 0, 1); PG8_STAGE(PG8_SB(0, 0), b2, voffB); PG8_STAGE(PG8_SB(0, 1), b2 + hstepB, voffB); PG8_STAGE(PG8_SA(0, 0), a2, voffA);
;             PG8_WAIT_V(8); PG8_WAIT_L(0); PG8_BAR; PG8_MMA(1, 0, At, B0); PG8_MMA(1, 1, At, B1); PG8_BAR; PG8_SCHED;
.LBB0_2142:
	s_ashr_i32 s13, s12, 31
	v_cmp_lt_i64_e64 s[44:45], s[14:15], v[176:177]
	s_lshl_b64 s[14:15], s[12:13], 20
	s_add_u32 s14, s93, s14
	s_addc_u32 s15, s92, s15
	s_and_b64 s[16:17], s[44:45], exec
	s_cselect_b32 s3, s15, s23
	s_cselect_b32 s13, s14, s22
	s_ashr_i32 s11, s10, 31
	s_lshl_b64 s[16:17], s[10:11], 20
	v_readlane_b32 s24, v254, 58
	v_readlane_b32 s25, v254, 59
	s_add_u32 s16, s24, s16
	s_addc_u32 s17, s25, s17
	s_and_b64 s[24:25], s[44:45], exec
	s_cselect_b32 s11, s17, s21
	s_cselect_b32 s19, s16, s20
	s_add_u32 s24, s20, 0x100
	s_addc_u32 s25, s21, 0
	s_add_u32 s20, s22, 0x80080
	s_addc_u32 s21, s23, 0
	s_mov_b32 s34, -2
	s_waitcnt vmcnt(0)
	v_readfirstlane_b32 s98, v0
	s_nop 3
	s_lshr_b32 s98, s98, 6
	s_cmp_ge_u32 s98, 4
	s_cbranch_scc0 .Lprio_2143
	s_setprio 1
.Lprio_2143:
	ds_read_b128 v[34:37], v202
	ds_read_b128 v[38:41], v202 offset:1024
	ds_read_b128 v[42:45], v202 offset:2048
	ds_read_b128 v[46:49], v202 offset:3072
	ds_read_b128 v[98:101], v203
	ds_read_b128 v[102:105], v203 offset:1024
	ds_read_b128 v[106:109], v203 offset:2048
	ds_read_b128 v[110:113], v203 offset:3072
	s_add_u32 s22, s20, 0xfff80080
	s_addc_u32 s23, s21, -1
	s_cmp_eq_u32 s34, 28
	s_cselect_b32 s37, s3, s23
	s_cselect_b32 s36, s13, s22
	s_cselect_b32 s23, s11, s25
	s_cselect_b32 s22, s19, s24
	v_lshl_add_u64 v[182:183], s[20:21], 0, v[174:175]
	s_add_i32 m0, s28, 0xc000
	ds_read_b128 v[210:213], v204
	ds_read_b128 v[214:217], v204 offset:1024
	ds_read_b128 v[218:221], v204 offset:2048
	ds_read_b128 v[222:225], v204 offset:3072
	ds_read_b128 v[226:229], v204 offset:4096
	ds_read_b128 v[230:233], v204 offset:5120
	ds_read_b128 v[234:237], v204 offset:6144
	ds_read_b128 v[238:241], v204 offset:7168
	global_load_lds_dwordx4 v[182:183], off
	v_lshl_add_u64 v[182:183], s[20:21], 0, v[172:173]
	s_add_i32 m0, s28, 0xe000
	s_nop 0
	global_load_lds_dwordx4 v[182:183], off
	s_waitcnt lgkmcnt(0)
	s_barrier
	s_waitcnt lgkmcnt(0)
	v_mfma_f32_16x16x32_bf16 v[158:161], v[34:37], v[210:213], 0
	v_mfma_f32_16x16x32_bf16 v[154:157], v[42:45], v[210:213], 0
	v_mfma_f32_16x16x32_bf16 v[142:145], v[34:37], v[218:221], 0
	v_mfma_f32_16x16x32_bf16 v[138:141], v[42:45], v[218:221], 0
	v_mfma_f32_16x16x32_bf16 v[126:129], v[34:37], v[226:229], 0
	v_mfma_f32_16x16x32_bf16 v[122:125], v[42:45], v[226:229], 0
	v_mfma_f32_16x16x32_bf16 v[94:97], v[34:37], v[234:237], 0
	v_mfma_f32_16x16x32_bf16 v[90:93], v[42:45], v[234:237], 0
	v_mfma_f32_16x16x32_bf16 v[158:161], v[38:41], v[214:217], v[158:161]
	v_mfma_f32_16x16x32_bf16 v[154:157], v[46:49], v[214:217], v[154:157]
	v_mfma_f32_16x16x32_bf16 v[142:145], v[38:41], v[222:225], v[142:145]
	v_mfma_f32_16x16x32_bf16 v[138:141], v[46:49], v[222:225], v[138:141]
	v_mfma_f32_16x16x32_bf16 v[126:129], v[38:41], v[230:233], v[126:129]
	v_mfma_f32_16x16x32_bf16 v[122:125], v[46:49], v[230:233], v[122:125]
	v_mfma_f32_16x16x32_bf16 v[94:97], v[38:41], v[238:241], v[94:97]
	v_mfma_f32_16x16x32_bf16 v[90:93], v[46:49], v[238:241], v[90:93]
	v_mfma_f32_16x16x32_bf16 v[150:153], v[98:101], v[210:213], 0
	v_mfma_f32_16x16x32_bf16 v[146:149], v[106:109], v[210:213], 0
	v_mfma_f32_16x16x32_bf16 v[134:137], v[98:101], v[218:221], 0
	v_mfma_f32_16x16x32_bf16 v[130:133], v[106:109], v[218:221], 0
	v_mfma_f32_16x16x32_bf16 v[118:121], v[98:101], v[226:229], 0
	v_mfma_f32_16x16x32_bf16 v[114:117], v[106:109], v[226:229], 0
	v_mfma_f32_16x16x32_bf16 v[86:89], v[98:101], v[234:237], 0
	v_mfma_f32_16x16x32_bf16 v[82:85], v[106:109], v[234:237], 0
	v_mfma_f32_16x16x32_bf16 v[150:153], v[102:105], v[214:217], v[150:153]
	v_mfma_f32_16x16x32_bf16 v[146:149], v[110:113], v[214:217], v[146:149]
	v_mfma_f32_16x16x32_bf16 v[134:137], v[102:105], v[222:225], v[134:137]
	v_mfma_f32_16x16x32_bf16 v[130:133], v[110:113], v[222:225], v[130:133]
	v_mfma_f32_16x16x32_bf16 v[118:121], v[102:105], v[230:233], v[118:121]
	v_mfma_f32_16x16x32_bf16 v[114:117], v[110:113], v[230:233], v[114:117]
	v_mfma_f32_16x16x32_bf16 v[86:89], v[102:105], v[238:241], v[86:89]
	v_mfma_f32_16x16x32_bf16 v[82:85], v[110:113], v[238:241], v[82:85]
	s_barrier
	s_add_i32 s35, s56, s27
	v_lshl_add_u64 v[182:183], s[22:23], 0, v[164:165]
	s_mov_b32 m0, s35
	ds_read_b128 v[210:213], v204 offset:16384
	ds_read_b128 v[214:217], v204 offset:17408
	ds_read_b128 v[218:221], v204 offset:18432
	ds_read_b128 v[222:225], v204 offset:19456
	ds_read_b128 v[226:229], v204 offset:20480
	ds_read_b128 v[230:233], v204 offset:21504
	ds_read_b128 v[234:237], v204 offset:22528
	ds_read_b128 v[238:241], v204 offset:23552
	global_load_lds_dwordx4 v[182:183], off
	s_add_i32 m0, s35, 0x2000
	s_add_u32 s46, s22, 0x20000
	v_lshl_add_u64 v[242:243], s[22:23], 0, v[168:169]
	s_addc_u32 s47, s23, 0
	s_add_i32 s35, s57, s27
	global_load_lds_dwordx4 v[242:243], off
	v_lshl_add_u64 v[244:245], s[46:47], 0, v[164:165]
	s_mov_b32 m0, s35
	v_lshl_add_u64 v[246:247], s[36:37], 0, v[166:167]
	global_load_lds_dwordx4 v[244:245], off
	v_lshl_add_u64 v[244:245], s[46:47], 0, v[168:169]
	s_add_i32 m0, s35, 0x2000
	s_nop 0
	global_load_lds_dwordx4 v[244:245], off
	v_lshl_add_u64 v[244:245], s[36:37], 0, v[162:163]
	s_mov_b32 m0, s28
	s_nop 0
	global_load_lds_dwordx4 v[244:245], off
	s_mov_b32 m0, s29
	s_nop 0
	global_load_lds_dwordx4 v[246:247], off
	s_waitcnt lgkmcnt(0)
	s_barrier
; #define PG8_STAGE(bufoff, gbase, voff) do { _Pragma("unroll") for (int _i = 0; _i < 2; ++_i) \
;         __builtin_amdgcn_global_load_lds((const unsigned*)((const char*)(gbase) + (voff)[_i]), (LAS unsigned*)(lds + (bufoff) + ldsw + _i * 8192), 16, 0, 0); } while (0)
; #define PG8_LDA(dst, b, h) do { _Pragma("unroll") for (int m = 0; m < 4; ++m) _Pragma("unroll") for (int k = 0; k < 2; ++k) dst[m][k] = *(const LAS bf16x8*)(lds + PG8_SA(b, h) + aoff + m * 2048 + k * 1024); } while (0)
; #define PG8_LDB(dst, b, h) do { _Pragma("unroll") for (int n = 0; n < 2; ++n) _Pragma("unroll") for (int k = 0; k < 2; ++k) dst[n][k] = *(const LAS bf16x8*)(lds + PG8_SB(b, h) + boff + n * 2048 + k * 1024); } while (0)
; #define PG8_MMA(ai, bj, At, Bt) do { __builtin_amdgcn_s_setprio(1); _Pragma("unroll") for (int m = 0; m < 4; ++m) _Pragma("unroll") for (int n = 0; n < 2; ++n) _Pragma("unroll") for (int k = 0; k < 2; ++k) \
;         acc[ai][bj][m][n] = __builtin_amdgcn_mfma_f32_16x16x32_bf16(Bt[n][k], At[m][k], acc[ai][bj][m][n], 0, 0, 0); __builtin_amdgcn_s_setprio(0); } while (0)
; #define PG8_WAIT_V(n) asm volatile("s_waitcnt vmcnt(" #n ")" ::: "memory")
; #define PG8_WAIT_L(n) asm volatile("s_waitcnt lgkmcnt(" #n ")" ::: "memory")
; #define PG8_BAR __builtin_amdgcn_s_barrier()
; #define PG8_SCHED __builtin_amdgcn_sched_barrier(0)
; template <class Epi, class Sched, bool ALIGN_EPI = false, bool SP2 = false>
; __device__ __forceinline__ void gemm_phase(LAS unsigned char* lds, const Gemm g, const Sched& S, const Epi& E) {
;     ...
;             PG8_WAIT_V(8); PG8_WAIT_L(0); PG8_BAR; PG8_MMA(1, 0, At, B0); PG8_MMA(1, 1, At, B1); PG8_BAR; PG8_SCHED;
;             PG8_LDB(B0, 1, 0); PG8_LDB(B1, 1, 1); PG8_SCHED; PG8_LDA(At, 1, 0); PG8_STAGE(PG8_SA(0, 1), a2 + hstep, voffA);
;             PG8_WAIT_V(8); PG8_WAIT_L(0); PG8_BAR; PG8_MMA(0, 0, At, B0); PG8_MMA(0, 1, At, B1); PG8_BAR; PG8_SCHED;
	s_waitcnt lgkmcnt(0)
	v_mfma_f32_16x16x32_bf16 v[78:81], v[34:37], v[210:213], 0
	v_mfma_f32_16x16x32_bf16 v[74:77], v[42:45], v[210:213], 0
	v_mfma_f32_16x16x32_bf16 v[62:65], v[34:37], v[218:221], 0
	v_mfma_f32_16x16x32_bf16 v[58:61], v[42:45], v[218:221], 0
	v_mfma_f32_16x16x32_bf16 v[30:33], v[34:37], v[226:229], 0
	v_mfma_f32_16x16x32_bf16 v[26:29], v[42:45], v[226:229], 0
	v_mfma_f32_16x16x32_bf16 v[14:17], v[34:37], v[234:237], 0
	v_mfma_f32_16x16x32_bf16 v[10:13], v[42:45], v[234:237], 0
	v_mfma_f32_16x16x32_bf16 v[78:81], v[38:41], v[214:217], v[78:81]
	v_mfma_f32_16x16x32_bf16 v[74:77], v[46:49], v[214:217], v[74:77]
	v_mfma_f32_16x16x32_bf16 v[62:65], v[38:41], v[222:225], v[62:65]
	v_mfma_f32_16x16x32_bf16 v[58:61], v[46:49], v[222:225], v[58:61]
	v_mfma_f32_16x16x32_bf16 v[30:33], v[38:41], v[230:233], v[30:33]
	v_mfma_f32_16x16x32_bf16 v[26:29], v[46:49], v[230:233], v[26:29]
	v_mfma_f32_16x16x32_bf16 v[14:17], v[38:41], v[238:241], v[14:17]
	v_mfma_f32_16x16x32_bf16 v[10:13], v[46:49], v[238:241], v[10:13]
	v_mfma_f32_16x16x32_bf16 v[22:25], v[98:101], v[226:229], 0
	v_mfma_f32_16x16x32_bf16 v[18:21], v[106:109], v[226:229], 0
	v_mfma_f32_16x16x32_bf16 v[6:9], v[98:101], v[234:237], 0
	v_mfma_f32_16x16x32_bf16 v[2:5], v[106:109], v[234:237], 0
	v_mfma_f32_16x16x32_bf16 v[34:37], v[98:101], v[210:213], 0
	v_mfma_f32_16x16x32_bf16 v[38:41], v[106:109], v[210:213], 0
	v_mfma_f32_16x16x32_bf16 v[42:45], v[98:101], v[218:221], 0
	v_mfma_f32_16x16x32_bf16 v[46:49], v[106:109], v[218:221], 0
	v_mfma_f32_16x16x32_bf16 v[22:25], v[102:105], v[230:233], v[22:25]
	v_mfma_f32_16x16x32_bf16 v[18:21], v[110:113], v[230:233], v[18:21]
	v_mfma_f32_16x16x32_bf16 v[6:9], v[102:105], v[238:241], v[6:9]
	v_mfma_f32_16x16x32_bf16 v[2:5], v[110:113], v[238:241], v[2:5]
	v_mfma_f32_16x16x32_bf16 v[34:37], v[102:105], v[214:217], v[34:37]
	v_mfma_f32_16x16x32_bf16 v[38:41], v[110:113], v[214:217], v[38:41]
	v_mfma_f32_16x16x32_bf16 v[42:45], v[102:105], v[222:225], v[42:45]
	v_mfma_f32_16x16x32_bf16 v[46:49], v[110:113], v[222:225], v[46:49]
	s_barrier
	s_add_i32 s35, 0, 0x18000
	s_add_i32 s46, 0, 0x1c000
	v_add_u32_e32 v70, s35, v185
	v_add_u32_e32 v110, s46, v185
	ds_read_b128 v[50:53], v70
	ds_read_b128 v[54:57], v70 offset:1024
	ds_read_b128 v[66:69], v70 offset:2048
	ds_read_b128 v[70:73], v70 offset:3072
	ds_read_b128 v[98:101], v110
	ds_read_b128 v[102:105], v110 offset:1024
	ds_read_b128 v[106:109], v110 offset:2048
	ds_read_b128 v[110:113], v110 offset:3072
	s_add_u32 s36, s36, 0x80000
	s_addc_u32 s37, s37, 0
	s_mov_b32 m0, s30
	v_lshl_add_u64 v[248:249], s[36:37], 0, v[162:163]
	ds_read_b128 v[210:213], v204 offset:32768
	ds_read_b128 v[214:217], v204 offset:33792
	ds_read_b128 v[218:221], v204 offset:34816
	ds_read_b128 v[222:225], v204 offset:35840
	ds_read_b128 v[226:229], v204 offset:36864
	ds_read_b128 v[230:233], v204 offset:37888
	ds_read_b128 v[234:237], v204 offset:38912
	ds_read_b128 v[238:241], v204 offset:39936
	global_load_lds_dwordx4 v[248:249], off
	v_lshl_add_u64 v[248:249], s[36:37], 0, v[166:167]
	s_mov_b32 m0, s31
	s_nop 0
	global_load_lds_dwordx4 v[248:249], off
	s_waitcnt vmcnt(8)
	s_waitcnt lgkmcnt(0)
	s_barrier
	s_waitcnt lgkmcnt(0)
	v_mfma_f32_16x16x32_bf16 v[158:161], v[50:53], v[210:213], v[158:161]
	v_mfma_f32_16x16x32_bf16 v[154:157], v[66:69], v[210:213], v[154:157]
	v_mfma_f32_16x16x32_bf16 v[142:145], v[50:53], v[218:221], v[142:145]
	v_mfma_f32_16x16x32_bf16 v[138:141], v[66:69], v[218:221], v[138:141]
	v_mfma_f32_16x16x32_bf16 v[126:129], v[50:53], v[226:229], v[126:129]
	v_mfma_f32_16x16x32_bf16 v[122:125], v[66:69], v[226:229], v[122:125]
	v_mfma_f32_16x16x32_bf16 v[94:97], v[50:53], v[234:237], v[94:97]
	v_mfma_f32_16x16x32_bf16 v[90:93], v[66:69], v[234:237], v[90:93]
	v_mfma_f32_16x16x32_bf16 v[158:161], v[54:57], v[214:217], v[158:161]
	v_mfma_f32_16x16x32_bf16 v[154:157], v[70:73], v[214:217], v[154:157]
	v_mfma_f32_16x16x32_bf16 v[142:145], v[54:57], v[222:225], v[142:145]
	v_mfma_f32_16x16x32_bf16 v[138:141], v[70:73], v[222:225], v[138:141]
	v_mfma_f32_16x16x32_bf16 v[126:129], v[54:57], v[230:233], v[126:129]
	v_mfma_f32_16x16x32_bf16 v[122:125], v[70:73], v[230:233], v[122:125]
	v_mfma_f32_16x16x32_bf16 v[94:97], v[54:57], v[238:241], v[94:97]
	v_mfma_f32_16x16x32_bf16 v[90:93], v[70:73], v[238:241], v[90:93]
	v_mfma_f32_16x16x32_bf16 v[150:153], v[98:101], v[210:213], v[150:153]
	v_mfma_f32_16x16x32_bf16 v[146:149], v[106:109], v[210:213], v[146:149]
	v_mfma_f32_16x16x32_bf16 v[134:137], v[98:101], v[218:221], v[134:137]
	v_mfma_f32_16x16x32_bf16 v[130:133], v[106:109], v[218:221], v[130:133]
	v_mfma_f32_16x16x32_bf16 v[118:121], v[98:101], v[226:229], v[118:121]
	v_mfma_f32_16x16x32_bf16 v[114:117], v[106:109], v[226:229], v[114:117]
	v_mfma_f32_16x16x32_bf16 v[86:89], v[98:101], v[234:237], v[86:89]
	v_mfma_f32_16x16x32_bf16 v[82:85], v[106:109], v[234:237], v[82:85]
	v_mfma_f32_16x16x32_bf16 v[150:153], v[102:105], v[214:217], v[150:153]
	v_mfma_f32_16x16x32_bf16 v[146:149], v[110:113], v[214:217], v[146:149]
	v_mfma_f32_16x16x32_bf16 v[134:137], v[102:105], v[222:225], v[134:137]
	v_mfma_f32_16x16x32_bf16 v[130:133], v[110:113], v[222:225], v[130:133]
	v_mfma_f32_16x16x32_bf16 v[118:121], v[102:105], v[230:233], v[118:121]
	v_mfma_f32_16x16x32_bf16 v[114:117], v[110:113], v[230:233], v[114:117]
	v_mfma_f32_16x16x32_bf16 v[86:89], v[102:105], v[238:241], v[86:89]
	v_mfma_f32_16x16x32_bf16 v[82:85], v[110:113], v[238:241], v[82:85]
	s_barrier
; #define PG8_STAGE(bufoff, gbase, voff) do { _Pragma("unroll") for (int _i = 0; _i < 2; ++_i) \
;         __builtin_amdgcn_global_load_lds((const unsigned*)((const char*)(gbase) + (voff)[_i]), (LAS unsigned*)(lds + (bufoff) + ldsw + _i * 8192), 16, 0, 0); } while (0)
; #define PG8_LDA(dst, b, h) do { _Pragma("unroll") for (int m = 0; m < 4; ++m) _Pragma("unroll") for (int k = 0; k < 2; ++k) dst[m][k] = *(const LAS bf16x8*)(lds + PG8_SA(b, h) + aoff + m * 2048 + k * 1024); } while (0)
; #define PG8_LDB(dst, b, h) do { _Pragma("unroll") for (int n = 0; n < 2; ++n) _Pragma("unroll") for (int k = 0; k < 2; ++k) dst[n][k] = *(const LAS bf16x8*)(lds + PG8_SB(b, h) + boff + n * 2048 + k * 1024); } while (0)
; #define PG8_MMA(ai, bj, At, Bt) do { __builtin_amdgcn_s_setprio(1); _Pragma("unroll") for (int m = 0; m < 4; ++m) _Pragma("unroll") for (int n = 0; n < 2; ++n) _Pragma("unroll") for (int k = 0; k < 2; ++k) \
;         acc[ai][bj][m][n] = __builtin_amdgcn_mfma_f32_16x16x32_bf16(Bt[n][k], At[m][k], acc[ai][bj][m][n], 0, 0, 0); __builtin_amdgcn_s_setprio(0); } while (0)
; #define PG8_WAIT_V(n) asm volatile("s_waitcnt vmcnt(" #n ")" ::: "memory")
; #define PG8_WAIT_L(n) asm volatile("s_waitcnt lgkmcnt(" #n ")" ::: "memory")
; #define PG8_BAR __builtin_amdgcn_s_barrier()
; #define PG8_SCHED __builtin_amdgcn_sched_barrier(0)
; template <class Epi, class Sched, bool ALIGN_EPI = false, bool SP2 = false>
; __device__ __forceinline__ void gemm_phase(LAS unsigned char* lds, const Gemm g, const Sched& S, const Epi& E) {
;     ...
;         for (int t = 0; t < nt; t += 2) {
;             const bool last = (t == nt - 2);
;             const char* a1 = cA + (size_t)(t + 1) * kstep;
;             const char* a2 = last ? nA : cA + (size_t)(t + 2) * kstep; const char* b2 = last ? nB : cB + (size_t)(t + 2) * kstep;
;             const char* a3 = a2 + kstep; const char* b3 = b2 + kstep;
;             if (last && has_next) S.a_ready(nxt);
;             if constexpr (SP2) {
;             PG8_LDB(B0, 0, 0); PG8_LDB(B1, 0, 1); PG8_SCHED; PG8_LDA(At, 0, 0); PG8_STAGE(PG8_SA(1, 1), a1 + hstep, voffA);
;     ...
;             PG8_LDA(At, 1, 1); PG8_STAGE(PG8_SB(1, 0), b3, voffB); PG8_STAGE(PG8_SB(1, 1), b3 + hstepB, voffB); PG8_STAGE(PG8_SA(1, 0), a3, voffA);
;             PG8_WAIT_V(8); PG8_WAIT_L(0); PG8_BAR; PG8_MMA(1, 0, At, B0); PG8_MMA(1, 1, At, B1); PG8_BAR; PG8_SCHED;
	s_add_i32 s35, s35, s27
	v_lshl_add_u64 v[182:183], v[182:183], 0, s[4:5]
	s_mov_b32 m0, s35
	ds_read_b128 v[210:213], v204 offset:49152
	ds_read_b128 v[214:217], v204 offset:50176
	ds_read_b128 v[218:221], v204 offset:51200
	ds_read_b128 v[222:225], v204 offset:52224
	ds_read_b128 v[226:229], v204 offset:53248
	ds_read_b128 v[230:233], v204 offset:54272
	ds_read_b128 v[234:237], v204 offset:55296
	ds_read_b128 v[238:241], v204 offset:56320
	global_load_lds_dwordx4 v[182:183], off
	s_add_i32 m0, s35, 0x2000
	s_add_u32 s22, s22, 0x20080
	v_lshl_add_u64 v[182:183], v[242:243], 0, s[4:5]
	s_addc_u32 s23, s23, 0
	s_add_i32 s35, s46, s27
	global_load_lds_dwordx4 v[182:183], off
	v_lshl_add_u64 v[182:183], s[22:23], 0, v[164:165]
	s_mov_b32 m0, s35
	s_nop 0
	global_load_lds_dwordx4 v[182:183], off
	v_lshl_add_u64 v[182:183], s[22:23], 0, v[168:169]
	s_add_i32 m0, s35, 0x2000
	s_nop 0
	global_load_lds_dwordx4 v[182:183], off
	v_lshl_add_u64 v[182:183], v[244:245], 0, s[4:5]
	s_mov_b32 m0, s53
	s_nop 0
	global_load_lds_dwordx4 v[182:183], off
	v_lshl_add_u64 v[182:183], v[246:247], 0, s[4:5]
	s_mov_b32 m0, s54
	s_nop 0
	global_load_lds_dwordx4 v[182:183], off
	s_waitcnt vmcnt(8)
	s_waitcnt lgkmcnt(0)
	s_barrier
	s_waitcnt lgkmcnt(0)
	v_mfma_f32_16x16x32_bf16 v[78:81], v[50:53], v[210:213], v[78:81]
	v_mfma_f32_16x16x32_bf16 v[74:77], v[66:69], v[210:213], v[74:77]
	v_mfma_f32_16x16x32_bf16 v[62:65], v[50:53], v[218:221], v[62:65]
	v_mfma_f32_16x16x32_bf16 v[58:61], v[66:69], v[218:221], v[58:61]
	v_mfma_f32_16x16x32_bf16 v[30:33], v[50:53], v[226:229], v[30:33]
	v_mfma_f32_16x16x32_bf16 v[26:29], v[66:69], v[226:229], v[26:29]
	v_mfma_f32_16x16x32_bf16 v[14:17], v[50:53], v[234:237], v[14:17]
	v_mfma_f32_16x16x32_bf16 v[10:13], v[66:69], v[234:237], v[10:13]
	v_mfma_f32_16x16x32_bf16 v[78:81], v[54:57], v[214:217], v[78:81]
	v_mfma_f32_16x16x32_bf16 v[74:77], v[70:73], v[214:217], v[74:77]
	v_mfma_f32_16x16x32_bf16 v[62:65], v[54:57], v[222:225], v[62:65]
	v_mfma_f32_16x16x32_bf16 v[58:61], v[70:73], v[222:225], v[58:61]
	v_mfma_f32_16x16x32_bf16 v[30:33], v[54:57], v[230:233], v[30:33]
	v_mfma_f32_16x16x32_bf16 v[26:29], v[70:73], v[230:233], v[26:29]
	v_mfma_f32_16x16x32_bf16 v[14:17], v[54:57], v[238:241], v[14:17]
	v_mfma_f32_16x16x32_bf16 v[10:13], v[70:73], v[238:241], v[10:13]
	v_mfma_f32_16x16x32_bf16 v[34:37], v[98:101], v[210:213], v[34:37]
	v_mfma_f32_16x16x32_bf16 v[70:73], v[102:105], v[214:217], v[34:37]
	v_mfma_f32_16x16x32_bf16 v[34:37], v[106:109], v[210:213], v[38:41]
	v_mfma_f32_16x16x32_bf16 v[66:69], v[110:113], v[214:217], v[34:37]
	v_mfma_f32_16x16x32_bf16 v[34:37], v[98:101], v[218:221], v[42:45]
	v_mfma_f32_16x16x32_bf16 v[54:57], v[102:105], v[222:225], v[34:37]
	v_mfma_f32_16x16x32_bf16 v[34:37], v[106:109], v[218:221], v[46:49]
	v_mfma_f32_16x16x32_bf16 v[22:25], v[98:101], v[226:229], v[22:25]
	v_mfma_f32_16x16x32_bf16 v[18:21], v[106:109], v[226:229], v[18:21]
	v_mfma_f32_16x16x32_bf16 v[6:9], v[98:101], v[234:237], v[6:9]
	v_mfma_f32_16x16x32_bf16 v[2:5], v[106:109], v[234:237], v[2:5]
	v_mfma_f32_16x16x32_bf16 v[50:53], v[110:113], v[222:225], v[34:37]
	v_mfma_f32_16x16x32_bf16 v[22:25], v[102:105], v[230:233], v[22:25]
	v_mfma_f32_16x16x32_bf16 v[18:21], v[110:113], v[230:233], v[18:21]
	v_mfma_f32_16x16x32_bf16 v[6:9], v[102:105], v[238:241], v[6:9]
	v_mfma_f32_16x16x32_bf16 v[2:5], v[110:113], v[238:241], v[2:5]
	s_barrier
	s_add_i32 s34, s34, 2
	s_add_u32 s24, s24, 0x100
	s_addc_u32 s25, s25, 0
	s_add_u32 s20, s20, 0x100
	s_addc_u32 s21, s21, 0
	s_cmp_lt_u32 s34, 30
.LBB0_2143:
	ds_read_b128 v[34:37], v202
	ds_read_b128 v[38:41], v202 offset:1024
	ds_read_b128 v[42:45], v202 offset:2048
	ds_read_b128 v[46:49], v202 offset:3072
	ds_read_b128 v[98:101], v203
	ds_read_b128 v[102:105], v203 offset:1024
	ds_read_b128 v[106:109], v203 offset:2048
	ds_read_b128 v[110:113], v203 offset:3072
	s_add_u32 s22, s20, 0xfff80080
	s_addc_u32 s23, s21, -1
	s_cmp_eq_u32 s34, 28
	s_cselect_b32 s37, s3, s23
	s_cselect_b32 s36, s13, s22
	s_cselect_b32 s23, s11, s25
	s_cselect_b32 s22, s19, s24
	v_lshl_add_u64 v[182:183], s[20:21], 0, v[174:175]
	s_add_i32 m0, s28, 0xc000
	ds_read_b128 v[210:213], v204
	ds_read_b128 v[214:217], v204 offset:1024
	ds_read_b128 v[218:221], v204 offset:2048
	ds_read_b128 v[222:225], v204 offset:3072
	ds_read_b128 v[226:229], v204 offset:4096
	ds_read_b128 v[230:233], v204 offset:5120
	ds_read_b128 v[234:237], v204 offset:6144
	ds_read_b128 v[238:241], v204 offset:7168
	global_load_lds_dwordx4 v[182:183], off
	v_lshl_add_u64 v[182:183], s[20:21], 0, v[172:173]
	s_add_i32 m0, s28, 0xe000
	s_nop 0
	global_load_lds_dwordx4 v[182:183], off
	s_waitcnt vmcnt(8)
	s_waitcnt lgkmcnt(0)
	s_barrier
; #define PG8_STAGE(bufoff, gbase, voff) do { _Pragma("unroll") for (int _i = 0; _i < 2; ++_i) \
;         __builtin_amdgcn_global_load_lds((const unsigned*)((const char*)(gbase) + (voff)[_i]), (LAS unsigned*)(lds + (bufoff) + ldsw + _i * 8192), 16, 0, 0); } while (0)
; #define PG8_LDA(dst, b, h) do { _Pragma("unroll") for (int m = 0; m < 4; ++m) _Pragma("unroll") for (int k = 0; k < 2; ++k) dst[m][k] = *(const LAS bf16x8*)(lds + PG8_SA(b, h) + aoff + m * 2048 + k * 1024); } while (0)
; #define PG8_LDB(dst, b, h) do { _Pragma("unroll") for (int n = 0; n < 2; ++n) _Pragma("unroll") for (int k = 0; k < 2; ++k) dst[n][k] = *(const LAS bf16x8*)(lds + PG8_SB(b, h) + boff + n * 2048 + k * 1024); } while (0)
; #define PG8_MMA(ai, bj, At, Bt) do { __builtin_amdgcn_s_setprio(1); _Pragma("unroll") for (int m = 0; m < 4; ++m) _Pragma("unroll") for (int n = 0; n < 2; ++n) _Pragma("unroll") for (int k = 0; k < 2; ++k) \
;         acc[ai][bj][m][n] = __builtin_amdgcn_mfma_f32_16x16x32_bf16(Bt[n][k], At[m][k], acc[ai][bj][m][n], 0, 0, 0); __builtin_amdgcn_s_setprio(0); } while (0)
; #define PG8_WAIT_V(n) asm volatile("s_waitcnt vmcnt(" #n ")" ::: "memory")
; #define PG8_WAIT_L(n) asm volatile("s_waitcnt lgkmcnt(" #n ")" ::: "memory")
; #define PG8_BAR __builtin_amdgcn_s_barrier()
; #define PG8_SCHED __builtin_amdgcn_sched_barrier(0)
; template <class Epi, class Sched, bool ALIGN_EPI = false, bool SP2 = false>
; __device__ __forceinline__ void gemm_phase(LAS unsigned char* lds, const Gemm g, const Sched& S, const Epi& E) {
;     ...
;             PG8_WAIT_V(8); PG8_WAIT_L(0); PG8_BAR; PG8_MMA(0, 0, At, B0); PG8_MMA(0, 1, At, B1); PG8_BAR; PG8_SCHED;
;             PG8_LDA(At, 0, 1); PG8_STAGE(PG8_SB(0, 0), b2, voffB); PG8_STAGE(PG8_SB(0, 1), b2 + hstepB, voffB); PG8_STAGE(PG8_SA(0, 0), a2, voffA);
;             PG8_WAIT_V(8); PG8_WAIT_L(0); PG8_BAR; PG8_MMA(1, 0, At, B0); PG8_MMA(1, 1, At, B1); PG8_BAR; PG8_SCHED;
;             PG8_LDB(B0, 1, 0); PG8_LDB(B1, 1, 1); PG8_SCHED; PG8_LDA(At, 1, 0); PG8_STAGE(PG8_SA(0, 1), a2 + hstep, voffA);
;             PG8_WAIT_V(8); PG8_WAIT_L(0); PG8_BAR; PG8_MMA(0, 0, At, B0); PG8_MMA(0, 1, At, B1); PG8_BAR; PG8_SCHED;
	s_waitcnt lgkmcnt(0)
	v_mfma_f32_16x16x32_bf16 v[158:161], v[34:37], v[210:213], v[158:161]
	v_mfma_f32_16x16x32_bf16 v[154:157], v[42:45], v[210:213], v[154:157]
	v_mfma_f32_16x16x32_bf16 v[142:145], v[34:37], v[218:221], v[142:145]
	v_mfma_f32_16x16x32_bf16 v[138:141], v[42:45], v[218:221], v[138:141]
	v_mfma_f32_16x16x32_bf16 v[126:129], v[34:37], v[226:229], v[126:129]
	v_mfma_f32_16x16x32_bf16 v[122:125], v[42:45], v[226:229], v[122:125]
	v_mfma_f32_16x16x32_bf16 v[94:97], v[34:37], v[234:237], v[94:97]
	v_mfma_f32_16x16x32_bf16 v[90:93], v[42:45], v[234:237], v[90:93]
	v_mfma_f32_16x16x32_bf16 v[158:161], v[38:41], v[214:217], v[158:161]
	v_mfma_f32_16x16x32_bf16 v[154:157], v[46:49], v[214:217], v[154:157]
	v_mfma_f32_16x16x32_bf16 v[142:145], v[38:41], v[222:225], v[142:145]
	v_mfma_f32_16x16x32_bf16 v[138:141], v[46:49], v[222:225], v[138:141]
	v_mfma_f32_16x16x32_bf16 v[126:129], v[38:41], v[230:233], v[126:129]
	v_mfma_f32_16x16x32_bf16 v[122:125], v[46:49], v[230:233], v[122:125]
	v_mfma_f32_16x16x32_bf16 v[94:97], v[38:41], v[238:241], v[94:97]
	v_mfma_f32_16x16x32_bf16 v[90:93], v[46:49], v[238:241], v[90:93]
	v_mfma_f32_16x16x32_bf16 v[150:153], v[98:101], v[210:213], v[150:153]
	v_mfma_f32_16x16x32_bf16 v[146:149], v[106:109], v[210:213], v[146:149]
	v_mfma_f32_16x16x32_bf16 v[134:137], v[98:101], v[218:221], v[134:137]
	v_mfma_f32_16x16x32_bf16 v[130:133], v[106:109], v[218:221], v[130:133]
	v_mfma_f32_16x16x32_bf16 v[118:121], v[98:101], v[226:229], v[118:121]
	v_mfma_f32_16x16x32_bf16 v[114:117], v[106:109], v[226:229], v[114:117]
	v_mfma_f32_16x16x32_bf16 v[86:89], v[98:101], v[234:237], v[86:89]
	v_mfma_f32_16x16x32_bf16 v[82:85], v[106:109], v[234:237], v[82:85]
	v_mfma_f32_16x16x32_bf16 v[150:153], v[102:105], v[214:217], v[150:153]
	v_mfma_f32_16x16x32_bf16 v[146:149], v[110:113], v[214:217], v[146:149]
	v_mfma_f32_16x16x32_bf16 v[134:137], v[102:105], v[222:225], v[134:137]
	v_mfma_f32_16x16x32_bf16 v[130:133], v[110:113], v[222:225], v[130:133]
	v_mfma_f32_16x16x32_bf16 v[118:121], v[102:105], v[230:233], v[118:121]
	v_mfma_f32_16x16x32_bf16 v[114:117], v[110:113], v[230:233], v[114:117]
	v_mfma_f32_16x16x32_bf16 v[86:89], v[102:105], v[238:241], v[86:89]
	v_mfma_f32_16x16x32_bf16 v[82:85], v[110:113], v[238:241], v[82:85]
	s_barrier
	s_add_i32 s35, s56, s27
	v_lshl_add_u64 v[182:183], s[22:23], 0, v[164:165]
	s_mov_b32 m0, s35
	ds_read_b128 v[210:213], v204 offset:16384
	ds_read_b128 v[214:217], v204 offset:17408
	ds_read_b128 v[218:221], v204 offset:18432
	ds_read_b128 v[222:225], v204 offset:19456
	ds_read_b128 v[226:229], v204 offset:20480
	ds_read_b128 v[230:233], v204 offset:21504
	ds_read_b128 v[234:237], v204 offset:22528
	ds_read_b128 v[238:241], v204 offset:23552
	global_load_lds_dwordx4 v[182:183], off
	s_add_i32 m0, s35, 0x2000
	s_add_u32 s46, s22, 0x20000
	v_lshl_add_u64 v[242:243], s[22:23], 0, v[168:169]
	s_addc_u32 s47, s23, 0
	s_add_i32 s35, s57, s27
	global_load_lds_dwordx4 v[242:243], off
	v_lshl_add_u64 v[244:245], s[46:47], 0, v[164:165]
	s_mov_b32 m0, s35
	v_lshl_add_u64 v[246:247], s[36:37], 0, v[166:167]
	global_load_lds_dwordx4 v[244:245], off
	v_lshl_add_u64 v[244:245], s[46:47], 0, v[168:169]
	s_add_i32 m0, s35, 0x2000
	s_nop 0
	global_load_lds_dwordx4 v[244:245], off
	v_lshl_add_u64 v[244:245], s[36:37], 0, v[162:163]
	s_mov_b32 m0, s28
	s_nop 0
	global_load_lds_dwordx4 v[244:245], off
	s_mov_b32 m0, s29
	s_nop 0
	global_load_lds_dwordx4 v[246:247], off
	s_waitcnt vmcnt(8)
	s_waitcnt lgkmcnt(0)
	s_barrier
	s_waitcnt lgkmcnt(0)
	v_mfma_f32_16x16x32_bf16 v[78:81], v[34:37], v[210:213], v[78:81]
	v_mfma_f32_16x16x32_bf16 v[74:77], v[42:45], v[210:213], v[74:77]
	v_mfma_f32_16x16x32_bf16 v[62:65], v[34:37], v[218:221], v[62:65]
	v_mfma_f32_16x16x32_bf16 v[58:61], v[42:45], v[218:221], v[58:61]
	v_mfma_f32_16x16x32_bf16 v[30:33], v[34:37], v[226:229], v[30:33]
	v_mfma_f32_16x16x32_bf16 v[26:29], v[42:45], v[226:229], v[26:29]
	v_mfma_f32_16x16x32_bf16 v[14:17], v[34:37], v[234:237], v[14:17]
	v_mfma_f32_16x16x32_bf16 v[10:13], v[42:45], v[234:237], v[10:13]
	v_mfma_f32_16x16x32_bf16 v[78:81], v[38:41], v[214:217], v[78:81]
	v_mfma_f32_16x16x32_bf16 v[74:77], v[46:49], v[214:217], v[74:77]
	v_mfma_f32_16x16x32_bf16 v[62:65], v[38:41], v[222:225], v[62:65]
	v_mfma_f32_16x16x32_bf16 v[58:61], v[46:49], v[222:225], v[58:61]
	v_mfma_f32_16x16x32_bf16 v[30:33], v[38:41], v[230:233], v[30:33]
	v_mfma_f32_16x16x32_bf16 v[26:29], v[46:49], v[230:233], v[26:29]
	v_mfma_f32_16x16x32_bf16 v[14:17], v[38:41], v[238:241], v[14:17]
	v_mfma_f32_16x16x32_bf16 v[10:13], v[46:49], v[238:241], v[10:13]
	v_mfma_f32_16x16x32_bf16 v[22:25], v[98:101], v[226:229], v[22:25]
	v_mfma_f32_16x16x32_bf16 v[18:21], v[106:109], v[226:229], v[18:21]
	v_mfma_f32_16x16x32_bf16 v[6:9], v[98:101], v[234:237], v[6:9]
	v_mfma_f32_16x16x32_bf16 v[2:5], v[106:109], v[234:237], v[2:5]
	v_mfma_f32_16x16x32_bf16 v[34:37], v[98:101], v[210:213], v[70:73]
	v_mfma_f32_16x16x32_bf16 v[38:41], v[106:109], v[210:213], v[66:69]
	v_mfma_f32_16x16x32_bf16 v[42:45], v[98:101], v[218:221], v[54:57]
	v_mfma_f32_16x16x32_bf16 v[46:49], v[106:109], v[218:221], v[50:53]
	v_mfma_f32_16x16x32_bf16 v[22:25], v[102:105], v[230:233], v[22:25]
	v_mfma_f32_16x16x32_bf16 v[18:21], v[110:113], v[230:233], v[18:21]
	v_mfma_f32_16x16x32_bf16 v[6:9], v[102:105], v[238:241], v[6:9]
	v_mfma_f32_16x16x32_bf16 v[2:5], v[110:113], v[238:241], v[2:5]
	v_mfma_f32_16x16x32_bf16 v[34:37], v[102:105], v[214:217], v[34:37]
	v_mfma_f32_16x16x32_bf16 v[38:41], v[110:113], v[214:217], v[38:41]
	v_mfma_f32_16x16x32_bf16 v[42:45], v[102:105], v[222:225], v[42:45]
	v_mfma_f32_16x16x32_bf16 v[46:49], v[110:113], v[222:225], v[46:49]
	s_barrier
; #define PG8_STAGE(bufoff, gbase, voff) do { _Pragma("unroll") for (int _i = 0; _i < 2; ++_i) \
;         __builtin_amdgcn_global_load_lds((const unsigned*)((const char*)(gbase) + (voff)[_i]), (LAS unsigned*)(lds + (bufoff) + ldsw + _i * 8192), 16, 0, 0); } while (0)
; #define PG8_LDA(dst, b, h) do { _Pragma("unroll") for (int m = 0; m < 4; ++m) _Pragma("unroll") for (int k = 0; k < 2; ++k) dst[m][k] = *(const LAS bf16x8*)(lds + PG8_SA(b, h) + aoff + m * 2048 + k * 1024); } while (0)
; #define PG8_LDB(dst, b, h) do { _Pragma("unroll") for (int n = 0; n < 2; ++n) _Pragma("unroll") for (int k = 0; k < 2; ++k) dst[n][k] = *(const LAS bf16x8*)(lds + PG8_SB(b, h) + boff + n * 2048 + k * 1024); } while (0)
; #define PG8_MMA(ai, bj, At, Bt) do { __builtin_amdgcn_s_setprio(1); _Pragma("unroll") for (int m = 0; m < 4; ++m) _Pragma("unroll") for (int n = 0; n < 2; ++n) _Pragma("unroll") for (int k = 0; k < 2; ++k) \
;         acc[ai][bj][m][n] = __builtin_amdgcn_mfma_f32_16x16x32_bf16(Bt[n][k], At[m][k], acc[ai][bj][m][n], 0, 0, 0); __builtin_amdgcn_s_setprio(0); } while (0)
; #define PG8_WAIT_V(n) asm volatile("s_waitcnt vmcnt(" #n ")" ::: "memory")
; #define PG8_WAIT_L(n) asm volatile("s_waitcnt lgkmcnt(" #n ")" ::: "memory")
; #define PG8_BAR __builtin_amdgcn_s_barrier()
; #define PG8_SCHED __builtin_amdgcn_sched_barrier(0)
; template <class Epi, class Sched, bool ALIGN_EPI = false, bool SP2 = false>
; __device__ __forceinline__ void gemm_phase(LAS unsigned char* lds, const Gemm g, const Sched& S, const Epi& E) {
;     ...
;             PG8_LDB(B0, 1, 0); PG8_LDB(B1, 1, 1); PG8_SCHED; PG8_LDA(At, 1, 0); PG8_STAGE(PG8_SA(0, 1), a2 + hstep, voffA);
;             PG8_WAIT_V(8); PG8_WAIT_L(0); PG8_BAR; PG8_MMA(0, 0, At, B0); PG8_MMA(0, 1, At, B1); PG8_BAR; PG8_SCHED;
	s_add_i32 s35, 0, 0x18000
	s_add_i32 s46, 0, 0x1c000
	v_add_u32_e32 v70, s35, v185
	v_add_u32_e32 v110, s46, v185
	ds_read_b128 v[50:53], v70
	ds_read_b128 v[54:57], v70 offset:1024
	ds_read_b128 v[66:69], v70 offset:2048
	ds_read_b128 v[70:73], v70 offset:3072
	ds_read_b128 v[98:101], v110
	ds_read_b128 v[102:105], v110 offset:1024
	ds_read_b128 v[106:109], v110 offset:2048
	ds_read_b128 v[110:113], v110 offset:3072
	s_add_u32 s36, s36, 0x80000
	s_addc_u32 s37, s37, 0
	s_mov_b32 m0, s30
	v_lshl_add_u64 v[248:249], s[36:37], 0, v[162:163]
	ds_read_b128 v[210:213], v204 offset:32768
	ds_read_b128 v[214:217], v204 offset:33792
	ds_read_b128 v[218:221], v204 offset:34816
	ds_read_b128 v[222:225], v204 offset:35840
	ds_read_b128 v[226:229], v204 offset:36864
	ds_read_b128 v[230:233], v204 offset:37888
	ds_read_b128 v[234:237], v204 offset:38912
	ds_read_b128 v[238:241], v204 offset:39936
	global_load_lds_dwordx4 v[248:249], off
	v_lshl_add_u64 v[248:249], s[36:37], 0, v[166:167]
	s_mov_b32 m0, s31
	s_nop 0
	global_load_lds_dwordx4 v[248:249], off
	s_waitcnt vmcnt(8)
	s_waitcnt lgkmcnt(0)
	s_barrier
	s_waitcnt lgkmcnt(0)
	v_mfma_f32_16x16x32_bf16 v[158:161], v[50:53], v[210:213], v[158:161]
	v_mfma_f32_16x16x32_bf16 v[154:157], v[66:69], v[210:213], v[154:157]
	v_mfma_f32_16x16x32_bf16 v[142:145], v[50:53], v[218:221], v[142:145]
	v_mfma_f32_16x16x32_bf16 v[138:141], v[66:69], v[218:221], v[138:141]
	v_mfma_f32_16x16x32_bf16 v[126:129], v[50:53], v[226:229], v[126:129]
	v_mfma_f32_16x16x32_bf16 v[122:125], v[66:69], v[226:229], v[122:125]
	v_mfma_f32_16x16x32_bf16 v[94:97], v[50:53], v[234:237], v[94:97]
	v_mfma_f32_16x16x32_bf16 v[90:93], v[66:69], v[234:237], v[90:93]
	v_mfma_f32_16x16x32_bf16 v[158:161], v[54:57], v[214:217], v[158:161]
	v_mfma_f32_16x16x32_bf16 v[154:157], v[70:73], v[214:217], v[154:157]
	v_mfma_f32_16x16x32_bf16 v[142:145], v[54:57], v[222:225], v[142:145]
	v_mfma_f32_16x16x32_bf16 v[138:141], v[70:73], v[222:225], v[138:141]
	v_mfma_f32_16x16x32_bf16 v[126:129], v[54:57], v[230:233], v[126:129]
	v_mfma_f32_16x16x32_bf16 v[122:125], v[70:73], v[230:233], v[122:125]
	v_mfma_f32_16x16x32_bf16 v[94:97], v[54:57], v[238:241], v[94:97]
	v_mfma_f32_16x16x32_bf16 v[90:93], v[70:73], v[238:241], v[90:93]
	v_mfma_f32_16x16x32_bf16 v[150:153], v[98:101], v[210:213], v[150:153]
	v_mfma_f32_16x16x32_bf16 v[146:149], v[106:109], v[210:213], v[146:149]
	v_mfma_f32_16x16x32_bf16 v[134:137], v[98:101], v[218:221], v[134:137]
	v_mfma_f32_16x16x32_bf16 v[130:133], v[106:109], v[218:221], v[130:133]
	v_mfma_f32_16x16x32_bf16 v[118:121], v[98:101], v[226:229], v[118:121]
	v_mfma_f32_16x16x32_bf16 v[114:117], v[106:109], v[226:229], v[114:117]
	v_mfma_f32_16x16x32_bf16 v[86:89], v[98:101], v[234:237], v[86:89]
	v_mfma_f32_16x16x32_bf16 v[82:85], v[106:109], v[234:237], v[82:85]
	v_mfma_f32_16x16x32_bf16 v[150:153], v[102:105], v[214:217], v[150:153]
	v_mfma_f32_16x16x32_bf16 v[146:149], v[110:113], v[214:217], v[146:149]
	v_mfma_f32_16x16x32_bf16 v[134:137], v[102:105], v[222:225], v[134:137]
	v_mfma_f32_16x16x32_bf16 v[130:133], v[110:113], v[222:225], v[130:133]
	v_mfma_f32_16x16x32_bf16 v[118:121], v[102:105], v[230:233], v[118:121]
	v_mfma_f32_16x16x32_bf16 v[114:117], v[110:113], v[230:233], v[114:117]
	v_mfma_f32_16x16x32_bf16 v[86:89], v[102:105], v[238:241], v[86:89]
	v_mfma_f32_16x16x32_bf16 v[82:85], v[110:113], v[238:241], v[82:85]
	s_barrier
; #define PG8_STAGE(bufoff, gbase, voff) do { _Pragma("unroll") for (int _i = 0; _i < 2; ++_i) \
;         __builtin_amdgcn_global_load_lds((const unsigned*)((const char*)(gbase) + (voff)[_i]), (LAS unsigned*)(lds + (bufoff) + ldsw + _i * 8192), 16, 0, 0); } while (0)
; #define PG8_LDA(dst, b, h) do { _Pragma("unroll") for (int m = 0; m < 4; ++m) _Pragma("unroll") for (int k = 0; k < 2; ++k) dst[m][k] = *(const LAS bf16x8*)(lds + PG8_SA(b, h) + aoff + m * 2048 + k * 1024); } while (0)
; #define PG8_MMA(ai, bj, At, Bt) do { __builtin_amdgcn_s_setprio(1); _Pragma("unroll") for (int m = 0; m < 4; ++m) _Pragma("unroll") for (int n = 0; n < 2; ++n) _Pragma("unroll") for (int k = 0; k < 2; ++k) \
;         acc[ai][bj][m][n] = __builtin_amdgcn_mfma_f32_16x16x32_bf16(Bt[n][k], At[m][k], acc[ai][bj][m][n], 0, 0, 0); __builtin_amdgcn_s_setprio(0); } while (0)
; #define PG8_WAIT_V(n) asm volatile("s_waitcnt vmcnt(" #n ")" ::: "memory")
; #define PG8_WAIT_L(n) asm volatile("s_waitcnt lgkmcnt(" #n ")" ::: "memory")
; #define PG8_BAR __builtin_amdgcn_s_barrier()
; #define PG8_SCHED __builtin_amdgcn_sched_barrier(0)
; template <class Epi, class Sched, bool ALIGN_EPI = false, bool SP2 = false>
; __device__ __forceinline__ void gemm_phase(LAS unsigned char* lds, const Gemm g, const Sched& S, const Epi& E) {
;     ...
;             PG8_LDA(At, 1, 1); PG8_STAGE(PG8_SB(1, 0), b3, voffB); PG8_STAGE(PG8_SB(1, 1), b3 + hstepB, voffB); PG8_STAGE(PG8_SA(1, 0), a3, voffA);
;             PG8_WAIT_V(8); PG8_WAIT_L(0); PG8_BAR; PG8_MMA(1, 0, At, B0); PG8_MMA(1, 1, At, B1); PG8_BAR; PG8_SCHED;
;     ...
;         if constexpr (ALIGN_EPI) { if (wr == 0) PG8_BAR; }
	s_add_i32 s35, s35, s27
	v_lshl_add_u64 v[182:183], v[182:183], 0, s[4:5]
	s_mov_b32 m0, s35
	ds_read_b128 v[210:213], v204 offset:49152
	ds_read_b128 v[214:217], v204 offset:50176
	ds_read_b128 v[218:221], v204 offset:51200
	ds_read_b128 v[222:225], v204 offset:52224
	ds_read_b128 v[226:229], v204 offset:53248
	ds_read_b128 v[230:233], v204 offset:54272
	ds_read_b128 v[234:237], v204 offset:55296
	ds_read_b128 v[238:241], v204 offset:56320
	global_load_lds_dwordx4 v[182:183], off
	s_add_i32 m0, s35, 0x2000
	s_add_u32 s22, s22, 0x20080
	v_lshl_add_u64 v[182:183], v[242:243], 0, s[4:5]
	s_addc_u32 s23, s23, 0
	s_add_i32 s35, s46, s27
	global_load_lds_dwordx4 v[182:183], off
	v_lshl_add_u64 v[182:183], s[22:23], 0, v[164:165]
	s_mov_b32 m0, s35
	s_nop 0
	global_load_lds_dwordx4 v[182:183], off
	v_lshl_add_u64 v[182:183], s[22:23], 0, v[168:169]
	s_add_i32 m0, s35, 0x2000
	s_nop 0
	global_load_lds_dwordx4 v[182:183], off
	v_lshl_add_u64 v[182:183], v[244:245], 0, s[4:5]
	s_mov_b32 m0, s53
	s_nop 0
	global_load_lds_dwordx4 v[182:183], off
	v_lshl_add_u64 v[182:183], v[246:247], 0, s[4:5]
	s_mov_b32 m0, s54
	s_nop 0
	global_load_lds_dwordx4 v[182:183], off
	s_waitcnt vmcnt(8)
	s_waitcnt lgkmcnt(0)
	s_barrier
	s_waitcnt lgkmcnt(0)
	v_mfma_f32_16x16x32_bf16 v[78:81], v[50:53], v[210:213], v[78:81]
	v_mfma_f32_16x16x32_bf16 v[74:77], v[66:69], v[210:213], v[74:77]
	v_mfma_f32_16x16x32_bf16 v[62:65], v[50:53], v[218:221], v[62:65]
	v_mfma_f32_16x16x32_bf16 v[58:61], v[66:69], v[218:221], v[58:61]
	v_mfma_f32_16x16x32_bf16 v[30:33], v[50:53], v[226:229], v[30:33]
	v_mfma_f32_16x16x32_bf16 v[26:29], v[66:69], v[226:229], v[26:29]
	v_mfma_f32_16x16x32_bf16 v[14:17], v[50:53], v[234:237], v[14:17]
	v_mfma_f32_16x16x32_bf16 v[10:13], v[66:69], v[234:237], v[10:13]
	v_mfma_f32_16x16x32_bf16 v[78:81], v[54:57], v[214:217], v[78:81]
	v_mfma_f32_16x16x32_bf16 v[74:77], v[70:73], v[214:217], v[74:77]
	v_mfma_f32_16x16x32_bf16 v[62:65], v[54:57], v[222:225], v[62:65]
	v_mfma_f32_16x16x32_bf16 v[58:61], v[70:73], v[222:225], v[58:61]
	v_mfma_f32_16x16x32_bf16 v[30:33], v[54:57], v[230:233], v[30:33]
	v_mfma_f32_16x16x32_bf16 v[26:29], v[70:73], v[230:233], v[26:29]
	v_mfma_f32_16x16x32_bf16 v[14:17], v[54:57], v[238:241], v[14:17]
	v_mfma_f32_16x16x32_bf16 v[10:13], v[70:73], v[238:241], v[10:13]
	v_mfma_f32_16x16x32_bf16 v[34:37], v[98:101], v[210:213], v[34:37]
	v_mfma_f32_16x16x32_bf16 v[70:73], v[102:105], v[214:217], v[34:37]
	v_mfma_f32_16x16x32_bf16 v[34:37], v[106:109], v[210:213], v[38:41]
	v_mfma_f32_16x16x32_bf16 v[66:69], v[110:113], v[214:217], v[34:37]
	v_mfma_f32_16x16x32_bf16 v[34:37], v[98:101], v[218:221], v[42:45]
	v_mfma_f32_16x16x32_bf16 v[54:57], v[102:105], v[222:225], v[34:37]
	v_mfma_f32_16x16x32_bf16 v[34:37], v[106:109], v[218:221], v[46:49]
	v_mfma_f32_16x16x32_bf16 v[22:25], v[98:101], v[226:229], v[22:25]
	v_mfma_f32_16x16x32_bf16 v[18:21], v[106:109], v[226:229], v[18:21]
	v_mfma_f32_16x16x32_bf16 v[6:9], v[98:101], v[234:237], v[6:9]
	v_mfma_f32_16x16x32_bf16 v[2:5], v[106:109], v[234:237], v[2:5]
	v_mfma_f32_16x16x32_bf16 v[50:53], v[110:113], v[222:225], v[34:37]
	v_mfma_f32_16x16x32_bf16 v[22:25], v[102:105], v[230:233], v[22:25]
	v_mfma_f32_16x16x32_bf16 v[18:21], v[110:113], v[230:233], v[18:21]
	v_mfma_f32_16x16x32_bf16 v[6:9], v[102:105], v[238:241], v[6:9]
	v_mfma_f32_16x16x32_bf16 v[2:5], v[110:113], v[238:241], v[2:5]
	s_barrier
	s_add_i32 s34, s34, 2
	s_add_u32 s24, s24, 0x100
	s_addc_u32 s25, s25, 0
	s_add_u32 s20, s20, 0x100
	s_addc_u32 s21, s21, 0
	s_cmp_lt_u32 s34, 30
	s_cbranch_scc1 .LBB0_2143
	s_setprio 0
	s_andn2_b64 vcc, exec, s[8:9]
	s_cbranch_vccnz .LBB0_2146
	s_barrier

;     __device__ bool next(int i, Unit& u) const { if (i != 0 || c >= 128) return false; const int t = c >> 2; u.pm = t & 3; u.pn = t >> 2; u.koff = koff_bytes; u.q = c & 3; return true; }
; #define PG8_STAGE(bufoff, gbase, voff) do { _Pragma("unroll") for (int _i = 0; _i < 2; ++_i) \
;         __builtin_amdgcn_global_load_lds((const unsigned*)((const char*)(gbase) + (voff)[_i]), (LAS unsigned*)(lds + (bufoff) + ldsw + _i * 8192), 16, 0, 0); } while (0)
; #define PG8_LDA(dst, b, h) do { _Pragma("unroll") for (int m = 0; m < 4; ++m) _Pragma("unroll") for (int k = 0; k < 2; ++k) dst[m][k] = *(const LAS bf16x8*)(lds + PG8_SA(b, h) + aoff + m * 2048 + k * 1024); } while (0)
; #define PG8_LDB(dst, b, h) do { _Pragma("unroll") for (int n = 0; n < 2; ++n) _Pragma("unroll") for (int k = 0; k < 2; ++k) dst[n][k] = *(const LAS bf16x8*)(lds + PG8_SB(b, h) + boff + n * 2048 + k * 1024); } while (0)
; #define PG8_MMA(ai, bj, At, Bt) do { __builtin_amdgcn_s_setprio(1); _Pragma("unroll") for (int m = 0; m < 4; ++m) _Pragma("unroll") for (int n = 0; n < 2; ++n) _Pragma("unroll") for (int k = 0; k < 2; ++k) \
;         acc[ai][bj][m][n] = __builtin_amdgcn_mfma_f32_16x16x32_bf16(Bt[n][k], At[m][k], acc[ai][bj][m][n], 0, 0, 0); __builtin_amdgcn_s_setprio(0); } while (0)
; #define PG8_WAIT_V(n) asm volatile("s_waitcnt vmcnt(" #n ")" ::: "memory")
; #define PG8_BAR __builtin_amdgcn_s_barrier()
; template <class Epi, class Sched, bool ALIGN_EPI = false, bool SP2 = false>
; __device__ __forceinline__ void gemm_phase(LAS unsigned char* lds, const Gemm g, const Sched& S, const Epi& E) {
;     ...
;         const bool has_next = S.next(ui + 1, nxt);
;         const char* nA = has_next ? (const char*)g.A + (size_t)nxt.pm * tstep + nxt.koff : cA; const char* nB = has_next ? (const char*)g.Bt + (size_t)nxt.pn * tstep + nxt.koff : cB;
;     ...
;             if constexpr (SP2) {
;             PG8_LDB(B0, 0, 0); PG8_LDB(B1, 0, 1); PG8_SCHED; PG8_LDA(At, 0, 0); PG8_STAGE(PG8_SA(1, 1), a1 + hstep, voffA);
;             PG8_WAIT_V(8); PG8_WAIT_L(0); PG8_BAR; PG8_MMA(0, 0, At, B0); PG8_MMA(0, 1, At, B1); PG8_BAR; PG8_SCHED;
;             PG8_LDA(At, 0, 1); PG8_STAGE(PG8_SB(0, 0), b2, voffB); PG8_STAGE(PG8_SB(0, 1), b2 + hstepB, voffB); PG8_STAGE(PG8_SA(0, 0), a2, voffA);
;             PG8_WAIT_V(8); PG8_WAIT_L(0); PG8_BAR; PG8_MMA(1, 0, At, B0); PG8_MMA(1, 1, At, B1); PG8_BAR; PG8_SCHED;
.LBB0_2765:
	s_ashr_i32 s15, s14, 31
	v_cmp_lt_i64_e64 s[42:43], s[16:17], v[170:171]
	s_lshl_b64 s[16:17], s[14:15], 20
	v_readlane_b32 s3, v252, 25
	s_add_u32 s16, s3, s16
	v_readlane_b32 s3, v252, 26
	s_addc_u32 s17, s3, s17
	s_and_b64 s[18:19], s[42:43], exec
	s_cselect_b32 s3, s17, s35
	s_cselect_b32 s15, s16, s34
	s_ashr_i32 s13, s12, 31
	s_lshl_b64 s[18:19], s[12:13], 20
	v_readlane_b32 s4, v254, 56
	v_readlane_b32 s5, v254, 57
	s_add_u32 s18, s4, s18
	s_addc_u32 s19, s5, s19
	s_and_b64 s[24:25], s[42:43], exec
	s_cselect_b32 s13, s19, s23
	s_cselect_b32 s21, s18, s22
	s_add_u32 s53, s22, 0x100
	s_addc_u32 s54, s23, 0
	s_add_u32 s22, s34, 0x80080
	s_mov_b64 s[70:71], s[58:59]
	s_addc_u32 s23, s35, 0
	s_mov_b32 s55, -2
	s_waitcnt vmcnt(0)
	v_readfirstlane_b32 s98, v0
	s_nop 3
	s_lshr_b32 s98, s98, 6
	s_cmp_ge_u32 s98, 4
	s_cbranch_scc0 .Lprio_2766
	s_setprio 1
.Lprio_2766:
	ds_read_b128 v[50:53], v196
	ds_read_b128 v[54:57], v196 offset:1024
	ds_read_b128 v[138:141], v196 offset:2048
	ds_read_b128 v[142:145], v196 offset:3072
	ds_read_b128 v[146:149], v197
	ds_read_b128 v[150:153], v197 offset:1024
	ds_read_b128 v[174:177], v197 offset:2048
	ds_read_b128 v[178:181], v197 offset:3072
	s_add_u32 s24, s22, 0xfff80080
	s_addc_u32 s25, s23, -1
	s_cmp_eq_u32 s55, 28
	s_cselect_b32 s35, s3, s25
	s_cselect_b32 s34, s15, s24
	s_cselect_b32 s25, s13, s54
	s_cselect_b32 s24, s21, s53
	v_lshl_add_u64 v[190:191], s[22:23], 0, v[168:169]
	s_add_i32 m0, s28, 0xc000
	ds_read_b128 v[182:185], v198
	ds_read_b128 v[186:189], v198 offset:1024
	ds_read_b128 v[202:205], v198 offset:2048
	ds_read_b128 v[206:209], v198 offset:3072
	ds_read_b128 v[210:213], v198 offset:4096
	ds_read_b128 v[214:217], v198 offset:5120
	ds_read_b128 v[218:221], v198 offset:6144
	ds_read_b128 v[222:225], v198 offset:7168
	global_load_lds_dwordx4 v[190:191], off
	v_lshl_add_u64 v[190:191], s[22:23], 0, v[166:167]
	s_add_i32 m0, s28, 0xe000
	s_nop 0
	global_load_lds_dwordx4 v[190:191], off
	s_waitcnt lgkmcnt(0)
	s_barrier
	s_waitcnt lgkmcnt(0)
	v_mfma_f32_16x16x32_bf16 v[134:137], v[50:53], v[182:185], 0
	v_mfma_f32_16x16x32_bf16 v[130:133], v[138:141], v[182:185], 0
	v_mfma_f32_16x16x32_bf16 v[118:121], v[50:53], v[202:205], 0
	v_mfma_f32_16x16x32_bf16 v[114:117], v[138:141], v[202:205], 0
	v_mfma_f32_16x16x32_bf16 v[102:105], v[50:53], v[210:213], 0
	v_mfma_f32_16x16x32_bf16 v[98:101], v[138:141], v[210:213], 0
	v_mfma_f32_16x16x32_bf16 v[86:89], v[50:53], v[218:221], 0
	v_mfma_f32_16x16x32_bf16 v[82:85], v[138:141], v[218:221], 0
	v_mfma_f32_16x16x32_bf16 v[134:137], v[54:57], v[186:189], v[134:137]
	v_mfma_f32_16x16x32_bf16 v[130:133], v[142:145], v[186:189], v[130:133]
	v_mfma_f32_16x16x32_bf16 v[118:121], v[54:57], v[206:209], v[118:121]
	v_mfma_f32_16x16x32_bf16 v[114:117], v[142:145], v[206:209], v[114:117]
	v_mfma_f32_16x16x32_bf16 v[102:105], v[54:57], v[214:217], v[102:105]
	v_mfma_f32_16x16x32_bf16 v[98:101], v[142:145], v[214:217], v[98:101]
	v_mfma_f32_16x16x32_bf16 v[86:89], v[54:57], v[222:225], v[86:89]
	v_mfma_f32_16x16x32_bf16 v[82:85], v[142:145], v[222:225], v[82:85]
	v_mfma_f32_16x16x32_bf16 v[126:129], v[146:149], v[182:185], 0
	v_mfma_f32_16x16x32_bf16 v[122:125], v[174:177], v[182:185], 0
	v_mfma_f32_16x16x32_bf16 v[110:113], v[146:149], v[202:205], 0
	v_mfma_f32_16x16x32_bf16 v[106:109], v[174:177], v[202:205], 0
	v_mfma_f32_16x16x32_bf16 v[94:97], v[146:149], v[210:213], 0
	v_mfma_f32_16x16x32_bf16 v[90:93], v[174:177], v[210:213], 0
	v_mfma_f32_16x16x32_bf16 v[78:81], v[146:149], v[218:221], 0
	v_mfma_f32_16x16x32_bf16 v[74:77], v[174:177], v[218:221], 0
	v_mfma_f32_16x16x32_bf16 v[126:129], v[150:153], v[186:189], v[126:129]
	v_mfma_f32_16x16x32_bf16 v[122:125], v[178:181], v[186:189], v[122:125]
	v_mfma_f32_16x16x32_bf16 v[110:113], v[150:153], v[206:209], v[110:113]
	v_mfma_f32_16x16x32_bf16 v[106:109], v[178:181], v[206:209], v[106:109]
	v_mfma_f32_16x16x32_bf16 v[94:97], v[150:153], v[214:217], v[94:97]
	v_mfma_f32_16x16x32_bf16 v[90:93], v[178:181], v[214:217], v[90:93]
	v_mfma_f32_16x16x32_bf16 v[78:81], v[150:153], v[222:225], v[78:81]
	v_mfma_f32_16x16x32_bf16 v[74:77], v[178:181], v[222:225], v[74:77]
	s_barrier
	s_add_i32 s56, s51, s27
	v_lshl_add_u64 v[190:191], s[24:25], 0, v[156:157]
	s_mov_b32 m0, s56
	ds_read_b128 v[182:185], v198 offset:16384
	ds_read_b128 v[186:189], v198 offset:17408
	ds_read_b128 v[202:205], v198 offset:18432
	ds_read_b128 v[206:209], v198 offset:19456
	ds_read_b128 v[210:213], v198 offset:20480
	ds_read_b128 v[214:217], v198 offset:21504
	ds_read_b128 v[218:221], v198 offset:22528
	ds_read_b128 v[222:225], v198 offset:23552
	global_load_lds_dwordx4 v[190:191], off
	s_add_i32 m0, s56, 0x2000
	s_add_u32 s56, s24, 0x20000
	v_lshl_add_u64 v[226:227], s[24:25], 0, v[160:161]
	s_addc_u32 s57, s25, 0
	s_add_i32 s58, s52, s27
	global_load_lds_dwordx4 v[226:227], off
	v_lshl_add_u64 v[228:229], s[56:57], 0, v[156:157]
	s_mov_b32 m0, s58
	v_lshl_add_u64 v[230:231], s[34:35], 0, v[158:159]
	global_load_lds_dwordx4 v[228:229], off
	v_lshl_add_u64 v[228:229], s[56:57], 0, v[160:161]
	s_add_i32 m0, s58, 0x2000
	s_nop 0
	global_load_lds_dwordx4 v[228:229], off
	v_lshl_add_u64 v[228:229], s[34:35], 0, v[154:155]
	s_mov_b32 m0, s28
	s_nop 0
	global_load_lds_dwordx4 v[228:229], off
	s_mov_b32 m0, s29
	s_nop 0
	global_load_lds_dwordx4 v[230:231], off
	s_waitcnt lgkmcnt(0)
	s_barrier
; #define PG8_STAGE(bufoff, gbase, voff) do { _Pragma("unroll") for (int _i = 0; _i < 2; ++_i) \
;         __builtin_amdgcn_global_load_lds((const unsigned*)((const char*)(gbase) + (voff)[_i]), (LAS unsigned*)(lds + (bufoff) + ldsw + _i * 8192), 16, 0, 0); } while (0)
; #define PG8_LDA(dst, b, h) do { _Pragma("unroll") for (int m = 0; m < 4; ++m) _Pragma("unroll") for (int k = 0; k < 2; ++k) dst[m][k] = *(const LAS bf16x8*)(lds + PG8_SA(b, h) + aoff + m * 2048 + k * 1024); } while (0)
; #define PG8_LDB(dst, b, h) do { _Pragma("unroll") for (int n = 0; n < 2; ++n) _Pragma("unroll") for (int k = 0; k < 2; ++k) dst[n][k] = *(const LAS bf16x8*)(lds + PG8_SB(b, h) + boff + n * 2048 + k * 1024); } while (0)
; #define PG8_MMA(ai, bj, At, Bt) do { __builtin_amdgcn_s_setprio(1); _Pragma("unroll") for (int m = 0; m < 4; ++m) _Pragma("unroll") for (int n = 0; n < 2; ++n) _Pragma("unroll") for (int k = 0; k < 2; ++k) \
;         acc[ai][bj][m][n] = __builtin_amdgcn_mfma_f32_16x16x32_bf16(Bt[n][k], At[m][k], acc[ai][bj][m][n], 0, 0, 0); __builtin_amdgcn_s_setprio(0); } while (0)
; #define PG8_WAIT_V(n) asm volatile("s_waitcnt vmcnt(" #n ")" ::: "memory")
; #define PG8_WAIT_L(n) asm volatile("s_waitcnt lgkmcnt(" #n ")" ::: "memory")
; #define PG8_BAR __builtin_amdgcn_s_barrier()
; #define PG8_SCHED __builtin_amdgcn_sched_barrier(0)
; template <class Epi, class Sched, bool ALIGN_EPI = false, bool SP2 = false>
; __device__ __forceinline__ void gemm_phase(LAS unsigned char* lds, const Gemm g, const Sched& S, const Epi& E) {
;     ...
;             PG8_WAIT_V(8); PG8_WAIT_L(0); PG8_BAR; PG8_MMA(1, 0, At, B0); PG8_MMA(1, 1, At, B1); PG8_BAR; PG8_SCHED;
;             PG8_LDB(B0, 1, 0); PG8_LDB(B1, 1, 1); PG8_SCHED; PG8_LDA(At, 1, 0); PG8_STAGE(PG8_SA(0, 1), a2 + hstep, voffA);
;             PG8_WAIT_V(8); PG8_WAIT_L(0); PG8_BAR; PG8_MMA(0, 0, At, B0); PG8_MMA(0, 1, At, B1); PG8_BAR; PG8_SCHED;
	s_waitcnt lgkmcnt(0)
	v_mfma_f32_16x16x32_bf16 v[70:73], v[50:53], v[182:185], 0
	v_mfma_f32_16x16x32_bf16 v[66:69], v[138:141], v[182:185], 0
	v_mfma_f32_16x16x32_bf16 v[46:49], v[50:53], v[202:205], 0
	v_mfma_f32_16x16x32_bf16 v[42:45], v[138:141], v[202:205], 0
	v_mfma_f32_16x16x32_bf16 v[30:33], v[50:53], v[210:213], 0
	v_mfma_f32_16x16x32_bf16 v[26:29], v[138:141], v[210:213], 0
	v_mfma_f32_16x16x32_bf16 v[14:17], v[50:53], v[218:221], 0
	v_mfma_f32_16x16x32_bf16 v[10:13], v[138:141], v[218:221], 0
	v_mfma_f32_16x16x32_bf16 v[70:73], v[54:57], v[186:189], v[70:73]
	v_mfma_f32_16x16x32_bf16 v[66:69], v[142:145], v[186:189], v[66:69]
	v_mfma_f32_16x16x32_bf16 v[46:49], v[54:57], v[206:209], v[46:49]
	v_mfma_f32_16x16x32_bf16 v[42:45], v[142:145], v[206:209], v[42:45]
	v_mfma_f32_16x16x32_bf16 v[30:33], v[54:57], v[214:217], v[30:33]
	v_mfma_f32_16x16x32_bf16 v[26:29], v[142:145], v[214:217], v[26:29]
	v_mfma_f32_16x16x32_bf16 v[14:17], v[54:57], v[222:225], v[14:17]
	v_mfma_f32_16x16x32_bf16 v[10:13], v[142:145], v[222:225], v[10:13]
	v_mfma_f32_16x16x32_bf16 v[38:41], v[146:149], v[202:205], 0
	v_mfma_f32_16x16x32_bf16 v[34:37], v[174:177], v[202:205], 0
	v_mfma_f32_16x16x32_bf16 v[22:25], v[146:149], v[210:213], 0
	v_mfma_f32_16x16x32_bf16 v[18:21], v[174:177], v[210:213], 0
	v_mfma_f32_16x16x32_bf16 v[6:9], v[146:149], v[218:221], 0
	v_mfma_f32_16x16x32_bf16 v[2:5], v[174:177], v[218:221], 0
	v_mfma_f32_16x16x32_bf16 v[50:53], v[146:149], v[182:185], 0
	v_mfma_f32_16x16x32_bf16 v[54:57], v[174:177], v[182:185], 0
	v_mfma_f32_16x16x32_bf16 v[38:41], v[150:153], v[206:209], v[38:41]
	v_mfma_f32_16x16x32_bf16 v[34:37], v[178:181], v[206:209], v[34:37]
	v_mfma_f32_16x16x32_bf16 v[22:25], v[150:153], v[214:217], v[22:25]
	v_mfma_f32_16x16x32_bf16 v[18:21], v[178:181], v[214:217], v[18:21]
	v_mfma_f32_16x16x32_bf16 v[6:9], v[150:153], v[222:225], v[6:9]
	v_mfma_f32_16x16x32_bf16 v[2:5], v[178:181], v[222:225], v[2:5]
	v_mfma_f32_16x16x32_bf16 v[50:53], v[150:153], v[186:189], v[50:53]
	v_mfma_f32_16x16x32_bf16 v[54:57], v[178:181], v[186:189], v[54:57]
	s_barrier
	s_add_i32 s56, 0, 0x18000
	s_add_i32 s57, 0, 0x1c000
	v_add_u32_e32 v142, s56, v1
	v_add_u32_e32 v162, s57, v1
	ds_read_b128 v[58:61], v142
	ds_read_b128 v[62:65], v142 offset:1024
	ds_read_b128 v[138:141], v142 offset:2048
	ds_read_b128 v[142:145], v142 offset:3072
	ds_read_b128 v[146:149], v162
	ds_read_b128 v[150:153], v162 offset:1024
	ds_read_b128 v[174:177], v162 offset:2048
	ds_read_b128 v[178:181], v162 offset:3072
	s_add_u32 s34, s34, 0x80000
	s_addc_u32 s35, s35, 0
	s_mov_b32 m0, s30
	v_lshl_add_u64 v[232:233], s[34:35], 0, v[154:155]
	ds_read_b128 v[182:185], v198 offset:32768
	ds_read_b128 v[186:189], v198 offset:33792
	ds_read_b128 v[202:205], v198 offset:34816
	ds_read_b128 v[206:209], v198 offset:35840
	ds_read_b128 v[210:213], v198 offset:36864
	ds_read_b128 v[214:217], v198 offset:37888
	ds_read_b128 v[218:221], v198 offset:38912
	ds_read_b128 v[222:225], v198 offset:39936
	global_load_lds_dwordx4 v[232:233], off
	v_lshl_add_u64 v[232:233], s[34:35], 0, v[158:159]
	s_mov_b32 m0, s31
	s_nop 0
	global_load_lds_dwordx4 v[232:233], off
	s_waitcnt vmcnt(8)
	s_waitcnt lgkmcnt(0)
	s_barrier
	s_waitcnt lgkmcnt(0)
	v_mfma_f32_16x16x32_bf16 v[134:137], v[58:61], v[182:185], v[134:137]
	v_mfma_f32_16x16x32_bf16 v[130:133], v[138:141], v[182:185], v[130:133]
	v_mfma_f32_16x16x32_bf16 v[118:121], v[58:61], v[202:205], v[118:121]
	v_mfma_f32_16x16x32_bf16 v[114:117], v[138:141], v[202:205], v[114:117]
	v_mfma_f32_16x16x32_bf16 v[102:105], v[58:61], v[210:213], v[102:105]
	v_mfma_f32_16x16x32_bf16 v[98:101], v[138:141], v[210:213], v[98:101]
	v_mfma_f32_16x16x32_bf16 v[86:89], v[58:61], v[218:221], v[86:89]
	v_mfma_f32_16x16x32_bf16 v[82:85], v[138:141], v[218:221], v[82:85]
	v_mfma_f32_16x16x32_bf16 v[134:137], v[62:65], v[186:189], v[134:137]
	v_mfma_f32_16x16x32_bf16 v[130:133], v[142:145], v[186:189], v[130:133]
	v_mfma_f32_16x16x32_bf16 v[118:121], v[62:65], v[206:209], v[118:121]
	v_mfma_f32_16x16x32_bf16 v[114:117], v[142:145], v[206:209], v[114:117]
	v_mfma_f32_16x16x32_bf16 v[102:105], v[62:65], v[214:217], v[102:105]
	v_mfma_f32_16x16x32_bf16 v[98:101], v[142:145], v[214:217], v[98:101]
	v_mfma_f32_16x16x32_bf16 v[86:89], v[62:65], v[222:225], v[86:89]
	v_mfma_f32_16x16x32_bf16 v[82:85], v[142:145], v[222:225], v[82:85]
	v_mfma_f32_16x16x32_bf16 v[126:129], v[146:149], v[182:185], v[126:129]
	v_mfma_f32_16x16x32_bf16 v[122:125], v[174:177], v[182:185], v[122:125]
	v_mfma_f32_16x16x32_bf16 v[110:113], v[146:149], v[202:205], v[110:113]
	v_mfma_f32_16x16x32_bf16 v[106:109], v[174:177], v[202:205], v[106:109]
	v_mfma_f32_16x16x32_bf16 v[94:97], v[146:149], v[210:213], v[94:97]
	v_mfma_f32_16x16x32_bf16 v[90:93], v[174:177], v[210:213], v[90:93]
	v_mfma_f32_16x16x32_bf16 v[78:81], v[146:149], v[218:221], v[78:81]
	v_mfma_f32_16x16x32_bf16 v[74:77], v[174:177], v[218:221], v[74:77]
	v_mfma_f32_16x16x32_bf16 v[126:129], v[150:153], v[186:189], v[126:129]
	v_mfma_f32_16x16x32_bf16 v[122:125], v[178:181], v[186:189], v[122:125]
	v_mfma_f32_16x16x32_bf16 v[110:113], v[150:153], v[206:209], v[110:113]
	v_mfma_f32_16x16x32_bf16 v[106:109], v[178:181], v[206:209], v[106:109]
	v_mfma_f32_16x16x32_bf16 v[94:97], v[150:153], v[214:217], v[94:97]
	v_mfma_f32_16x16x32_bf16 v[90:93], v[178:181], v[214:217], v[90:93]
	v_mfma_f32_16x16x32_bf16 v[78:81], v[150:153], v[222:225], v[78:81]
	v_mfma_f32_16x16x32_bf16 v[74:77], v[178:181], v[222:225], v[74:77]
	s_barrier
; #define PG8_STAGE(bufoff, gbase, voff) do { _Pragma("unroll") for (int _i = 0; _i < 2; ++_i) \
;         __builtin_amdgcn_global_load_lds((const unsigned*)((const char*)(gbase) + (voff)[_i]), (LAS unsigned*)(lds + (bufoff) + ldsw + _i * 8192), 16, 0, 0); } while (0)
; #define PG8_LDA(dst, b, h) do { _Pragma("unroll") for (int m = 0; m < 4; ++m) _Pragma("unroll") for (int k = 0; k < 2; ++k) dst[m][k] = *(const LAS bf16x8*)(lds + PG8_SA(b, h) + aoff + m * 2048 + k * 1024); } while (0)
; #define PG8_LDB(dst, b, h) do { _Pragma("unroll") for (int n = 0; n < 2; ++n) _Pragma("unroll") for (int k = 0; k < 2; ++k) dst[n][k] = *(const LAS bf16x8*)(lds + PG8_SB(b, h) + boff + n * 2048 + k * 1024); } while (0)
; #define PG8_MMA(ai, bj, At, Bt) do { __builtin_amdgcn_s_setprio(1); _Pragma("unroll") for (int m = 0; m < 4; ++m) _Pragma("unroll") for (int n = 0; n < 2; ++n) _Pragma("unroll") for (int k = 0; k < 2; ++k) \
;         acc[ai][bj][m][n] = __builtin_amdgcn_mfma_f32_16x16x32_bf16(Bt[n][k], At[m][k], acc[ai][bj][m][n], 0, 0, 0); __builtin_amdgcn_s_setprio(0); } while (0)
; #define PG8_WAIT_V(n) asm volatile("s_waitcnt vmcnt(" #n ")" ::: "memory")
; #define PG8_WAIT_L(n) asm volatile("s_waitcnt lgkmcnt(" #n ")" ::: "memory")
; #define PG8_BAR __builtin_amdgcn_s_barrier()
; #define PG8_SCHED __builtin_amdgcn_sched_barrier(0)
; template <class Epi, class Sched, bool ALIGN_EPI = false, bool SP2 = false>
; __device__ __forceinline__ void gemm_phase(LAS unsigned char* lds, const Gemm g, const Sched& S, const Epi& E) {
;     ...
;         for (int t = 0; t < nt; t += 2) {
;             const bool last = (t == nt - 2);
;             const char* a1 = cA + (size_t)(t + 1) * kstep;
;             const char* a2 = last ? nA : cA + (size_t)(t + 2) * kstep; const char* b2 = last ? nB : cB + (size_t)(t + 2) * kstep;
;             const char* a3 = a2 + kstep; const char* b3 = b2 + kstep;
;             if (last && has_next) S.a_ready(nxt);
;             if constexpr (SP2) {
;             PG8_LDB(B0, 0, 0); PG8_LDB(B1, 0, 1); PG8_SCHED; PG8_LDA(At, 0, 0); PG8_STAGE(PG8_SA(1, 1), a1 + hstep, voffA);
;     ...
;             PG8_LDA(At, 1, 1); PG8_STAGE(PG8_SB(1, 0), b3, voffB); PG8_STAGE(PG8_SB(1, 1), b3 + hstepB, voffB); PG8_STAGE(PG8_SA(1, 0), a3, voffA);
;             PG8_WAIT_V(8); PG8_WAIT_L(0); PG8_BAR; PG8_MMA(1, 0, At, B0); PG8_MMA(1, 1, At, B1); PG8_BAR; PG8_SCHED;
	s_add_i32 s34, s56, s27
	v_lshl_add_u64 v[190:191], v[190:191], 0, s[8:9]
	s_mov_b32 m0, s34
	ds_read_b128 v[182:185], v198 offset:49152
	ds_read_b128 v[186:189], v198 offset:50176
	ds_read_b128 v[202:205], v198 offset:51200
	ds_read_b128 v[206:209], v198 offset:52224
	ds_read_b128 v[210:213], v198 offset:53248
	ds_read_b128 v[214:217], v198 offset:54272
	ds_read_b128 v[218:221], v198 offset:55296
	ds_read_b128 v[222:225], v198 offset:56320
	global_load_lds_dwordx4 v[190:191], off
	s_add_i32 m0, s34, 0x2000
	s_add_u32 s24, s24, 0x20080
	v_lshl_add_u64 v[190:191], v[226:227], 0, s[8:9]
	s_addc_u32 s25, s25, 0
	s_add_i32 s34, s57, s27
	global_load_lds_dwordx4 v[190:191], off
	v_lshl_add_u64 v[190:191], s[24:25], 0, v[156:157]
	s_mov_b32 m0, s34
	s_nop 0
	global_load_lds_dwordx4 v[190:191], off
	v_lshl_add_u64 v[190:191], s[24:25], 0, v[160:161]
	s_add_i32 m0, s34, 0x2000
	s_nop 0
	global_load_lds_dwordx4 v[190:191], off
	v_lshl_add_u64 v[190:191], v[228:229], 0, s[8:9]
	s_mov_b32 m0, s48
	s_nop 0
	global_load_lds_dwordx4 v[190:191], off
	v_lshl_add_u64 v[190:191], v[230:231], 0, s[8:9]
	s_mov_b32 m0, s49
	s_nop 0
	global_load_lds_dwordx4 v[190:191], off
	s_waitcnt vmcnt(8)
	s_waitcnt lgkmcnt(0)
	s_barrier
	s_waitcnt lgkmcnt(0)
	v_mfma_f32_16x16x32_bf16 v[70:73], v[58:61], v[182:185], v[70:73]
	v_mfma_f32_16x16x32_bf16 v[66:69], v[138:141], v[182:185], v[66:69]
	v_mfma_f32_16x16x32_bf16 v[46:49], v[58:61], v[202:205], v[46:49]
	v_mfma_f32_16x16x32_bf16 v[42:45], v[138:141], v[202:205], v[42:45]
	v_mfma_f32_16x16x32_bf16 v[30:33], v[58:61], v[210:213], v[30:33]
	v_mfma_f32_16x16x32_bf16 v[26:29], v[138:141], v[210:213], v[26:29]
	v_mfma_f32_16x16x32_bf16 v[14:17], v[58:61], v[218:221], v[14:17]
	v_mfma_f32_16x16x32_bf16 v[10:13], v[138:141], v[218:221], v[10:13]
	v_mfma_f32_16x16x32_bf16 v[70:73], v[62:65], v[186:189], v[70:73]
	v_mfma_f32_16x16x32_bf16 v[66:69], v[142:145], v[186:189], v[66:69]
	v_mfma_f32_16x16x32_bf16 v[46:49], v[62:65], v[206:209], v[46:49]
	v_mfma_f32_16x16x32_bf16 v[42:45], v[142:145], v[206:209], v[42:45]
	v_mfma_f32_16x16x32_bf16 v[30:33], v[62:65], v[214:217], v[30:33]
	v_mfma_f32_16x16x32_bf16 v[26:29], v[142:145], v[214:217], v[26:29]
	v_mfma_f32_16x16x32_bf16 v[14:17], v[62:65], v[222:225], v[14:17]
	v_mfma_f32_16x16x32_bf16 v[10:13], v[142:145], v[222:225], v[10:13]
	v_mfma_f32_16x16x32_bf16 v[50:53], v[146:149], v[182:185], v[50:53]
	v_mfma_f32_16x16x32_bf16 v[62:65], v[150:153], v[186:189], v[50:53]
	v_mfma_f32_16x16x32_bf16 v[50:53], v[174:177], v[182:185], v[54:57]
	v_mfma_f32_16x16x32_bf16 v[38:41], v[146:149], v[202:205], v[38:41]
	v_mfma_f32_16x16x32_bf16 v[34:37], v[174:177], v[202:205], v[34:37]
	v_mfma_f32_16x16x32_bf16 v[22:25], v[146:149], v[210:213], v[22:25]
	v_mfma_f32_16x16x32_bf16 v[18:21], v[174:177], v[210:213], v[18:21]
	v_mfma_f32_16x16x32_bf16 v[6:9], v[146:149], v[218:221], v[6:9]
	v_mfma_f32_16x16x32_bf16 v[2:5], v[174:177], v[218:221], v[2:5]
	v_mfma_f32_16x16x32_bf16 v[58:61], v[178:181], v[186:189], v[50:53]
	v_mfma_f32_16x16x32_bf16 v[38:41], v[150:153], v[206:209], v[38:41]
	v_mfma_f32_16x16x32_bf16 v[34:37], v[178:181], v[206:209], v[34:37]
	v_mfma_f32_16x16x32_bf16 v[22:25], v[150:153], v[214:217], v[22:25]
	v_mfma_f32_16x16x32_bf16 v[18:21], v[178:181], v[214:217], v[18:21]
	v_mfma_f32_16x16x32_bf16 v[6:9], v[150:153], v[222:225], v[6:9]
	v_mfma_f32_16x16x32_bf16 v[2:5], v[178:181], v[222:225], v[2:5]
	s_barrier
	s_add_i32 s55, s55, 2
	s_add_u32 s53, s53, 0x100
	s_addc_u32 s54, s54, 0
	s_add_u32 s22, s22, 0x100
	s_addc_u32 s23, s23, 0
	s_cmp_lt_u32 s55, 30
.LBB0_2766:
	ds_read_b128 v[50:53], v196
	ds_read_b128 v[54:57], v196 offset:1024
	ds_read_b128 v[138:141], v196 offset:2048
	ds_read_b128 v[142:145], v196 offset:3072
	ds_read_b128 v[146:149], v197
	ds_read_b128 v[150:153], v197 offset:1024
	ds_read_b128 v[174:177], v197 offset:2048
	ds_read_b128 v[178:181], v197 offset:3072
	s_add_u32 s24, s22, 0xfff80080
	s_addc_u32 s25, s23, -1
	s_cmp_eq_u32 s55, 28
	s_cselect_b32 s35, s3, s25
	s_cselect_b32 s34, s15, s24
	s_cselect_b32 s25, s13, s54
	s_cselect_b32 s24, s21, s53
	v_lshl_add_u64 v[190:191], s[22:23], 0, v[168:169]
	s_add_i32 m0, s28, 0xc000
	ds_read_b128 v[182:185], v198
	ds_read_b128 v[186:189], v198 offset:1024
	ds_read_b128 v[202:205], v198 offset:2048
	ds_read_b128 v[206:209], v198 offset:3072
	ds_read_b128 v[210:213], v198 offset:4096
	ds_read_b128 v[214:217], v198 offset:5120
	ds_read_b128 v[218:221], v198 offset:6144
	ds_read_b128 v[222:225], v198 offset:7168
	global_load_lds_dwordx4 v[190:191], off
	v_lshl_add_u64 v[190:191], s[22:23], 0, v[166:167]
	s_add_i32 m0, s28, 0xe000
	s_nop 0
	global_load_lds_dwordx4 v[190:191], off
	s_waitcnt vmcnt(8)
	s_waitcnt lgkmcnt(0)
	s_barrier
; #define PG8_STAGE(bufoff, gbase, voff) do { _Pragma("unroll") for (int _i = 0; _i < 2; ++_i) \
;         __builtin_amdgcn_global_load_lds((const unsigned*)((const char*)(gbase) + (voff)[_i]), (LAS unsigned*)(lds + (bufoff) + ldsw + _i * 8192), 16, 0, 0); } while (0)
; #define PG8_LDA(dst, b, h) do { _Pragma("unroll") for (int m = 0; m < 4; ++m) _Pragma("unroll") for (int k = 0; k < 2; ++k) dst[m][k] = *(const LAS bf16x8*)(lds + PG8_SA(b, h) + aoff + m * 2048 + k * 1024); } while (0)
; #define PG8_LDB(dst, b, h) do { _Pragma("unroll") for (int n = 0; n < 2; ++n) _Pragma("unroll") for (int k = 0; k < 2; ++k) dst[n][k] = *(const LAS bf16x8*)(lds + PG8_SB(b, h) + boff + n * 2048 + k * 1024); } while (0)
; #define PG8_MMA(ai, bj, At, Bt) do { __builtin_amdgcn_s_setprio(1); _Pragma("unroll") for (int m = 0; m < 4; ++m) _Pragma("unroll") for (int n = 0; n < 2; ++n) _Pragma("unroll") for (int k = 0; k < 2; ++k) \
;         acc[ai][bj][m][n] = __builtin_amdgcn_mfma_f32_16x16x32_bf16(Bt[n][k], At[m][k], acc[ai][bj][m][n], 0, 0, 0); __builtin_amdgcn_s_setprio(0); } while (0)
; #define PG8_WAIT_V(n) asm volatile("s_waitcnt vmcnt(" #n ")" ::: "memory")
; #define PG8_WAIT_L(n) asm volatile("s_waitcnt lgkmcnt(" #n ")" ::: "memory")
; #define PG8_BAR __builtin_amdgcn_s_barrier()
; #define PG8_SCHED __builtin_amdgcn_sched_barrier(0)
; template <class Epi, class Sched, bool ALIGN_EPI = false, bool SP2 = false>
; __device__ __forceinline__ void gemm_phase(LAS unsigned char* lds, const Gemm g, const Sched& S, const Epi& E) {
;     ...
;             if constexpr (SP2) {
;             PG8_LDB(B0, 0, 0); PG8_LDB(B1, 0, 1); PG8_SCHED; PG8_LDA(At, 0, 0); PG8_STAGE(PG8_SA(1, 1), a1 + hstep, voffA);
;             PG8_WAIT_V(8); PG8_WAIT_L(0); PG8_BAR; PG8_MMA(0, 0, At, B0); PG8_MMA(0, 1, At, B1); PG8_BAR; PG8_SCHED;
;             PG8_LDA(At, 0, 1); PG8_STAGE(PG8_SB(0, 0), b2, voffB); PG8_STAGE(PG8_SB(0, 1), b2 + hstepB, voffB); PG8_STAGE(PG8_SA(0, 0), a2, voffA);
;             PG8_WAIT_V(8); PG8_WAIT_L(0); PG8_BAR; PG8_MMA(1, 0, At, B0); PG8_MMA(1, 1, At, B1); PG8_BAR; PG8_SCHED;
	s_waitcnt lgkmcnt(0)
	v_mfma_f32_16x16x32_bf16 v[134:137], v[50:53], v[182:185], v[134:137]
	v_mfma_f32_16x16x32_bf16 v[130:133], v[138:141], v[182:185], v[130:133]
	v_mfma_f32_16x16x32_bf16 v[118:121], v[50:53], v[202:205], v[118:121]
	v_mfma_f32_16x16x32_bf16 v[114:117], v[138:141], v[202:205], v[114:117]
	v_mfma_f32_16x16x32_bf16 v[102:105], v[50:53], v[210:213], v[102:105]
	v_mfma_f32_16x16x32_bf16 v[98:101], v[138:141], v[210:213], v[98:101]
	v_mfma_f32_16x16x32_bf16 v[86:89], v[50:53], v[218:221], v[86:89]
	v_mfma_f32_16x16x32_bf16 v[82:85], v[138:141], v[218:221], v[82:85]
	v_mfma_f32_16x16x32_bf16 v[134:137], v[54:57], v[186:189], v[134:137]
	v_mfma_f32_16x16x32_bf16 v[130:133], v[142:145], v[186:189], v[130:133]
	v_mfma_f32_16x16x32_bf16 v[118:121], v[54:57], v[206:209], v[118:121]
	v_mfma_f32_16x16x32_bf16 v[114:117], v[142:145], v[206:209], v[114:117]
	v_mfma_f32_16x16x32_bf16 v[102:105], v[54:57], v[214:217], v[102:105]
	v_mfma_f32_16x16x32_bf16 v[98:101], v[142:145], v[214:217], v[98:101]
	v_mfma_f32_16x16x32_bf16 v[86:89], v[54:57], v[222:225], v[86:89]
	v_mfma_f32_16x16x32_bf16 v[82:85], v[142:145], v[222:225], v[82:85]
	v_mfma_f32_16x16x32_bf16 v[126:129], v[146:149], v[182:185], v[126:129]
	v_mfma_f32_16x16x32_bf16 v[122:125], v[174:177], v[182:185], v[122:125]
	v_mfma_f32_16x16x32_bf16 v[110:113], v[146:149], v[202:205], v[110:113]
	v_mfma_f32_16x16x32_bf16 v[106:109], v[174:177], v[202:205], v[106:109]
	v_mfma_f32_16x16x32_bf16 v[94:97], v[146:149], v[210:213], v[94:97]
	v_mfma_f32_16x16x32_bf16 v[90:93], v[174:177], v[210:213], v[90:93]
	v_mfma_f32_16x16x32_bf16 v[78:81], v[146:149], v[218:221], v[78:81]
	v_mfma_f32_16x16x32_bf16 v[74:77], v[174:177], v[218:221], v[74:77]
	v_mfma_f32_16x16x32_bf16 v[126:129], v[150:153], v[186:189], v[126:129]
	v_mfma_f32_16x16x32_bf16 v[122:125], v[178:181], v[186:189], v[122:125]
	v_mfma_f32_16x16x32_bf16 v[110:113], v[150:153], v[206:209], v[110:113]
	v_mfma_f32_16x16x32_bf16 v[106:109], v[178:181], v[206:209], v[106:109]
	v_mfma_f32_16x16x32_bf16 v[94:97], v[150:153], v[214:217], v[94:97]
	v_mfma_f32_16x16x32_bf16 v[90:93], v[178:181], v[214:217], v[90:93]
	v_mfma_f32_16x16x32_bf16 v[78:81], v[150:153], v[222:225], v[78:81]
	v_mfma_f32_16x16x32_bf16 v[74:77], v[178:181], v[222:225], v[74:77]
	s_barrier
	s_add_i32 s56, s51, s27
	v_lshl_add_u64 v[190:191], s[24:25], 0, v[156:157]
	s_mov_b32 m0, s56
	ds_read_b128 v[182:185], v198 offset:16384
	ds_read_b128 v[186:189], v198 offset:17408
	ds_read_b128 v[202:205], v198 offset:18432
	ds_read_b128 v[206:209], v198 offset:19456
	ds_read_b128 v[210:213], v198 offset:20480
	ds_read_b128 v[214:217], v198 offset:21504
	ds_read_b128 v[218:221], v198 offset:22528
	ds_read_b128 v[222:225], v198 offset:23552
	global_load_lds_dwordx4 v[190:191], off
	s_add_i32 m0, s56, 0x2000
	s_add_u32 s56, s24, 0x20000
	v_lshl_add_u64 v[226:227], s[24:25], 0, v[160:161]
	s_addc_u32 s57, s25, 0
	s_add_i32 s58, s52, s27
	global_load_lds_dwordx4 v[226:227], off
	v_lshl_add_u64 v[228:229], s[56:57], 0, v[156:157]
	s_mov_b32 m0, s58
	v_lshl_add_u64 v[230:231], s[34:35], 0, v[158:159]
	global_load_lds_dwordx4 v[228:229], off
	v_lshl_add_u64 v[228:229], s[56:57], 0, v[160:161]
	s_add_i32 m0, s58, 0x2000
	s_nop 0
	global_load_lds_dwordx4 v[228:229], off
	v_lshl_add_u64 v[228:229], s[34:35], 0, v[154:155]
	s_mov_b32 m0, s28
	s_nop 0
	global_load_lds_dwordx4 v[228:229], off
	s_mov_b32 m0, s29
	s_nop 0
	global_load_lds_dwordx4 v[230:231], off
	s_waitcnt vmcnt(8)
	s_waitcnt lgkmcnt(0)
	s_barrier
	s_waitcnt lgkmcnt(0)
	v_mfma_f32_16x16x32_bf16 v[70:73], v[50:53], v[182:185], v[70:73]
	v_mfma_f32_16x16x32_bf16 v[66:69], v[138:141], v[182:185], v[66:69]
	v_mfma_f32_16x16x32_bf16 v[46:49], v[50:53], v[202:205], v[46:49]
	v_mfma_f32_16x16x32_bf16 v[42:45], v[138:141], v[202:205], v[42:45]
	v_mfma_f32_16x16x32_bf16 v[30:33], v[50:53], v[210:213], v[30:33]
	v_mfma_f32_16x16x32_bf16 v[26:29], v[138:141], v[210:213], v[26:29]
	v_mfma_f32_16x16x32_bf16 v[14:17], v[50:53], v[218:221], v[14:17]
	v_mfma_f32_16x16x32_bf16 v[10:13], v[138:141], v[218:221], v[10:13]
	v_mfma_f32_16x16x32_bf16 v[70:73], v[54:57], v[186:189], v[70:73]
	v_mfma_f32_16x16x32_bf16 v[66:69], v[142:145], v[186:189], v[66:69]
	v_mfma_f32_16x16x32_bf16 v[46:49], v[54:57], v[206:209], v[46:49]
	v_mfma_f32_16x16x32_bf16 v[42:45], v[142:145], v[206:209], v[42:45]
	v_mfma_f32_16x16x32_bf16 v[30:33], v[54:57], v[214:217], v[30:33]
	v_mfma_f32_16x16x32_bf16 v[26:29], v[142:145], v[214:217], v[26:29]
	v_mfma_f32_16x16x32_bf16 v[14:17], v[54:57], v[222:225], v[14:17]
	v_mfma_f32_16x16x32_bf16 v[10:13], v[142:145], v[222:225], v[10:13]
	v_mfma_f32_16x16x32_bf16 v[38:41], v[146:149], v[202:205], v[38:41]
	v_mfma_f32_16x16x32_bf16 v[34:37], v[174:177], v[202:205], v[34:37]
	v_mfma_f32_16x16x32_bf16 v[22:25], v[146:149], v[210:213], v[22:25]
	v_mfma_f32_16x16x32_bf16 v[18:21], v[174:177], v[210:213], v[18:21]
	v_mfma_f32_16x16x32_bf16 v[6:9], v[146:149], v[218:221], v[6:9]
	v_mfma_f32_16x16x32_bf16 v[2:5], v[174:177], v[218:221], v[2:5]
	v_mfma_f32_16x16x32_bf16 v[50:53], v[146:149], v[182:185], v[62:65]
	v_mfma_f32_16x16x32_bf16 v[54:57], v[174:177], v[182:185], v[58:61]
	v_mfma_f32_16x16x32_bf16 v[38:41], v[150:153], v[206:209], v[38:41]
	v_mfma_f32_16x16x32_bf16 v[34:37], v[178:181], v[206:209], v[34:37]
	v_mfma_f32_16x16x32_bf16 v[22:25], v[150:153], v[214:217], v[22:25]
	v_mfma_f32_16x16x32_bf16 v[18:21], v[178:181], v[214:217], v[18:21]
	v_mfma_f32_16x16x32_bf16 v[6:9], v[150:153], v[222:225], v[6:9]
	v_mfma_f32_16x16x32_bf16 v[2:5], v[178:181], v[222:225], v[2:5]
	v_mfma_f32_16x16x32_bf16 v[50:53], v[150:153], v[186:189], v[50:53]
	v_mfma_f32_16x16x32_bf16 v[54:57], v[178:181], v[186:189], v[54:57]
	s_barrier
; #define PG8_STAGE(bufoff, gbase, voff) do { _Pragma("unroll") for (int _i = 0; _i < 2; ++_i) \
;         __builtin_amdgcn_global_load_lds((const unsigned*)((const char*)(gbase) + (voff)[_i]), (LAS unsigned*)(lds + (bufoff) + ldsw + _i * 8192), 16, 0, 0); } while (0)
; #define PG8_LDA(dst, b, h) do { _Pragma("unroll") for (int m = 0; m < 4; ++m) _Pragma("unroll") for (int k = 0; k < 2; ++k) dst[m][k] = *(const LAS bf16x8*)(lds + PG8_SA(b, h) + aoff + m * 2048 + k * 1024); } while (0)
; #define PG8_LDB(dst, b, h) do { _Pragma("unroll") for (int n = 0; n < 2; ++n) _Pragma("unroll") for (int k = 0; k < 2; ++k) dst[n][k] = *(const LAS bf16x8*)(lds + PG8_SB(b, h) + boff + n * 2048 + k * 1024); } while (0)
; #define PG8_MMA(ai, bj, At, Bt) do { __builtin_amdgcn_s_setprio(1); _Pragma("unroll") for (int m = 0; m < 4; ++m) _Pragma("unroll") for (int n = 0; n < 2; ++n) _Pragma("unroll") for (int k = 0; k < 2; ++k) \
;         acc[ai][bj][m][n] = __builtin_amdgcn_mfma_f32_16x16x32_bf16(Bt[n][k], At[m][k], acc[ai][bj][m][n], 0, 0, 0); __builtin_amdgcn_s_setprio(0); } while (0)
; #define PG8_WAIT_V(n) asm volatile("s_waitcnt vmcnt(" #n ")" ::: "memory")
; #define PG8_WAIT_L(n) asm volatile("s_waitcnt lgkmcnt(" #n ")" ::: "memory")
; #define PG8_BAR __builtin_amdgcn_s_barrier()
; #define PG8_SCHED __builtin_amdgcn_sched_barrier(0)
; template <class Epi, class Sched, bool ALIGN_EPI = false, bool SP2 = false>
; __device__ __forceinline__ void gemm_phase(LAS unsigned char* lds, const Gemm g, const Sched& S, const Epi& E) {
;     ...
;             PG8_LDB(B0, 1, 0); PG8_LDB(B1, 1, 1); PG8_SCHED; PG8_LDA(At, 1, 0); PG8_STAGE(PG8_SA(0, 1), a2 + hstep, voffA);
;             PG8_WAIT_V(8); PG8_WAIT_L(0); PG8_BAR; PG8_MMA(0, 0, At, B0); PG8_MMA(0, 1, At, B1); PG8_BAR; PG8_SCHED;
	s_add_i32 s56, 0, 0x18000
	s_add_i32 s57, 0, 0x1c000
	v_add_u32_e32 v142, s56, v1
	v_add_u32_e32 v162, s57, v1
	ds_read_b128 v[58:61], v142
	ds_read_b128 v[62:65], v142 offset:1024
	ds_read_b128 v[138:141], v142 offset:2048
	ds_read_b128 v[142:145], v142 offset:3072
	ds_read_b128 v[146:149], v162
	ds_read_b128 v[150:153], v162 offset:1024
	ds_read_b128 v[174:177], v162 offset:2048
	ds_read_b128 v[178:181], v162 offset:3072
	s_add_u32 s34, s34, 0x80000
	s_addc_u32 s35, s35, 0
	s_mov_b32 m0, s30
	v_lshl_add_u64 v[232:233], s[34:35], 0, v[154:155]
	ds_read_b128 v[182:185], v198 offset:32768
	ds_read_b128 v[186:189], v198 offset:33792
	ds_read_b128 v[202:205], v198 offset:34816
	ds_read_b128 v[206:209], v198 offset:35840
	ds_read_b128 v[210:213], v198 offset:36864
	ds_read_b128 v[214:217], v198 offset:37888
	ds_read_b128 v[218:221], v198 offset:38912
	ds_read_b128 v[222:225], v198 offset:39936
	global_load_lds_dwordx4 v[232:233], off
	v_lshl_add_u64 v[232:233], s[34:35], 0, v[158:159]
	s_mov_b32 m0, s31
	s_nop 0
	global_load_lds_dwordx4 v[232:233], off
	s_waitcnt vmcnt(8)
	s_waitcnt lgkmcnt(0)
	s_barrier
	s_waitcnt lgkmcnt(0)
	v_mfma_f32_16x16x32_bf16 v[134:137], v[58:61], v[182:185], v[134:137]
	v_mfma_f32_16x16x32_bf16 v[130:133], v[138:141], v[182:185], v[130:133]
	v_mfma_f32_16x16x32_bf16 v[118:121], v[58:61], v[202:205], v[118:121]
	v_mfma_f32_16x16x32_bf16 v[114:117], v[138:141], v[202:205], v[114:117]
	v_mfma_f32_16x16x32_bf16 v[102:105], v[58:61], v[210:213], v[102:105]
	v_mfma_f32_16x16x32_bf16 v[98:101], v[138:141], v[210:213], v[98:101]
	v_mfma_f32_16x16x32_bf16 v[86:89], v[58:61], v[218:221], v[86:89]
	v_mfma_f32_16x16x32_bf16 v[82:85], v[138:141], v[218:221], v[82:85]
	v_mfma_f32_16x16x32_bf16 v[134:137], v[62:65], v[186:189], v[134:137]
	v_mfma_f32_16x16x32_bf16 v[130:133], v[142:145], v[186:189], v[130:133]
	v_mfma_f32_16x16x32_bf16 v[118:121], v[62:65], v[206:209], v[118:121]
	v_mfma_f32_16x16x32_bf16 v[114:117], v[142:145], v[206:209], v[114:117]
	v_mfma_f32_16x16x32_bf16 v[102:105], v[62:65], v[214:217], v[102:105]
	v_mfma_f32_16x16x32_bf16 v[98:101], v[142:145], v[214:217], v[98:101]
	v_mfma_f32_16x16x32_bf16 v[86:89], v[62:65], v[222:225], v[86:89]
	v_mfma_f32_16x16x32_bf16 v[82:85], v[142:145], v[222:225], v[82:85]
	v_mfma_f32_16x16x32_bf16 v[126:129], v[146:149], v[182:185], v[126:129]
	v_mfma_f32_16x16x32_bf16 v[122:125], v[174:177], v[182:185], v[122:125]
	v_mfma_f32_16x16x32_bf16 v[110:113], v[146:149], v[202:205], v[110:113]
	v_mfma_f32_16x16x32_bf16 v[106:109], v[174:177], v[202:205], v[106:109]
	v_mfma_f32_16x16x32_bf16 v[94:97], v[146:149], v[210:213], v[94:97]
	v_mfma_f32_16x16x32_bf16 v[90:93], v[174:177], v[210:213], v[90:93]
	v_mfma_f32_16x16x32_bf16 v[78:81], v[146:149], v[218:221], v[78:81]
	v_mfma_f32_16x16x32_bf16 v[74:77], v[174:177], v[218:221], v[74:77]
	v_mfma_f32_16x16x32_bf16 v[126:129], v[150:153], v[186:189], v[126:129]
	v_mfma_f32_16x16x32_bf16 v[122:125], v[178:181], v[186:189], v[122:125]
	v_mfma_f32_16x16x32_bf16 v[110:113], v[150:153], v[206:209], v[110:113]
	v_mfma_f32_16x16x32_bf16 v[106:109], v[178:181], v[206:209], v[106:109]
	v_mfma_f32_16x16x32_bf16 v[94:97], v[150:153], v[214:217], v[94:97]
	v_mfma_f32_16x16x32_bf16 v[90:93], v[178:181], v[214:217], v[90:93]
	v_mfma_f32_16x16x32_bf16 v[78:81], v[150:153], v[222:225], v[78:81]
	v_mfma_f32_16x16x32_bf16 v[74:77], v[178:181], v[222:225], v[74:77]
	s_barrier
; #define PG8_STAGE(bufoff, gbase, voff) do { _Pragma("unroll") for (int _i = 0; _i < 2; ++_i) \
;         __builtin_amdgcn_global_load_lds((const unsigned*)((const char*)(gbase) + (voff)[_i]), (LAS unsigned*)(lds + (bufoff) + ldsw + _i * 8192), 16, 0, 0); } while (0)
; #define PG8_LDA(dst, b, h) do { _Pragma("unroll") for (int m = 0; m < 4; ++m) _Pragma("unroll") for (int k = 0; k < 2; ++k) dst[m][k] = *(const LAS bf16x8*)(lds + PG8_SA(b, h) + aoff + m * 2048 + k * 1024); } while (0)
; #define PG8_MMA(ai, bj, At, Bt) do { __builtin_amdgcn_s_setprio(1); _Pragma("unroll") for (int m = 0; m < 4; ++m) _Pragma("unroll") for (int n = 0; n < 2; ++n) _Pragma("unroll") for (int k = 0; k < 2; ++k) \
;         acc[ai][bj][m][n] = __builtin_amdgcn_mfma_f32_16x16x32_bf16(Bt[n][k], At[m][k], acc[ai][bj][m][n], 0, 0, 0); __builtin_amdgcn_s_setprio(0); } while (0)
; #define PG8_WAIT_V(n) asm volatile("s_waitcnt vmcnt(" #n ")" ::: "memory")
; #define PG8_WAIT_L(n) asm volatile("s_waitcnt lgkmcnt(" #n ")" ::: "memory")
; #define PG8_BAR __builtin_amdgcn_s_barrier()
; #define PG8_SCHED __builtin_amdgcn_sched_barrier(0)
; template <class Epi, class Sched, bool ALIGN_EPI = false, bool SP2 = false>
; __device__ __forceinline__ void gemm_phase(LAS unsigned char* lds, const Gemm g, const Sched& S, const Epi& E) {
;     ...
;         for (int t = 0; t < nt; t += 2) {
;     ...
;             PG8_LDA(At, 1, 1); PG8_STAGE(PG8_SB(1, 0), b3, voffB); PG8_STAGE(PG8_SB(1, 1), b3 + hstepB, voffB); PG8_STAGE(PG8_SA(1, 0), a3, voffA);
;             PG8_WAIT_V(8); PG8_WAIT_L(0); PG8_BAR; PG8_MMA(1, 0, At, B0); PG8_MMA(1, 1, At, B1); PG8_BAR; PG8_SCHED;
;     ...
;         if constexpr (ALIGN_EPI) { if (wr == 0) PG8_BAR; }
	s_add_i32 s34, s56, s27
	v_lshl_add_u64 v[190:191], v[190:191], 0, s[8:9]
	s_mov_b32 m0, s34
	ds_read_b128 v[182:185], v198 offset:49152
	ds_read_b128 v[186:189], v198 offset:50176
	ds_read_b128 v[202:205], v198 offset:51200
	ds_read_b128 v[206:209], v198 offset:52224
	ds_read_b128 v[210:213], v198 offset:53248
	ds_read_b128 v[214:217], v198 offset:54272
	ds_read_b128 v[218:221], v198 offset:55296
	ds_read_b128 v[222:225], v198 offset:56320
	global_load_lds_dwordx4 v[190:191], off
	s_add_i32 m0, s34, 0x2000
	s_add_u32 s24, s24, 0x20080
	v_lshl_add_u64 v[190:191], v[226:227], 0, s[8:9]
	s_addc_u32 s25, s25, 0
	s_add_i32 s34, s57, s27
	global_load_lds_dwordx4 v[190:191], off
	v_lshl_add_u64 v[190:191], s[24:25], 0, v[156:157]
	s_mov_b32 m0, s34
	s_nop 0
	global_load_lds_dwordx4 v[190:191], off
	v_lshl_add_u64 v[190:191], s[24:25], 0, v[160:161]
	s_add_i32 m0, s34, 0x2000
	s_nop 0
	global_load_lds_dwordx4 v[190:191], off
	v_lshl_add_u64 v[190:191], v[228:229], 0, s[8:9]
	s_mov_b32 m0, s48
	s_nop 0
	global_load_lds_dwordx4 v[190:191], off
	v_lshl_add_u64 v[190:191], v[230:231], 0, s[8:9]
	s_mov_b32 m0, s49
	s_nop 0
	global_load_lds_dwordx4 v[190:191], off
	s_waitcnt vmcnt(8)
	s_waitcnt lgkmcnt(0)
	s_barrier
	s_waitcnt lgkmcnt(0)
	v_mfma_f32_16x16x32_bf16 v[70:73], v[58:61], v[182:185], v[70:73]
	v_mfma_f32_16x16x32_bf16 v[66:69], v[138:141], v[182:185], v[66:69]
	v_mfma_f32_16x16x32_bf16 v[46:49], v[58:61], v[202:205], v[46:49]
	v_mfma_f32_16x16x32_bf16 v[42:45], v[138:141], v[202:205], v[42:45]
	v_mfma_f32_16x16x32_bf16 v[30:33], v[58:61], v[210:213], v[30:33]
	v_mfma_f32_16x16x32_bf16 v[26:29], v[138:141], v[210:213], v[26:29]
	v_mfma_f32_16x16x32_bf16 v[14:17], v[58:61], v[218:221], v[14:17]
	v_mfma_f32_16x16x32_bf16 v[10:13], v[138:141], v[218:221], v[10:13]
	v_mfma_f32_16x16x32_bf16 v[70:73], v[62:65], v[186:189], v[70:73]
	v_mfma_f32_16x16x32_bf16 v[66:69], v[142:145], v[186:189], v[66:69]
	v_mfma_f32_16x16x32_bf16 v[46:49], v[62:65], v[206:209], v[46:49]
	v_mfma_f32_16x16x32_bf16 v[42:45], v[142:145], v[206:209], v[42:45]
	v_mfma_f32_16x16x32_bf16 v[30:33], v[62:65], v[214:217], v[30:33]
	v_mfma_f32_16x16x32_bf16 v[26:29], v[142:145], v[214:217], v[26:29]
	v_mfma_f32_16x16x32_bf16 v[14:17], v[62:65], v[222:225], v[14:17]
	v_mfma_f32_16x16x32_bf16 v[10:13], v[142:145], v[222:225], v[10:13]
	v_mfma_f32_16x16x32_bf16 v[50:53], v[146:149], v[182:185], v[50:53]
	v_mfma_f32_16x16x32_bf16 v[62:65], v[150:153], v[186:189], v[50:53]
	v_mfma_f32_16x16x32_bf16 v[50:53], v[174:177], v[182:185], v[54:57]
	v_mfma_f32_16x16x32_bf16 v[38:41], v[146:149], v[202:205], v[38:41]
	v_mfma_f32_16x16x32_bf16 v[34:37], v[174:177], v[202:205], v[34:37]
	v_mfma_f32_16x16x32_bf16 v[22:25], v[146:149], v[210:213], v[22:25]
	v_mfma_f32_16x16x32_bf16 v[18:21], v[174:177], v[210:213], v[18:21]
	v_mfma_f32_16x16x32_bf16 v[6:9], v[146:149], v[218:221], v[6:9]
	v_mfma_f32_16x16x32_bf16 v[2:5], v[174:177], v[218:221], v[2:5]
	v_mfma_f32_16x16x32_bf16 v[58:61], v[178:181], v[186:189], v[50:53]
	v_mfma_f32_16x16x32_bf16 v[38:41], v[150:153], v[206:209], v[38:41]
	v_mfma_f32_16x16x32_bf16 v[34:37], v[178:181], v[206:209], v[34:37]
	v_mfma_f32_16x16x32_bf16 v[22:25], v[150:153], v[214:217], v[22:25]
	v_mfma_f32_16x16x32_bf16 v[18:21], v[178:181], v[214:217], v[18:21]
	v_mfma_f32_16x16x32_bf16 v[6:9], v[150:153], v[222:225], v[6:9]
	v_mfma_f32_16x16x32_bf16 v[2:5], v[178:181], v[222:225], v[2:5]
	s_barrier
	s_add_i32 s55, s55, 2
	s_add_u32 s53, s53, 0x100
	s_addc_u32 s54, s54, 0
	s_add_u32 s22, s22, 0x100
	s_addc_u32 s23, s23, 0
	s_cmp_lt_u32 s55, 30
	s_cbranch_scc1 .LBB0_2766
	s_setprio 0
	s_andn2_b64 vcc, exec, s[10:11]
	s_cbranch_vccnz .LBB0_2769
	s_barrier

; __device__ __forceinline__ float row_rstd(const float* ss, int row) { return 1.0f / sqrtf(ss[row] * (1.0f / DM) + 1e-6f); }
; #define PG8_STAGE(bufoff, gbase, voff) do { _Pragma("unroll") for (int _i = 0; _i < 2; ++_i) \
;         __builtin_amdgcn_global_load_lds((const unsigned*)((const char*)(gbase) + (voff)[_i]), (LAS unsigned*)(lds + (bufoff) + ldsw + _i * 8192), 16, 0, 0); } while (0)
; #define PG8_LDA(dst, b, h) do { _Pragma("unroll") for (int m = 0; m < 4; ++m) _Pragma("unroll") for (int k = 0; k < 2; ++k) dst[m][k] = *(const LAS bf16x8*)(lds + PG8_SA(b, h) + aoff + m * 2048 + k * 1024); } while (0)
; #define PG8_LDB(dst, b, h) do { _Pragma("unroll") for (int n = 0; n < 2; ++n) _Pragma("unroll") for (int k = 0; k < 2; ++k) dst[n][k] = *(const LAS bf16x8*)(lds + PG8_SB(b, h) + boff + n * 2048 + k * 1024); } while (0)
; #define PG8_MMA(ai, bj, At, Bt) do { __builtin_amdgcn_s_setprio(1); _Pragma("unroll") for (int m = 0; m < 4; ++m) _Pragma("unroll") for (int n = 0; n < 2; ++n) _Pragma("unroll") for (int k = 0; k < 2; ++k) \
;         acc[ai][bj][m][n] = __builtin_amdgcn_mfma_f32_16x16x32_bf16(Bt[n][k], At[m][k], acc[ai][bj][m][n], 0, 0, 0); __builtin_amdgcn_s_setprio(0); } while (0)
; #define PG8_WAIT_V(n) asm volatile("s_waitcnt vmcnt(" #n ")" ::: "memory")
; #define PG8_WAIT_L(n) asm volatile("s_waitcnt lgkmcnt(" #n ")" ::: "memory")
;     __device__ __forceinline__ void operator()(const f32x4 (&acc)[2][2][4][2], const Unit& u, int wr, int wc, int fr, int fq) const {
;     ...
;         const float* bp = bias + (size_t)s * BIAS_N + u.pn * BM + wc * 32 + 8 * fq;
;         const f32x4 ba0 = *(const f32x4*)bp, ba1 = *(const f32x4*)(bp + 4), bb0 = *(const f32x4*)(bp + HALF), bb1 = *(const f32x4*)(bp + HALF + 4);
;         const int lane = fq * 16 + fr;
;         const float rsl0 = row_rstd(ss, u.pm * BM + wr * 64 + lane), rsl1 = row_rstd(ss, u.pm * BM + HALF + wr * 64 + lane);
; template <class Epi, class Sched, bool ALIGN_EPI = false, bool SP2 = false>
; __device__ __forceinline__ void gemm_phase(LAS unsigned char* lds, const Gemm g, const Sched& S, const Epi& E) {
;     ...
;             if constexpr (SP2) {
;             PG8_LDB(B0, 0, 0); PG8_LDB(B1, 0, 1); PG8_SCHED; PG8_LDA(At, 0, 0); PG8_STAGE(PG8_SA(1, 1), a1 + hstep, voffA);
;             PG8_WAIT_V(8); PG8_WAIT_L(0); PG8_BAR; PG8_MMA(0, 0, At, B0); PG8_MMA(0, 1, At, B1); PG8_BAR; PG8_SCHED;
.Lpre_up2l1:
	s_lshl_b64 s[98:99], s[98:99], 2
	s_add_u32 s98, s35, s98
	s_addc_u32 s99, s38, s99
	s_lshl_b32 s100, s3, 8
	s_ashr_i32 s101, s100, 31
	s_lshl_b64 s[100:101], s[100:101], 2
	s_add_u32 s98, s98, s100
	s_addc_u32 s99, s99, s101
	s_add_u32 s98, s98, s44
	s_addc_u32 s99, s99, 0
	s_lshl_b32 s100, s2, 8
	s_add_i32 s100, s100, s34
	v_or_b32_e32 v162, s100, v170
	v_ashrrev_i32_e32 v163, 31, v162
	v_lshl_add_u64 v[162:163], v[162:163], 2, s[0:1]
	v_add_u32_e32 v164, s100, v171
	v_ashrrev_i32_e32 v165, 31, v164
	v_lshl_add_u64 v[164:165], v[164:165], 2, s[0:1]
	global_load_dwordx4 v[234:237], v176, s[98:99] offset:16
	global_load_dwordx4 v[238:241], v176, s[98:99]
	global_load_dwordx4 v[242:245], v176, s[98:99] offset:528
	global_load_dwordx4 v[246:249], v176, s[98:99] offset:512
	global_load_dword v250, v[162:163], off
	global_load_dword v251, v[164:165], off
	v_readfirstlane_b32 s98, v0
	s_nop 3
	s_lshr_b32 s98, s98, 6
	s_cmp_ge_u32 s98, 4
	s_cbranch_scc0 .Lprio_2916
	s_setprio 1
.Lprio_2916:
	ds_read_b128 v[66:69], v173
	ds_read_b128 v[70:73], v173 offset:1024
	ds_read_b128 v[74:77], v173 offset:2048
	ds_read_b128 v[78:81], v173 offset:3072
	ds_read_b128 v[162:165], v174
	ds_read_b128 v[180:183], v174 offset:1024
	ds_read_b128 v[184:187], v174 offset:2048
	ds_read_b128 v[188:191], v174 offset:3072
	s_add_u32 s20, s18, 0xfff80080
	s_addc_u32 s21, s19, -1
	s_cmp_eq_u32 s50, 28
	s_cselect_b32 s23, s13, s21
	s_cselect_b32 s22, s46, s20
	s_cselect_b32 s21, s11, s49
	s_cselect_b32 s20, s47, s48
	v_lshl_add_u64 v[166:167], s[18:19], 0, v[156:157]
	s_add_i32 m0, s28, 0xc000
	ds_read_b128 v[192:195], v175
	ds_read_b128 v[196:199], v175 offset:1024
	ds_read_b128 v[200:203], v175 offset:2048
	ds_read_b128 v[204:207], v175 offset:3072
	ds_read_b128 v[208:211], v175 offset:4096
	ds_read_b128 v[212:215], v175 offset:5120
	ds_read_b128 v[216:219], v175 offset:6144
	ds_read_b128 v[220:223], v175 offset:7168
	global_load_lds_dwordx4 v[166:167], off
	v_lshl_add_u64 v[166:167], s[18:19], 0, v[154:155]
	s_add_i32 m0, s28, 0xe000
	s_nop 0
	global_load_lds_dwordx4 v[166:167], off
	s_waitcnt lgkmcnt(0)
	s_barrier
	s_waitcnt lgkmcnt(0)
	v_mfma_f32_16x16x32_bf16 v[142:145], v[66:69], v[192:195], 0
	v_mfma_f32_16x16x32_bf16 v[138:141], v[74:77], v[192:195], 0
	v_mfma_f32_16x16x32_bf16 v[126:129], v[66:69], v[200:203], 0
	v_mfma_f32_16x16x32_bf16 v[122:125], v[74:77], v[200:203], 0
	v_mfma_f32_16x16x32_bf16 v[110:113], v[66:69], v[208:211], 0
	v_mfma_f32_16x16x32_bf16 v[106:109], v[74:77], v[208:211], 0
	v_mfma_f32_16x16x32_bf16 v[94:97], v[66:69], v[216:219], 0
	v_mfma_f32_16x16x32_bf16 v[90:93], v[74:77], v[216:219], 0
	v_mfma_f32_16x16x32_bf16 v[142:145], v[70:73], v[196:199], v[142:145]
	v_mfma_f32_16x16x32_bf16 v[138:141], v[78:81], v[196:199], v[138:141]
	v_mfma_f32_16x16x32_bf16 v[126:129], v[70:73], v[204:207], v[126:129]
	v_mfma_f32_16x16x32_bf16 v[122:125], v[78:81], v[204:207], v[122:125]
	v_mfma_f32_16x16x32_bf16 v[110:113], v[70:73], v[212:215], v[110:113]
	v_mfma_f32_16x16x32_bf16 v[106:109], v[78:81], v[212:215], v[106:109]
	v_mfma_f32_16x16x32_bf16 v[94:97], v[70:73], v[220:223], v[94:97]
	v_mfma_f32_16x16x32_bf16 v[90:93], v[78:81], v[220:223], v[90:93]
	v_mfma_f32_16x16x32_bf16 v[134:137], v[162:165], v[192:195], 0
	v_mfma_f32_16x16x32_bf16 v[130:133], v[184:187], v[192:195], 0
	v_mfma_f32_16x16x32_bf16 v[118:121], v[162:165], v[200:203], 0
	v_mfma_f32_16x16x32_bf16 v[114:117], v[184:187], v[200:203], 0
	v_mfma_f32_16x16x32_bf16 v[102:105], v[162:165], v[208:211], 0
	v_mfma_f32_16x16x32_bf16 v[98:101], v[184:187], v[208:211], 0
	v_mfma_f32_16x16x32_bf16 v[86:89], v[162:165], v[216:219], 0
	v_mfma_f32_16x16x32_bf16 v[82:85], v[184:187], v[216:219], 0
	v_mfma_f32_16x16x32_bf16 v[134:137], v[180:183], v[196:199], v[134:137]
	v_mfma_f32_16x16x32_bf16 v[130:133], v[188:191], v[196:199], v[130:133]
	v_mfma_f32_16x16x32_bf16 v[118:121], v[180:183], v[204:207], v[118:121]
	v_mfma_f32_16x16x32_bf16 v[114:117], v[188:191], v[204:207], v[114:117]
	v_mfma_f32_16x16x32_bf16 v[102:105], v[180:183], v[212:215], v[102:105]
	v_mfma_f32_16x16x32_bf16 v[98:101], v[188:191], v[212:215], v[98:101]
	v_mfma_f32_16x16x32_bf16 v[86:89], v[180:183], v[220:223], v[86:89]
	v_mfma_f32_16x16x32_bf16 v[82:85], v[188:191], v[220:223], v[82:85]
	s_barrier
	s_add_i32 s51, s41, s25
	v_lshl_add_u64 v[166:167], s[20:21], 0, v[150:151]
	s_mov_b32 m0, s51
	ds_read_b128 v[192:195], v175 offset:16384
	ds_read_b128 v[196:199], v175 offset:17408
	ds_read_b128 v[200:203], v175 offset:18432
	ds_read_b128 v[204:207], v175 offset:19456
	ds_read_b128 v[208:211], v175 offset:20480
	ds_read_b128 v[212:215], v175 offset:21504
	ds_read_b128 v[216:219], v175 offset:22528
	ds_read_b128 v[220:223], v175 offset:23552
	global_load_lds_dwordx4 v[166:167], off
	s_add_i32 m0, s51, 0x2000
	s_add_u32 s52, s20, 0x80000
	v_lshl_add_u64 v[224:225], s[20:21], 0, v[146:147]
	s_addc_u32 s53, s21, 0
	s_add_i32 s51, s42, s25
	global_load_lds_dwordx4 v[224:225], off
	v_lshl_add_u64 v[226:227], s[52:53], 0, v[150:151]
	s_mov_b32 m0, s51
	v_lshl_add_u64 v[228:229], s[22:23], 0, v[148:149]
	global_load_lds_dwordx4 v[226:227], off
	v_lshl_add_u64 v[226:227], s[52:53], 0, v[146:147]
	s_add_i32 m0, s51, 0x2000
	s_nop 0
	global_load_lds_dwordx4 v[226:227], off
	v_lshl_add_u64 v[226:227], s[22:23], 0, v[152:153]
	s_mov_b32 m0, s28
	s_nop 0
	global_load_lds_dwordx4 v[226:227], off
	s_mov_b32 m0, s29
	s_nop 0
	global_load_lds_dwordx4 v[228:229], off
	s_waitcnt lgkmcnt(0)
	s_barrier
; #define PG8_STAGE(bufoff, gbase, voff) do { _Pragma("unroll") for (int _i = 0; _i < 2; ++_i) \
;         __builtin_amdgcn_global_load_lds((const unsigned*)((const char*)(gbase) + (voff)[_i]), (LAS unsigned*)(lds + (bufoff) + ldsw + _i * 8192), 16, 0, 0); } while (0)
; #define PG8_LDA(dst, b, h) do { _Pragma("unroll") for (int m = 0; m < 4; ++m) _Pragma("unroll") for (int k = 0; k < 2; ++k) dst[m][k] = *(const LAS bf16x8*)(lds + PG8_SA(b, h) + aoff + m * 2048 + k * 1024); } while (0)
; #define PG8_LDB(dst, b, h) do { _Pragma("unroll") for (int n = 0; n < 2; ++n) _Pragma("unroll") for (int k = 0; k < 2; ++k) dst[n][k] = *(const LAS bf16x8*)(lds + PG8_SB(b, h) + boff + n * 2048 + k * 1024); } while (0)
; #define PG8_MMA(ai, bj, At, Bt) do { __builtin_amdgcn_s_setprio(1); _Pragma("unroll") for (int m = 0; m < 4; ++m) _Pragma("unroll") for (int n = 0; n < 2; ++n) _Pragma("unroll") for (int k = 0; k < 2; ++k) \
;         acc[ai][bj][m][n] = __builtin_amdgcn_mfma_f32_16x16x32_bf16(Bt[n][k], At[m][k], acc[ai][bj][m][n], 0, 0, 0); __builtin_amdgcn_s_setprio(0); } while (0)
; #define PG8_WAIT_V(n) asm volatile("s_waitcnt vmcnt(" #n ")" ::: "memory")
; #define PG8_WAIT_L(n) asm volatile("s_waitcnt lgkmcnt(" #n ")" ::: "memory")
; #define PG8_BAR __builtin_amdgcn_s_barrier()
; #define PG8_SCHED __builtin_amdgcn_sched_barrier(0)
; template <class Epi, class Sched, bool ALIGN_EPI = false, bool SP2 = false>
; __device__ __forceinline__ void gemm_phase(LAS unsigned char* lds, const Gemm g, const Sched& S, const Epi& E) {
;     ...
;             PG8_WAIT_V(8); PG8_WAIT_L(0); PG8_BAR; PG8_MMA(0, 0, At, B0); PG8_MMA(0, 1, At, B1); PG8_BAR; PG8_SCHED;
;             PG8_LDA(At, 0, 1); PG8_STAGE(PG8_SB(0, 0), b2, voffB); PG8_STAGE(PG8_SB(0, 1), b2 + hstepB, voffB); PG8_STAGE(PG8_SA(0, 0), a2, voffA);
;             PG8_WAIT_V(8); PG8_WAIT_L(0); PG8_BAR; PG8_MMA(1, 0, At, B0); PG8_MMA(1, 1, At, B1); PG8_BAR; PG8_SCHED;
;             PG8_LDB(B0, 1, 0); PG8_LDB(B1, 1, 1); PG8_SCHED; PG8_LDA(At, 1, 0); PG8_STAGE(PG8_SA(0, 1), a2 + hstep, voffA);
;             PG8_WAIT_V(8); PG8_WAIT_L(0); PG8_BAR; PG8_MMA(0, 0, At, B0); PG8_MMA(0, 1, At, B1); PG8_BAR; PG8_SCHED;
	s_waitcnt lgkmcnt(0)
	v_mfma_f32_16x16x32_bf16 v[62:65], v[66:69], v[192:195], 0
	v_mfma_f32_16x16x32_bf16 v[58:61], v[74:77], v[192:195], 0
	v_mfma_f32_16x16x32_bf16 v[46:49], v[66:69], v[200:203], 0
	v_mfma_f32_16x16x32_bf16 v[42:45], v[74:77], v[200:203], 0
	v_mfma_f32_16x16x32_bf16 v[30:33], v[66:69], v[208:211], 0
	v_mfma_f32_16x16x32_bf16 v[26:29], v[74:77], v[208:211], 0
	v_mfma_f32_16x16x32_bf16 v[14:17], v[66:69], v[216:219], 0
	v_mfma_f32_16x16x32_bf16 v[10:13], v[74:77], v[216:219], 0
	v_mfma_f32_16x16x32_bf16 v[62:65], v[70:73], v[196:199], v[62:65]
	v_mfma_f32_16x16x32_bf16 v[58:61], v[78:81], v[196:199], v[58:61]
	v_mfma_f32_16x16x32_bf16 v[46:49], v[70:73], v[204:207], v[46:49]
	v_mfma_f32_16x16x32_bf16 v[42:45], v[78:81], v[204:207], v[42:45]
	v_mfma_f32_16x16x32_bf16 v[30:33], v[70:73], v[212:215], v[30:33]
	v_mfma_f32_16x16x32_bf16 v[26:29], v[78:81], v[212:215], v[26:29]
	v_mfma_f32_16x16x32_bf16 v[14:17], v[70:73], v[220:223], v[14:17]
	v_mfma_f32_16x16x32_bf16 v[10:13], v[78:81], v[220:223], v[10:13]
	v_mfma_f32_16x16x32_bf16 v[54:57], v[162:165], v[192:195], 0
	v_mfma_f32_16x16x32_bf16 v[50:53], v[184:187], v[192:195], 0
	v_mfma_f32_16x16x32_bf16 v[38:41], v[162:165], v[200:203], 0
	v_mfma_f32_16x16x32_bf16 v[34:37], v[184:187], v[200:203], 0
	v_mfma_f32_16x16x32_bf16 v[22:25], v[162:165], v[208:211], 0
	v_mfma_f32_16x16x32_bf16 v[18:21], v[184:187], v[208:211], 0
	v_mfma_f32_16x16x32_bf16 v[6:9], v[162:165], v[216:219], 0
	v_mfma_f32_16x16x32_bf16 v[2:5], v[184:187], v[216:219], 0
	v_mfma_f32_16x16x32_bf16 v[54:57], v[180:183], v[196:199], v[54:57]
	v_mfma_f32_16x16x32_bf16 v[50:53], v[188:191], v[196:199], v[50:53]
	v_mfma_f32_16x16x32_bf16 v[38:41], v[180:183], v[204:207], v[38:41]
	v_mfma_f32_16x16x32_bf16 v[34:37], v[188:191], v[204:207], v[34:37]
	v_mfma_f32_16x16x32_bf16 v[22:25], v[180:183], v[212:215], v[22:25]
	v_mfma_f32_16x16x32_bf16 v[18:21], v[188:191], v[212:215], v[18:21]
	v_mfma_f32_16x16x32_bf16 v[6:9], v[180:183], v[220:223], v[6:9]
	v_mfma_f32_16x16x32_bf16 v[2:5], v[188:191], v[220:223], v[2:5]
	s_barrier
	s_add_i32 s51, 0, 0x18000
	s_add_i32 s52, 0, 0x1c000
	v_add_u32_e32 v78, s51, v169
	v_add_u32_e32 v168, s52, v169
	ds_read_b128 v[66:69], v78
	ds_read_b128 v[70:73], v78 offset:1024
	ds_read_b128 v[74:77], v78 offset:2048
	ds_read_b128 v[78:81], v78 offset:3072
	ds_read_b128 v[162:165], v168
	ds_read_b128 v[180:183], v168 offset:1024
	ds_read_b128 v[184:187], v168 offset:2048
	ds_read_b128 v[188:191], v168 offset:3072
	s_add_u32 s22, s22, 0x80000
	s_addc_u32 s23, s23, 0
	s_mov_b32 m0, s30
	v_lshl_add_u64 v[230:231], s[22:23], 0, v[152:153]
	ds_read_b128 v[192:195], v175 offset:32768
	ds_read_b128 v[196:199], v175 offset:33792
	ds_read_b128 v[200:203], v175 offset:34816
	ds_read_b128 v[204:207], v175 offset:35840
	ds_read_b128 v[208:211], v175 offset:36864
	ds_read_b128 v[212:215], v175 offset:37888
	ds_read_b128 v[216:219], v175 offset:38912
	ds_read_b128 v[220:223], v175 offset:39936
	global_load_lds_dwordx4 v[230:231], off
	v_lshl_add_u64 v[230:231], s[22:23], 0, v[148:149]
	s_mov_b32 m0, s31
	s_nop 0
	global_load_lds_dwordx4 v[230:231], off
	s_waitcnt vmcnt(8)
	s_waitcnt lgkmcnt(0)
	s_barrier
	s_waitcnt lgkmcnt(0)
	v_mfma_f32_16x16x32_bf16 v[142:145], v[66:69], v[192:195], v[142:145]
	v_mfma_f32_16x16x32_bf16 v[138:141], v[74:77], v[192:195], v[138:141]
	v_mfma_f32_16x16x32_bf16 v[126:129], v[66:69], v[200:203], v[126:129]
	v_mfma_f32_16x16x32_bf16 v[122:125], v[74:77], v[200:203], v[122:125]
	v_mfma_f32_16x16x32_bf16 v[110:113], v[66:69], v[208:211], v[110:113]
	v_mfma_f32_16x16x32_bf16 v[106:109], v[74:77], v[208:211], v[106:109]
	v_mfma_f32_16x16x32_bf16 v[94:97], v[66:69], v[216:219], v[94:97]
	v_mfma_f32_16x16x32_bf16 v[90:93], v[74:77], v[216:219], v[90:93]
	v_mfma_f32_16x16x32_bf16 v[142:145], v[70:73], v[196:199], v[142:145]
	v_mfma_f32_16x16x32_bf16 v[138:141], v[78:81], v[196:199], v[138:141]
	v_mfma_f32_16x16x32_bf16 v[126:129], v[70:73], v[204:207], v[126:129]
	v_mfma_f32_16x16x32_bf16 v[122:125], v[78:81], v[204:207], v[122:125]
	v_mfma_f32_16x16x32_bf16 v[110:113], v[70:73], v[212:215], v[110:113]
	v_mfma_f32_16x16x32_bf16 v[106:109], v[78:81], v[212:215], v[106:109]
	v_mfma_f32_16x16x32_bf16 v[94:97], v[70:73], v[220:223], v[94:97]
	v_mfma_f32_16x16x32_bf16 v[90:93], v[78:81], v[220:223], v[90:93]
	v_mfma_f32_16x16x32_bf16 v[134:137], v[162:165], v[192:195], v[134:137]
	v_mfma_f32_16x16x32_bf16 v[130:133], v[184:187], v[192:195], v[130:133]
	v_mfma_f32_16x16x32_bf16 v[118:121], v[162:165], v[200:203], v[118:121]
	v_mfma_f32_16x16x32_bf16 v[114:117], v[184:187], v[200:203], v[114:117]
	v_mfma_f32_16x16x32_bf16 v[102:105], v[162:165], v[208:211], v[102:105]
	v_mfma_f32_16x16x32_bf16 v[98:101], v[184:187], v[208:211], v[98:101]
	v_mfma_f32_16x16x32_bf16 v[86:89], v[162:165], v[216:219], v[86:89]
	v_mfma_f32_16x16x32_bf16 v[82:85], v[184:187], v[216:219], v[82:85]
	v_mfma_f32_16x16x32_bf16 v[134:137], v[180:183], v[196:199], v[134:137]
	v_mfma_f32_16x16x32_bf16 v[130:133], v[188:191], v[196:199], v[130:133]
	v_mfma_f32_16x16x32_bf16 v[118:121], v[180:183], v[204:207], v[118:121]
	v_mfma_f32_16x16x32_bf16 v[114:117], v[188:191], v[204:207], v[114:117]
	v_mfma_f32_16x16x32_bf16 v[102:105], v[180:183], v[212:215], v[102:105]
	v_mfma_f32_16x16x32_bf16 v[98:101], v[188:191], v[212:215], v[98:101]
	v_mfma_f32_16x16x32_bf16 v[86:89], v[180:183], v[220:223], v[86:89]
	v_mfma_f32_16x16x32_bf16 v[82:85], v[188:191], v[220:223], v[82:85]
	s_barrier
; #define PG8_STAGE(bufoff, gbase, voff) do { _Pragma("unroll") for (int _i = 0; _i < 2; ++_i) \
;         __builtin_amdgcn_global_load_lds((const unsigned*)((const char*)(gbase) + (voff)[_i]), (LAS unsigned*)(lds + (bufoff) + ldsw + _i * 8192), 16, 0, 0); } while (0)
; #define PG8_LDA(dst, b, h) do { _Pragma("unroll") for (int m = 0; m < 4; ++m) _Pragma("unroll") for (int k = 0; k < 2; ++k) dst[m][k] = *(const LAS bf16x8*)(lds + PG8_SA(b, h) + aoff + m * 2048 + k * 1024); } while (0)
; #define PG8_LDB(dst, b, h) do { _Pragma("unroll") for (int n = 0; n < 2; ++n) _Pragma("unroll") for (int k = 0; k < 2; ++k) dst[n][k] = *(const LAS bf16x8*)(lds + PG8_SB(b, h) + boff + n * 2048 + k * 1024); } while (0)
; #define PG8_MMA(ai, bj, At, Bt) do { __builtin_amdgcn_s_setprio(1); _Pragma("unroll") for (int m = 0; m < 4; ++m) _Pragma("unroll") for (int n = 0; n < 2; ++n) _Pragma("unroll") for (int k = 0; k < 2; ++k) \
;         acc[ai][bj][m][n] = __builtin_amdgcn_mfma_f32_16x16x32_bf16(Bt[n][k], At[m][k], acc[ai][bj][m][n], 0, 0, 0); __builtin_amdgcn_s_setprio(0); } while (0)
; #define PG8_WAIT_V(n) asm volatile("s_waitcnt vmcnt(" #n ")" ::: "memory")
; #define PG8_WAIT_L(n) asm volatile("s_waitcnt lgkmcnt(" #n ")" ::: "memory")
; #define PG8_BAR __builtin_amdgcn_s_barrier()
; #define PG8_SCHED __builtin_amdgcn_sched_barrier(0)
; template <class Epi, class Sched, bool ALIGN_EPI = false, bool SP2 = false>
; __device__ __forceinline__ void gemm_phase(LAS unsigned char* lds, const Gemm g, const Sched& S, const Epi& E) {
;     ...
;         for (int t = 0; t < nt; t += 2) {
;             const bool last = (t == nt - 2);
;             const char* a1 = cA + (size_t)(t + 1) * kstep;
;             const char* a2 = last ? nA : cA + (size_t)(t + 2) * kstep; const char* b2 = last ? nB : cB + (size_t)(t + 2) * kstep;
;             const char* a3 = a2 + kstep; const char* b3 = b2 + kstep;
;             if (last && has_next) S.a_ready(nxt);
;             if constexpr (SP2) {
;             PG8_LDB(B0, 0, 0); PG8_LDB(B1, 0, 1); PG8_SCHED; PG8_LDA(At, 0, 0); PG8_STAGE(PG8_SA(1, 1), a1 + hstep, voffA);
;     ...
;             PG8_LDA(At, 1, 1); PG8_STAGE(PG8_SB(1, 0), b3, voffB); PG8_STAGE(PG8_SB(1, 1), b3 + hstepB, voffB); PG8_STAGE(PG8_SA(1, 0), a3, voffA);
;             PG8_WAIT_V(8); PG8_WAIT_L(0); PG8_BAR; PG8_MMA(1, 0, At, B0); PG8_MMA(1, 1, At, B1); PG8_BAR; PG8_SCHED;
	s_add_i32 s22, s51, s25
	v_lshl_add_u64 v[166:167], v[166:167], 0, s[6:7]
	s_mov_b32 m0, s22
	ds_read_b128 v[192:195], v175 offset:49152
	ds_read_b128 v[196:199], v175 offset:50176
	ds_read_b128 v[200:203], v175 offset:51200
	ds_read_b128 v[204:207], v175 offset:52224
	ds_read_b128 v[208:211], v175 offset:53248
	ds_read_b128 v[212:215], v175 offset:54272
	ds_read_b128 v[216:219], v175 offset:55296
	ds_read_b128 v[220:223], v175 offset:56320
	global_load_lds_dwordx4 v[166:167], off
	s_add_i32 m0, s22, 0x2000
	s_add_u32 s20, s20, 0x80080
	v_lshl_add_u64 v[166:167], v[224:225], 0, s[6:7]
	s_addc_u32 s21, s21, 0
	s_add_i32 s22, s52, s25
	global_load_lds_dwordx4 v[166:167], off
	v_lshl_add_u64 v[166:167], s[20:21], 0, v[150:151]
	s_mov_b32 m0, s22
	s_nop 0
	global_load_lds_dwordx4 v[166:167], off
	v_lshl_add_u64 v[166:167], s[20:21], 0, v[146:147]
	s_add_i32 m0, s22, 0x2000
	s_nop 0
	global_load_lds_dwordx4 v[166:167], off
	v_lshl_add_u64 v[166:167], v[226:227], 0, s[6:7]
	s_mov_b32 m0, s39
	s_nop 0
	global_load_lds_dwordx4 v[166:167], off
	v_lshl_add_u64 v[166:167], v[228:229], 0, s[6:7]
	s_mov_b32 m0, s40
	s_nop 0
	global_load_lds_dwordx4 v[166:167], off
	s_waitcnt vmcnt(8)
	s_waitcnt lgkmcnt(0)
	s_barrier
	s_waitcnt lgkmcnt(0)
	v_mfma_f32_16x16x32_bf16 v[62:65], v[66:69], v[192:195], v[62:65]
	v_mfma_f32_16x16x32_bf16 v[58:61], v[74:77], v[192:195], v[58:61]
	v_mfma_f32_16x16x32_bf16 v[46:49], v[66:69], v[200:203], v[46:49]
	v_mfma_f32_16x16x32_bf16 v[42:45], v[74:77], v[200:203], v[42:45]
	v_mfma_f32_16x16x32_bf16 v[30:33], v[66:69], v[208:211], v[30:33]
	v_mfma_f32_16x16x32_bf16 v[26:29], v[74:77], v[208:211], v[26:29]
	v_mfma_f32_16x16x32_bf16 v[14:17], v[66:69], v[216:219], v[14:17]
	v_mfma_f32_16x16x32_bf16 v[10:13], v[74:77], v[216:219], v[10:13]
	v_mfma_f32_16x16x32_bf16 v[62:65], v[70:73], v[196:199], v[62:65]
	v_mfma_f32_16x16x32_bf16 v[58:61], v[78:81], v[196:199], v[58:61]
	v_mfma_f32_16x16x32_bf16 v[46:49], v[70:73], v[204:207], v[46:49]
	v_mfma_f32_16x16x32_bf16 v[42:45], v[78:81], v[204:207], v[42:45]
	v_mfma_f32_16x16x32_bf16 v[30:33], v[70:73], v[212:215], v[30:33]
	v_mfma_f32_16x16x32_bf16 v[26:29], v[78:81], v[212:215], v[26:29]
	v_mfma_f32_16x16x32_bf16 v[14:17], v[70:73], v[220:223], v[14:17]
	v_mfma_f32_16x16x32_bf16 v[10:13], v[78:81], v[220:223], v[10:13]
	v_mfma_f32_16x16x32_bf16 v[54:57], v[162:165], v[192:195], v[54:57]
	v_mfma_f32_16x16x32_bf16 v[50:53], v[184:187], v[192:195], v[50:53]
	v_mfma_f32_16x16x32_bf16 v[38:41], v[162:165], v[200:203], v[38:41]
	v_mfma_f32_16x16x32_bf16 v[34:37], v[184:187], v[200:203], v[34:37]
	v_mfma_f32_16x16x32_bf16 v[22:25], v[162:165], v[208:211], v[22:25]
	v_mfma_f32_16x16x32_bf16 v[18:21], v[184:187], v[208:211], v[18:21]
	v_mfma_f32_16x16x32_bf16 v[6:9], v[162:165], v[216:219], v[6:9]
	v_mfma_f32_16x16x32_bf16 v[2:5], v[184:187], v[216:219], v[2:5]
	v_mfma_f32_16x16x32_bf16 v[54:57], v[180:183], v[196:199], v[54:57]
	v_mfma_f32_16x16x32_bf16 v[50:53], v[188:191], v[196:199], v[50:53]
	v_mfma_f32_16x16x32_bf16 v[38:41], v[180:183], v[204:207], v[38:41]
	v_mfma_f32_16x16x32_bf16 v[34:37], v[188:191], v[204:207], v[34:37]
	v_mfma_f32_16x16x32_bf16 v[22:25], v[180:183], v[212:215], v[22:25]
	v_mfma_f32_16x16x32_bf16 v[18:21], v[188:191], v[212:215], v[18:21]
	v_mfma_f32_16x16x32_bf16 v[6:9], v[180:183], v[220:223], v[6:9]
	v_mfma_f32_16x16x32_bf16 v[2:5], v[188:191], v[220:223], v[2:5]
	s_barrier
	s_add_i32 s50, s50, 2
	s_add_u32 s48, s48, 0x100
	s_addc_u32 s49, s49, 0
	s_add_u32 s18, s18, 0x100
	s_addc_u32 s19, s19, 0
	s_cmp_lt_u32 s50, 30
.LBB0_2916:
	ds_read_b128 v[66:69], v173
	ds_read_b128 v[70:73], v173 offset:1024
	ds_read_b128 v[74:77], v173 offset:2048
	ds_read_b128 v[78:81], v173 offset:3072
	ds_read_b128 v[162:165], v174
	ds_read_b128 v[180:183], v174 offset:1024
	ds_read_b128 v[184:187], v174 offset:2048
	ds_read_b128 v[188:191], v174 offset:3072
	s_add_u32 s20, s18, 0xfff80080
	s_addc_u32 s21, s19, -1
	s_cmp_eq_u32 s50, 28
	s_cselect_b32 s23, s13, s21
	s_cselect_b32 s22, s46, s20
	s_cselect_b32 s21, s11, s49
	s_cselect_b32 s20, s47, s48
	v_lshl_add_u64 v[166:167], s[18:19], 0, v[156:157]
	s_add_i32 m0, s28, 0xc000
	ds_read_b128 v[192:195], v175
	ds_read_b128 v[196:199], v175 offset:1024
	ds_read_b128 v[200:203], v175 offset:2048
	ds_read_b128 v[204:207], v175 offset:3072
	ds_read_b128 v[208:211], v175 offset:4096
	ds_read_b128 v[212:215], v175 offset:5120
	ds_read_b128 v[216:219], v175 offset:6144
	ds_read_b128 v[220:223], v175 offset:7168
	global_load_lds_dwordx4 v[166:167], off
	v_lshl_add_u64 v[166:167], s[18:19], 0, v[154:155]
	s_add_i32 m0, s28, 0xe000
	s_nop 0
	global_load_lds_dwordx4 v[166:167], off
	s_waitcnt vmcnt(8)
	s_waitcnt lgkmcnt(0)
	s_barrier
; #define PG8_STAGE(bufoff, gbase, voff) do { _Pragma("unroll") for (int _i = 0; _i < 2; ++_i) \
;         __builtin_amdgcn_global_load_lds((const unsigned*)((const char*)(gbase) + (voff)[_i]), (LAS unsigned*)(lds + (bufoff) + ldsw + _i * 8192), 16, 0, 0); } while (0)
; #define PG8_LDA(dst, b, h) do { _Pragma("unroll") for (int m = 0; m < 4; ++m) _Pragma("unroll") for (int k = 0; k < 2; ++k) dst[m][k] = *(const LAS bf16x8*)(lds + PG8_SA(b, h) + aoff + m * 2048 + k * 1024); } while (0)
; #define PG8_MMA(ai, bj, At, Bt) do { __builtin_amdgcn_s_setprio(1); _Pragma("unroll") for (int m = 0; m < 4; ++m) _Pragma("unroll") for (int n = 0; n < 2; ++n) _Pragma("unroll") for (int k = 0; k < 2; ++k) \
;         acc[ai][bj][m][n] = __builtin_amdgcn_mfma_f32_16x16x32_bf16(Bt[n][k], At[m][k], acc[ai][bj][m][n], 0, 0, 0); __builtin_amdgcn_s_setprio(0); } while (0)
; #define PG8_WAIT_V(n) asm volatile("s_waitcnt vmcnt(" #n ")" ::: "memory")
; #define PG8_WAIT_L(n) asm volatile("s_waitcnt lgkmcnt(" #n ")" ::: "memory")
; #define PG8_BAR __builtin_amdgcn_s_barrier()
; #define PG8_SCHED __builtin_amdgcn_sched_barrier(0)
; template <class Epi, class Sched, bool ALIGN_EPI = false, bool SP2 = false>
; __device__ __forceinline__ void gemm_phase(LAS unsigned char* lds, const Gemm g, const Sched& S, const Epi& E) {
;     ...
;             PG8_WAIT_V(8); PG8_WAIT_L(0); PG8_BAR; PG8_MMA(0, 0, At, B0); PG8_MMA(0, 1, At, B1); PG8_BAR; PG8_SCHED;
;             PG8_LDA(At, 0, 1); PG8_STAGE(PG8_SB(0, 0), b2, voffB); PG8_STAGE(PG8_SB(0, 1), b2 + hstepB, voffB); PG8_STAGE(PG8_SA(0, 0), a2, voffA);
;             PG8_WAIT_V(8); PG8_WAIT_L(0); PG8_BAR; PG8_MMA(1, 0, At, B0); PG8_MMA(1, 1, At, B1); PG8_BAR; PG8_SCHED;
	s_waitcnt lgkmcnt(0)
	v_mfma_f32_16x16x32_bf16 v[142:145], v[66:69], v[192:195], v[142:145]
	v_mfma_f32_16x16x32_bf16 v[138:141], v[74:77], v[192:195], v[138:141]
	v_mfma_f32_16x16x32_bf16 v[126:129], v[66:69], v[200:203], v[126:129]
	v_mfma_f32_16x16x32_bf16 v[122:125], v[74:77], v[200:203], v[122:125]
	v_mfma_f32_16x16x32_bf16 v[110:113], v[66:69], v[208:211], v[110:113]
	v_mfma_f32_16x16x32_bf16 v[106:109], v[74:77], v[208:211], v[106:109]
	v_mfma_f32_16x16x32_bf16 v[94:97], v[66:69], v[216:219], v[94:97]
	v_mfma_f32_16x16x32_bf16 v[90:93], v[74:77], v[216:219], v[90:93]
	v_mfma_f32_16x16x32_bf16 v[142:145], v[70:73], v[196:199], v[142:145]
	v_mfma_f32_16x16x32_bf16 v[138:141], v[78:81], v[196:199], v[138:141]
	v_mfma_f32_16x16x32_bf16 v[126:129], v[70:73], v[204:207], v[126:129]
	v_mfma_f32_16x16x32_bf16 v[122:125], v[78:81], v[204:207], v[122:125]
	v_mfma_f32_16x16x32_bf16 v[110:113], v[70:73], v[212:215], v[110:113]
	v_mfma_f32_16x16x32_bf16 v[106:109], v[78:81], v[212:215], v[106:109]
	v_mfma_f32_16x16x32_bf16 v[94:97], v[70:73], v[220:223], v[94:97]
	v_mfma_f32_16x16x32_bf16 v[90:93], v[78:81], v[220:223], v[90:93]
	v_mfma_f32_16x16x32_bf16 v[134:137], v[162:165], v[192:195], v[134:137]
	v_mfma_f32_16x16x32_bf16 v[130:133], v[184:187], v[192:195], v[130:133]
	v_mfma_f32_16x16x32_bf16 v[118:121], v[162:165], v[200:203], v[118:121]
	v_mfma_f32_16x16x32_bf16 v[114:117], v[184:187], v[200:203], v[114:117]
	v_mfma_f32_16x16x32_bf16 v[102:105], v[162:165], v[208:211], v[102:105]
	v_mfma_f32_16x16x32_bf16 v[98:101], v[184:187], v[208:211], v[98:101]
	v_mfma_f32_16x16x32_bf16 v[86:89], v[162:165], v[216:219], v[86:89]
	v_mfma_f32_16x16x32_bf16 v[82:85], v[184:187], v[216:219], v[82:85]
	v_mfma_f32_16x16x32_bf16 v[134:137], v[180:183], v[196:199], v[134:137]
	v_mfma_f32_16x16x32_bf16 v[130:133], v[188:191], v[196:199], v[130:133]
	v_mfma_f32_16x16x32_bf16 v[118:121], v[180:183], v[204:207], v[118:121]
	v_mfma_f32_16x16x32_bf16 v[114:117], v[188:191], v[204:207], v[114:117]
	v_mfma_f32_16x16x32_bf16 v[102:105], v[180:183], v[212:215], v[102:105]
	v_mfma_f32_16x16x32_bf16 v[98:101], v[188:191], v[212:215], v[98:101]
	v_mfma_f32_16x16x32_bf16 v[86:89], v[180:183], v[220:223], v[86:89]
	v_mfma_f32_16x16x32_bf16 v[82:85], v[188:191], v[220:223], v[82:85]
	s_barrier
	s_add_i32 s51, s41, s25
	v_lshl_add_u64 v[166:167], s[20:21], 0, v[150:151]
	s_mov_b32 m0, s51
	ds_read_b128 v[192:195], v175 offset:16384
	ds_read_b128 v[196:199], v175 offset:17408
	ds_read_b128 v[200:203], v175 offset:18432
	ds_read_b128 v[204:207], v175 offset:19456
	ds_read_b128 v[208:211], v175 offset:20480
	ds_read_b128 v[212:215], v175 offset:21504
	ds_read_b128 v[216:219], v175 offset:22528
	ds_read_b128 v[220:223], v175 offset:23552
	global_load_lds_dwordx4 v[166:167], off
	s_add_i32 m0, s51, 0x2000
	s_add_u32 s52, s20, 0x80000
	v_lshl_add_u64 v[224:225], s[20:21], 0, v[146:147]
	s_addc_u32 s53, s21, 0
	s_add_i32 s51, s42, s25
	global_load_lds_dwordx4 v[224:225], off
	v_lshl_add_u64 v[226:227], s[52:53], 0, v[150:151]
	s_mov_b32 m0, s51
	v_lshl_add_u64 v[228:229], s[22:23], 0, v[148:149]
	global_load_lds_dwordx4 v[226:227], off
	v_lshl_add_u64 v[226:227], s[52:53], 0, v[146:147]
	s_add_i32 m0, s51, 0x2000
	s_nop 0
	global_load_lds_dwordx4 v[226:227], off
	v_lshl_add_u64 v[226:227], s[22:23], 0, v[152:153]
	s_mov_b32 m0, s28
	s_nop 0
	global_load_lds_dwordx4 v[226:227], off
	s_mov_b32 m0, s29
	s_nop 0
	global_load_lds_dwordx4 v[228:229], off
	s_waitcnt vmcnt(8)
	s_waitcnt lgkmcnt(0)
	s_barrier
	s_waitcnt lgkmcnt(0)
	v_mfma_f32_16x16x32_bf16 v[62:65], v[66:69], v[192:195], v[62:65]
	v_mfma_f32_16x16x32_bf16 v[58:61], v[74:77], v[192:195], v[58:61]
	v_mfma_f32_16x16x32_bf16 v[46:49], v[66:69], v[200:203], v[46:49]
	v_mfma_f32_16x16x32_bf16 v[42:45], v[74:77], v[200:203], v[42:45]
	v_mfma_f32_16x16x32_bf16 v[30:33], v[66:69], v[208:211], v[30:33]
	v_mfma_f32_16x16x32_bf16 v[26:29], v[74:77], v[208:211], v[26:29]
	v_mfma_f32_16x16x32_bf16 v[14:17], v[66:69], v[216:219], v[14:17]
	v_mfma_f32_16x16x32_bf16 v[10:13], v[74:77], v[216:219], v[10:13]
	v_mfma_f32_16x16x32_bf16 v[62:65], v[70:73], v[196:199], v[62:65]
	v_mfma_f32_16x16x32_bf16 v[58:61], v[78:81], v[196:199], v[58:61]
	v_mfma_f32_16x16x32_bf16 v[46:49], v[70:73], v[204:207], v[46:49]
	v_mfma_f32_16x16x32_bf16 v[42:45], v[78:81], v[204:207], v[42:45]
	v_mfma_f32_16x16x32_bf16 v[30:33], v[70:73], v[212:215], v[30:33]
	v_mfma_f32_16x16x32_bf16 v[26:29], v[78:81], v[212:215], v[26:29]
	v_mfma_f32_16x16x32_bf16 v[14:17], v[70:73], v[220:223], v[14:17]
	v_mfma_f32_16x16x32_bf16 v[10:13], v[78:81], v[220:223], v[10:13]
	v_mfma_f32_16x16x32_bf16 v[54:57], v[162:165], v[192:195], v[54:57]
	v_mfma_f32_16x16x32_bf16 v[50:53], v[184:187], v[192:195], v[50:53]
	v_mfma_f32_16x16x32_bf16 v[38:41], v[162:165], v[200:203], v[38:41]
	v_mfma_f32_16x16x32_bf16 v[34:37], v[184:187], v[200:203], v[34:37]
	v_mfma_f32_16x16x32_bf16 v[22:25], v[162:165], v[208:211], v[22:25]
	v_mfma_f32_16x16x32_bf16 v[18:21], v[184:187], v[208:211], v[18:21]
	v_mfma_f32_16x16x32_bf16 v[6:9], v[162:165], v[216:219], v[6:9]
	v_mfma_f32_16x16x32_bf16 v[2:5], v[184:187], v[216:219], v[2:5]
	v_mfma_f32_16x16x32_bf16 v[54:57], v[180:183], v[196:199], v[54:57]
	v_mfma_f32_16x16x32_bf16 v[50:53], v[188:191], v[196:199], v[50:53]
	v_mfma_f32_16x16x32_bf16 v[38:41], v[180:183], v[204:207], v[38:41]
	v_mfma_f32_16x16x32_bf16 v[34:37], v[188:191], v[204:207], v[34:37]
	v_mfma_f32_16x16x32_bf16 v[22:25], v[180:183], v[212:215], v[22:25]
	v_mfma_f32_16x16x32_bf16 v[18:21], v[188:191], v[212:215], v[18:21]
	v_mfma_f32_16x16x32_bf16 v[6:9], v[180:183], v[220:223], v[6:9]
	v_mfma_f32_16x16x32_bf16 v[2:5], v[188:191], v[220:223], v[2:5]
	s_barrier
; #define PG8_STAGE(bufoff, gbase, voff) do { _Pragma("unroll") for (int _i = 0; _i < 2; ++_i) \
;         __builtin_amdgcn_global_load_lds((const unsigned*)((const char*)(gbase) + (voff)[_i]), (LAS unsigned*)(lds + (bufoff) + ldsw + _i * 8192), 16, 0, 0); } while (0)
; #define PG8_LDA(dst, b, h) do { _Pragma("unroll") for (int m = 0; m < 4; ++m) _Pragma("unroll") for (int k = 0; k < 2; ++k) dst[m][k] = *(const LAS bf16x8*)(lds + PG8_SA(b, h) + aoff + m * 2048 + k * 1024); } while (0)
; #define PG8_LDB(dst, b, h) do { _Pragma("unroll") for (int n = 0; n < 2; ++n) _Pragma("unroll") for (int k = 0; k < 2; ++k) dst[n][k] = *(const LAS bf16x8*)(lds + PG8_SB(b, h) + boff + n * 2048 + k * 1024); } while (0)
; #define PG8_MMA(ai, bj, At, Bt) do { __builtin_amdgcn_s_setprio(1); _Pragma("unroll") for (int m = 0; m < 4; ++m) _Pragma("unroll") for (int n = 0; n < 2; ++n) _Pragma("unroll") for (int k = 0; k < 2; ++k) \
;         acc[ai][bj][m][n] = __builtin_amdgcn_mfma_f32_16x16x32_bf16(Bt[n][k], At[m][k], acc[ai][bj][m][n], 0, 0, 0); __builtin_amdgcn_s_setprio(0); } while (0)
; #define PG8_WAIT_V(n) asm volatile("s_waitcnt vmcnt(" #n ")" ::: "memory")
; #define PG8_WAIT_L(n) asm volatile("s_waitcnt lgkmcnt(" #n ")" ::: "memory")
; #define PG8_BAR __builtin_amdgcn_s_barrier()
; #define PG8_SCHED __builtin_amdgcn_sched_barrier(0)
; template <class Epi, class Sched, bool ALIGN_EPI = false, bool SP2 = false>
; __device__ __forceinline__ void gemm_phase(LAS unsigned char* lds, const Gemm g, const Sched& S, const Epi& E) {
;     ...
;             PG8_LDB(B0, 1, 0); PG8_LDB(B1, 1, 1); PG8_SCHED; PG8_LDA(At, 1, 0); PG8_STAGE(PG8_SA(0, 1), a2 + hstep, voffA);
;             PG8_WAIT_V(8); PG8_WAIT_L(0); PG8_BAR; PG8_MMA(0, 0, At, B0); PG8_MMA(0, 1, At, B1); PG8_BAR; PG8_SCHED;
	s_add_i32 s51, 0, 0x18000
	s_add_i32 s52, 0, 0x1c000
	v_add_u32_e32 v78, s51, v169
	v_add_u32_e32 v168, s52, v169
	ds_read_b128 v[66:69], v78
	ds_read_b128 v[70:73], v78 offset:1024
	ds_read_b128 v[74:77], v78 offset:2048
	ds_read_b128 v[78:81], v78 offset:3072
	ds_read_b128 v[162:165], v168
	ds_read_b128 v[180:183], v168 offset:1024
	ds_read_b128 v[184:187], v168 offset:2048
	ds_read_b128 v[188:191], v168 offset:3072
	s_add_u32 s22, s22, 0x80000
	s_addc_u32 s23, s23, 0
	s_mov_b32 m0, s30
	v_lshl_add_u64 v[230:231], s[22:23], 0, v[152:153]
	ds_read_b128 v[192:195], v175 offset:32768
	ds_read_b128 v[196:199], v175 offset:33792
	ds_read_b128 v[200:203], v175 offset:34816
	ds_read_b128 v[204:207], v175 offset:35840
	ds_read_b128 v[208:211], v175 offset:36864
	ds_read_b128 v[212:215], v175 offset:37888
	ds_read_b128 v[216:219], v175 offset:38912
	ds_read_b128 v[220:223], v175 offset:39936
	global_load_lds_dwordx4 v[230:231], off
	v_lshl_add_u64 v[230:231], s[22:23], 0, v[148:149]
	s_mov_b32 m0, s31
	s_nop 0
	global_load_lds_dwordx4 v[230:231], off
	s_waitcnt vmcnt(8)
	s_waitcnt lgkmcnt(0)
	s_barrier
	s_waitcnt lgkmcnt(0)
	v_mfma_f32_16x16x32_bf16 v[142:145], v[66:69], v[192:195], v[142:145]
	v_mfma_f32_16x16x32_bf16 v[138:141], v[74:77], v[192:195], v[138:141]
	v_mfma_f32_16x16x32_bf16 v[126:129], v[66:69], v[200:203], v[126:129]
	v_mfma_f32_16x16x32_bf16 v[122:125], v[74:77], v[200:203], v[122:125]
	v_mfma_f32_16x16x32_bf16 v[110:113], v[66:69], v[208:211], v[110:113]
	v_mfma_f32_16x16x32_bf16 v[106:109], v[74:77], v[208:211], v[106:109]
	v_mfma_f32_16x16x32_bf16 v[94:97], v[66:69], v[216:219], v[94:97]
	v_mfma_f32_16x16x32_bf16 v[90:93], v[74:77], v[216:219], v[90:93]
	v_mfma_f32_16x16x32_bf16 v[142:145], v[70:73], v[196:199], v[142:145]
	v_mfma_f32_16x16x32_bf16 v[138:141], v[78:81], v[196:199], v[138:141]
	v_mfma_f32_16x16x32_bf16 v[126:129], v[70:73], v[204:207], v[126:129]
	v_mfma_f32_16x16x32_bf16 v[122:125], v[78:81], v[204:207], v[122:125]
	v_mfma_f32_16x16x32_bf16 v[110:113], v[70:73], v[212:215], v[110:113]
	v_mfma_f32_16x16x32_bf16 v[106:109], v[78:81], v[212:215], v[106:109]
	v_mfma_f32_16x16x32_bf16 v[94:97], v[70:73], v[220:223], v[94:97]
	v_mfma_f32_16x16x32_bf16 v[90:93], v[78:81], v[220:223], v[90:93]
	v_mfma_f32_16x16x32_bf16 v[134:137], v[162:165], v[192:195], v[134:137]
	v_mfma_f32_16x16x32_bf16 v[130:133], v[184:187], v[192:195], v[130:133]
	v_mfma_f32_16x16x32_bf16 v[118:121], v[162:165], v[200:203], v[118:121]
	v_mfma_f32_16x16x32_bf16 v[114:117], v[184:187], v[200:203], v[114:117]
	v_mfma_f32_16x16x32_bf16 v[102:105], v[162:165], v[208:211], v[102:105]
	v_mfma_f32_16x16x32_bf16 v[98:101], v[184:187], v[208:211], v[98:101]
	v_mfma_f32_16x16x32_bf16 v[86:89], v[162:165], v[216:219], v[86:89]
	v_mfma_f32_16x16x32_bf16 v[82:85], v[184:187], v[216:219], v[82:85]
	v_mfma_f32_16x16x32_bf16 v[134:137], v[180:183], v[196:199], v[134:137]
	v_mfma_f32_16x16x32_bf16 v[130:133], v[188:191], v[196:199], v[130:133]
	v_mfma_f32_16x16x32_bf16 v[118:121], v[180:183], v[204:207], v[118:121]
	v_mfma_f32_16x16x32_bf16 v[114:117], v[188:191], v[204:207], v[114:117]
	v_mfma_f32_16x16x32_bf16 v[102:105], v[180:183], v[212:215], v[102:105]
	v_mfma_f32_16x16x32_bf16 v[98:101], v[188:191], v[212:215], v[98:101]
	v_mfma_f32_16x16x32_bf16 v[86:89], v[180:183], v[220:223], v[86:89]
	v_mfma_f32_16x16x32_bf16 v[82:85], v[188:191], v[220:223], v[82:85]
	s_barrier
; #define PG8_STAGE(bufoff, gbase, voff) do { _Pragma("unroll") for (int _i = 0; _i < 2; ++_i) \
;         __builtin_amdgcn_global_load_lds((const unsigned*)((const char*)(gbase) + (voff)[_i]), (LAS unsigned*)(lds + (bufoff) + ldsw + _i * 8192), 16, 0, 0); } while (0)
; #define PG8_LDA(dst, b, h) do { _Pragma("unroll") for (int m = 0; m < 4; ++m) _Pragma("unroll") for (int k = 0; k < 2; ++k) dst[m][k] = *(const LAS bf16x8*)(lds + PG8_SA(b, h) + aoff + m * 2048 + k * 1024); } while (0)
; #define PG8_MMA(ai, bj, At, Bt) do { __builtin_amdgcn_s_setprio(1); _Pragma("unroll") for (int m = 0; m < 4; ++m) _Pragma("unroll") for (int n = 0; n < 2; ++n) _Pragma("unroll") for (int k = 0; k < 2; ++k) \
;         acc[ai][bj][m][n] = __builtin_amdgcn_mfma_f32_16x16x32_bf16(Bt[n][k], At[m][k], acc[ai][bj][m][n], 0, 0, 0); __builtin_amdgcn_s_setprio(0); } while (0)
; #define PG8_WAIT_V(n) asm volatile("s_waitcnt vmcnt(" #n ")" ::: "memory")
; #define PG8_WAIT_L(n) asm volatile("s_waitcnt lgkmcnt(" #n ")" ::: "memory")
; #define PG8_BAR __builtin_amdgcn_s_barrier()
; #define PG8_SCHED __builtin_amdgcn_sched_barrier(0)
; template <class Epi, class Sched, bool ALIGN_EPI = false, bool SP2 = false>
; __device__ __forceinline__ void gemm_phase(LAS unsigned char* lds, const Gemm g, const Sched& S, const Epi& E) {
;     ...
;         for (int t = 0; t < nt; t += 2) {
;     ...
;             PG8_LDA(At, 1, 1); PG8_STAGE(PG8_SB(1, 0), b3, voffB); PG8_STAGE(PG8_SB(1, 1), b3 + hstepB, voffB); PG8_STAGE(PG8_SA(1, 0), a3, voffA);
;             PG8_WAIT_V(8); PG8_WAIT_L(0); PG8_BAR; PG8_MMA(1, 0, At, B0); PG8_MMA(1, 1, At, B1); PG8_BAR; PG8_SCHED;
;     ...
;         if constexpr (ALIGN_EPI) { if (wr == 0) PG8_BAR; }
	s_add_i32 s22, s51, s25
	v_lshl_add_u64 v[166:167], v[166:167], 0, s[6:7]
	s_mov_b32 m0, s22
	ds_read_b128 v[192:195], v175 offset:49152
	ds_read_b128 v[196:199], v175 offset:50176
	ds_read_b128 v[200:203], v175 offset:51200
	ds_read_b128 v[204:207], v175 offset:52224
	ds_read_b128 v[208:211], v175 offset:53248
	ds_read_b128 v[212:215], v175 offset:54272
	ds_read_b128 v[216:219], v175 offset:55296
	ds_read_b128 v[220:223], v175 offset:56320
	global_load_lds_dwordx4 v[166:167], off
	s_add_i32 m0, s22, 0x2000
	s_add_u32 s20, s20, 0x80080
	v_lshl_add_u64 v[166:167], v[224:225], 0, s[6:7]
	s_addc_u32 s21, s21, 0
	s_add_i32 s22, s52, s25
	global_load_lds_dwordx4 v[166:167], off
	v_lshl_add_u64 v[166:167], s[20:21], 0, v[150:151]
	s_mov_b32 m0, s22
	s_nop 0
	global_load_lds_dwordx4 v[166:167], off
	v_lshl_add_u64 v[166:167], s[20:21], 0, v[146:147]
	s_add_i32 m0, s22, 0x2000
	s_nop 0
	global_load_lds_dwordx4 v[166:167], off
	v_lshl_add_u64 v[166:167], v[226:227], 0, s[6:7]
	s_mov_b32 m0, s39
	s_nop 0
	global_load_lds_dwordx4 v[166:167], off
	v_lshl_add_u64 v[166:167], v[228:229], 0, s[6:7]
	s_mov_b32 m0, s40
	s_nop 0
	global_load_lds_dwordx4 v[166:167], off
	s_waitcnt vmcnt(8)
	s_waitcnt lgkmcnt(0)
	s_barrier
	s_waitcnt lgkmcnt(0)
	v_mfma_f32_16x16x32_bf16 v[62:65], v[66:69], v[192:195], v[62:65]
	v_mfma_f32_16x16x32_bf16 v[58:61], v[74:77], v[192:195], v[58:61]
	v_mfma_f32_16x16x32_bf16 v[46:49], v[66:69], v[200:203], v[46:49]
	v_mfma_f32_16x16x32_bf16 v[42:45], v[74:77], v[200:203], v[42:45]
	v_mfma_f32_16x16x32_bf16 v[30:33], v[66:69], v[208:211], v[30:33]
	v_mfma_f32_16x16x32_bf16 v[26:29], v[74:77], v[208:211], v[26:29]
	v_mfma_f32_16x16x32_bf16 v[14:17], v[66:69], v[216:219], v[14:17]
	v_mfma_f32_16x16x32_bf16 v[10:13], v[74:77], v[216:219], v[10:13]
	v_mfma_f32_16x16x32_bf16 v[62:65], v[70:73], v[196:199], v[62:65]
	v_mfma_f32_16x16x32_bf16 v[58:61], v[78:81], v[196:199], v[58:61]
	v_mfma_f32_16x16x32_bf16 v[46:49], v[70:73], v[204:207], v[46:49]
	v_mfma_f32_16x16x32_bf16 v[42:45], v[78:81], v[204:207], v[42:45]
	v_mfma_f32_16x16x32_bf16 v[30:33], v[70:73], v[212:215], v[30:33]
	v_mfma_f32_16x16x32_bf16 v[26:29], v[78:81], v[212:215], v[26:29]
	v_mfma_f32_16x16x32_bf16 v[14:17], v[70:73], v[220:223], v[14:17]
	v_mfma_f32_16x16x32_bf16 v[10:13], v[78:81], v[220:223], v[10:13]
	v_mfma_f32_16x16x32_bf16 v[54:57], v[162:165], v[192:195], v[54:57]
	v_mfma_f32_16x16x32_bf16 v[50:53], v[184:187], v[192:195], v[50:53]
	v_mfma_f32_16x16x32_bf16 v[38:41], v[162:165], v[200:203], v[38:41]
	v_mfma_f32_16x16x32_bf16 v[34:37], v[184:187], v[200:203], v[34:37]
	v_mfma_f32_16x16x32_bf16 v[22:25], v[162:165], v[208:211], v[22:25]
	v_mfma_f32_16x16x32_bf16 v[18:21], v[184:187], v[208:211], v[18:21]
	v_mfma_f32_16x16x32_bf16 v[6:9], v[162:165], v[216:219], v[6:9]
	v_mfma_f32_16x16x32_bf16 v[2:5], v[184:187], v[216:219], v[2:5]
	v_mfma_f32_16x16x32_bf16 v[54:57], v[180:183], v[196:199], v[54:57]
	v_mfma_f32_16x16x32_bf16 v[50:53], v[188:191], v[196:199], v[50:53]
	v_mfma_f32_16x16x32_bf16 v[38:41], v[180:183], v[204:207], v[38:41]
	v_mfma_f32_16x16x32_bf16 v[34:37], v[188:191], v[204:207], v[34:37]
	v_mfma_f32_16x16x32_bf16 v[22:25], v[180:183], v[212:215], v[22:25]
	v_mfma_f32_16x16x32_bf16 v[18:21], v[188:191], v[212:215], v[18:21]
	v_mfma_f32_16x16x32_bf16 v[6:9], v[180:183], v[220:223], v[6:9]
	v_mfma_f32_16x16x32_bf16 v[2:5], v[188:191], v[220:223], v[2:5]
	s_barrier
	s_add_i32 s50, s50, 2
	s_add_u32 s48, s48, 0x100
	s_addc_u32 s49, s49, 0
	s_add_u32 s18, s18, 0x100
	s_addc_u32 s19, s19, 0
	s_cmp_lt_u32 s50, 30
	s_cbranch_scc1 .LBB0_2916
	s_setprio 0
	s_andn2_b64 vcc, exec, s[8:9]
	s_cbranch_vccnz .LBB0_2919
	s_barrier

; #define PG8_STAGE(bufoff, gbase, voff) do { _Pragma("unroll") for (int _i = 0; _i < 2; ++_i) \
;         __builtin_amdgcn_global_load_lds((const unsigned*)((const char*)(gbase) + (voff)[_i]), (LAS unsigned*)(lds + (bufoff) + ldsw + _i * 8192), 16, 0, 0); } while (0)
; #define PG8_LDA(dst, b, h) do { _Pragma("unroll") for (int m = 0; m < 4; ++m) _Pragma("unroll") for (int k = 0; k < 2; ++k) dst[m][k] = *(const LAS bf16x8*)(lds + PG8_SA(b, h) + aoff + m * 2048 + k * 1024); } while (0)
; #define PG8_LDB(dst, b, h) do { _Pragma("unroll") for (int n = 0; n < 2; ++n) _Pragma("unroll") for (int k = 0; k < 2; ++k) dst[n][k] = *(const LAS bf16x8*)(lds + PG8_SB(b, h) + boff + n * 2048 + k * 1024); } while (0)
; #define PG8_MMA(ai, bj, At, Bt) do { __builtin_amdgcn_s_setprio(1); _Pragma("unroll") for (int m = 0; m < 4; ++m) _Pragma("unroll") for (int n = 0; n < 2; ++n) _Pragma("unroll") for (int k = 0; k < 2; ++k) \
;         acc[ai][bj][m][n] = __builtin_amdgcn_mfma_f32_16x16x32_bf16(Bt[n][k], At[m][k], acc[ai][bj][m][n], 0, 0, 0); __builtin_amdgcn_s_setprio(0); } while (0)
; #define PG8_WAIT_V(n) asm volatile("s_waitcnt vmcnt(" #n ")" ::: "memory")
; #define PG8_WAIT_L(n) asm volatile("s_waitcnt lgkmcnt(" #n ")" ::: "memory")
; #define PG8_BAR __builtin_amdgcn_s_barrier()
; #define PG8_SCHED __builtin_amdgcn_sched_barrier(0)
; template <class Epi, class Sched, bool ALIGN_EPI = false, bool SP2 = false>
; __device__ __forceinline__ void gemm_phase(LAS unsigned char* lds, const Gemm g, const Sched& S, const Epi& E) {
;     ...
;             if constexpr (SP2) {
;             PG8_LDB(B0, 0, 0); PG8_LDB(B1, 0, 1); PG8_SCHED; PG8_LDA(At, 0, 0); PG8_STAGE(PG8_SA(1, 1), a1 + hstep, voffA);
;             PG8_WAIT_V(8); PG8_WAIT_L(0); PG8_BAR; PG8_MMA(0, 0, At, B0); PG8_MMA(0, 1, At, B1); PG8_BAR; PG8_SCHED;
.LBB0_3001:
	s_add_u32 s13, s16, 0x100
	s_addc_u32 s39, s17, 0
	s_mov_b32 s40, -2
	s_waitcnt vmcnt(0)
	v_readfirstlane_b32 s98, v0
	s_nop 3
	s_lshr_b32 s98, s98, 6
	s_cmp_ge_u32 s98, 4
	s_cbranch_scc0 .Lprio_3002
	s_setprio 1
.Lprio_3002:
	ds_read_b128 v[152:155], v147
	ds_read_b128 v[156:159], v147 offset:1024
	ds_read_b128 v[160:163], v147 offset:2048
	ds_read_b128 v[164:167], v147 offset:3072
	ds_read_b128 v[168:171], v148
	ds_read_b128 v[172:175], v148 offset:1024
	ds_read_b128 v[176:179], v148 offset:2048
	ds_read_b128 v[180:183], v148 offset:3072
	s_add_u32 s16, s14, 0x100
	s_addc_u32 s17, s15, 0
	s_cmpk_eq_i32 s40, 0x54
	s_cselect_b32 s21, s11, s17
	s_cselect_b32 s20, s10, s16
	s_cselect_b32 s19, s3, s39
	s_cselect_b32 s18, s2, s13
	v_lshl_add_u64 v[216:217], s[14:15], 0, v[138:139]
	s_add_i32 m0, s24, 0xc000
	ds_read_b128 v[184:187], v149
	ds_read_b128 v[188:191], v149 offset:1024
	ds_read_b128 v[192:195], v149 offset:2048
	ds_read_b128 v[196:199], v149 offset:3072
	ds_read_b128 v[200:203], v149 offset:4096
	ds_read_b128 v[204:207], v149 offset:5120
	ds_read_b128 v[208:211], v149 offset:6144
	ds_read_b128 v[212:215], v149 offset:7168
	global_load_lds_dwordx4 v[216:217], off
	v_lshl_add_u64 v[216:217], s[14:15], 0, v[136:137]
	s_add_i32 m0, s24, 0xe000
	s_nop 0
	global_load_lds_dwordx4 v[216:217], off
	s_waitcnt lgkmcnt(0)
	s_barrier
	s_waitcnt lgkmcnt(0)
	v_mfma_f32_16x16x32_bf16 v[124:127], v[152:155], v[184:187], 0
	v_mfma_f32_16x16x32_bf16 v[120:123], v[160:163], v[184:187], 0
	v_mfma_f32_16x16x32_bf16 v[112:115], v[152:155], v[192:195], 0
	v_mfma_f32_16x16x32_bf16 v[104:107], v[160:163], v[192:195], 0
	v_mfma_f32_16x16x32_bf16 v[92:95], v[152:155], v[200:203], 0
	v_mfma_f32_16x16x32_bf16 v[88:91], v[160:163], v[200:203], 0
	v_mfma_f32_16x16x32_bf16 v[76:79], v[152:155], v[208:211], 0
	v_mfma_f32_16x16x32_bf16 v[72:75], v[160:163], v[208:211], 0
	v_mfma_f32_16x16x32_bf16 v[124:127], v[156:159], v[188:191], v[124:127]
	v_mfma_f32_16x16x32_bf16 v[120:123], v[164:167], v[188:191], v[120:123]
	v_mfma_f32_16x16x32_bf16 v[112:115], v[156:159], v[196:199], v[112:115]
	v_mfma_f32_16x16x32_bf16 v[104:107], v[164:167], v[196:199], v[104:107]
	v_mfma_f32_16x16x32_bf16 v[92:95], v[156:159], v[204:207], v[92:95]
	v_mfma_f32_16x16x32_bf16 v[88:91], v[164:167], v[204:207], v[88:91]
	v_mfma_f32_16x16x32_bf16 v[76:79], v[156:159], v[212:215], v[76:79]
	v_mfma_f32_16x16x32_bf16 v[72:75], v[164:167], v[212:215], v[72:75]
	v_mfma_f32_16x16x32_bf16 v[116:119], v[168:171], v[184:187], 0
	v_mfma_f32_16x16x32_bf16 v[108:111], v[176:179], v[184:187], 0
	v_mfma_f32_16x16x32_bf16 v[100:103], v[168:171], v[192:195], 0
	v_mfma_f32_16x16x32_bf16 v[96:99], v[176:179], v[192:195], 0
	v_mfma_f32_16x16x32_bf16 v[84:87], v[168:171], v[200:203], 0
	v_mfma_f32_16x16x32_bf16 v[80:83], v[176:179], v[200:203], 0
	v_mfma_f32_16x16x32_bf16 v[68:71], v[168:171], v[208:211], 0
	v_mfma_f32_16x16x32_bf16 v[64:67], v[176:179], v[208:211], 0
	v_mfma_f32_16x16x32_bf16 v[116:119], v[172:175], v[188:191], v[116:119]
	v_mfma_f32_16x16x32_bf16 v[108:111], v[180:183], v[188:191], v[108:111]
	v_mfma_f32_16x16x32_bf16 v[100:103], v[172:175], v[196:199], v[100:103]
	v_mfma_f32_16x16x32_bf16 v[96:99], v[180:183], v[196:199], v[96:99]
	v_mfma_f32_16x16x32_bf16 v[84:87], v[172:175], v[204:207], v[84:87]
	v_mfma_f32_16x16x32_bf16 v[80:83], v[180:183], v[204:207], v[80:83]
	v_mfma_f32_16x16x32_bf16 v[68:71], v[172:175], v[212:215], v[68:71]
	v_mfma_f32_16x16x32_bf16 v[64:67], v[180:183], v[212:215], v[64:67]
	s_barrier
	s_add_i32 s14, s34, s23
	v_lshl_add_u64 v[216:217], s[18:19], 0, v[130:131]
	s_mov_b32 m0, s14
	ds_read_b128 v[184:187], v149 offset:16384
	ds_read_b128 v[188:191], v149 offset:17408
	ds_read_b128 v[192:195], v149 offset:18432
	ds_read_b128 v[196:199], v149 offset:19456
	ds_read_b128 v[200:203], v149 offset:20480
	ds_read_b128 v[204:207], v149 offset:21504
	ds_read_b128 v[208:211], v149 offset:22528
	ds_read_b128 v[212:215], v149 offset:23552
	global_load_lds_dwordx4 v[216:217], off
	s_add_i32 m0, s14, 0x2000
	s_add_u32 s14, s18, 0x58000
	v_lshl_add_u64 v[218:219], s[18:19], 0, v[134:135]
	s_addc_u32 s15, s19, 0
	s_add_i32 s41, s35, s23
	global_load_lds_dwordx4 v[218:219], off
	v_lshl_add_u64 v[220:221], s[14:15], 0, v[130:131]
	s_mov_b32 m0, s41
	v_lshl_add_u64 v[222:223], s[20:21], 0, v[132:133]
	global_load_lds_dwordx4 v[220:221], off
	v_lshl_add_u64 v[220:221], s[14:15], 0, v[134:135]
	s_add_i32 m0, s41, 0x2000
	s_nop 0
	global_load_lds_dwordx4 v[220:221], off
	v_lshl_add_u64 v[220:221], s[20:21], 0, v[128:129]
	s_mov_b32 m0, s24
	s_nop 0
	global_load_lds_dwordx4 v[220:221], off
	s_mov_b32 m0, s25
	s_nop 0
	global_load_lds_dwordx4 v[222:223], off
	s_waitcnt lgkmcnt(0)
	s_barrier
; #define PG8_STAGE(bufoff, gbase, voff) do { _Pragma("unroll") for (int _i = 0; _i < 2; ++_i) \
;         __builtin_amdgcn_global_load_lds((const unsigned*)((const char*)(gbase) + (voff)[_i]), (LAS unsigned*)(lds + (bufoff) + ldsw + _i * 8192), 16, 0, 0); } while (0)
; #define PG8_LDA(dst, b, h) do { _Pragma("unroll") for (int m = 0; m < 4; ++m) _Pragma("unroll") for (int k = 0; k < 2; ++k) dst[m][k] = *(const LAS bf16x8*)(lds + PG8_SA(b, h) + aoff + m * 2048 + k * 1024); } while (0)
; #define PG8_LDB(dst, b, h) do { _Pragma("unroll") for (int n = 0; n < 2; ++n) _Pragma("unroll") for (int k = 0; k < 2; ++k) dst[n][k] = *(const LAS bf16x8*)(lds + PG8_SB(b, h) + boff + n * 2048 + k * 1024); } while (0)
; #define PG8_MMA(ai, bj, At, Bt) do { __builtin_amdgcn_s_setprio(1); _Pragma("unroll") for (int m = 0; m < 4; ++m) _Pragma("unroll") for (int n = 0; n < 2; ++n) _Pragma("unroll") for (int k = 0; k < 2; ++k) \
;         acc[ai][bj][m][n] = __builtin_amdgcn_mfma_f32_16x16x32_bf16(Bt[n][k], At[m][k], acc[ai][bj][m][n], 0, 0, 0); __builtin_amdgcn_s_setprio(0); } while (0)
; #define PG8_WAIT_V(n) asm volatile("s_waitcnt vmcnt(" #n ")" ::: "memory")
; #define PG8_WAIT_L(n) asm volatile("s_waitcnt lgkmcnt(" #n ")" ::: "memory")
; #define PG8_BAR __builtin_amdgcn_s_barrier()
; #define PG8_SCHED __builtin_amdgcn_sched_barrier(0)
; template <class Epi, class Sched, bool ALIGN_EPI = false, bool SP2 = false>
; __device__ __forceinline__ void gemm_phase(LAS unsigned char* lds, const Gemm g, const Sched& S, const Epi& E) {
;     ...
;             PG8_WAIT_V(8); PG8_WAIT_L(0); PG8_BAR; PG8_MMA(0, 0, At, B0); PG8_MMA(0, 1, At, B1); PG8_BAR; PG8_SCHED;
;             PG8_LDA(At, 0, 1); PG8_STAGE(PG8_SB(0, 0), b2, voffB); PG8_STAGE(PG8_SB(0, 1), b2 + hstepB, voffB); PG8_STAGE(PG8_SA(0, 0), a2, voffA);
;             PG8_WAIT_V(8); PG8_WAIT_L(0); PG8_BAR; PG8_MMA(1, 0, At, B0); PG8_MMA(1, 1, At, B1); PG8_BAR; PG8_SCHED;
;             PG8_LDB(B0, 1, 0); PG8_LDB(B1, 1, 1); PG8_SCHED; PG8_LDA(At, 1, 0); PG8_STAGE(PG8_SA(0, 1), a2 + hstep, voffA);
;             PG8_WAIT_V(8); PG8_WAIT_L(0); PG8_BAR; PG8_MMA(0, 0, At, B0); PG8_MMA(0, 1, At, B1); PG8_BAR; PG8_SCHED;
	s_waitcnt lgkmcnt(0)
	v_mfma_f32_16x16x32_bf16 v[60:63], v[152:155], v[184:187], 0
	v_mfma_f32_16x16x32_bf16 v[56:59], v[160:163], v[184:187], 0
	v_mfma_f32_16x16x32_bf16 v[44:47], v[152:155], v[192:195], 0
	v_mfma_f32_16x16x32_bf16 v[40:43], v[160:163], v[192:195], 0
	v_mfma_f32_16x16x32_bf16 v[28:31], v[152:155], v[200:203], 0
	v_mfma_f32_16x16x32_bf16 v[24:27], v[160:163], v[200:203], 0
	v_mfma_f32_16x16x32_bf16 v[12:15], v[152:155], v[208:211], 0
	v_mfma_f32_16x16x32_bf16 v[8:11], v[160:163], v[208:211], 0
	v_mfma_f32_16x16x32_bf16 v[60:63], v[156:159], v[188:191], v[60:63]
	v_mfma_f32_16x16x32_bf16 v[56:59], v[164:167], v[188:191], v[56:59]
	v_mfma_f32_16x16x32_bf16 v[44:47], v[156:159], v[196:199], v[44:47]
	v_mfma_f32_16x16x32_bf16 v[40:43], v[164:167], v[196:199], v[40:43]
	v_mfma_f32_16x16x32_bf16 v[28:31], v[156:159], v[204:207], v[28:31]
	v_mfma_f32_16x16x32_bf16 v[24:27], v[164:167], v[204:207], v[24:27]
	v_mfma_f32_16x16x32_bf16 v[12:15], v[156:159], v[212:215], v[12:15]
	v_mfma_f32_16x16x32_bf16 v[8:11], v[164:167], v[212:215], v[8:11]
	v_mfma_f32_16x16x32_bf16 v[52:55], v[168:171], v[184:187], 0
	v_mfma_f32_16x16x32_bf16 v[48:51], v[176:179], v[184:187], 0
	v_mfma_f32_16x16x32_bf16 v[36:39], v[168:171], v[192:195], 0
	v_mfma_f32_16x16x32_bf16 v[32:35], v[176:179], v[192:195], 0
	v_mfma_f32_16x16x32_bf16 v[20:23], v[168:171], v[200:203], 0
	v_mfma_f32_16x16x32_bf16 v[16:19], v[176:179], v[200:203], 0
	v_mfma_f32_16x16x32_bf16 v[4:7], v[168:171], v[208:211], 0
	v_mfma_f32_16x16x32_bf16 v[0:3], v[176:179], v[208:211], 0
	v_mfma_f32_16x16x32_bf16 v[52:55], v[172:175], v[188:191], v[52:55]
	v_mfma_f32_16x16x32_bf16 v[48:51], v[180:183], v[188:191], v[48:51]
	v_mfma_f32_16x16x32_bf16 v[36:39], v[172:175], v[196:199], v[36:39]
	v_mfma_f32_16x16x32_bf16 v[32:35], v[180:183], v[196:199], v[32:35]
	v_mfma_f32_16x16x32_bf16 v[20:23], v[172:175], v[204:207], v[20:23]
	v_mfma_f32_16x16x32_bf16 v[16:19], v[180:183], v[204:207], v[16:19]
	v_mfma_f32_16x16x32_bf16 v[4:7], v[172:175], v[212:215], v[4:7]
	v_mfma_f32_16x16x32_bf16 v[0:3], v[180:183], v[212:215], v[0:3]
	s_barrier
	s_add_i32 s41, 0, 0x18000
	s_add_i32 s42, 0, 0x1c000
	v_add_u32_e32 v164, s41, v144
	v_add_u32_e32 v180, s42, v144
	ds_read_b128 v[152:155], v164
	ds_read_b128 v[156:159], v164 offset:1024
	ds_read_b128 v[160:163], v164 offset:2048
	ds_read_b128 v[164:167], v164 offset:3072
	ds_read_b128 v[168:171], v180
	ds_read_b128 v[172:175], v180 offset:1024
	ds_read_b128 v[176:179], v180 offset:2048
	ds_read_b128 v[180:183], v180 offset:3072
	s_add_u32 s14, s20, 0x160000
	s_addc_u32 s15, s21, 0
	s_mov_b32 m0, s26
	v_lshl_add_u64 v[224:225], s[14:15], 0, v[128:129]
	ds_read_b128 v[184:187], v149 offset:32768
	ds_read_b128 v[188:191], v149 offset:33792
	ds_read_b128 v[192:195], v149 offset:34816
	ds_read_b128 v[196:199], v149 offset:35840
	ds_read_b128 v[200:203], v149 offset:36864
	ds_read_b128 v[204:207], v149 offset:37888
	ds_read_b128 v[208:211], v149 offset:38912
	ds_read_b128 v[212:215], v149 offset:39936
	global_load_lds_dwordx4 v[224:225], off
	v_lshl_add_u64 v[224:225], s[14:15], 0, v[132:133]
	s_mov_b32 m0, s27
	s_nop 0
	global_load_lds_dwordx4 v[224:225], off
	s_waitcnt vmcnt(8)
	s_waitcnt lgkmcnt(0)
	s_barrier
	s_waitcnt lgkmcnt(0)
	v_mfma_f32_16x16x32_bf16 v[124:127], v[152:155], v[184:187], v[124:127]
	v_mfma_f32_16x16x32_bf16 v[120:123], v[160:163], v[184:187], v[120:123]
	v_mfma_f32_16x16x32_bf16 v[112:115], v[152:155], v[192:195], v[112:115]
	v_mfma_f32_16x16x32_bf16 v[104:107], v[160:163], v[192:195], v[104:107]
	v_mfma_f32_16x16x32_bf16 v[92:95], v[152:155], v[200:203], v[92:95]
	v_mfma_f32_16x16x32_bf16 v[88:91], v[160:163], v[200:203], v[88:91]
	v_mfma_f32_16x16x32_bf16 v[76:79], v[152:155], v[208:211], v[76:79]
	v_mfma_f32_16x16x32_bf16 v[72:75], v[160:163], v[208:211], v[72:75]
	v_mfma_f32_16x16x32_bf16 v[124:127], v[156:159], v[188:191], v[124:127]
	v_mfma_f32_16x16x32_bf16 v[120:123], v[164:167], v[188:191], v[120:123]
	v_mfma_f32_16x16x32_bf16 v[112:115], v[156:159], v[196:199], v[112:115]
	v_mfma_f32_16x16x32_bf16 v[104:107], v[164:167], v[196:199], v[104:107]
	v_mfma_f32_16x16x32_bf16 v[92:95], v[156:159], v[204:207], v[92:95]
	v_mfma_f32_16x16x32_bf16 v[88:91], v[164:167], v[204:207], v[88:91]
	v_mfma_f32_16x16x32_bf16 v[76:79], v[156:159], v[212:215], v[76:79]
	v_mfma_f32_16x16x32_bf16 v[72:75], v[164:167], v[212:215], v[72:75]
	v_mfma_f32_16x16x32_bf16 v[116:119], v[168:171], v[184:187], v[116:119]
	v_mfma_f32_16x16x32_bf16 v[108:111], v[176:179], v[184:187], v[108:111]
	v_mfma_f32_16x16x32_bf16 v[100:103], v[168:171], v[192:195], v[100:103]
	v_mfma_f32_16x16x32_bf16 v[96:99], v[176:179], v[192:195], v[96:99]
	v_mfma_f32_16x16x32_bf16 v[84:87], v[168:171], v[200:203], v[84:87]
	v_mfma_f32_16x16x32_bf16 v[80:83], v[176:179], v[200:203], v[80:83]
	v_mfma_f32_16x16x32_bf16 v[68:71], v[168:171], v[208:211], v[68:71]
	v_mfma_f32_16x16x32_bf16 v[64:67], v[176:179], v[208:211], v[64:67]
	v_mfma_f32_16x16x32_bf16 v[116:119], v[172:175], v[188:191], v[116:119]
	v_mfma_f32_16x16x32_bf16 v[108:111], v[180:183], v[188:191], v[108:111]
	v_mfma_f32_16x16x32_bf16 v[100:103], v[172:175], v[196:199], v[100:103]
	v_mfma_f32_16x16x32_bf16 v[96:99], v[180:183], v[196:199], v[96:99]
	v_mfma_f32_16x16x32_bf16 v[84:87], v[172:175], v[204:207], v[84:87]
	v_mfma_f32_16x16x32_bf16 v[80:83], v[180:183], v[204:207], v[80:83]
	v_mfma_f32_16x16x32_bf16 v[68:71], v[172:175], v[212:215], v[68:71]
	v_mfma_f32_16x16x32_bf16 v[64:67], v[180:183], v[212:215], v[64:67]
	s_barrier
; #define PG8_STAGE(bufoff, gbase, voff) do { _Pragma("unroll") for (int _i = 0; _i < 2; ++_i) \
;         __builtin_amdgcn_global_load_lds((const unsigned*)((const char*)(gbase) + (voff)[_i]), (LAS unsigned*)(lds + (bufoff) + ldsw + _i * 8192), 16, 0, 0); } while (0)
; #define PG8_LDA(dst, b, h) do { _Pragma("unroll") for (int m = 0; m < 4; ++m) _Pragma("unroll") for (int k = 0; k < 2; ++k) dst[m][k] = *(const LAS bf16x8*)(lds + PG8_SA(b, h) + aoff + m * 2048 + k * 1024); } while (0)
; #define PG8_LDB(dst, b, h) do { _Pragma("unroll") for (int n = 0; n < 2; ++n) _Pragma("unroll") for (int k = 0; k < 2; ++k) dst[n][k] = *(const LAS bf16x8*)(lds + PG8_SB(b, h) + boff + n * 2048 + k * 1024); } while (0)
; #define PG8_MMA(ai, bj, At, Bt) do { __builtin_amdgcn_s_setprio(1); _Pragma("unroll") for (int m = 0; m < 4; ++m) _Pragma("unroll") for (int n = 0; n < 2; ++n) _Pragma("unroll") for (int k = 0; k < 2; ++k) \
;         acc[ai][bj][m][n] = __builtin_amdgcn_mfma_f32_16x16x32_bf16(Bt[n][k], At[m][k], acc[ai][bj][m][n], 0, 0, 0); __builtin_amdgcn_s_setprio(0); } while (0)
; #define PG8_WAIT_V(n) asm volatile("s_waitcnt vmcnt(" #n ")" ::: "memory")
; #define PG8_WAIT_L(n) asm volatile("s_waitcnt lgkmcnt(" #n ")" ::: "memory")
; #define PG8_BAR __builtin_amdgcn_s_barrier()
; #define PG8_SCHED __builtin_amdgcn_sched_barrier(0)
; template <class Epi, class Sched, bool ALIGN_EPI = false, bool SP2 = false>
; __device__ __forceinline__ void gemm_phase(LAS unsigned char* lds, const Gemm g, const Sched& S, const Epi& E) {
;     ...
;         for (int t = 0; t < nt; t += 2) {
;             const bool last = (t == nt - 2);
;             const char* a1 = cA + (size_t)(t + 1) * kstep;
;             const char* a2 = last ? nA : cA + (size_t)(t + 2) * kstep; const char* b2 = last ? nB : cB + (size_t)(t + 2) * kstep;
;             const char* a3 = a2 + kstep; const char* b3 = b2 + kstep;
;             if (last && has_next) S.a_ready(nxt);
;             if constexpr (SP2) {
;             PG8_LDB(B0, 0, 0); PG8_LDB(B1, 0, 1); PG8_SCHED; PG8_LDA(At, 0, 0); PG8_STAGE(PG8_SA(1, 1), a1 + hstep, voffA);
;     ...
;             PG8_LDA(At, 1, 1); PG8_STAGE(PG8_SB(1, 0), b3, voffB); PG8_STAGE(PG8_SB(1, 1), b3 + hstepB, voffB); PG8_STAGE(PG8_SA(1, 0), a3, voffA);
;             PG8_WAIT_V(8); PG8_WAIT_L(0); PG8_BAR; PG8_MMA(1, 0, At, B0); PG8_MMA(1, 1, At, B1); PG8_BAR; PG8_SCHED;
	s_add_i32 s14, s41, s23
	v_lshl_add_u64 v[216:217], v[216:217], 0, s[6:7]
	s_mov_b32 m0, s14
	ds_read_b128 v[184:187], v149 offset:49152
	ds_read_b128 v[188:191], v149 offset:50176
	ds_read_b128 v[192:195], v149 offset:51200
	ds_read_b128 v[196:199], v149 offset:52224
	ds_read_b128 v[200:203], v149 offset:53248
	ds_read_b128 v[204:207], v149 offset:54272
	ds_read_b128 v[208:211], v149 offset:55296
	ds_read_b128 v[212:215], v149 offset:56320
	global_load_lds_dwordx4 v[216:217], off
	s_add_i32 m0, s14, 0x2000
	s_add_u32 s14, s18, 0x58080
	v_lshl_add_u64 v[216:217], v[218:219], 0, s[6:7]
	s_addc_u32 s15, s19, 0
	s_add_i32 s18, s42, s23
	global_load_lds_dwordx4 v[216:217], off
	v_lshl_add_u64 v[216:217], s[14:15], 0, v[130:131]
	s_mov_b32 m0, s18
	s_nop 0
	global_load_lds_dwordx4 v[216:217], off
	v_lshl_add_u64 v[216:217], s[14:15], 0, v[134:135]
	s_add_i32 m0, s18, 0x2000
	s_nop 0
	global_load_lds_dwordx4 v[216:217], off
	v_lshl_add_u64 v[216:217], v[220:221], 0, s[6:7]
	s_mov_b32 m0, s31
	s_nop 0
	global_load_lds_dwordx4 v[216:217], off
	v_lshl_add_u64 v[216:217], v[222:223], 0, s[6:7]
	s_mov_b32 m0, s33
	s_nop 0
	global_load_lds_dwordx4 v[216:217], off
	s_waitcnt vmcnt(8)
	s_waitcnt lgkmcnt(0)
	s_barrier
	s_waitcnt lgkmcnt(0)
	v_mfma_f32_16x16x32_bf16 v[60:63], v[152:155], v[184:187], v[60:63]
	v_mfma_f32_16x16x32_bf16 v[56:59], v[160:163], v[184:187], v[56:59]
	v_mfma_f32_16x16x32_bf16 v[44:47], v[152:155], v[192:195], v[44:47]
	v_mfma_f32_16x16x32_bf16 v[40:43], v[160:163], v[192:195], v[40:43]
	v_mfma_f32_16x16x32_bf16 v[28:31], v[152:155], v[200:203], v[28:31]
	v_mfma_f32_16x16x32_bf16 v[24:27], v[160:163], v[200:203], v[24:27]
	v_mfma_f32_16x16x32_bf16 v[12:15], v[152:155], v[208:211], v[12:15]
	v_mfma_f32_16x16x32_bf16 v[8:11], v[160:163], v[208:211], v[8:11]
	v_mfma_f32_16x16x32_bf16 v[60:63], v[156:159], v[188:191], v[60:63]
	v_mfma_f32_16x16x32_bf16 v[56:59], v[164:167], v[188:191], v[56:59]
	v_mfma_f32_16x16x32_bf16 v[44:47], v[156:159], v[196:199], v[44:47]
	v_mfma_f32_16x16x32_bf16 v[40:43], v[164:167], v[196:199], v[40:43]
	v_mfma_f32_16x16x32_bf16 v[28:31], v[156:159], v[204:207], v[28:31]
	v_mfma_f32_16x16x32_bf16 v[24:27], v[164:167], v[204:207], v[24:27]
	v_mfma_f32_16x16x32_bf16 v[12:15], v[156:159], v[212:215], v[12:15]
	v_mfma_f32_16x16x32_bf16 v[8:11], v[164:167], v[212:215], v[8:11]
	v_mfma_f32_16x16x32_bf16 v[52:55], v[168:171], v[184:187], v[52:55]
	v_mfma_f32_16x16x32_bf16 v[48:51], v[176:179], v[184:187], v[48:51]
	v_mfma_f32_16x16x32_bf16 v[36:39], v[168:171], v[192:195], v[36:39]
	v_mfma_f32_16x16x32_bf16 v[32:35], v[176:179], v[192:195], v[32:35]
	v_mfma_f32_16x16x32_bf16 v[20:23], v[168:171], v[200:203], v[20:23]
	v_mfma_f32_16x16x32_bf16 v[16:19], v[176:179], v[200:203], v[16:19]
	v_mfma_f32_16x16x32_bf16 v[4:7], v[168:171], v[208:211], v[4:7]
	v_mfma_f32_16x16x32_bf16 v[0:3], v[176:179], v[208:211], v[0:3]
	v_mfma_f32_16x16x32_bf16 v[52:55], v[172:175], v[188:191], v[52:55]
	v_mfma_f32_16x16x32_bf16 v[48:51], v[180:183], v[188:191], v[48:51]
	v_mfma_f32_16x16x32_bf16 v[36:39], v[172:175], v[196:199], v[36:39]
	v_mfma_f32_16x16x32_bf16 v[32:35], v[180:183], v[196:199], v[32:35]
	v_mfma_f32_16x16x32_bf16 v[20:23], v[172:175], v[204:207], v[20:23]
	v_mfma_f32_16x16x32_bf16 v[16:19], v[180:183], v[204:207], v[16:19]
	v_mfma_f32_16x16x32_bf16 v[4:7], v[172:175], v[212:215], v[4:7]
	v_mfma_f32_16x16x32_bf16 v[0:3], v[180:183], v[212:215], v[0:3]
	s_barrier
	s_add_i32 s40, s40, 2
	s_add_u32 s13, s13, 0x100
	s_addc_u32 s39, s39, 0
	s_cmpk_lt_u32 s40, 0x56
	s_mov_b64 s[14:15], s[16:17]
.LBB0_3002:
	ds_read_b128 v[152:155], v147
	ds_read_b128 v[156:159], v147 offset:1024
	ds_read_b128 v[160:163], v147 offset:2048
	ds_read_b128 v[164:167], v147 offset:3072
	ds_read_b128 v[168:171], v148
	ds_read_b128 v[172:175], v148 offset:1024
	ds_read_b128 v[176:179], v148 offset:2048
	ds_read_b128 v[180:183], v148 offset:3072
	s_add_u32 s16, s14, 0x100
	s_addc_u32 s17, s15, 0
	s_cmpk_eq_i32 s40, 0x54
	s_cselect_b32 s21, s11, s17
	s_cselect_b32 s20, s10, s16
	s_cselect_b32 s19, s3, s39
	s_cselect_b32 s18, s2, s13
	v_lshl_add_u64 v[216:217], s[14:15], 0, v[138:139]
	s_add_i32 m0, s24, 0xc000
	ds_read_b128 v[184:187], v149
	ds_read_b128 v[188:191], v149 offset:1024
	ds_read_b128 v[192:195], v149 offset:2048
	ds_read_b128 v[196:199], v149 offset:3072
	ds_read_b128 v[200:203], v149 offset:4096
	ds_read_b128 v[204:207], v149 offset:5120
	ds_read_b128 v[208:211], v149 offset:6144
	ds_read_b128 v[212:215], v149 offset:7168
	global_load_lds_dwordx4 v[216:217], off
	v_lshl_add_u64 v[216:217], s[14:15], 0, v[136:137]
	s_add_i32 m0, s24, 0xe000
	s_nop 0
	global_load_lds_dwordx4 v[216:217], off
	s_waitcnt vmcnt(8)
	s_waitcnt lgkmcnt(0)
	s_barrier
; #define PG8_STAGE(bufoff, gbase, voff) do { _Pragma("unroll") for (int _i = 0; _i < 2; ++_i) \
;         __builtin_amdgcn_global_load_lds((const unsigned*)((const char*)(gbase) + (voff)[_i]), (LAS unsigned*)(lds + (bufoff) + ldsw + _i * 8192), 16, 0, 0); } while (0)
; #define PG8_LDA(dst, b, h) do { _Pragma("unroll") for (int m = 0; m < 4; ++m) _Pragma("unroll") for (int k = 0; k < 2; ++k) dst[m][k] = *(const LAS bf16x8*)(lds + PG8_SA(b, h) + aoff + m * 2048 + k * 1024); } while (0)
; #define PG8_MMA(ai, bj, At, Bt) do { __builtin_amdgcn_s_setprio(1); _Pragma("unroll") for (int m = 0; m < 4; ++m) _Pragma("unroll") for (int n = 0; n < 2; ++n) _Pragma("unroll") for (int k = 0; k < 2; ++k) \
;         acc[ai][bj][m][n] = __builtin_amdgcn_mfma_f32_16x16x32_bf16(Bt[n][k], At[m][k], acc[ai][bj][m][n], 0, 0, 0); __builtin_amdgcn_s_setprio(0); } while (0)
; #define PG8_WAIT_V(n) asm volatile("s_waitcnt vmcnt(" #n ")" ::: "memory")
; #define PG8_WAIT_L(n) asm volatile("s_waitcnt lgkmcnt(" #n ")" ::: "memory")
; #define PG8_BAR __builtin_amdgcn_s_barrier()
; #define PG8_SCHED __builtin_amdgcn_sched_barrier(0)
; template <class Epi, class Sched, bool ALIGN_EPI = false, bool SP2 = false>
; __device__ __forceinline__ void gemm_phase(LAS unsigned char* lds, const Gemm g, const Sched& S, const Epi& E) {
;     ...
;             PG8_WAIT_V(8); PG8_WAIT_L(0); PG8_BAR; PG8_MMA(0, 0, At, B0); PG8_MMA(0, 1, At, B1); PG8_BAR; PG8_SCHED;
;             PG8_LDA(At, 0, 1); PG8_STAGE(PG8_SB(0, 0), b2, voffB); PG8_STAGE(PG8_SB(0, 1), b2 + hstepB, voffB); PG8_STAGE(PG8_SA(0, 0), a2, voffA);
;             PG8_WAIT_V(8); PG8_WAIT_L(0); PG8_BAR; PG8_MMA(1, 0, At, B0); PG8_MMA(1, 1, At, B1); PG8_BAR; PG8_SCHED;
	s_waitcnt lgkmcnt(0)
	v_mfma_f32_16x16x32_bf16 v[124:127], v[152:155], v[184:187], v[124:127]
	v_mfma_f32_16x16x32_bf16 v[120:123], v[160:163], v[184:187], v[120:123]
	v_mfma_f32_16x16x32_bf16 v[112:115], v[152:155], v[192:195], v[112:115]
	v_mfma_f32_16x16x32_bf16 v[104:107], v[160:163], v[192:195], v[104:107]
	v_mfma_f32_16x16x32_bf16 v[92:95], v[152:155], v[200:203], v[92:95]
	v_mfma_f32_16x16x32_bf16 v[88:91], v[160:163], v[200:203], v[88:91]
	v_mfma_f32_16x16x32_bf16 v[76:79], v[152:155], v[208:211], v[76:79]
	v_mfma_f32_16x16x32_bf16 v[72:75], v[160:163], v[208:211], v[72:75]
	v_mfma_f32_16x16x32_bf16 v[124:127], v[156:159], v[188:191], v[124:127]
	v_mfma_f32_16x16x32_bf16 v[120:123], v[164:167], v[188:191], v[120:123]
	v_mfma_f32_16x16x32_bf16 v[112:115], v[156:159], v[196:199], v[112:115]
	v_mfma_f32_16x16x32_bf16 v[104:107], v[164:167], v[196:199], v[104:107]
	v_mfma_f32_16x16x32_bf16 v[92:95], v[156:159], v[204:207], v[92:95]
	v_mfma_f32_16x16x32_bf16 v[88:91], v[164:167], v[204:207], v[88:91]
	v_mfma_f32_16x16x32_bf16 v[76:79], v[156:159], v[212:215], v[76:79]
	v_mfma_f32_16x16x32_bf16 v[72:75], v[164:167], v[212:215], v[72:75]
	v_mfma_f32_16x16x32_bf16 v[116:119], v[168:171], v[184:187], v[116:119]
	v_mfma_f32_16x16x32_bf16 v[108:111], v[176:179], v[184:187], v[108:111]
	v_mfma_f32_16x16x32_bf16 v[100:103], v[168:171], v[192:195], v[100:103]
	v_mfma_f32_16x16x32_bf16 v[96:99], v[176:179], v[192:195], v[96:99]
	v_mfma_f32_16x16x32_bf16 v[84:87], v[168:171], v[200:203], v[84:87]
	v_mfma_f32_16x16x32_bf16 v[80:83], v[176:179], v[200:203], v[80:83]
	v_mfma_f32_16x16x32_bf16 v[68:71], v[168:171], v[208:211], v[68:71]
	v_mfma_f32_16x16x32_bf16 v[64:67], v[176:179], v[208:211], v[64:67]
	v_mfma_f32_16x16x32_bf16 v[116:119], v[172:175], v[188:191], v[116:119]
	v_mfma_f32_16x16x32_bf16 v[108:111], v[180:183], v[188:191], v[108:111]
	v_mfma_f32_16x16x32_bf16 v[100:103], v[172:175], v[196:199], v[100:103]
	v_mfma_f32_16x16x32_bf16 v[96:99], v[180:183], v[196:199], v[96:99]
	v_mfma_f32_16x16x32_bf16 v[84:87], v[172:175], v[204:207], v[84:87]
	v_mfma_f32_16x16x32_bf16 v[80:83], v[180:183], v[204:207], v[80:83]
	v_mfma_f32_16x16x32_bf16 v[68:71], v[172:175], v[212:215], v[68:71]
	v_mfma_f32_16x16x32_bf16 v[64:67], v[180:183], v[212:215], v[64:67]
	s_barrier
	s_add_i32 s14, s34, s23
	v_lshl_add_u64 v[216:217], s[18:19], 0, v[130:131]
	s_mov_b32 m0, s14
	ds_read_b128 v[184:187], v149 offset:16384
	ds_read_b128 v[188:191], v149 offset:17408
	ds_read_b128 v[192:195], v149 offset:18432
	ds_read_b128 v[196:199], v149 offset:19456
	ds_read_b128 v[200:203], v149 offset:20480
	ds_read_b128 v[204:207], v149 offset:21504
	ds_read_b128 v[208:211], v149 offset:22528
	ds_read_b128 v[212:215], v149 offset:23552
	global_load_lds_dwordx4 v[216:217], off
	s_add_i32 m0, s14, 0x2000
	s_add_u32 s14, s18, 0x58000
	v_lshl_add_u64 v[218:219], s[18:19], 0, v[134:135]
	s_addc_u32 s15, s19, 0
	s_add_i32 s41, s35, s23
	global_load_lds_dwordx4 v[218:219], off
	v_lshl_add_u64 v[220:221], s[14:15], 0, v[130:131]
	s_mov_b32 m0, s41
	v_lshl_add_u64 v[222:223], s[20:21], 0, v[132:133]
	global_load_lds_dwordx4 v[220:221], off
	v_lshl_add_u64 v[220:221], s[14:15], 0, v[134:135]
	s_add_i32 m0, s41, 0x2000
	s_nop 0
	global_load_lds_dwordx4 v[220:221], off
	v_lshl_add_u64 v[220:221], s[20:21], 0, v[128:129]
	s_mov_b32 m0, s24
	s_nop 0
	global_load_lds_dwordx4 v[220:221], off
	s_mov_b32 m0, s25
	s_nop 0
	global_load_lds_dwordx4 v[222:223], off
	s_waitcnt vmcnt(8)
	s_waitcnt lgkmcnt(0)
	s_barrier
	s_waitcnt lgkmcnt(0)
	v_mfma_f32_16x16x32_bf16 v[60:63], v[152:155], v[184:187], v[60:63]
	v_mfma_f32_16x16x32_bf16 v[56:59], v[160:163], v[184:187], v[56:59]
	v_mfma_f32_16x16x32_bf16 v[44:47], v[152:155], v[192:195], v[44:47]
	v_mfma_f32_16x16x32_bf16 v[40:43], v[160:163], v[192:195], v[40:43]
	v_mfma_f32_16x16x32_bf16 v[28:31], v[152:155], v[200:203], v[28:31]
	v_mfma_f32_16x16x32_bf16 v[24:27], v[160:163], v[200:203], v[24:27]
	v_mfma_f32_16x16x32_bf16 v[12:15], v[152:155], v[208:211], v[12:15]
	v_mfma_f32_16x16x32_bf16 v[8:11], v[160:163], v[208:211], v[8:11]
	v_mfma_f32_16x16x32_bf16 v[60:63], v[156:159], v[188:191], v[60:63]
	v_mfma_f32_16x16x32_bf16 v[56:59], v[164:167], v[188:191], v[56:59]
	v_mfma_f32_16x16x32_bf16 v[44:47], v[156:159], v[196:199], v[44:47]
	v_mfma_f32_16x16x32_bf16 v[40:43], v[164:167], v[196:199], v[40:43]
	v_mfma_f32_16x16x32_bf16 v[28:31], v[156:159], v[204:207], v[28:31]
	v_mfma_f32_16x16x32_bf16 v[24:27], v[164:167], v[204:207], v[24:27]
	v_mfma_f32_16x16x32_bf16 v[12:15], v[156:159], v[212:215], v[12:15]
	v_mfma_f32_16x16x32_bf16 v[8:11], v[164:167], v[212:215], v[8:11]
	v_mfma_f32_16x16x32_bf16 v[52:55], v[168:171], v[184:187], v[52:55]
	v_mfma_f32_16x16x32_bf16 v[48:51], v[176:179], v[184:187], v[48:51]
	v_mfma_f32_16x16x32_bf16 v[36:39], v[168:171], v[192:195], v[36:39]
	v_mfma_f32_16x16x32_bf16 v[32:35], v[176:179], v[192:195], v[32:35]
	v_mfma_f32_16x16x32_bf16 v[20:23], v[168:171], v[200:203], v[20:23]
	v_mfma_f32_16x16x32_bf16 v[16:19], v[176:179], v[200:203], v[16:19]
	v_mfma_f32_16x16x32_bf16 v[4:7], v[168:171], v[208:211], v[4:7]
	v_mfma_f32_16x16x32_bf16 v[0:3], v[176:179], v[208:211], v[0:3]
	v_mfma_f32_16x16x32_bf16 v[52:55], v[172:175], v[188:191], v[52:55]
	v_mfma_f32_16x16x32_bf16 v[48:51], v[180:183], v[188:191], v[48:51]
	v_mfma_f32_16x16x32_bf16 v[36:39], v[172:175], v[196:199], v[36:39]
	v_mfma_f32_16x16x32_bf16 v[32:35], v[180:183], v[196:199], v[32:35]
	v_mfma_f32_16x16x32_bf16 v[20:23], v[172:175], v[204:207], v[20:23]
	v_mfma_f32_16x16x32_bf16 v[16:19], v[180:183], v[204:207], v[16:19]
	v_mfma_f32_16x16x32_bf16 v[4:7], v[172:175], v[212:215], v[4:7]
	v_mfma_f32_16x16x32_bf16 v[0:3], v[180:183], v[212:215], v[0:3]
	s_barrier
; #define PG8_STAGE(bufoff, gbase, voff) do { _Pragma("unroll") for (int _i = 0; _i < 2; ++_i) \
;         __builtin_amdgcn_global_load_lds((const unsigned*)((const char*)(gbase) + (voff)[_i]), (LAS unsigned*)(lds + (bufoff) + ldsw + _i * 8192), 16, 0, 0); } while (0)
; #define PG8_LDA(dst, b, h) do { _Pragma("unroll") for (int m = 0; m < 4; ++m) _Pragma("unroll") for (int k = 0; k < 2; ++k) dst[m][k] = *(const LAS bf16x8*)(lds + PG8_SA(b, h) + aoff + m * 2048 + k * 1024); } while (0)
; #define PG8_LDB(dst, b, h) do { _Pragma("unroll") for (int n = 0; n < 2; ++n) _Pragma("unroll") for (int k = 0; k < 2; ++k) dst[n][k] = *(const LAS bf16x8*)(lds + PG8_SB(b, h) + boff + n * 2048 + k * 1024); } while (0)
; #define PG8_MMA(ai, bj, At, Bt) do { __builtin_amdgcn_s_setprio(1); _Pragma("unroll") for (int m = 0; m < 4; ++m) _Pragma("unroll") for (int n = 0; n < 2; ++n) _Pragma("unroll") for (int k = 0; k < 2; ++k) \
;         acc[ai][bj][m][n] = __builtin_amdgcn_mfma_f32_16x16x32_bf16(Bt[n][k], At[m][k], acc[ai][bj][m][n], 0, 0, 0); __builtin_amdgcn_s_setprio(0); } while (0)
; #define PG8_WAIT_V(n) asm volatile("s_waitcnt vmcnt(" #n ")" ::: "memory")
; #define PG8_WAIT_L(n) asm volatile("s_waitcnt lgkmcnt(" #n ")" ::: "memory")
; #define PG8_BAR __builtin_amdgcn_s_barrier()
; #define PG8_SCHED __builtin_amdgcn_sched_barrier(0)
; template <class Epi, class Sched, bool ALIGN_EPI = false, bool SP2 = false>
; __device__ __forceinline__ void gemm_phase(LAS unsigned char* lds, const Gemm g, const Sched& S, const Epi& E) {
;     ...
;             PG8_LDB(B0, 1, 0); PG8_LDB(B1, 1, 1); PG8_SCHED; PG8_LDA(At, 1, 0); PG8_STAGE(PG8_SA(0, 1), a2 + hstep, voffA);
;             PG8_WAIT_V(8); PG8_WAIT_L(0); PG8_BAR; PG8_MMA(0, 0, At, B0); PG8_MMA(0, 1, At, B1); PG8_BAR; PG8_SCHED;
	s_add_i32 s41, 0, 0x18000
	s_add_i32 s42, 0, 0x1c000
	v_add_u32_e32 v164, s41, v144
	v_add_u32_e32 v180, s42, v144
	ds_read_b128 v[152:155], v164
	ds_read_b128 v[156:159], v164 offset:1024
	ds_read_b128 v[160:163], v164 offset:2048
	ds_read_b128 v[164:167], v164 offset:3072
	ds_read_b128 v[168:171], v180
	ds_read_b128 v[172:175], v180 offset:1024
	ds_read_b128 v[176:179], v180 offset:2048
	ds_read_b128 v[180:183], v180 offset:3072
	s_add_u32 s14, s20, 0x160000
	s_addc_u32 s15, s21, 0
	s_mov_b32 m0, s26
	v_lshl_add_u64 v[224:225], s[14:15], 0, v[128:129]
	ds_read_b128 v[184:187], v149 offset:32768
	ds_read_b128 v[188:191], v149 offset:33792
	ds_read_b128 v[192:195], v149 offset:34816
	ds_read_b128 v[196:199], v149 offset:35840
	ds_read_b128 v[200:203], v149 offset:36864
	ds_read_b128 v[204:207], v149 offset:37888
	ds_read_b128 v[208:211], v149 offset:38912
	ds_read_b128 v[212:215], v149 offset:39936
	global_load_lds_dwordx4 v[224:225], off
	v_lshl_add_u64 v[224:225], s[14:15], 0, v[132:133]
	s_mov_b32 m0, s27
	s_nop 0
	global_load_lds_dwordx4 v[224:225], off
	s_waitcnt vmcnt(8)
	s_waitcnt lgkmcnt(0)
	s_barrier
	s_waitcnt lgkmcnt(0)
	v_mfma_f32_16x16x32_bf16 v[124:127], v[152:155], v[184:187], v[124:127]
	v_mfma_f32_16x16x32_bf16 v[120:123], v[160:163], v[184:187], v[120:123]
	v_mfma_f32_16x16x32_bf16 v[112:115], v[152:155], v[192:195], v[112:115]
	v_mfma_f32_16x16x32_bf16 v[104:107], v[160:163], v[192:195], v[104:107]
	v_mfma_f32_16x16x32_bf16 v[92:95], v[152:155], v[200:203], v[92:95]
	v_mfma_f32_16x16x32_bf16 v[88:91], v[160:163], v[200:203], v[88:91]
	v_mfma_f32_16x16x32_bf16 v[76:79], v[152:155], v[208:211], v[76:79]
	v_mfma_f32_16x16x32_bf16 v[72:75], v[160:163], v[208:211], v[72:75]
	v_mfma_f32_16x16x32_bf16 v[124:127], v[156:159], v[188:191], v[124:127]
	v_mfma_f32_16x16x32_bf16 v[120:123], v[164:167], v[188:191], v[120:123]
	v_mfma_f32_16x16x32_bf16 v[112:115], v[156:159], v[196:199], v[112:115]
	v_mfma_f32_16x16x32_bf16 v[104:107], v[164:167], v[196:199], v[104:107]
	v_mfma_f32_16x16x32_bf16 v[92:95], v[156:159], v[204:207], v[92:95]
	v_mfma_f32_16x16x32_bf16 v[88:91], v[164:167], v[204:207], v[88:91]
	v_mfma_f32_16x16x32_bf16 v[76:79], v[156:159], v[212:215], v[76:79]
	v_mfma_f32_16x16x32_bf16 v[72:75], v[164:167], v[212:215], v[72:75]
	v_mfma_f32_16x16x32_bf16 v[116:119], v[168:171], v[184:187], v[116:119]
	v_mfma_f32_16x16x32_bf16 v[108:111], v[176:179], v[184:187], v[108:111]
	v_mfma_f32_16x16x32_bf16 v[100:103], v[168:171], v[192:195], v[100:103]
	v_mfma_f32_16x16x32_bf16 v[96:99], v[176:179], v[192:195], v[96:99]
	v_mfma_f32_16x16x32_bf16 v[84:87], v[168:171], v[200:203], v[84:87]
	v_mfma_f32_16x16x32_bf16 v[80:83], v[176:179], v[200:203], v[80:83]
	v_mfma_f32_16x16x32_bf16 v[68:71], v[168:171], v[208:211], v[68:71]
	v_mfma_f32_16x16x32_bf16 v[64:67], v[176:179], v[208:211], v[64:67]
	v_mfma_f32_16x16x32_bf16 v[116:119], v[172:175], v[188:191], v[116:119]
	v_mfma_f32_16x16x32_bf16 v[108:111], v[180:183], v[188:191], v[108:111]
	v_mfma_f32_16x16x32_bf16 v[100:103], v[172:175], v[196:199], v[100:103]
	v_mfma_f32_16x16x32_bf16 v[96:99], v[180:183], v[196:199], v[96:99]
	v_mfma_f32_16x16x32_bf16 v[84:87], v[172:175], v[204:207], v[84:87]
	v_mfma_f32_16x16x32_bf16 v[80:83], v[180:183], v[204:207], v[80:83]
	v_mfma_f32_16x16x32_bf16 v[68:71], v[172:175], v[212:215], v[68:71]
	v_mfma_f32_16x16x32_bf16 v[64:67], v[180:183], v[212:215], v[64:67]
	s_barrier
; #define PG8_STAGE(bufoff, gbase, voff) do { _Pragma("unroll") for (int _i = 0; _i < 2; ++_i) \
;         __builtin_amdgcn_global_load_lds((const unsigned*)((const char*)(gbase) + (voff)[_i]), (LAS unsigned*)(lds + (bufoff) + ldsw + _i * 8192), 16, 0, 0); } while (0)
; #define PG8_LDA(dst, b, h) do { _Pragma("unroll") for (int m = 0; m < 4; ++m) _Pragma("unroll") for (int k = 0; k < 2; ++k) dst[m][k] = *(const LAS bf16x8*)(lds + PG8_SA(b, h) + aoff + m * 2048 + k * 1024); } while (0)
; #define PG8_MMA(ai, bj, At, Bt) do { __builtin_amdgcn_s_setprio(1); _Pragma("unroll") for (int m = 0; m < 4; ++m) _Pragma("unroll") for (int n = 0; n < 2; ++n) _Pragma("unroll") for (int k = 0; k < 2; ++k) \
;         acc[ai][bj][m][n] = __builtin_amdgcn_mfma_f32_16x16x32_bf16(Bt[n][k], At[m][k], acc[ai][bj][m][n], 0, 0, 0); __builtin_amdgcn_s_setprio(0); } while (0)
; #define PG8_WAIT_V(n) asm volatile("s_waitcnt vmcnt(" #n ")" ::: "memory")
; #define PG8_WAIT_L(n) asm volatile("s_waitcnt lgkmcnt(" #n ")" ::: "memory")
; #define PG8_BAR __builtin_amdgcn_s_barrier()
; #define PG8_SCHED __builtin_amdgcn_sched_barrier(0)
; template <class Epi, class Sched, bool ALIGN_EPI = false, bool SP2 = false>
; __device__ __forceinline__ void gemm_phase(LAS unsigned char* lds, const Gemm g, const Sched& S, const Epi& E) {
;     ...
;         for (int t = 0; t < nt; t += 2) {
;     ...
;             PG8_LDA(At, 1, 1); PG8_STAGE(PG8_SB(1, 0), b3, voffB); PG8_STAGE(PG8_SB(1, 1), b3 + hstepB, voffB); PG8_STAGE(PG8_SA(1, 0), a3, voffA);
;             PG8_WAIT_V(8); PG8_WAIT_L(0); PG8_BAR; PG8_MMA(1, 0, At, B0); PG8_MMA(1, 1, At, B1); PG8_BAR; PG8_SCHED;
;     ...
;         if constexpr (ALIGN_EPI) { if (wr == 0) PG8_BAR; }
	s_add_i32 s14, s41, s23
	v_lshl_add_u64 v[216:217], v[216:217], 0, s[6:7]
	s_mov_b32 m0, s14
	ds_read_b128 v[184:187], v149 offset:49152
	ds_read_b128 v[188:191], v149 offset:50176
	ds_read_b128 v[192:195], v149 offset:51200
	ds_read_b128 v[196:199], v149 offset:52224
	ds_read_b128 v[200:203], v149 offset:53248
	ds_read_b128 v[204:207], v149 offset:54272
	ds_read_b128 v[208:211], v149 offset:55296
	ds_read_b128 v[212:215], v149 offset:56320
	global_load_lds_dwordx4 v[216:217], off
	s_add_i32 m0, s14, 0x2000
	s_add_u32 s14, s18, 0x58080
	v_lshl_add_u64 v[216:217], v[218:219], 0, s[6:7]
	s_addc_u32 s15, s19, 0
	s_add_i32 s18, s42, s23
	global_load_lds_dwordx4 v[216:217], off
	v_lshl_add_u64 v[216:217], s[14:15], 0, v[130:131]
	s_mov_b32 m0, s18
	s_nop 0
	global_load_lds_dwordx4 v[216:217], off
	v_lshl_add_u64 v[216:217], s[14:15], 0, v[134:135]
	s_add_i32 m0, s18, 0x2000
	s_nop 0
	global_load_lds_dwordx4 v[216:217], off
	v_lshl_add_u64 v[216:217], v[220:221], 0, s[6:7]
	s_mov_b32 m0, s31
	s_nop 0
	global_load_lds_dwordx4 v[216:217], off
	v_lshl_add_u64 v[216:217], v[222:223], 0, s[6:7]
	s_mov_b32 m0, s33
	s_nop 0
	global_load_lds_dwordx4 v[216:217], off
	s_waitcnt vmcnt(8)
	s_waitcnt lgkmcnt(0)
	s_barrier
	s_waitcnt lgkmcnt(0)
	v_mfma_f32_16x16x32_bf16 v[60:63], v[152:155], v[184:187], v[60:63]
	v_mfma_f32_16x16x32_bf16 v[56:59], v[160:163], v[184:187], v[56:59]
	v_mfma_f32_16x16x32_bf16 v[44:47], v[152:155], v[192:195], v[44:47]
	v_mfma_f32_16x16x32_bf16 v[40:43], v[160:163], v[192:195], v[40:43]
	v_mfma_f32_16x16x32_bf16 v[28:31], v[152:155], v[200:203], v[28:31]
	v_mfma_f32_16x16x32_bf16 v[24:27], v[160:163], v[200:203], v[24:27]
	v_mfma_f32_16x16x32_bf16 v[12:15], v[152:155], v[208:211], v[12:15]
	v_mfma_f32_16x16x32_bf16 v[8:11], v[160:163], v[208:211], v[8:11]
	v_mfma_f32_16x16x32_bf16 v[60:63], v[156:159], v[188:191], v[60:63]
	v_mfma_f32_16x16x32_bf16 v[56:59], v[164:167], v[188:191], v[56:59]
	v_mfma_f32_16x16x32_bf16 v[44:47], v[156:159], v[196:199], v[44:47]
	v_mfma_f32_16x16x32_bf16 v[40:43], v[164:167], v[196:199], v[40:43]
	v_mfma_f32_16x16x32_bf16 v[28:31], v[156:159], v[204:207], v[28:31]
	v_mfma_f32_16x16x32_bf16 v[24:27], v[164:167], v[204:207], v[24:27]
	v_mfma_f32_16x16x32_bf16 v[12:15], v[156:159], v[212:215], v[12:15]
	v_mfma_f32_16x16x32_bf16 v[8:11], v[164:167], v[212:215], v[8:11]
	v_mfma_f32_16x16x32_bf16 v[52:55], v[168:171], v[184:187], v[52:55]
	v_mfma_f32_16x16x32_bf16 v[48:51], v[176:179], v[184:187], v[48:51]
	v_mfma_f32_16x16x32_bf16 v[36:39], v[168:171], v[192:195], v[36:39]
	v_mfma_f32_16x16x32_bf16 v[32:35], v[176:179], v[192:195], v[32:35]
	v_mfma_f32_16x16x32_bf16 v[20:23], v[168:171], v[200:203], v[20:23]
	v_mfma_f32_16x16x32_bf16 v[16:19], v[176:179], v[200:203], v[16:19]
	v_mfma_f32_16x16x32_bf16 v[4:7], v[168:171], v[208:211], v[4:7]
	v_mfma_f32_16x16x32_bf16 v[0:3], v[176:179], v[208:211], v[0:3]
	v_mfma_f32_16x16x32_bf16 v[52:55], v[172:175], v[188:191], v[52:55]
	v_mfma_f32_16x16x32_bf16 v[48:51], v[180:183], v[188:191], v[48:51]
	v_mfma_f32_16x16x32_bf16 v[36:39], v[172:175], v[196:199], v[36:39]
	v_mfma_f32_16x16x32_bf16 v[32:35], v[180:183], v[196:199], v[32:35]
	v_mfma_f32_16x16x32_bf16 v[20:23], v[172:175], v[204:207], v[20:23]
	v_mfma_f32_16x16x32_bf16 v[16:19], v[180:183], v[204:207], v[16:19]
	v_mfma_f32_16x16x32_bf16 v[4:7], v[172:175], v[212:215], v[4:7]
	v_mfma_f32_16x16x32_bf16 v[0:3], v[180:183], v[212:215], v[0:3]
	s_barrier
	s_add_i32 s40, s40, 2
	s_add_u32 s13, s13, 0x100
	s_addc_u32 s39, s39, 0
	s_cmpk_lt_u32 s40, 0x56
	s_mov_b64 s[14:15], s[16:17]
	s_cbranch_scc1 .LBB0_3002
	s_setprio 0
	s_andn2_b64 vcc, exec, s[8:9]
	s_cbranch_vccnz .LBB0_3005
	s_barrier
